# tail_gemm K sections restaged through LDS: coalesced global_load_lds (4 lanes per 64B row segment instead of 16 rows per 16-lane group) + ds_read_b128 fragments, 2-deep, per-wave LDS region; plus v16
# speedup vs baseline: 1.0190x; 1.0190x over previous
.LBB0_122:
	v_lshrrev_b32_e32 v122, 2, v214
	v_and_b32_e32 v123, 15, v214
	v_sub_u32_e32 v122, v122, v123
	v_mul_i32_i24_e32 v122, 0x1000, v122
	v_bfe_u32 v125, v214, 5, 1
	v_lshlrev_b32_e32 v125, 1, v125
	v_and_b32_e32 v124, 3, v214
	v_xor_b32_e32 v125, v125, v124
	v_lshrrev_b32_e32 v124, 4, v214
	v_sub_u32_e32 v125, v125, v124
	v_lshl_add_u32 v122, v125, 4, v122
	v_ashrrev_i32_e32 v125, 31, v122
	v_add_co_u32_e32 v118, vcc, v66, v122
	s_nop 1
	v_addc_co_u32_e32 v119, vcc, v67, v125, vcc
	v_add_co_u32_e32 v120, vcc, v64, v122
	s_nop 1
	v_addc_co_u32_e32 v121, vcc, v65, v125, vcc
	v_add_co_u32_e32 v82, vcc, s84, v118
	s_nop 1
	v_addc_co_u32_e32 v83, vcc, 0, v119, vcc
	v_add_co_u32_e32 v104, vcc, s85, v118
	s_nop 1
	v_addc_co_u32_e32 v105, vcc, 0, v119, vcc
	v_add_co_u32_e32 v106, vcc, s88, v118
	s_nop 1
	v_addc_co_u32_e32 v107, vcc, 0, v119, vcc
	v_add_co_u32_e32 v108, vcc, s89, v118
	s_nop 1
	v_addc_co_u32_e32 v109, vcc, 0, v119, vcc
	v_add_co_u32_e32 v110, vcc, 0x5808000, v120
	s_nop 1
	v_addc_co_u32_e32 v111, vcc, 0, v121, vcc
	v_add_co_u32_e32 v112, vcc, 0x5818000, v120
	s_nop 1
	v_addc_co_u32_e32 v113, vcc, 0, v121, vcc
	v_add_co_u32_e32 v114, vcc, 0x5888000, v120
	s_nop 1
	v_addc_co_u32_e32 v115, vcc, 0, v121, vcc
	v_add_co_u32_e32 v116, vcc, 0x5898000, v120
	s_nop 1
	v_addc_co_u32_e32 v117, vcc, 0, v121, vcc
	v_readfirstlane_b32 vcc_lo, v210
	v_bfe_u32 v125, v214, 3, 1
	v_lshlrev_b32_e32 v125, 1, v125
	v_xor_b32_e32 v125, v125, v124
	v_lshlrev_b32_e32 v125, 4, v125
	v_lshl_add_u32 v125, v123, 6, v125
	s_lshr_b32 vcc_lo, vcc_lo, 6
	s_lshl_b32 vcc_lo, vcc_lo, 14
	s_mov_b32 s94, 64
	v_add_u32_e32 v124, vcc_lo, v125
	s_add_i32 m0, vcc_lo, 0x0
	s_nop 0
	global_load_lds_dwordx4 v[82:83], off
	v_lshl_add_u64 v[82:83], v[82:83], 0, s[94:95]
	s_add_i32 m0, vcc_lo, 0x400
	s_nop 0
	global_load_lds_dwordx4 v[104:105], off
	v_lshl_add_u64 v[104:105], v[104:105], 0, s[94:95]
	s_add_i32 m0, vcc_lo, 0x800
	s_nop 0
	global_load_lds_dwordx4 v[106:107], off
	v_lshl_add_u64 v[106:107], v[106:107], 0, s[94:95]
	s_add_i32 m0, vcc_lo, 0xc00
	s_nop 0
	global_load_lds_dwordx4 v[108:109], off
	v_lshl_add_u64 v[108:109], v[108:109], 0, s[94:95]
	s_add_i32 m0, vcc_lo, 0x1000
	s_nop 0
	global_load_lds_dwordx4 v[110:111], off
	v_lshl_add_u64 v[110:111], v[110:111], 0, s[94:95]
	s_add_i32 m0, vcc_lo, 0x1400
	s_nop 0
	global_load_lds_dwordx4 v[112:113], off
	v_lshl_add_u64 v[112:113], v[112:113], 0, s[94:95]
	s_add_i32 m0, vcc_lo, 0x1800
	s_nop 0
	global_load_lds_dwordx4 v[114:115], off
	v_lshl_add_u64 v[114:115], v[114:115], 0, s[94:95]
	s_add_i32 m0, vcc_lo, 0x1c00
	s_nop 0
	global_load_lds_dwordx4 v[116:117], off
	v_lshl_add_u64 v[116:117], v[116:117], 0, s[94:95]
	s_add_i32 m0, vcc_lo, 0x2000
	s_nop 0
	global_load_lds_dwordx4 v[82:83], off
	v_lshl_add_u64 v[82:83], v[82:83], 0, s[94:95]
	s_add_i32 m0, vcc_lo, 0x2400
	s_nop 0
	global_load_lds_dwordx4 v[104:105], off
	v_lshl_add_u64 v[104:105], v[104:105], 0, s[94:95]
	s_add_i32 m0, vcc_lo, 0x2800
	s_nop 0
	global_load_lds_dwordx4 v[106:107], off
	v_lshl_add_u64 v[106:107], v[106:107], 0, s[94:95]
	s_add_i32 m0, vcc_lo, 0x2c00
	s_nop 0
	global_load_lds_dwordx4 v[108:109], off
	v_lshl_add_u64 v[108:109], v[108:109], 0, s[94:95]
	s_add_i32 m0, vcc_lo, 0x3000
	s_nop 0
	global_load_lds_dwordx4 v[110:111], off
	v_lshl_add_u64 v[110:111], v[110:111], 0, s[94:95]
	s_add_i32 m0, vcc_lo, 0x3400
	s_nop 0
	global_load_lds_dwordx4 v[112:113], off
	v_lshl_add_u64 v[112:113], v[112:113], 0, s[94:95]
	s_add_i32 m0, vcc_lo, 0x3800
	s_nop 0
	global_load_lds_dwordx4 v[114:115], off
	v_lshl_add_u64 v[114:115], v[114:115], 0, s[94:95]
	s_add_i32 m0, vcc_lo, 0x3c00
	s_nop 0
	global_load_lds_dwordx4 v[116:117], off
	v_lshl_add_u64 v[116:117], v[116:117], 0, s[94:95]
	s_waitcnt vmcnt(8)
	ds_read_b128 v[68:71], v124
	ds_read_b128 v[72:75], v124 offset:1024
	ds_read_b128 v[76:79], v124 offset:2048
	ds_read_b128 v[84:87], v124 offset:3072
	ds_read_b128 v[88:91], v124 offset:4096
	ds_read_b128 v[92:95], v124 offset:5120
	ds_read_b128 v[96:99], v124 offset:6144
	ds_read_b128 v[100:103], v124 offset:7168
	s_waitcnt lgkmcnt(0)
	s_add_i32 m0, vcc_lo, 0x0
	s_nop 0
	global_load_lds_dwordx4 v[82:83], off
	v_lshl_add_u64 v[82:83], v[82:83], 0, s[94:95]
	s_add_i32 m0, vcc_lo, 0x400
	s_nop 0
	global_load_lds_dwordx4 v[104:105], off
	v_lshl_add_u64 v[104:105], v[104:105], 0, s[94:95]
	s_add_i32 m0, vcc_lo, 0x800
	s_nop 0
	global_load_lds_dwordx4 v[106:107], off
	v_lshl_add_u64 v[106:107], v[106:107], 0, s[94:95]
	s_add_i32 m0, vcc_lo, 0xc00
	s_nop 0
	global_load_lds_dwordx4 v[108:109], off
	v_lshl_add_u64 v[108:109], v[108:109], 0, s[94:95]
	s_add_i32 m0, vcc_lo, 0x1000
	s_nop 0
	global_load_lds_dwordx4 v[110:111], off
	v_lshl_add_u64 v[110:111], v[110:111], 0, s[94:95]
	s_add_i32 m0, vcc_lo, 0x1400
	s_nop 0
	global_load_lds_dwordx4 v[112:113], off
	v_lshl_add_u64 v[112:113], v[112:113], 0, s[94:95]
	s_add_i32 m0, vcc_lo, 0x1800
	s_nop 0
	global_load_lds_dwordx4 v[114:115], off
	v_lshl_add_u64 v[114:115], v[114:115], 0, s[94:95]
	s_add_i32 m0, vcc_lo, 0x1c00
	s_nop 0
	global_load_lds_dwordx4 v[116:117], off
	v_lshl_add_u64 v[116:117], v[116:117], 0, s[94:95]
	v_mfma_f32_16x16x32_bf16 v[56:59], v[88:91], v[68:71], 0
	v_mfma_f32_16x16x32_bf16 v[52:55], v[88:91], v[72:75], 0
	v_mfma_f32_16x16x32_bf16 v[48:51], v[88:91], v[76:79], 0
	v_mfma_f32_16x16x32_bf16 v[44:47], v[88:91], v[84:87], 0
	v_mfma_f32_16x16x32_bf16 v[12:15], v[92:95], v[68:71], 0
	v_mfma_f32_16x16x32_bf16 v[8:11], v[92:95], v[72:75], 0
	v_mfma_f32_16x16x32_bf16 v[4:7], v[92:95], v[76:79], 0
	v_mfma_f32_16x16x32_bf16 v[0:3], v[92:95], v[84:87], 0
	v_mfma_f32_16x16x32_bf16 v[16:19], v[96:99], v[68:71], 0
	v_mfma_f32_16x16x32_bf16 v[24:27], v[96:99], v[72:75], 0
	v_mfma_f32_16x16x32_bf16 v[28:31], v[96:99], v[76:79], 0
	v_mfma_f32_16x16x32_bf16 v[36:39], v[96:99], v[84:87], 0
	v_mfma_f32_16x16x32_bf16 v[20:23], v[100:103], v[68:71], 0
	v_mfma_f32_16x16x32_bf16 v[32:35], v[100:103], v[72:75], 0
	v_mfma_f32_16x16x32_bf16 v[40:43], v[100:103], v[76:79], 0
	v_mfma_f32_16x16x32_bf16 v[60:63], v[100:103], v[84:87], 0
	s_waitcnt vmcnt(8)
	ds_read_b128 v[68:71], v124 offset:8192
	ds_read_b128 v[72:75], v124 offset:9216
	ds_read_b128 v[76:79], v124 offset:10240
	ds_read_b128 v[84:87], v124 offset:11264
	ds_read_b128 v[88:91], v124 offset:12288
	ds_read_b128 v[92:95], v124 offset:13312
	ds_read_b128 v[96:99], v124 offset:14336
	ds_read_b128 v[100:103], v124 offset:15360
	s_waitcnt lgkmcnt(0)
	s_add_i32 m0, vcc_lo, 0x2000
	s_nop 0
	global_load_lds_dwordx4 v[82:83], off
	v_lshl_add_u64 v[82:83], v[82:83], 0, s[94:95]
	s_add_i32 m0, vcc_lo, 0x2400
	s_nop 0
	global_load_lds_dwordx4 v[104:105], off
	v_lshl_add_u64 v[104:105], v[104:105], 0, s[94:95]
	s_add_i32 m0, vcc_lo, 0x2800
	s_nop 0
	global_load_lds_dwordx4 v[106:107], off
	v_lshl_add_u64 v[106:107], v[106:107], 0, s[94:95]
	s_add_i32 m0, vcc_lo, 0x2c00
	s_nop 0
	global_load_lds_dwordx4 v[108:109], off
	v_lshl_add_u64 v[108:109], v[108:109], 0, s[94:95]
	s_add_i32 m0, vcc_lo, 0x3000
	s_nop 0
	global_load_lds_dwordx4 v[110:111], off
	v_lshl_add_u64 v[110:111], v[110:111], 0, s[94:95]
	s_add_i32 m0, vcc_lo, 0x3400
	s_nop 0
	global_load_lds_dwordx4 v[112:113], off
	v_lshl_add_u64 v[112:113], v[112:113], 0, s[94:95]
	s_add_i32 m0, vcc_lo, 0x3800
	s_nop 0
	global_load_lds_dwordx4 v[114:115], off
	v_lshl_add_u64 v[114:115], v[114:115], 0, s[94:95]
	s_add_i32 m0, vcc_lo, 0x3c00
	s_nop 0
	global_load_lds_dwordx4 v[116:117], off
	v_lshl_add_u64 v[116:117], v[116:117], 0, s[94:95]
	v_mfma_f32_16x16x32_bf16 v[56:59], v[88:91], v[68:71], v[56:59]
	v_mfma_f32_16x16x32_bf16 v[52:55], v[88:91], v[72:75], v[52:55]
	v_mfma_f32_16x16x32_bf16 v[48:51], v[88:91], v[76:79], v[48:51]
	v_mfma_f32_16x16x32_bf16 v[44:47], v[88:91], v[84:87], v[44:47]
	v_mfma_f32_16x16x32_bf16 v[12:15], v[92:95], v[68:71], v[12:15]
	v_mfma_f32_16x16x32_bf16 v[8:11], v[92:95], v[72:75], v[8:11]
	v_mfma_f32_16x16x32_bf16 v[4:7], v[92:95], v[76:79], v[4:7]
	v_mfma_f32_16x16x32_bf16 v[0:3], v[92:95], v[84:87], v[0:3]
	v_mfma_f32_16x16x32_bf16 v[16:19], v[96:99], v[68:71], v[16:19]
	v_mfma_f32_16x16x32_bf16 v[24:27], v[96:99], v[72:75], v[24:27]
	v_mfma_f32_16x16x32_bf16 v[28:31], v[96:99], v[76:79], v[28:31]
	v_mfma_f32_16x16x32_bf16 v[36:39], v[96:99], v[84:87], v[36:39]
	v_mfma_f32_16x16x32_bf16 v[20:23], v[100:103], v[68:71], v[20:23]
	v_mfma_f32_16x16x32_bf16 v[32:35], v[100:103], v[72:75], v[32:35]
	v_mfma_f32_16x16x32_bf16 v[40:43], v[100:103], v[76:79], v[40:43]
	v_mfma_f32_16x16x32_bf16 v[60:63], v[100:103], v[84:87], v[60:63]
	s_waitcnt vmcnt(8)
	ds_read_b128 v[68:71], v124
	ds_read_b128 v[72:75], v124 offset:1024
	ds_read_b128 v[76:79], v124 offset:2048
	ds_read_b128 v[84:87], v124 offset:3072
	ds_read_b128 v[88:91], v124 offset:4096
	ds_read_b128 v[92:95], v124 offset:5120
	ds_read_b128 v[96:99], v124 offset:6144
	ds_read_b128 v[100:103], v124 offset:7168
	s_waitcnt lgkmcnt(0)
	s_add_i32 m0, vcc_lo, 0x0
	s_nop 0
	global_load_lds_dwordx4 v[82:83], off
	v_lshl_add_u64 v[82:83], v[82:83], 0, s[94:95]
	s_add_i32 m0, vcc_lo, 0x400
	s_nop 0
	global_load_lds_dwordx4 v[104:105], off
	v_lshl_add_u64 v[104:105], v[104:105], 0, s[94:95]
	s_add_i32 m0, vcc_lo, 0x800
	s_nop 0
	global_load_lds_dwordx4 v[106:107], off
	v_lshl_add_u64 v[106:107], v[106:107], 0, s[94:95]
	s_add_i32 m0, vcc_lo, 0xc00
	s_nop 0
	global_load_lds_dwordx4 v[108:109], off
	v_lshl_add_u64 v[108:109], v[108:109], 0, s[94:95]
	s_add_i32 m0, vcc_lo, 0x1000
	s_nop 0
	global_load_lds_dwordx4 v[110:111], off
	v_lshl_add_u64 v[110:111], v[110:111], 0, s[94:95]
	s_add_i32 m0, vcc_lo, 0x1400
	s_nop 0
	global_load_lds_dwordx4 v[112:113], off
	v_lshl_add_u64 v[112:113], v[112:113], 0, s[94:95]
	s_add_i32 m0, vcc_lo, 0x1800
	s_nop 0
	global_load_lds_dwordx4 v[114:115], off
	v_lshl_add_u64 v[114:115], v[114:115], 0, s[94:95]
	s_add_i32 m0, vcc_lo, 0x1c00
	s_nop 0
	global_load_lds_dwordx4 v[116:117], off
	v_lshl_add_u64 v[116:117], v[116:117], 0, s[94:95]
	v_mfma_f32_16x16x32_bf16 v[56:59], v[88:91], v[68:71], v[56:59]
	v_mfma_f32_16x16x32_bf16 v[52:55], v[88:91], v[72:75], v[52:55]
	v_mfma_f32_16x16x32_bf16 v[48:51], v[88:91], v[76:79], v[48:51]
	v_mfma_f32_16x16x32_bf16 v[44:47], v[88:91], v[84:87], v[44:47]
	v_mfma_f32_16x16x32_bf16 v[12:15], v[92:95], v[68:71], v[12:15]
	v_mfma_f32_16x16x32_bf16 v[8:11], v[92:95], v[72:75], v[8:11]
	v_mfma_f32_16x16x32_bf16 v[4:7], v[92:95], v[76:79], v[4:7]
	v_mfma_f32_16x16x32_bf16 v[0:3], v[92:95], v[84:87], v[0:3]
	v_mfma_f32_16x16x32_bf16 v[16:19], v[96:99], v[68:71], v[16:19]
	v_mfma_f32_16x16x32_bf16 v[24:27], v[96:99], v[72:75], v[24:27]
	v_mfma_f32_16x16x32_bf16 v[28:31], v[96:99], v[76:79], v[28:31]
	v_mfma_f32_16x16x32_bf16 v[36:39], v[96:99], v[84:87], v[36:39]
	v_mfma_f32_16x16x32_bf16 v[20:23], v[100:103], v[68:71], v[20:23]
	v_mfma_f32_16x16x32_bf16 v[32:35], v[100:103], v[72:75], v[32:35]
	v_mfma_f32_16x16x32_bf16 v[40:43], v[100:103], v[76:79], v[40:43]
	v_mfma_f32_16x16x32_bf16 v[60:63], v[100:103], v[84:87], v[60:63]
	s_waitcnt vmcnt(8)
	ds_read_b128 v[68:71], v124 offset:8192
	ds_read_b128 v[72:75], v124 offset:9216
	ds_read_b128 v[76:79], v124 offset:10240
	ds_read_b128 v[84:87], v124 offset:11264
	ds_read_b128 v[88:91], v124 offset:12288
	ds_read_b128 v[92:95], v124 offset:13312
	ds_read_b128 v[96:99], v124 offset:14336
	ds_read_b128 v[100:103], v124 offset:15360
	s_waitcnt lgkmcnt(0)
	s_add_i32 m0, vcc_lo, 0x2000
	s_nop 0
	global_load_lds_dwordx4 v[82:83], off
	v_lshl_add_u64 v[82:83], v[82:83], 0, s[94:95]
	s_add_i32 m0, vcc_lo, 0x2400
	s_nop 0
	global_load_lds_dwordx4 v[104:105], off
	v_lshl_add_u64 v[104:105], v[104:105], 0, s[94:95]
	s_add_i32 m0, vcc_lo, 0x2800
	s_nop 0
	global_load_lds_dwordx4 v[106:107], off
	v_lshl_add_u64 v[106:107], v[106:107], 0, s[94:95]
	s_add_i32 m0, vcc_lo, 0x2c00
	s_nop 0
	global_load_lds_dwordx4 v[108:109], off
	v_lshl_add_u64 v[108:109], v[108:109], 0, s[94:95]
	s_add_i32 m0, vcc_lo, 0x3000
	s_nop 0
	global_load_lds_dwordx4 v[110:111], off
	v_lshl_add_u64 v[110:111], v[110:111], 0, s[94:95]
	s_add_i32 m0, vcc_lo, 0x3400
	s_nop 0
	global_load_lds_dwordx4 v[112:113], off
	v_lshl_add_u64 v[112:113], v[112:113], 0, s[94:95]
	s_add_i32 m0, vcc_lo, 0x3800
	s_nop 0
	global_load_lds_dwordx4 v[114:115], off
	v_lshl_add_u64 v[114:115], v[114:115], 0, s[94:95]
	s_add_i32 m0, vcc_lo, 0x3c00
	s_nop 0
	global_load_lds_dwordx4 v[116:117], off
	v_lshl_add_u64 v[116:117], v[116:117], 0, s[94:95]
	v_mfma_f32_16x16x32_bf16 v[56:59], v[88:91], v[68:71], v[56:59]
	v_mfma_f32_16x16x32_bf16 v[52:55], v[88:91], v[72:75], v[52:55]
	v_mfma_f32_16x16x32_bf16 v[48:51], v[88:91], v[76:79], v[48:51]
	v_mfma_f32_16x16x32_bf16 v[44:47], v[88:91], v[84:87], v[44:47]
	v_mfma_f32_16x16x32_bf16 v[12:15], v[92:95], v[68:71], v[12:15]
	v_mfma_f32_16x16x32_bf16 v[8:11], v[92:95], v[72:75], v[8:11]
	v_mfma_f32_16x16x32_bf16 v[4:7], v[92:95], v[76:79], v[4:7]
	v_mfma_f32_16x16x32_bf16 v[0:3], v[92:95], v[84:87], v[0:3]
	v_mfma_f32_16x16x32_bf16 v[16:19], v[96:99], v[68:71], v[16:19]
	v_mfma_f32_16x16x32_bf16 v[24:27], v[96:99], v[72:75], v[24:27]
	v_mfma_f32_16x16x32_bf16 v[28:31], v[96:99], v[76:79], v[28:31]
	v_mfma_f32_16x16x32_bf16 v[36:39], v[96:99], v[84:87], v[36:39]
	v_mfma_f32_16x16x32_bf16 v[20:23], v[100:103], v[68:71], v[20:23]
	v_mfma_f32_16x16x32_bf16 v[32:35], v[100:103], v[72:75], v[32:35]
	v_mfma_f32_16x16x32_bf16 v[40:43], v[100:103], v[76:79], v[40:43]
	v_mfma_f32_16x16x32_bf16 v[60:63], v[100:103], v[84:87], v[60:63]
	s_waitcnt vmcnt(8)
	ds_read_b128 v[68:71], v124
	ds_read_b128 v[72:75], v124 offset:1024
	ds_read_b128 v[76:79], v124 offset:2048
	ds_read_b128 v[84:87], v124 offset:3072
	ds_read_b128 v[88:91], v124 offset:4096
	ds_read_b128 v[92:95], v124 offset:5120
	ds_read_b128 v[96:99], v124 offset:6144
	ds_read_b128 v[100:103], v124 offset:7168
	s_waitcnt lgkmcnt(0)
	s_add_i32 m0, vcc_lo, 0x0
	s_nop 0
	global_load_lds_dwordx4 v[82:83], off
	v_lshl_add_u64 v[82:83], v[82:83], 0, s[94:95]
	s_add_i32 m0, vcc_lo, 0x400
	s_nop 0
	global_load_lds_dwordx4 v[104:105], off
	v_lshl_add_u64 v[104:105], v[104:105], 0, s[94:95]
	s_add_i32 m0, vcc_lo, 0x800
	s_nop 0
	global_load_lds_dwordx4 v[106:107], off
	v_lshl_add_u64 v[106:107], v[106:107], 0, s[94:95]
	s_add_i32 m0, vcc_lo, 0xc00
	s_nop 0
	global_load_lds_dwordx4 v[108:109], off
	v_lshl_add_u64 v[108:109], v[108:109], 0, s[94:95]
	s_add_i32 m0, vcc_lo, 0x1000
	s_nop 0
	global_load_lds_dwordx4 v[110:111], off
	v_lshl_add_u64 v[110:111], v[110:111], 0, s[94:95]
	s_add_i32 m0, vcc_lo, 0x1400
	s_nop 0
	global_load_lds_dwordx4 v[112:113], off
	v_lshl_add_u64 v[112:113], v[112:113], 0, s[94:95]
	s_add_i32 m0, vcc_lo, 0x1800
	s_nop 0
	global_load_lds_dwordx4 v[114:115], off
	v_lshl_add_u64 v[114:115], v[114:115], 0, s[94:95]
	s_add_i32 m0, vcc_lo, 0x1c00
	s_nop 0
	global_load_lds_dwordx4 v[116:117], off
	v_lshl_add_u64 v[116:117], v[116:117], 0, s[94:95]
	v_mfma_f32_16x16x32_bf16 v[56:59], v[88:91], v[68:71], v[56:59]
	v_mfma_f32_16x16x32_bf16 v[52:55], v[88:91], v[72:75], v[52:55]
	v_mfma_f32_16x16x32_bf16 v[48:51], v[88:91], v[76:79], v[48:51]
	v_mfma_f32_16x16x32_bf16 v[44:47], v[88:91], v[84:87], v[44:47]
	v_mfma_f32_16x16x32_bf16 v[12:15], v[92:95], v[68:71], v[12:15]
	v_mfma_f32_16x16x32_bf16 v[8:11], v[92:95], v[72:75], v[8:11]
	v_mfma_f32_16x16x32_bf16 v[4:7], v[92:95], v[76:79], v[4:7]
	v_mfma_f32_16x16x32_bf16 v[0:3], v[92:95], v[84:87], v[0:3]
	v_mfma_f32_16x16x32_bf16 v[16:19], v[96:99], v[68:71], v[16:19]
	v_mfma_f32_16x16x32_bf16 v[24:27], v[96:99], v[72:75], v[24:27]
	v_mfma_f32_16x16x32_bf16 v[28:31], v[96:99], v[76:79], v[28:31]
	v_mfma_f32_16x16x32_bf16 v[36:39], v[96:99], v[84:87], v[36:39]
	v_mfma_f32_16x16x32_bf16 v[20:23], v[100:103], v[68:71], v[20:23]
	v_mfma_f32_16x16x32_bf16 v[32:35], v[100:103], v[72:75], v[32:35]
	v_mfma_f32_16x16x32_bf16 v[40:43], v[100:103], v[76:79], v[40:43]
	v_mfma_f32_16x16x32_bf16 v[60:63], v[100:103], v[84:87], v[60:63]
	s_waitcnt vmcnt(8)
	ds_read_b128 v[68:71], v124 offset:8192
	ds_read_b128 v[72:75], v124 offset:9216
	ds_read_b128 v[76:79], v124 offset:10240
	ds_read_b128 v[84:87], v124 offset:11264
	ds_read_b128 v[88:91], v124 offset:12288
	ds_read_b128 v[92:95], v124 offset:13312
	ds_read_b128 v[96:99], v124 offset:14336
	ds_read_b128 v[100:103], v124 offset:15360
	s_waitcnt lgkmcnt(0)
	s_add_i32 m0, vcc_lo, 0x2000
	s_nop 0
	global_load_lds_dwordx4 v[82:83], off
	v_lshl_add_u64 v[82:83], v[82:83], 0, s[94:95]
	s_add_i32 m0, vcc_lo, 0x2400
	s_nop 0
	global_load_lds_dwordx4 v[104:105], off
	v_lshl_add_u64 v[104:105], v[104:105], 0, s[94:95]
	s_add_i32 m0, vcc_lo, 0x2800
	s_nop 0
	global_load_lds_dwordx4 v[106:107], off
	v_lshl_add_u64 v[106:107], v[106:107], 0, s[94:95]
	s_add_i32 m0, vcc_lo, 0x2c00
	s_nop 0
	global_load_lds_dwordx4 v[108:109], off
	v_lshl_add_u64 v[108:109], v[108:109], 0, s[94:95]
	s_add_i32 m0, vcc_lo, 0x3000
	s_nop 0
	global_load_lds_dwordx4 v[110:111], off
	v_lshl_add_u64 v[110:111], v[110:111], 0, s[94:95]
	s_add_i32 m0, vcc_lo, 0x3400
	s_nop 0
	global_load_lds_dwordx4 v[112:113], off
	v_lshl_add_u64 v[112:113], v[112:113], 0, s[94:95]
	s_add_i32 m0, vcc_lo, 0x3800
	s_nop 0
	global_load_lds_dwordx4 v[114:115], off
	v_lshl_add_u64 v[114:115], v[114:115], 0, s[94:95]
	s_add_i32 m0, vcc_lo, 0x3c00
	s_nop 0
	global_load_lds_dwordx4 v[116:117], off
	v_lshl_add_u64 v[116:117], v[116:117], 0, s[94:95]
	v_mfma_f32_16x16x32_bf16 v[56:59], v[88:91], v[68:71], v[56:59]
	v_mfma_f32_16x16x32_bf16 v[52:55], v[88:91], v[72:75], v[52:55]
	v_mfma_f32_16x16x32_bf16 v[48:51], v[88:91], v[76:79], v[48:51]
	v_mfma_f32_16x16x32_bf16 v[44:47], v[88:91], v[84:87], v[44:47]
	v_mfma_f32_16x16x32_bf16 v[12:15], v[92:95], v[68:71], v[12:15]
	v_mfma_f32_16x16x32_bf16 v[8:11], v[92:95], v[72:75], v[8:11]
	v_mfma_f32_16x16x32_bf16 v[4:7], v[92:95], v[76:79], v[4:7]
	v_mfma_f32_16x16x32_bf16 v[0:3], v[92:95], v[84:87], v[0:3]
	v_mfma_f32_16x16x32_bf16 v[16:19], v[96:99], v[68:71], v[16:19]
	v_mfma_f32_16x16x32_bf16 v[24:27], v[96:99], v[72:75], v[24:27]
	v_mfma_f32_16x16x32_bf16 v[28:31], v[96:99], v[76:79], v[28:31]
	v_mfma_f32_16x16x32_bf16 v[36:39], v[96:99], v[84:87], v[36:39]
	v_mfma_f32_16x16x32_bf16 v[20:23], v[100:103], v[68:71], v[20:23]
	v_mfma_f32_16x16x32_bf16 v[32:35], v[100:103], v[72:75], v[32:35]
	v_mfma_f32_16x16x32_bf16 v[40:43], v[100:103], v[76:79], v[40:43]
	v_mfma_f32_16x16x32_bf16 v[60:63], v[100:103], v[84:87], v[60:63]
	s_waitcnt vmcnt(8)
	ds_read_b128 v[68:71], v124
	ds_read_b128 v[72:75], v124 offset:1024
	ds_read_b128 v[76:79], v124 offset:2048
	ds_read_b128 v[84:87], v124 offset:3072
	ds_read_b128 v[88:91], v124 offset:4096
	ds_read_b128 v[92:95], v124 offset:5120
	ds_read_b128 v[96:99], v124 offset:6144
	ds_read_b128 v[100:103], v124 offset:7168
	s_waitcnt lgkmcnt(0)
	v_mfma_f32_16x16x32_bf16 v[56:59], v[88:91], v[68:71], v[56:59]
	v_mfma_f32_16x16x32_bf16 v[52:55], v[88:91], v[72:75], v[52:55]
	v_mfma_f32_16x16x32_bf16 v[48:51], v[88:91], v[76:79], v[48:51]
	v_mfma_f32_16x16x32_bf16 v[44:47], v[88:91], v[84:87], v[44:47]
	v_mfma_f32_16x16x32_bf16 v[12:15], v[92:95], v[68:71], v[12:15]
	v_mfma_f32_16x16x32_bf16 v[8:11], v[92:95], v[72:75], v[8:11]
	v_mfma_f32_16x16x32_bf16 v[4:7], v[92:95], v[76:79], v[4:7]
	v_mfma_f32_16x16x32_bf16 v[0:3], v[92:95], v[84:87], v[0:3]
	v_mfma_f32_16x16x32_bf16 v[16:19], v[96:99], v[68:71], v[16:19]
	v_mfma_f32_16x16x32_bf16 v[24:27], v[96:99], v[72:75], v[24:27]
	v_mfma_f32_16x16x32_bf16 v[28:31], v[96:99], v[76:79], v[28:31]
	v_mfma_f32_16x16x32_bf16 v[36:39], v[96:99], v[84:87], v[36:39]
	v_mfma_f32_16x16x32_bf16 v[20:23], v[100:103], v[68:71], v[20:23]
	v_mfma_f32_16x16x32_bf16 v[32:35], v[100:103], v[72:75], v[32:35]
	v_mfma_f32_16x16x32_bf16 v[40:43], v[100:103], v[76:79], v[40:43]
	v_mfma_f32_16x16x32_bf16 v[60:63], v[100:103], v[84:87], v[60:63]
	s_waitcnt vmcnt(0)
	ds_read_b128 v[68:71], v124 offset:8192
	ds_read_b128 v[72:75], v124 offset:9216
	ds_read_b128 v[76:79], v124 offset:10240
	ds_read_b128 v[84:87], v124 offset:11264
	ds_read_b128 v[88:91], v124 offset:12288
	ds_read_b128 v[92:95], v124 offset:13312
	ds_read_b128 v[96:99], v124 offset:14336
	ds_read_b128 v[100:103], v124 offset:15360
	s_waitcnt lgkmcnt(0)
	v_mfma_f32_16x16x32_bf16 v[56:59], v[88:91], v[68:71], v[56:59]
	v_mfma_f32_16x16x32_bf16 v[52:55], v[88:91], v[72:75], v[52:55]
	v_mfma_f32_16x16x32_bf16 v[48:51], v[88:91], v[76:79], v[48:51]
	v_mfma_f32_16x16x32_bf16 v[44:47], v[88:91], v[84:87], v[44:47]
	v_mfma_f32_16x16x32_bf16 v[12:15], v[92:95], v[68:71], v[12:15]
	v_mfma_f32_16x16x32_bf16 v[8:11], v[92:95], v[72:75], v[8:11]
	v_mfma_f32_16x16x32_bf16 v[4:7], v[92:95], v[76:79], v[4:7]
	v_mfma_f32_16x16x32_bf16 v[0:3], v[92:95], v[84:87], v[0:3]
	v_mfma_f32_16x16x32_bf16 v[16:19], v[96:99], v[68:71], v[16:19]
	v_mfma_f32_16x16x32_bf16 v[24:27], v[96:99], v[72:75], v[24:27]
	v_mfma_f32_16x16x32_bf16 v[28:31], v[96:99], v[76:79], v[28:31]
	v_mfma_f32_16x16x32_bf16 v[36:39], v[96:99], v[84:87], v[36:39]
	v_mfma_f32_16x16x32_bf16 v[20:23], v[100:103], v[68:71], v[20:23]
	v_mfma_f32_16x16x32_bf16 v[32:35], v[100:103], v[72:75], v[32:35]
	v_mfma_f32_16x16x32_bf16 v[40:43], v[100:103], v[76:79], v[40:43]
	v_mfma_f32_16x16x32_bf16 v[60:63], v[100:103], v[84:87], v[60:63]
	s_nop 7
	s_nop 3
	v_and_b32_e32 v65, 63, v81
	s_ashr_i32 s2, s4, 7
	v_lshl_add_u32 v65, v65, 4, 0
	s_lshl_b32 s3, s2, 4
	v_lshl_add_u32 v66, s5, 14, v65
	s_addk_i32 s3, 0x4000
	ds_write_b128 v66, v[56:59]
	ds_write_b128 v66, v[52:55] offset:1024
	ds_write_b128 v66, v[48:51] offset:2048
	ds_write_b128 v66, v[44:47] offset:3072
	ds_write_b128 v66, v[12:15] offset:4096
	ds_write_b128 v66, v[8:11] offset:5120
	ds_write_b128 v66, v[4:7] offset:6144
	ds_write_b128 v66, v[0:3] offset:7168
	ds_write_b128 v66, v[16:19] offset:8192
	ds_write_b128 v66, v[24:27] offset:9216
	ds_write_b128 v66, v[28:31] offset:10240
	ds_write_b128 v66, v[36:39] offset:11264
	ds_write_b128 v66, v[20:23] offset:12288
	ds_write_b128 v66, v[32:35] offset:13312
	ds_write_b128 v66, v[40:43] offset:14336
	ds_write_b128 v66, v[60:63] offset:15360
	v_or_b32_e32 v0, s3, v80
	v_ashrrev_i32_e32 v1, 31, v0
	v_bfe_u32 v64, v81, 4, 2
	v_lshlrev_b64 v[2:3], 7, v[0:1]
	v_lshl_add_u64 v[2:3], s[8:9], 0, v[2:3]
	v_lshlrev_b32_e32 v128, 5, v64
	v_lshl_add_u64 v[6:7], v[2:3], 0, v[128:129]
	s_waitcnt lgkmcnt(0)
	s_barrier
	global_load_dwordx4 v[2:5], v[6:7], off
	s_nop 0
	global_load_dwordx4 v[6:9], v[6:7], off offset:16
	s_bfe_u32 s3, s4, 0x10006
	s_lshl_b32 s4, s3, 2
	s_add_i32 s4, s4, s2
	v_lshl_add_u32 v62, s4, 10, v65
	ds_read_b128 v[10:13], v62
	ds_read_b128 v[14:17], v62 offset:8192
	ds_read_b128 v[18:21], v62 offset:16384
	ds_read_b128 v[22:25], v62 offset:24576
	ds_read_b128 v[26:29], v62 offset:32768
	ds_read_b128 v[30:33], v62 offset:40960
	ds_read_b128 v[34:37], v62 offset:49152
	ds_read_b128 v[38:41], v62 offset:57344
	s_waitcnt lgkmcnt(0)
	v_pk_add_f32 v[10:11], v[10:11], 0 op_sel_hi:[1,0]
	v_pk_add_f32 v[12:13], v[12:13], 0 op_sel_hi:[1,0]
	v_pk_add_f32 v[10:11], v[10:11], v[18:19]
	v_pk_add_f32 v[12:13], v[12:13], v[20:21]
	v_add_u32_e32 v42, 0x10000, v62
	v_add_u32_e32 v46, 0x12000, v62
	v_add_u32_e32 v50, 0x14000, v62
	v_add_u32_e32 v54, 0x16000, v62
	v_add_u32_e32 v58, 0x18000, v62
	v_add_u32_e32 v63, 0x1a000, v62
	ds_read_b128 v[42:45], v42
	ds_read_b128 v[46:49], v46
	ds_read_b128 v[50:53], v50
	ds_read_b128 v[54:57], v54
	ds_read_b128 v[58:61], v58
	ds_read_b128 v[66:69], v63
	v_pk_add_f32 v[10:11], v[10:11], v[26:27]
	v_pk_add_f32 v[14:15], v[14:15], 0 op_sel_hi:[1,0]
	v_pk_add_f32 v[10:11], v[10:11], v[34:35]
	v_pk_add_f32 v[12:13], v[12:13], v[28:29]
	s_waitcnt lgkmcnt(0)
	v_pk_add_f32 v[10:11], v[10:11], v[42:43]
	v_pk_add_f32 v[16:17], v[16:17], 0 op_sel_hi:[1,0]
	v_pk_add_f32 v[10:11], v[10:11], v[50:51]
	v_pk_add_f32 v[14:15], v[14:15], v[22:23]
	v_pk_add_f32 v[10:11], v[10:11], v[58:59]
	v_pk_add_f32 v[12:13], v[12:13], v[36:37]
	v_pk_add_f32 v[16:17], v[16:17], v[24:25]
	v_pk_add_f32 v[14:15], v[14:15], v[30:31]
	v_pk_add_f32 v[12:13], v[12:13], v[44:45]
	v_pk_add_f32 v[16:17], v[16:17], v[32:33]
	v_pk_add_f32 v[14:15], v[14:15], v[38:39]
	v_pk_add_f32 v[12:13], v[12:13], v[52:53]
	v_pk_add_f32 v[16:17], v[16:17], v[40:41]
	v_pk_add_f32 v[14:15], v[14:15], v[46:47]
	v_pk_add_f32 v[12:13], v[12:13], v[60:61]
	v_pk_add_f32 v[16:17], v[16:17], v[48:49]
	v_pk_add_f32 v[14:15], v[14:15], v[54:55]
	v_lshlrev_b64 v[0:1], 12, v[0:1]
	s_and_b32 s0, s0, 0x700
	v_pk_add_f32 v[16:17], v[16:17], v[56:57]
	v_pk_add_f32 v[14:15], v[14:15], v[66:67]
	v_lshl_add_u64 v[0:1], s[6:7], 0, v[0:1]
	s_lshl_b32 s94, s0, 1
	v_pk_add_f32 v[16:17], v[16:17], v[68:69]
	v_lshl_add_u64 v[0:1], v[0:1], 0, s[94:95]
	s_waitcnt vmcnt(0)
	v_mov_b32_e32 v18, v2
	v_mov_b32_e32 v19, v6
	v_mov_b32_e32 v6, v3
	v_pk_add_f32 v[2:3], v[18:19], v[6:7]
	v_mov_b32_e32 v6, v4
	v_mov_b32_e32 v7, v8
	v_mov_b32_e32 v8, v5
	v_pk_add_f32 v[4:5], v[6:7], v[8:9]
	v_add_u32_e32 v6, 0x1e000, v62
	v_pk_add_f32 v[2:3], v[2:3], v[4:5]
	s_nop 0
	v_add_f32_e32 v18, v2, v3
	v_and_b32_e32 v3, 64, v214
	v_xor_b32_e32 v2, 16, v214
	v_add_u32_e32 v19, 64, v3
	v_cmp_lt_i32_e32 vcc, v2, v19
	s_nop 1
	v_cndmask_b32_e32 v2, v214, v2, vcc
	v_lshlrev_b32_e32 v2, 2, v2
	ds_bpermute_b32 v20, v2, v18
	v_add_u32_e32 v2, 0x1c000, v62
	ds_read_b128 v[2:5], v2
	ds_read_b128 v[6:9], v6
	s_waitcnt lgkmcnt(2)
	v_add_f32_e32 v18, v18, v20
	v_xor_b32_e32 v20, 32, v214
	v_cmp_lt_i32_e32 vcc, v20, v19
	s_waitcnt lgkmcnt(1)
	v_pk_add_f32 v[2:3], v[10:11], v[2:3]
	v_pk_add_f32 v[4:5], v[12:13], v[4:5]
	v_cndmask_b32_e32 v19, v214, v20, vcc
	v_lshlrev_b32_e32 v19, 2, v19
	ds_bpermute_b32 v19, v19, v18
	s_waitcnt lgkmcnt(1)
	v_pk_add_f32 v[6:7], v[14:15], v[6:7]
	v_pk_add_f32 v[8:9], v[16:17], v[8:9]
	s_waitcnt lgkmcnt(0)
	v_add_f32_e32 v10, v18, v19
	v_fmamk_f32 v10, v10, 0x3a000000, v190
	v_mul_f32_e32 v11, 0x4b800000, v10
	v_cmp_gt_f32_e32 vcc, s70, v10
	s_nop 1
	v_cndmask_b32_e32 v10, v10, v11, vcc
	v_rsq_f32_e32 v10, v10
	v_lshlrev_b32_e32 v11, 2, v64
	v_lshl_or_b32 v11, s3, 4, v11
	v_or_b32_e32 v11, s1, v11
	v_mul_f32_e32 v12, 0x45800000, v10
	v_cndmask_b32_e32 v10, v10, v12, vcc
	v_lshlrev_b32_e32 v128, 1, v11
	v_pk_mul_f32 v[4:5], v[4:5], v[10:11] op_sel_hi:[1,0]
	v_pk_mul_f32 v[2:3], v[2:3], v[10:11] op_sel_hi:[1,0]
	v_lshl_add_u64 v[0:1], v[0:1], 0, v[128:129]
	v_cvt_pk_bf16_f32 v2, v2, v3
	v_cvt_pk_bf16_f32 v3, v4, v5
	v_pk_mul_f32 v[4:5], v[6:7], v[10:11] op_sel_hi:[1,0]
	global_store_dwordx2 v[0:1], v[2:3], off
	v_pk_mul_f32 v[2:3], v[8:9], v[10:11] op_sel_hi:[1,0]
	v_cvt_pk_bf16_f32 v4, v4, v5
	s_nop 0
	v_cvt_pk_bf16_f32 v5, v2, v3
	global_store_dwordx2 v[0:1], v[4:5], off offset:256
	s_waitcnt lgkmcnt(0)
	s_barrier

.LBB0_199:
	v_lshrrev_b32_e32 v122, 2, v214
	v_and_b32_e32 v123, 15, v214
	v_sub_u32_e32 v122, v122, v123
	v_mul_i32_i24_e32 v122, 0x1000, v122
	v_bfe_u32 v125, v214, 5, 1
	v_lshlrev_b32_e32 v125, 1, v125
	v_and_b32_e32 v124, 3, v214
	v_xor_b32_e32 v125, v125, v124
	v_lshrrev_b32_e32 v124, 4, v214
	v_sub_u32_e32 v125, v125, v124
	v_lshl_add_u32 v122, v125, 4, v122
	v_ashrrev_i32_e32 v125, 31, v122
	v_add_co_u32_e32 v118, vcc, v66, v122
	s_nop 1
	v_addc_co_u32_e32 v119, vcc, v67, v125, vcc
	v_add_co_u32_e32 v120, vcc, v64, v122
	s_nop 1
	v_addc_co_u32_e32 v121, vcc, v65, v125, vcc
	v_add_co_u32_e32 v82, vcc, s84, v118
	s_nop 1
	v_addc_co_u32_e32 v83, vcc, 0, v119, vcc
	v_add_co_u32_e32 v104, vcc, s85, v118
	s_nop 1
	v_addc_co_u32_e32 v105, vcc, 0, v119, vcc
	v_add_co_u32_e32 v106, vcc, s88, v118
	s_nop 1
	v_addc_co_u32_e32 v107, vcc, 0, v119, vcc
	v_add_co_u32_e32 v108, vcc, s89, v118
	s_nop 1
	v_addc_co_u32_e32 v109, vcc, 0, v119, vcc
	v_add_co_u32_e32 v110, vcc, 0x4008000, v120
	s_nop 1
	v_addc_co_u32_e32 v111, vcc, 0, v121, vcc
	v_add_co_u32_e32 v112, vcc, 0x4018000, v120
	s_nop 1
	v_addc_co_u32_e32 v113, vcc, 0, v121, vcc
	v_add_co_u32_e32 v114, vcc, 0x4088000, v120
	s_nop 1
	v_addc_co_u32_e32 v115, vcc, 0, v121, vcc
	v_add_co_u32_e32 v116, vcc, 0x4098000, v120
	s_nop 1
	v_addc_co_u32_e32 v117, vcc, 0, v121, vcc
	v_readfirstlane_b32 vcc_lo, v210
	v_bfe_u32 v125, v214, 3, 1
	v_lshlrev_b32_e32 v125, 1, v125
	v_xor_b32_e32 v125, v125, v124
	v_lshlrev_b32_e32 v125, 4, v125
	v_lshl_add_u32 v125, v123, 6, v125
	s_lshr_b32 vcc_lo, vcc_lo, 6
	s_lshl_b32 vcc_lo, vcc_lo, 14
	s_mov_b32 s94, 64
	v_add_u32_e32 v124, vcc_lo, v125
	s_add_i32 m0, vcc_lo, 0x0
	s_nop 0
	global_load_lds_dwordx4 v[82:83], off
	v_lshl_add_u64 v[82:83], v[82:83], 0, s[94:95]
	s_add_i32 m0, vcc_lo, 0x400
	s_nop 0
	global_load_lds_dwordx4 v[104:105], off
	v_lshl_add_u64 v[104:105], v[104:105], 0, s[94:95]
	s_add_i32 m0, vcc_lo, 0x800
	s_nop 0
	global_load_lds_dwordx4 v[106:107], off
	v_lshl_add_u64 v[106:107], v[106:107], 0, s[94:95]
	s_add_i32 m0, vcc_lo, 0xc00
	s_nop 0
	global_load_lds_dwordx4 v[108:109], off
	v_lshl_add_u64 v[108:109], v[108:109], 0, s[94:95]
	s_add_i32 m0, vcc_lo, 0x1000
	s_nop 0
	global_load_lds_dwordx4 v[110:111], off
	v_lshl_add_u64 v[110:111], v[110:111], 0, s[94:95]
	s_add_i32 m0, vcc_lo, 0x1400
	s_nop 0
	global_load_lds_dwordx4 v[112:113], off
	v_lshl_add_u64 v[112:113], v[112:113], 0, s[94:95]
	s_add_i32 m0, vcc_lo, 0x1800
	s_nop 0
	global_load_lds_dwordx4 v[114:115], off
	v_lshl_add_u64 v[114:115], v[114:115], 0, s[94:95]
	s_add_i32 m0, vcc_lo, 0x1c00
	s_nop 0
	global_load_lds_dwordx4 v[116:117], off
	v_lshl_add_u64 v[116:117], v[116:117], 0, s[94:95]
	s_add_i32 m0, vcc_lo, 0x2000
	s_nop 0
	global_load_lds_dwordx4 v[82:83], off
	v_lshl_add_u64 v[82:83], v[82:83], 0, s[94:95]
	s_add_i32 m0, vcc_lo, 0x2400
	s_nop 0
	global_load_lds_dwordx4 v[104:105], off
	v_lshl_add_u64 v[104:105], v[104:105], 0, s[94:95]
	s_add_i32 m0, vcc_lo, 0x2800
	s_nop 0
	global_load_lds_dwordx4 v[106:107], off
	v_lshl_add_u64 v[106:107], v[106:107], 0, s[94:95]
	s_add_i32 m0, vcc_lo, 0x2c00
	s_nop 0
	global_load_lds_dwordx4 v[108:109], off
	v_lshl_add_u64 v[108:109], v[108:109], 0, s[94:95]
	s_add_i32 m0, vcc_lo, 0x3000
	s_nop 0
	global_load_lds_dwordx4 v[110:111], off
	v_lshl_add_u64 v[110:111], v[110:111], 0, s[94:95]
	s_add_i32 m0, vcc_lo, 0x3400
	s_nop 0
	global_load_lds_dwordx4 v[112:113], off
	v_lshl_add_u64 v[112:113], v[112:113], 0, s[94:95]
	s_add_i32 m0, vcc_lo, 0x3800
	s_nop 0
	global_load_lds_dwordx4 v[114:115], off
	v_lshl_add_u64 v[114:115], v[114:115], 0, s[94:95]
	s_add_i32 m0, vcc_lo, 0x3c00
	s_nop 0
	global_load_lds_dwordx4 v[116:117], off
	v_lshl_add_u64 v[116:117], v[116:117], 0, s[94:95]
	s_waitcnt vmcnt(8)
	ds_read_b128 v[68:71], v124
	ds_read_b128 v[72:75], v124 offset:1024
	ds_read_b128 v[76:79], v124 offset:2048
	ds_read_b128 v[84:87], v124 offset:3072
	ds_read_b128 v[88:91], v124 offset:4096
	ds_read_b128 v[92:95], v124 offset:5120
	ds_read_b128 v[96:99], v124 offset:6144
	ds_read_b128 v[100:103], v124 offset:7168
	s_waitcnt lgkmcnt(0)
	s_add_i32 m0, vcc_lo, 0x0
	s_nop 0
	global_load_lds_dwordx4 v[82:83], off
	v_lshl_add_u64 v[82:83], v[82:83], 0, s[94:95]
	s_add_i32 m0, vcc_lo, 0x400
	s_nop 0
	global_load_lds_dwordx4 v[104:105], off
	v_lshl_add_u64 v[104:105], v[104:105], 0, s[94:95]
	s_add_i32 m0, vcc_lo, 0x800
	s_nop 0
	global_load_lds_dwordx4 v[106:107], off
	v_lshl_add_u64 v[106:107], v[106:107], 0, s[94:95]
	s_add_i32 m0, vcc_lo, 0xc00
	s_nop 0
	global_load_lds_dwordx4 v[108:109], off
	v_lshl_add_u64 v[108:109], v[108:109], 0, s[94:95]
	s_add_i32 m0, vcc_lo, 0x1000
	s_nop 0
	global_load_lds_dwordx4 v[110:111], off
	v_lshl_add_u64 v[110:111], v[110:111], 0, s[94:95]
	s_add_i32 m0, vcc_lo, 0x1400
	s_nop 0
	global_load_lds_dwordx4 v[112:113], off
	v_lshl_add_u64 v[112:113], v[112:113], 0, s[94:95]
	s_add_i32 m0, vcc_lo, 0x1800
	s_nop 0
	global_load_lds_dwordx4 v[114:115], off
	v_lshl_add_u64 v[114:115], v[114:115], 0, s[94:95]
	s_add_i32 m0, vcc_lo, 0x1c00
	s_nop 0
	global_load_lds_dwordx4 v[116:117], off
	v_lshl_add_u64 v[116:117], v[116:117], 0, s[94:95]
	v_mfma_f32_16x16x32_bf16 v[56:59], v[88:91], v[68:71], 0
	v_mfma_f32_16x16x32_bf16 v[52:55], v[88:91], v[72:75], 0
	v_mfma_f32_16x16x32_bf16 v[48:51], v[88:91], v[76:79], 0
	v_mfma_f32_16x16x32_bf16 v[44:47], v[88:91], v[84:87], 0
	v_mfma_f32_16x16x32_bf16 v[12:15], v[92:95], v[68:71], 0
	v_mfma_f32_16x16x32_bf16 v[8:11], v[92:95], v[72:75], 0
	v_mfma_f32_16x16x32_bf16 v[4:7], v[92:95], v[76:79], 0
	v_mfma_f32_16x16x32_bf16 v[0:3], v[92:95], v[84:87], 0
	v_mfma_f32_16x16x32_bf16 v[16:19], v[96:99], v[68:71], 0
	v_mfma_f32_16x16x32_bf16 v[24:27], v[96:99], v[72:75], 0
	v_mfma_f32_16x16x32_bf16 v[28:31], v[96:99], v[76:79], 0
	v_mfma_f32_16x16x32_bf16 v[36:39], v[96:99], v[84:87], 0
	v_mfma_f32_16x16x32_bf16 v[20:23], v[100:103], v[68:71], 0
	v_mfma_f32_16x16x32_bf16 v[32:35], v[100:103], v[72:75], 0
	v_mfma_f32_16x16x32_bf16 v[40:43], v[100:103], v[76:79], 0
	v_mfma_f32_16x16x32_bf16 v[60:63], v[100:103], v[84:87], 0
	s_waitcnt vmcnt(8)
	ds_read_b128 v[68:71], v124 offset:8192
	ds_read_b128 v[72:75], v124 offset:9216
	ds_read_b128 v[76:79], v124 offset:10240
	ds_read_b128 v[84:87], v124 offset:11264
	ds_read_b128 v[88:91], v124 offset:12288
	ds_read_b128 v[92:95], v124 offset:13312
	ds_read_b128 v[96:99], v124 offset:14336
	ds_read_b128 v[100:103], v124 offset:15360
	s_waitcnt lgkmcnt(0)
	s_add_i32 m0, vcc_lo, 0x2000
	s_nop 0
	global_load_lds_dwordx4 v[82:83], off
	v_lshl_add_u64 v[82:83], v[82:83], 0, s[94:95]
	s_add_i32 m0, vcc_lo, 0x2400
	s_nop 0
	global_load_lds_dwordx4 v[104:105], off
	v_lshl_add_u64 v[104:105], v[104:105], 0, s[94:95]
	s_add_i32 m0, vcc_lo, 0x2800
	s_nop 0
	global_load_lds_dwordx4 v[106:107], off
	v_lshl_add_u64 v[106:107], v[106:107], 0, s[94:95]
	s_add_i32 m0, vcc_lo, 0x2c00
	s_nop 0
	global_load_lds_dwordx4 v[108:109], off
	v_lshl_add_u64 v[108:109], v[108:109], 0, s[94:95]
	s_add_i32 m0, vcc_lo, 0x3000
	s_nop 0
	global_load_lds_dwordx4 v[110:111], off
	v_lshl_add_u64 v[110:111], v[110:111], 0, s[94:95]
	s_add_i32 m0, vcc_lo, 0x3400
	s_nop 0
	global_load_lds_dwordx4 v[112:113], off
	v_lshl_add_u64 v[112:113], v[112:113], 0, s[94:95]
	s_add_i32 m0, vcc_lo, 0x3800
	s_nop 0
	global_load_lds_dwordx4 v[114:115], off
	v_lshl_add_u64 v[114:115], v[114:115], 0, s[94:95]
	s_add_i32 m0, vcc_lo, 0x3c00
	s_nop 0
	global_load_lds_dwordx4 v[116:117], off
	v_lshl_add_u64 v[116:117], v[116:117], 0, s[94:95]
	v_mfma_f32_16x16x32_bf16 v[56:59], v[88:91], v[68:71], v[56:59]
	v_mfma_f32_16x16x32_bf16 v[52:55], v[88:91], v[72:75], v[52:55]
	v_mfma_f32_16x16x32_bf16 v[48:51], v[88:91], v[76:79], v[48:51]
	v_mfma_f32_16x16x32_bf16 v[44:47], v[88:91], v[84:87], v[44:47]
	v_mfma_f32_16x16x32_bf16 v[12:15], v[92:95], v[68:71], v[12:15]
	v_mfma_f32_16x16x32_bf16 v[8:11], v[92:95], v[72:75], v[8:11]
	v_mfma_f32_16x16x32_bf16 v[4:7], v[92:95], v[76:79], v[4:7]
	v_mfma_f32_16x16x32_bf16 v[0:3], v[92:95], v[84:87], v[0:3]
	v_mfma_f32_16x16x32_bf16 v[16:19], v[96:99], v[68:71], v[16:19]
	v_mfma_f32_16x16x32_bf16 v[24:27], v[96:99], v[72:75], v[24:27]
	v_mfma_f32_16x16x32_bf16 v[28:31], v[96:99], v[76:79], v[28:31]
	v_mfma_f32_16x16x32_bf16 v[36:39], v[96:99], v[84:87], v[36:39]
	v_mfma_f32_16x16x32_bf16 v[20:23], v[100:103], v[68:71], v[20:23]
	v_mfma_f32_16x16x32_bf16 v[32:35], v[100:103], v[72:75], v[32:35]
	v_mfma_f32_16x16x32_bf16 v[40:43], v[100:103], v[76:79], v[40:43]
	v_mfma_f32_16x16x32_bf16 v[60:63], v[100:103], v[84:87], v[60:63]
	s_waitcnt vmcnt(8)
	ds_read_b128 v[68:71], v124
	ds_read_b128 v[72:75], v124 offset:1024
	ds_read_b128 v[76:79], v124 offset:2048
	ds_read_b128 v[84:87], v124 offset:3072
	ds_read_b128 v[88:91], v124 offset:4096
	ds_read_b128 v[92:95], v124 offset:5120
	ds_read_b128 v[96:99], v124 offset:6144
	ds_read_b128 v[100:103], v124 offset:7168
	s_waitcnt lgkmcnt(0)
	s_add_i32 m0, vcc_lo, 0x0
	s_nop 0
	global_load_lds_dwordx4 v[82:83], off
	v_lshl_add_u64 v[82:83], v[82:83], 0, s[94:95]
	s_add_i32 m0, vcc_lo, 0x400
	s_nop 0
	global_load_lds_dwordx4 v[104:105], off
	v_lshl_add_u64 v[104:105], v[104:105], 0, s[94:95]
	s_add_i32 m0, vcc_lo, 0x800
	s_nop 0
	global_load_lds_dwordx4 v[106:107], off
	v_lshl_add_u64 v[106:107], v[106:107], 0, s[94:95]
	s_add_i32 m0, vcc_lo, 0xc00
	s_nop 0
	global_load_lds_dwordx4 v[108:109], off
	v_lshl_add_u64 v[108:109], v[108:109], 0, s[94:95]
	s_add_i32 m0, vcc_lo, 0x1000
	s_nop 0
	global_load_lds_dwordx4 v[110:111], off
	v_lshl_add_u64 v[110:111], v[110:111], 0, s[94:95]
	s_add_i32 m0, vcc_lo, 0x1400
	s_nop 0
	global_load_lds_dwordx4 v[112:113], off
	v_lshl_add_u64 v[112:113], v[112:113], 0, s[94:95]
	s_add_i32 m0, vcc_lo, 0x1800
	s_nop 0
	global_load_lds_dwordx4 v[114:115], off
	v_lshl_add_u64 v[114:115], v[114:115], 0, s[94:95]
	s_add_i32 m0, vcc_lo, 0x1c00
	s_nop 0
	global_load_lds_dwordx4 v[116:117], off
	v_lshl_add_u64 v[116:117], v[116:117], 0, s[94:95]
	v_mfma_f32_16x16x32_bf16 v[56:59], v[88:91], v[68:71], v[56:59]
	v_mfma_f32_16x16x32_bf16 v[52:55], v[88:91], v[72:75], v[52:55]
	v_mfma_f32_16x16x32_bf16 v[48:51], v[88:91], v[76:79], v[48:51]
	v_mfma_f32_16x16x32_bf16 v[44:47], v[88:91], v[84:87], v[44:47]
	v_mfma_f32_16x16x32_bf16 v[12:15], v[92:95], v[68:71], v[12:15]
	v_mfma_f32_16x16x32_bf16 v[8:11], v[92:95], v[72:75], v[8:11]
	v_mfma_f32_16x16x32_bf16 v[4:7], v[92:95], v[76:79], v[4:7]
	v_mfma_f32_16x16x32_bf16 v[0:3], v[92:95], v[84:87], v[0:3]
	v_mfma_f32_16x16x32_bf16 v[16:19], v[96:99], v[68:71], v[16:19]
	v_mfma_f32_16x16x32_bf16 v[24:27], v[96:99], v[72:75], v[24:27]
	v_mfma_f32_16x16x32_bf16 v[28:31], v[96:99], v[76:79], v[28:31]
	v_mfma_f32_16x16x32_bf16 v[36:39], v[96:99], v[84:87], v[36:39]
	v_mfma_f32_16x16x32_bf16 v[20:23], v[100:103], v[68:71], v[20:23]
	v_mfma_f32_16x16x32_bf16 v[32:35], v[100:103], v[72:75], v[32:35]
	v_mfma_f32_16x16x32_bf16 v[40:43], v[100:103], v[76:79], v[40:43]
	v_mfma_f32_16x16x32_bf16 v[60:63], v[100:103], v[84:87], v[60:63]
	s_waitcnt vmcnt(8)
	ds_read_b128 v[68:71], v124 offset:8192
	ds_read_b128 v[72:75], v124 offset:9216
	ds_read_b128 v[76:79], v124 offset:10240
	ds_read_b128 v[84:87], v124 offset:11264
	ds_read_b128 v[88:91], v124 offset:12288
	ds_read_b128 v[92:95], v124 offset:13312
	ds_read_b128 v[96:99], v124 offset:14336
	ds_read_b128 v[100:103], v124 offset:15360
	s_waitcnt lgkmcnt(0)
	s_add_i32 m0, vcc_lo, 0x2000
	s_nop 0
	global_load_lds_dwordx4 v[82:83], off
	v_lshl_add_u64 v[82:83], v[82:83], 0, s[94:95]
	s_add_i32 m0, vcc_lo, 0x2400
	s_nop 0
	global_load_lds_dwordx4 v[104:105], off
	v_lshl_add_u64 v[104:105], v[104:105], 0, s[94:95]
	s_add_i32 m0, vcc_lo, 0x2800
	s_nop 0
	global_load_lds_dwordx4 v[106:107], off
	v_lshl_add_u64 v[106:107], v[106:107], 0, s[94:95]
	s_add_i32 m0, vcc_lo, 0x2c00
	s_nop 0
	global_load_lds_dwordx4 v[108:109], off
	v_lshl_add_u64 v[108:109], v[108:109], 0, s[94:95]
	s_add_i32 m0, vcc_lo, 0x3000
	s_nop 0
	global_load_lds_dwordx4 v[110:111], off
	v_lshl_add_u64 v[110:111], v[110:111], 0, s[94:95]
	s_add_i32 m0, vcc_lo, 0x3400
	s_nop 0
	global_load_lds_dwordx4 v[112:113], off
	v_lshl_add_u64 v[112:113], v[112:113], 0, s[94:95]
	s_add_i32 m0, vcc_lo, 0x3800
	s_nop 0
	global_load_lds_dwordx4 v[114:115], off
	v_lshl_add_u64 v[114:115], v[114:115], 0, s[94:95]
	s_add_i32 m0, vcc_lo, 0x3c00
	s_nop 0
	global_load_lds_dwordx4 v[116:117], off
	v_lshl_add_u64 v[116:117], v[116:117], 0, s[94:95]
	v_mfma_f32_16x16x32_bf16 v[56:59], v[88:91], v[68:71], v[56:59]
	v_mfma_f32_16x16x32_bf16 v[52:55], v[88:91], v[72:75], v[52:55]
	v_mfma_f32_16x16x32_bf16 v[48:51], v[88:91], v[76:79], v[48:51]
	v_mfma_f32_16x16x32_bf16 v[44:47], v[88:91], v[84:87], v[44:47]
	v_mfma_f32_16x16x32_bf16 v[12:15], v[92:95], v[68:71], v[12:15]
	v_mfma_f32_16x16x32_bf16 v[8:11], v[92:95], v[72:75], v[8:11]
	v_mfma_f32_16x16x32_bf16 v[4:7], v[92:95], v[76:79], v[4:7]
	v_mfma_f32_16x16x32_bf16 v[0:3], v[92:95], v[84:87], v[0:3]
	v_mfma_f32_16x16x32_bf16 v[16:19], v[96:99], v[68:71], v[16:19]
	v_mfma_f32_16x16x32_bf16 v[24:27], v[96:99], v[72:75], v[24:27]
	v_mfma_f32_16x16x32_bf16 v[28:31], v[96:99], v[76:79], v[28:31]
	v_mfma_f32_16x16x32_bf16 v[36:39], v[96:99], v[84:87], v[36:39]
	v_mfma_f32_16x16x32_bf16 v[20:23], v[100:103], v[68:71], v[20:23]
	v_mfma_f32_16x16x32_bf16 v[32:35], v[100:103], v[72:75], v[32:35]
	v_mfma_f32_16x16x32_bf16 v[40:43], v[100:103], v[76:79], v[40:43]
	v_mfma_f32_16x16x32_bf16 v[60:63], v[100:103], v[84:87], v[60:63]
	s_waitcnt vmcnt(8)
	ds_read_b128 v[68:71], v124
	ds_read_b128 v[72:75], v124 offset:1024
	ds_read_b128 v[76:79], v124 offset:2048
	ds_read_b128 v[84:87], v124 offset:3072
	ds_read_b128 v[88:91], v124 offset:4096
	ds_read_b128 v[92:95], v124 offset:5120
	ds_read_b128 v[96:99], v124 offset:6144
	ds_read_b128 v[100:103], v124 offset:7168
	s_waitcnt lgkmcnt(0)
	s_add_i32 m0, vcc_lo, 0x0
	s_nop 0
	global_load_lds_dwordx4 v[82:83], off
	v_lshl_add_u64 v[82:83], v[82:83], 0, s[94:95]
	s_add_i32 m0, vcc_lo, 0x400
	s_nop 0
	global_load_lds_dwordx4 v[104:105], off
	v_lshl_add_u64 v[104:105], v[104:105], 0, s[94:95]
	s_add_i32 m0, vcc_lo, 0x800
	s_nop 0
	global_load_lds_dwordx4 v[106:107], off
	v_lshl_add_u64 v[106:107], v[106:107], 0, s[94:95]
	s_add_i32 m0, vcc_lo, 0xc00
	s_nop 0
	global_load_lds_dwordx4 v[108:109], off
	v_lshl_add_u64 v[108:109], v[108:109], 0, s[94:95]
	s_add_i32 m0, vcc_lo, 0x1000
	s_nop 0
	global_load_lds_dwordx4 v[110:111], off
	v_lshl_add_u64 v[110:111], v[110:111], 0, s[94:95]
	s_add_i32 m0, vcc_lo, 0x1400
	s_nop 0
	global_load_lds_dwordx4 v[112:113], off
	v_lshl_add_u64 v[112:113], v[112:113], 0, s[94:95]
	s_add_i32 m0, vcc_lo, 0x1800
	s_nop 0
	global_load_lds_dwordx4 v[114:115], off
	v_lshl_add_u64 v[114:115], v[114:115], 0, s[94:95]
	s_add_i32 m0, vcc_lo, 0x1c00
	s_nop 0
	global_load_lds_dwordx4 v[116:117], off
	v_lshl_add_u64 v[116:117], v[116:117], 0, s[94:95]
	v_mfma_f32_16x16x32_bf16 v[56:59], v[88:91], v[68:71], v[56:59]
	v_mfma_f32_16x16x32_bf16 v[52:55], v[88:91], v[72:75], v[52:55]
	v_mfma_f32_16x16x32_bf16 v[48:51], v[88:91], v[76:79], v[48:51]
	v_mfma_f32_16x16x32_bf16 v[44:47], v[88:91], v[84:87], v[44:47]
	v_mfma_f32_16x16x32_bf16 v[12:15], v[92:95], v[68:71], v[12:15]
	v_mfma_f32_16x16x32_bf16 v[8:11], v[92:95], v[72:75], v[8:11]
	v_mfma_f32_16x16x32_bf16 v[4:7], v[92:95], v[76:79], v[4:7]
	v_mfma_f32_16x16x32_bf16 v[0:3], v[92:95], v[84:87], v[0:3]
	v_mfma_f32_16x16x32_bf16 v[16:19], v[96:99], v[68:71], v[16:19]
	v_mfma_f32_16x16x32_bf16 v[24:27], v[96:99], v[72:75], v[24:27]
	v_mfma_f32_16x16x32_bf16 v[28:31], v[96:99], v[76:79], v[28:31]
	v_mfma_f32_16x16x32_bf16 v[36:39], v[96:99], v[84:87], v[36:39]
	v_mfma_f32_16x16x32_bf16 v[20:23], v[100:103], v[68:71], v[20:23]
	v_mfma_f32_16x16x32_bf16 v[32:35], v[100:103], v[72:75], v[32:35]
	v_mfma_f32_16x16x32_bf16 v[40:43], v[100:103], v[76:79], v[40:43]
	v_mfma_f32_16x16x32_bf16 v[60:63], v[100:103], v[84:87], v[60:63]
	s_waitcnt vmcnt(8)
	ds_read_b128 v[68:71], v124 offset:8192
	ds_read_b128 v[72:75], v124 offset:9216
	ds_read_b128 v[76:79], v124 offset:10240
	ds_read_b128 v[84:87], v124 offset:11264
	ds_read_b128 v[88:91], v124 offset:12288
	ds_read_b128 v[92:95], v124 offset:13312
	ds_read_b128 v[96:99], v124 offset:14336
	ds_read_b128 v[100:103], v124 offset:15360
	s_waitcnt lgkmcnt(0)
	s_add_i32 m0, vcc_lo, 0x2000
	s_nop 0
	global_load_lds_dwordx4 v[82:83], off
	v_lshl_add_u64 v[82:83], v[82:83], 0, s[94:95]
	s_add_i32 m0, vcc_lo, 0x2400
	s_nop 0
	global_load_lds_dwordx4 v[104:105], off
	v_lshl_add_u64 v[104:105], v[104:105], 0, s[94:95]
	s_add_i32 m0, vcc_lo, 0x2800
	s_nop 0
	global_load_lds_dwordx4 v[106:107], off
	v_lshl_add_u64 v[106:107], v[106:107], 0, s[94:95]
	s_add_i32 m0, vcc_lo, 0x2c00
	s_nop 0
	global_load_lds_dwordx4 v[108:109], off
	v_lshl_add_u64 v[108:109], v[108:109], 0, s[94:95]
	s_add_i32 m0, vcc_lo, 0x3000
	s_nop 0
	global_load_lds_dwordx4 v[110:111], off
	v_lshl_add_u64 v[110:111], v[110:111], 0, s[94:95]
	s_add_i32 m0, vcc_lo, 0x3400
	s_nop 0
	global_load_lds_dwordx4 v[112:113], off
	v_lshl_add_u64 v[112:113], v[112:113], 0, s[94:95]
	s_add_i32 m0, vcc_lo, 0x3800
	s_nop 0
	global_load_lds_dwordx4 v[114:115], off
	v_lshl_add_u64 v[114:115], v[114:115], 0, s[94:95]
	s_add_i32 m0, vcc_lo, 0x3c00
	s_nop 0
	global_load_lds_dwordx4 v[116:117], off
	v_lshl_add_u64 v[116:117], v[116:117], 0, s[94:95]
	v_mfma_f32_16x16x32_bf16 v[56:59], v[88:91], v[68:71], v[56:59]
	v_mfma_f32_16x16x32_bf16 v[52:55], v[88:91], v[72:75], v[52:55]
	v_mfma_f32_16x16x32_bf16 v[48:51], v[88:91], v[76:79], v[48:51]
	v_mfma_f32_16x16x32_bf16 v[44:47], v[88:91], v[84:87], v[44:47]
	v_mfma_f32_16x16x32_bf16 v[12:15], v[92:95], v[68:71], v[12:15]
	v_mfma_f32_16x16x32_bf16 v[8:11], v[92:95], v[72:75], v[8:11]
	v_mfma_f32_16x16x32_bf16 v[4:7], v[92:95], v[76:79], v[4:7]
	v_mfma_f32_16x16x32_bf16 v[0:3], v[92:95], v[84:87], v[0:3]
	v_mfma_f32_16x16x32_bf16 v[16:19], v[96:99], v[68:71], v[16:19]
	v_mfma_f32_16x16x32_bf16 v[24:27], v[96:99], v[72:75], v[24:27]
	v_mfma_f32_16x16x32_bf16 v[28:31], v[96:99], v[76:79], v[28:31]
	v_mfma_f32_16x16x32_bf16 v[36:39], v[96:99], v[84:87], v[36:39]
	v_mfma_f32_16x16x32_bf16 v[20:23], v[100:103], v[68:71], v[20:23]
	v_mfma_f32_16x16x32_bf16 v[32:35], v[100:103], v[72:75], v[32:35]
	v_mfma_f32_16x16x32_bf16 v[40:43], v[100:103], v[76:79], v[40:43]
	v_mfma_f32_16x16x32_bf16 v[60:63], v[100:103], v[84:87], v[60:63]
	s_waitcnt vmcnt(8)
	ds_read_b128 v[68:71], v124
	ds_read_b128 v[72:75], v124 offset:1024
	ds_read_b128 v[76:79], v124 offset:2048
	ds_read_b128 v[84:87], v124 offset:3072
	ds_read_b128 v[88:91], v124 offset:4096
	ds_read_b128 v[92:95], v124 offset:5120
	ds_read_b128 v[96:99], v124 offset:6144
	ds_read_b128 v[100:103], v124 offset:7168
	s_waitcnt lgkmcnt(0)
	v_mfma_f32_16x16x32_bf16 v[56:59], v[88:91], v[68:71], v[56:59]
	v_mfma_f32_16x16x32_bf16 v[52:55], v[88:91], v[72:75], v[52:55]
	v_mfma_f32_16x16x32_bf16 v[48:51], v[88:91], v[76:79], v[48:51]
	v_mfma_f32_16x16x32_bf16 v[44:47], v[88:91], v[84:87], v[44:47]
	v_mfma_f32_16x16x32_bf16 v[12:15], v[92:95], v[68:71], v[12:15]
	v_mfma_f32_16x16x32_bf16 v[8:11], v[92:95], v[72:75], v[8:11]
	v_mfma_f32_16x16x32_bf16 v[4:7], v[92:95], v[76:79], v[4:7]
	v_mfma_f32_16x16x32_bf16 v[0:3], v[92:95], v[84:87], v[0:3]
	v_mfma_f32_16x16x32_bf16 v[16:19], v[96:99], v[68:71], v[16:19]
	v_mfma_f32_16x16x32_bf16 v[24:27], v[96:99], v[72:75], v[24:27]
	v_mfma_f32_16x16x32_bf16 v[28:31], v[96:99], v[76:79], v[28:31]
	v_mfma_f32_16x16x32_bf16 v[36:39], v[96:99], v[84:87], v[36:39]
	v_mfma_f32_16x16x32_bf16 v[20:23], v[100:103], v[68:71], v[20:23]
	v_mfma_f32_16x16x32_bf16 v[32:35], v[100:103], v[72:75], v[32:35]
	v_mfma_f32_16x16x32_bf16 v[40:43], v[100:103], v[76:79], v[40:43]
	v_mfma_f32_16x16x32_bf16 v[60:63], v[100:103], v[84:87], v[60:63]
	s_waitcnt vmcnt(0)
	ds_read_b128 v[68:71], v124 offset:8192
	ds_read_b128 v[72:75], v124 offset:9216
	ds_read_b128 v[76:79], v124 offset:10240
	ds_read_b128 v[84:87], v124 offset:11264
	ds_read_b128 v[88:91], v124 offset:12288
	ds_read_b128 v[92:95], v124 offset:13312
	ds_read_b128 v[96:99], v124 offset:14336
	ds_read_b128 v[100:103], v124 offset:15360
	s_waitcnt lgkmcnt(0)
	v_mfma_f32_16x16x32_bf16 v[56:59], v[88:91], v[68:71], v[56:59]
	v_mfma_f32_16x16x32_bf16 v[52:55], v[88:91], v[72:75], v[52:55]
	v_mfma_f32_16x16x32_bf16 v[48:51], v[88:91], v[76:79], v[48:51]
	v_mfma_f32_16x16x32_bf16 v[44:47], v[88:91], v[84:87], v[44:47]
	v_mfma_f32_16x16x32_bf16 v[12:15], v[92:95], v[68:71], v[12:15]
	v_mfma_f32_16x16x32_bf16 v[8:11], v[92:95], v[72:75], v[8:11]
	v_mfma_f32_16x16x32_bf16 v[4:7], v[92:95], v[76:79], v[4:7]
	v_mfma_f32_16x16x32_bf16 v[0:3], v[92:95], v[84:87], v[0:3]
	v_mfma_f32_16x16x32_bf16 v[16:19], v[96:99], v[68:71], v[16:19]
	v_mfma_f32_16x16x32_bf16 v[24:27], v[96:99], v[72:75], v[24:27]
	v_mfma_f32_16x16x32_bf16 v[28:31], v[96:99], v[76:79], v[28:31]
	v_mfma_f32_16x16x32_bf16 v[36:39], v[96:99], v[84:87], v[36:39]
	v_mfma_f32_16x16x32_bf16 v[20:23], v[100:103], v[68:71], v[20:23]
	v_mfma_f32_16x16x32_bf16 v[32:35], v[100:103], v[72:75], v[32:35]
	v_mfma_f32_16x16x32_bf16 v[40:43], v[100:103], v[76:79], v[40:43]
	v_mfma_f32_16x16x32_bf16 v[60:63], v[100:103], v[84:87], v[60:63]
	s_nop 7
	s_nop 3
	v_and_b32_e32 v65, 63, v81
	s_ashr_i32 s2, s11, 7
	v_lshl_add_u32 v65, v65, 4, 0
	s_lshl_b32 s3, s2, 4
	v_lshl_add_u32 v66, s12, 14, v65
	s_addk_i32 s3, 0x4000
	ds_write_b128 v66, v[56:59]
	ds_write_b128 v66, v[52:55] offset:1024
	ds_write_b128 v66, v[48:51] offset:2048
	ds_write_b128 v66, v[44:47] offset:3072
	ds_write_b128 v66, v[12:15] offset:4096
	ds_write_b128 v66, v[8:11] offset:5120
	ds_write_b128 v66, v[4:7] offset:6144
	ds_write_b128 v66, v[0:3] offset:7168
	ds_write_b128 v66, v[16:19] offset:8192
	ds_write_b128 v66, v[24:27] offset:9216
	ds_write_b128 v66, v[28:31] offset:10240
	ds_write_b128 v66, v[36:39] offset:11264
	ds_write_b128 v66, v[20:23] offset:12288
	ds_write_b128 v66, v[32:35] offset:13312
	ds_write_b128 v66, v[40:43] offset:14336
	ds_write_b128 v66, v[60:63] offset:15360
	v_or_b32_e32 v0, s3, v80
	v_ashrrev_i32_e32 v1, 31, v0
	v_bfe_u32 v64, v81, 4, 2
	v_lshlrev_b64 v[2:3], 7, v[0:1]
	v_lshl_add_u64 v[2:3], s[6:7], 0, v[2:3]
	v_lshlrev_b32_e32 v128, 5, v64
	v_lshl_add_u64 v[6:7], v[2:3], 0, v[128:129]
	s_waitcnt lgkmcnt(0)
	s_barrier
	global_load_dwordx4 v[2:5], v[6:7], off
	s_nop 0
	global_load_dwordx4 v[6:9], v[6:7], off offset:16
	s_bfe_u32 s3, s11, 0x10006
	s_lshl_b32 s6, s3, 2
	s_add_i32 s6, s6, s2
	v_lshl_add_u32 v62, s6, 10, v65
	ds_read_b128 v[10:13], v62
	ds_read_b128 v[14:17], v62 offset:8192
	ds_read_b128 v[18:21], v62 offset:16384
	ds_read_b128 v[22:25], v62 offset:24576
	ds_read_b128 v[26:29], v62 offset:32768
	ds_read_b128 v[30:33], v62 offset:40960
	ds_read_b128 v[34:37], v62 offset:49152
	ds_read_b128 v[38:41], v62 offset:57344
	s_waitcnt lgkmcnt(0)
	v_pk_add_f32 v[10:11], v[10:11], 0 op_sel_hi:[1,0]
	v_pk_add_f32 v[12:13], v[12:13], 0 op_sel_hi:[1,0]
	v_pk_add_f32 v[10:11], v[10:11], v[18:19]
	v_pk_add_f32 v[12:13], v[12:13], v[20:21]
	v_add_u32_e32 v42, 0x10000, v62
	v_add_u32_e32 v46, 0x12000, v62
	v_add_u32_e32 v50, 0x14000, v62
	v_add_u32_e32 v54, 0x16000, v62
	v_add_u32_e32 v58, 0x18000, v62
	v_add_u32_e32 v63, 0x1a000, v62
	ds_read_b128 v[42:45], v42
	ds_read_b128 v[46:49], v46
	ds_read_b128 v[50:53], v50
	ds_read_b128 v[54:57], v54
	ds_read_b128 v[58:61], v58
	ds_read_b128 v[66:69], v63
	v_pk_add_f32 v[10:11], v[10:11], v[26:27]
	v_pk_add_f32 v[14:15], v[14:15], 0 op_sel_hi:[1,0]
	v_pk_add_f32 v[10:11], v[10:11], v[34:35]
	v_pk_add_f32 v[12:13], v[12:13], v[28:29]
	s_waitcnt lgkmcnt(0)
	v_pk_add_f32 v[10:11], v[10:11], v[42:43]
	v_pk_add_f32 v[16:17], v[16:17], 0 op_sel_hi:[1,0]
	v_pk_add_f32 v[10:11], v[10:11], v[50:51]
	v_pk_add_f32 v[14:15], v[14:15], v[22:23]
	v_pk_add_f32 v[10:11], v[10:11], v[58:59]
	v_pk_add_f32 v[12:13], v[12:13], v[36:37]
	s_ashr_i32 s2, s5, 5
	v_pk_add_f32 v[16:17], v[16:17], v[24:25]
	v_pk_add_f32 v[14:15], v[14:15], v[30:31]
	v_pk_add_f32 v[12:13], v[12:13], v[44:45]
	v_pk_add_f32 v[16:17], v[16:17], v[32:33]
	v_pk_add_f32 v[14:15], v[14:15], v[38:39]
	v_pk_add_f32 v[12:13], v[12:13], v[52:53]
	v_pk_add_f32 v[16:17], v[16:17], v[40:41]
	v_pk_add_f32 v[14:15], v[14:15], v[46:47]
	v_pk_add_f32 v[12:13], v[12:13], v[60:61]
	v_lshlrev_b64 v[0:1], 12, v[0:1]
	v_pk_add_f32 v[16:17], v[16:17], v[48:49]
	v_pk_add_f32 v[14:15], v[14:15], v[54:55]
	v_pk_add_f32 v[16:17], v[16:17], v[56:57]
	v_pk_add_f32 v[14:15], v[14:15], v[66:67]
	v_pk_add_f32 v[16:17], v[16:17], v[68:69]
	s_waitcnt vmcnt(0)
	v_mov_b32_e32 v18, v2
	v_mov_b32_e32 v19, v6
	v_mov_b32_e32 v6, v3
	v_pk_add_f32 v[2:3], v[18:19], v[6:7]
	v_mov_b32_e32 v6, v4
	v_mov_b32_e32 v7, v8
	v_mov_b32_e32 v8, v5
	v_pk_add_f32 v[4:5], v[6:7], v[8:9]
	v_add_u32_e32 v6, 0x1e000, v62
	v_pk_add_f32 v[2:3], v[2:3], v[4:5]
	s_nop 0
	v_add_f32_e32 v18, v2, v3
	v_and_b32_e32 v3, 64, v214
	v_xor_b32_e32 v2, 16, v214
	v_add_u32_e32 v19, 64, v3
	v_cmp_lt_i32_e32 vcc, v2, v19
	s_nop 1
	v_cndmask_b32_e32 v2, v214, v2, vcc
	v_lshlrev_b32_e32 v2, 2, v2
	ds_bpermute_b32 v20, v2, v18
	v_add_u32_e32 v2, 0x1c000, v62
	ds_read_b128 v[2:5], v2
	ds_read_b128 v[6:9], v6
	s_waitcnt lgkmcnt(2)
	v_add_f32_e32 v18, v18, v20
	v_xor_b32_e32 v20, 32, v214
	v_cmp_lt_i32_e32 vcc, v20, v19
	s_waitcnt lgkmcnt(1)
	v_pk_add_f32 v[2:3], v[10:11], v[2:3]
	v_pk_add_f32 v[4:5], v[12:13], v[4:5]
	v_cndmask_b32_e32 v19, v214, v20, vcc
	v_lshlrev_b32_e32 v19, 2, v19
	ds_bpermute_b32 v19, v19, v18
	s_waitcnt lgkmcnt(1)
	v_pk_add_f32 v[6:7], v[14:15], v[6:7]
	v_pk_add_f32 v[8:9], v[16:17], v[8:9]
	s_waitcnt lgkmcnt(0)
	v_add_f32_e32 v10, v18, v19
	v_fmamk_f32 v10, v10, 0x3a000000, v190
	v_mul_f32_e32 v11, 0x4b800000, v10
	v_cmp_gt_f32_e32 vcc, s70, v10
	s_nop 1
	v_cndmask_b32_e32 v10, v10, v11, vcc
	v_rsq_f32_e32 v10, v10
	v_lshlrev_b32_e32 v11, 2, v64
	v_lshl_or_b32 v11, s3, 4, v11
	s_mul_hi_i32 s3, s2, 0x4200000
	s_mul_i32 s2, s2, 0x4200000
	s_add_u32 s0, s0, s2
	s_addc_u32 s1, s1, s3
	v_mul_f32_e32 v12, 0x45800000, v10
	v_lshl_add_u64 v[0:1], s[0:1], 0, v[0:1]
	s_and_b32 s0, s4, 0x700
	v_or_b32_e32 v11, s10, v11
	v_cndmask_b32_e32 v10, v10, v12, vcc
	s_lshl_b32 s94, s0, 1
	v_lshl_add_u64 v[0:1], v[0:1], 0, s[94:95]
	v_lshlrev_b32_e32 v128, 1, v11
	v_pk_mul_f32 v[4:5], v[4:5], v[10:11] op_sel_hi:[1,0]
	v_pk_mul_f32 v[2:3], v[2:3], v[10:11] op_sel_hi:[1,0]
	v_lshl_add_u64 v[0:1], v[0:1], 0, v[128:129]
	v_cvt_pk_bf16_f32 v2, v2, v3
	v_cvt_pk_bf16_f32 v3, v4, v5
	v_pk_mul_f32 v[4:5], v[6:7], v[10:11] op_sel_hi:[1,0]
	global_store_dwordx2 v[0:1], v[2:3], off
	v_pk_mul_f32 v[2:3], v[8:9], v[10:11] op_sel_hi:[1,0]
	v_cvt_pk_bf16_f32 v4, v4, v5
	s_nop 0
	v_cvt_pk_bf16_f32 v5, v2, v3
	global_store_dwordx2 v[0:1], v[4:5], off offset:256
	s_waitcnt lgkmcnt(0)
	s_barrier

.LBB0_797:
	v_lshrrev_b32_e32 v122, 2, v214
	v_and_b32_e32 v123, 15, v214
	v_sub_u32_e32 v122, v122, v123
	v_mul_i32_i24_e32 v122, 0x1000, v122
	v_bfe_u32 v125, v214, 5, 1
	v_lshlrev_b32_e32 v125, 1, v125
	v_and_b32_e32 v124, 3, v214
	v_xor_b32_e32 v125, v125, v124
	v_lshrrev_b32_e32 v124, 4, v214
	v_sub_u32_e32 v125, v125, v124
	v_lshl_add_u32 v122, v125, 4, v122
	v_ashrrev_i32_e32 v125, 31, v122
	v_add_co_u32_e32 v118, vcc, v66, v122
	s_nop 1
	v_addc_co_u32_e32 v119, vcc, v67, v125, vcc
	v_add_co_u32_e32 v120, vcc, v64, v122
	s_nop 1
	v_addc_co_u32_e32 v121, vcc, v65, v125, vcc
	v_add_co_u32_e32 v82, vcc, 0x3f5d0000, v118
	s_nop 1
	v_addc_co_u32_e32 v83, vcc, 0, v119, vcc
	v_add_co_u32_e32 v104, vcc, 0x3f5e0000, v118
	s_nop 1
	v_addc_co_u32_e32 v105, vcc, 0, v119, vcc
	v_add_co_u32_e32 v106, vcc, 0x3f5f0000, v118
	s_nop 1
	v_addc_co_u32_e32 v107, vcc, 0, v119, vcc
	v_add_co_u32_e32 v108, vcc, 0x3f600000, v118
	s_nop 1
	v_addc_co_u32_e32 v109, vcc, 0, v119, vcc
	v_add_co_u32_e32 v110, vcc, 0x6008000, v120
	s_nop 1
	v_addc_co_u32_e32 v111, vcc, 0, v121, vcc
	v_add_co_u32_e32 v112, vcc, 0x6018000, v120
	s_nop 1
	v_addc_co_u32_e32 v113, vcc, 0, v121, vcc
	v_add_co_u32_e32 v114, vcc, 0x6088000, v120
	s_nop 1
	v_addc_co_u32_e32 v115, vcc, 0, v121, vcc
	v_add_co_u32_e32 v116, vcc, 0x6098000, v120
	s_nop 1
	v_addc_co_u32_e32 v117, vcc, 0, v121, vcc
	v_readfirstlane_b32 vcc_lo, v210
	v_bfe_u32 v125, v214, 3, 1
	v_lshlrev_b32_e32 v125, 1, v125
	v_xor_b32_e32 v125, v125, v124
	v_lshlrev_b32_e32 v125, 4, v125
	v_lshl_add_u32 v125, v123, 6, v125
	s_lshr_b32 vcc_lo, vcc_lo, 6
	s_lshl_b32 vcc_lo, vcc_lo, 14
	s_mov_b32 s94, 64
	v_add_u32_e32 v124, vcc_lo, v125
	s_add_i32 m0, vcc_lo, 0x0
	s_nop 0
	global_load_lds_dwordx4 v[82:83], off
	v_lshl_add_u64 v[82:83], v[82:83], 0, s[94:95]
	s_add_i32 m0, vcc_lo, 0x400
	s_nop 0
	global_load_lds_dwordx4 v[104:105], off
	v_lshl_add_u64 v[104:105], v[104:105], 0, s[94:95]
	s_add_i32 m0, vcc_lo, 0x800
	s_nop 0
	global_load_lds_dwordx4 v[106:107], off
	v_lshl_add_u64 v[106:107], v[106:107], 0, s[94:95]
	s_add_i32 m0, vcc_lo, 0xc00
	s_nop 0
	global_load_lds_dwordx4 v[108:109], off
	v_lshl_add_u64 v[108:109], v[108:109], 0, s[94:95]
	s_add_i32 m0, vcc_lo, 0x1000
	s_nop 0
	global_load_lds_dwordx4 v[110:111], off
	v_lshl_add_u64 v[110:111], v[110:111], 0, s[94:95]
	s_add_i32 m0, vcc_lo, 0x1400
	s_nop 0
	global_load_lds_dwordx4 v[112:113], off
	v_lshl_add_u64 v[112:113], v[112:113], 0, s[94:95]
	s_add_i32 m0, vcc_lo, 0x1800
	s_nop 0
	global_load_lds_dwordx4 v[114:115], off
	v_lshl_add_u64 v[114:115], v[114:115], 0, s[94:95]
	s_add_i32 m0, vcc_lo, 0x1c00
	s_nop 0
	global_load_lds_dwordx4 v[116:117], off
	v_lshl_add_u64 v[116:117], v[116:117], 0, s[94:95]
	s_add_i32 m0, vcc_lo, 0x2000
	s_nop 0
	global_load_lds_dwordx4 v[82:83], off
	v_lshl_add_u64 v[82:83], v[82:83], 0, s[94:95]
	s_add_i32 m0, vcc_lo, 0x2400
	s_nop 0
	global_load_lds_dwordx4 v[104:105], off
	v_lshl_add_u64 v[104:105], v[104:105], 0, s[94:95]
	s_add_i32 m0, vcc_lo, 0x2800
	s_nop 0
	global_load_lds_dwordx4 v[106:107], off
	v_lshl_add_u64 v[106:107], v[106:107], 0, s[94:95]
	s_add_i32 m0, vcc_lo, 0x2c00
	s_nop 0
	global_load_lds_dwordx4 v[108:109], off
	v_lshl_add_u64 v[108:109], v[108:109], 0, s[94:95]
	s_add_i32 m0, vcc_lo, 0x3000
	s_nop 0
	global_load_lds_dwordx4 v[110:111], off
	v_lshl_add_u64 v[110:111], v[110:111], 0, s[94:95]
	s_add_i32 m0, vcc_lo, 0x3400
	s_nop 0
	global_load_lds_dwordx4 v[112:113], off
	v_lshl_add_u64 v[112:113], v[112:113], 0, s[94:95]
	s_add_i32 m0, vcc_lo, 0x3800
	s_nop 0
	global_load_lds_dwordx4 v[114:115], off
	v_lshl_add_u64 v[114:115], v[114:115], 0, s[94:95]
	s_add_i32 m0, vcc_lo, 0x3c00
	s_nop 0
	global_load_lds_dwordx4 v[116:117], off
	v_lshl_add_u64 v[116:117], v[116:117], 0, s[94:95]
	s_waitcnt vmcnt(8)
	ds_read_b128 v[68:71], v124
	ds_read_b128 v[72:75], v124 offset:1024
	ds_read_b128 v[76:79], v124 offset:2048
	ds_read_b128 v[84:87], v124 offset:3072
	ds_read_b128 v[88:91], v124 offset:4096
	ds_read_b128 v[92:95], v124 offset:5120
	ds_read_b128 v[96:99], v124 offset:6144
	ds_read_b128 v[100:103], v124 offset:7168
	s_waitcnt lgkmcnt(0)
	s_add_i32 m0, vcc_lo, 0x0
	s_nop 0
	global_load_lds_dwordx4 v[82:83], off
	v_lshl_add_u64 v[82:83], v[82:83], 0, s[94:95]
	s_add_i32 m0, vcc_lo, 0x400
	s_nop 0
	global_load_lds_dwordx4 v[104:105], off
	v_lshl_add_u64 v[104:105], v[104:105], 0, s[94:95]
	s_add_i32 m0, vcc_lo, 0x800
	s_nop 0
	global_load_lds_dwordx4 v[106:107], off
	v_lshl_add_u64 v[106:107], v[106:107], 0, s[94:95]
	s_add_i32 m0, vcc_lo, 0xc00
	s_nop 0
	global_load_lds_dwordx4 v[108:109], off
	v_lshl_add_u64 v[108:109], v[108:109], 0, s[94:95]
	s_add_i32 m0, vcc_lo, 0x1000
	s_nop 0
	global_load_lds_dwordx4 v[110:111], off
	v_lshl_add_u64 v[110:111], v[110:111], 0, s[94:95]
	s_add_i32 m0, vcc_lo, 0x1400
	s_nop 0
	global_load_lds_dwordx4 v[112:113], off
	v_lshl_add_u64 v[112:113], v[112:113], 0, s[94:95]
	s_add_i32 m0, vcc_lo, 0x1800
	s_nop 0
	global_load_lds_dwordx4 v[114:115], off
	v_lshl_add_u64 v[114:115], v[114:115], 0, s[94:95]
	s_add_i32 m0, vcc_lo, 0x1c00
	s_nop 0
	global_load_lds_dwordx4 v[116:117], off
	v_lshl_add_u64 v[116:117], v[116:117], 0, s[94:95]
	v_mfma_f32_16x16x32_bf16 v[56:59], v[88:91], v[68:71], 0
	v_mfma_f32_16x16x32_bf16 v[52:55], v[88:91], v[72:75], 0
	v_mfma_f32_16x16x32_bf16 v[48:51], v[88:91], v[76:79], 0
	v_mfma_f32_16x16x32_bf16 v[44:47], v[88:91], v[84:87], 0
	v_mfma_f32_16x16x32_bf16 v[12:15], v[92:95], v[68:71], 0
	v_mfma_f32_16x16x32_bf16 v[8:11], v[92:95], v[72:75], 0
	v_mfma_f32_16x16x32_bf16 v[4:7], v[92:95], v[76:79], 0
	v_mfma_f32_16x16x32_bf16 v[0:3], v[92:95], v[84:87], 0
	v_mfma_f32_16x16x32_bf16 v[16:19], v[96:99], v[68:71], 0
	v_mfma_f32_16x16x32_bf16 v[24:27], v[96:99], v[72:75], 0
	v_mfma_f32_16x16x32_bf16 v[28:31], v[96:99], v[76:79], 0
	v_mfma_f32_16x16x32_bf16 v[36:39], v[96:99], v[84:87], 0
	v_mfma_f32_16x16x32_bf16 v[20:23], v[100:103], v[68:71], 0
	v_mfma_f32_16x16x32_bf16 v[32:35], v[100:103], v[72:75], 0
	v_mfma_f32_16x16x32_bf16 v[40:43], v[100:103], v[76:79], 0
	v_mfma_f32_16x16x32_bf16 v[60:63], v[100:103], v[84:87], 0
	s_waitcnt vmcnt(8)
	ds_read_b128 v[68:71], v124 offset:8192
	ds_read_b128 v[72:75], v124 offset:9216
	ds_read_b128 v[76:79], v124 offset:10240
	ds_read_b128 v[84:87], v124 offset:11264
	ds_read_b128 v[88:91], v124 offset:12288
	ds_read_b128 v[92:95], v124 offset:13312
	ds_read_b128 v[96:99], v124 offset:14336
	ds_read_b128 v[100:103], v124 offset:15360
	s_waitcnt lgkmcnt(0)
	s_add_i32 m0, vcc_lo, 0x2000
	s_nop 0
	global_load_lds_dwordx4 v[82:83], off
	v_lshl_add_u64 v[82:83], v[82:83], 0, s[94:95]
	s_add_i32 m0, vcc_lo, 0x2400
	s_nop 0
	global_load_lds_dwordx4 v[104:105], off
	v_lshl_add_u64 v[104:105], v[104:105], 0, s[94:95]
	s_add_i32 m0, vcc_lo, 0x2800
	s_nop 0
	global_load_lds_dwordx4 v[106:107], off
	v_lshl_add_u64 v[106:107], v[106:107], 0, s[94:95]
	s_add_i32 m0, vcc_lo, 0x2c00
	s_nop 0
	global_load_lds_dwordx4 v[108:109], off
	v_lshl_add_u64 v[108:109], v[108:109], 0, s[94:95]
	s_add_i32 m0, vcc_lo, 0x3000
	s_nop 0
	global_load_lds_dwordx4 v[110:111], off
	v_lshl_add_u64 v[110:111], v[110:111], 0, s[94:95]
	s_add_i32 m0, vcc_lo, 0x3400
	s_nop 0
	global_load_lds_dwordx4 v[112:113], off
	v_lshl_add_u64 v[112:113], v[112:113], 0, s[94:95]
	s_add_i32 m0, vcc_lo, 0x3800
	s_nop 0
	global_load_lds_dwordx4 v[114:115], off
	v_lshl_add_u64 v[114:115], v[114:115], 0, s[94:95]
	s_add_i32 m0, vcc_lo, 0x3c00
	s_nop 0
	global_load_lds_dwordx4 v[116:117], off
	v_lshl_add_u64 v[116:117], v[116:117], 0, s[94:95]
	v_mfma_f32_16x16x32_bf16 v[56:59], v[88:91], v[68:71], v[56:59]
	v_mfma_f32_16x16x32_bf16 v[52:55], v[88:91], v[72:75], v[52:55]
	v_mfma_f32_16x16x32_bf16 v[48:51], v[88:91], v[76:79], v[48:51]
	v_mfma_f32_16x16x32_bf16 v[44:47], v[88:91], v[84:87], v[44:47]
	v_mfma_f32_16x16x32_bf16 v[12:15], v[92:95], v[68:71], v[12:15]
	v_mfma_f32_16x16x32_bf16 v[8:11], v[92:95], v[72:75], v[8:11]
	v_mfma_f32_16x16x32_bf16 v[4:7], v[92:95], v[76:79], v[4:7]
	v_mfma_f32_16x16x32_bf16 v[0:3], v[92:95], v[84:87], v[0:3]
	v_mfma_f32_16x16x32_bf16 v[16:19], v[96:99], v[68:71], v[16:19]
	v_mfma_f32_16x16x32_bf16 v[24:27], v[96:99], v[72:75], v[24:27]
	v_mfma_f32_16x16x32_bf16 v[28:31], v[96:99], v[76:79], v[28:31]
	v_mfma_f32_16x16x32_bf16 v[36:39], v[96:99], v[84:87], v[36:39]
	v_mfma_f32_16x16x32_bf16 v[20:23], v[100:103], v[68:71], v[20:23]
	v_mfma_f32_16x16x32_bf16 v[32:35], v[100:103], v[72:75], v[32:35]
	v_mfma_f32_16x16x32_bf16 v[40:43], v[100:103], v[76:79], v[40:43]
	v_mfma_f32_16x16x32_bf16 v[60:63], v[100:103], v[84:87], v[60:63]
	s_waitcnt vmcnt(8)
	ds_read_b128 v[68:71], v124
	ds_read_b128 v[72:75], v124 offset:1024
	ds_read_b128 v[76:79], v124 offset:2048
	ds_read_b128 v[84:87], v124 offset:3072
	ds_read_b128 v[88:91], v124 offset:4096
	ds_read_b128 v[92:95], v124 offset:5120
	ds_read_b128 v[96:99], v124 offset:6144
	ds_read_b128 v[100:103], v124 offset:7168
	s_waitcnt lgkmcnt(0)
	s_add_i32 m0, vcc_lo, 0x0
	s_nop 0
	global_load_lds_dwordx4 v[82:83], off
	v_lshl_add_u64 v[82:83], v[82:83], 0, s[94:95]
	s_add_i32 m0, vcc_lo, 0x400
	s_nop 0
	global_load_lds_dwordx4 v[104:105], off
	v_lshl_add_u64 v[104:105], v[104:105], 0, s[94:95]
	s_add_i32 m0, vcc_lo, 0x800
	s_nop 0
	global_load_lds_dwordx4 v[106:107], off
	v_lshl_add_u64 v[106:107], v[106:107], 0, s[94:95]
	s_add_i32 m0, vcc_lo, 0xc00
	s_nop 0
	global_load_lds_dwordx4 v[108:109], off
	v_lshl_add_u64 v[108:109], v[108:109], 0, s[94:95]
	s_add_i32 m0, vcc_lo, 0x1000
	s_nop 0
	global_load_lds_dwordx4 v[110:111], off
	v_lshl_add_u64 v[110:111], v[110:111], 0, s[94:95]
	s_add_i32 m0, vcc_lo, 0x1400
	s_nop 0
	global_load_lds_dwordx4 v[112:113], off
	v_lshl_add_u64 v[112:113], v[112:113], 0, s[94:95]
	s_add_i32 m0, vcc_lo, 0x1800
	s_nop 0
	global_load_lds_dwordx4 v[114:115], off
	v_lshl_add_u64 v[114:115], v[114:115], 0, s[94:95]
	s_add_i32 m0, vcc_lo, 0x1c00
	s_nop 0
	global_load_lds_dwordx4 v[116:117], off
	v_lshl_add_u64 v[116:117], v[116:117], 0, s[94:95]
	v_mfma_f32_16x16x32_bf16 v[56:59], v[88:91], v[68:71], v[56:59]
	v_mfma_f32_16x16x32_bf16 v[52:55], v[88:91], v[72:75], v[52:55]
	v_mfma_f32_16x16x32_bf16 v[48:51], v[88:91], v[76:79], v[48:51]
	v_mfma_f32_16x16x32_bf16 v[44:47], v[88:91], v[84:87], v[44:47]
	v_mfma_f32_16x16x32_bf16 v[12:15], v[92:95], v[68:71], v[12:15]
	v_mfma_f32_16x16x32_bf16 v[8:11], v[92:95], v[72:75], v[8:11]
	v_mfma_f32_16x16x32_bf16 v[4:7], v[92:95], v[76:79], v[4:7]
	v_mfma_f32_16x16x32_bf16 v[0:3], v[92:95], v[84:87], v[0:3]
	v_mfma_f32_16x16x32_bf16 v[16:19], v[96:99], v[68:71], v[16:19]
	v_mfma_f32_16x16x32_bf16 v[24:27], v[96:99], v[72:75], v[24:27]
	v_mfma_f32_16x16x32_bf16 v[28:31], v[96:99], v[76:79], v[28:31]
	v_mfma_f32_16x16x32_bf16 v[36:39], v[96:99], v[84:87], v[36:39]
	v_mfma_f32_16x16x32_bf16 v[20:23], v[100:103], v[68:71], v[20:23]
	v_mfma_f32_16x16x32_bf16 v[32:35], v[100:103], v[72:75], v[32:35]
	v_mfma_f32_16x16x32_bf16 v[40:43], v[100:103], v[76:79], v[40:43]
	v_mfma_f32_16x16x32_bf16 v[60:63], v[100:103], v[84:87], v[60:63]
	s_waitcnt vmcnt(8)
	ds_read_b128 v[68:71], v124 offset:8192
	ds_read_b128 v[72:75], v124 offset:9216
	ds_read_b128 v[76:79], v124 offset:10240
	ds_read_b128 v[84:87], v124 offset:11264
	ds_read_b128 v[88:91], v124 offset:12288
	ds_read_b128 v[92:95], v124 offset:13312
	ds_read_b128 v[96:99], v124 offset:14336
	ds_read_b128 v[100:103], v124 offset:15360
	s_waitcnt lgkmcnt(0)
	s_add_i32 m0, vcc_lo, 0x2000
	s_nop 0
	global_load_lds_dwordx4 v[82:83], off
	v_lshl_add_u64 v[82:83], v[82:83], 0, s[94:95]
	s_add_i32 m0, vcc_lo, 0x2400
	s_nop 0
	global_load_lds_dwordx4 v[104:105], off
	v_lshl_add_u64 v[104:105], v[104:105], 0, s[94:95]
	s_add_i32 m0, vcc_lo, 0x2800
	s_nop 0
	global_load_lds_dwordx4 v[106:107], off
	v_lshl_add_u64 v[106:107], v[106:107], 0, s[94:95]
	s_add_i32 m0, vcc_lo, 0x2c00
	s_nop 0
	global_load_lds_dwordx4 v[108:109], off
	v_lshl_add_u64 v[108:109], v[108:109], 0, s[94:95]
	s_add_i32 m0, vcc_lo, 0x3000
	s_nop 0
	global_load_lds_dwordx4 v[110:111], off
	v_lshl_add_u64 v[110:111], v[110:111], 0, s[94:95]
	s_add_i32 m0, vcc_lo, 0x3400
	s_nop 0
	global_load_lds_dwordx4 v[112:113], off
	v_lshl_add_u64 v[112:113], v[112:113], 0, s[94:95]
	s_add_i32 m0, vcc_lo, 0x3800
	s_nop 0
	global_load_lds_dwordx4 v[114:115], off
	v_lshl_add_u64 v[114:115], v[114:115], 0, s[94:95]
	s_add_i32 m0, vcc_lo, 0x3c00
	s_nop 0
	global_load_lds_dwordx4 v[116:117], off
	v_lshl_add_u64 v[116:117], v[116:117], 0, s[94:95]
	v_mfma_f32_16x16x32_bf16 v[56:59], v[88:91], v[68:71], v[56:59]
	v_mfma_f32_16x16x32_bf16 v[52:55], v[88:91], v[72:75], v[52:55]
	v_mfma_f32_16x16x32_bf16 v[48:51], v[88:91], v[76:79], v[48:51]
	v_mfma_f32_16x16x32_bf16 v[44:47], v[88:91], v[84:87], v[44:47]
	v_mfma_f32_16x16x32_bf16 v[12:15], v[92:95], v[68:71], v[12:15]
	v_mfma_f32_16x16x32_bf16 v[8:11], v[92:95], v[72:75], v[8:11]
	v_mfma_f32_16x16x32_bf16 v[4:7], v[92:95], v[76:79], v[4:7]
	v_mfma_f32_16x16x32_bf16 v[0:3], v[92:95], v[84:87], v[0:3]
	v_mfma_f32_16x16x32_bf16 v[16:19], v[96:99], v[68:71], v[16:19]
	v_mfma_f32_16x16x32_bf16 v[24:27], v[96:99], v[72:75], v[24:27]
	v_mfma_f32_16x16x32_bf16 v[28:31], v[96:99], v[76:79], v[28:31]
	v_mfma_f32_16x16x32_bf16 v[36:39], v[96:99], v[84:87], v[36:39]
	v_mfma_f32_16x16x32_bf16 v[20:23], v[100:103], v[68:71], v[20:23]
	v_mfma_f32_16x16x32_bf16 v[32:35], v[100:103], v[72:75], v[32:35]
	v_mfma_f32_16x16x32_bf16 v[40:43], v[100:103], v[76:79], v[40:43]
	v_mfma_f32_16x16x32_bf16 v[60:63], v[100:103], v[84:87], v[60:63]
	s_waitcnt vmcnt(8)
	ds_read_b128 v[68:71], v124
	ds_read_b128 v[72:75], v124 offset:1024
	ds_read_b128 v[76:79], v124 offset:2048
	ds_read_b128 v[84:87], v124 offset:3072
	ds_read_b128 v[88:91], v124 offset:4096
	ds_read_b128 v[92:95], v124 offset:5120
	ds_read_b128 v[96:99], v124 offset:6144
	ds_read_b128 v[100:103], v124 offset:7168
	s_waitcnt lgkmcnt(0)
	s_add_i32 m0, vcc_lo, 0x0
	s_nop 0
	global_load_lds_dwordx4 v[82:83], off
	v_lshl_add_u64 v[82:83], v[82:83], 0, s[94:95]
	s_add_i32 m0, vcc_lo, 0x400
	s_nop 0
	global_load_lds_dwordx4 v[104:105], off
	v_lshl_add_u64 v[104:105], v[104:105], 0, s[94:95]
	s_add_i32 m0, vcc_lo, 0x800
	s_nop 0
	global_load_lds_dwordx4 v[106:107], off
	v_lshl_add_u64 v[106:107], v[106:107], 0, s[94:95]
	s_add_i32 m0, vcc_lo, 0xc00
	s_nop 0
	global_load_lds_dwordx4 v[108:109], off
	v_lshl_add_u64 v[108:109], v[108:109], 0, s[94:95]
	s_add_i32 m0, vcc_lo, 0x1000
	s_nop 0
	global_load_lds_dwordx4 v[110:111], off
	v_lshl_add_u64 v[110:111], v[110:111], 0, s[94:95]
	s_add_i32 m0, vcc_lo, 0x1400
	s_nop 0
	global_load_lds_dwordx4 v[112:113], off
	v_lshl_add_u64 v[112:113], v[112:113], 0, s[94:95]
	s_add_i32 m0, vcc_lo, 0x1800
	s_nop 0
	global_load_lds_dwordx4 v[114:115], off
	v_lshl_add_u64 v[114:115], v[114:115], 0, s[94:95]
	s_add_i32 m0, vcc_lo, 0x1c00
	s_nop 0
	global_load_lds_dwordx4 v[116:117], off
	v_lshl_add_u64 v[116:117], v[116:117], 0, s[94:95]
	v_mfma_f32_16x16x32_bf16 v[56:59], v[88:91], v[68:71], v[56:59]
	v_mfma_f32_16x16x32_bf16 v[52:55], v[88:91], v[72:75], v[52:55]
	v_mfma_f32_16x16x32_bf16 v[48:51], v[88:91], v[76:79], v[48:51]
	v_mfma_f32_16x16x32_bf16 v[44:47], v[88:91], v[84:87], v[44:47]
	v_mfma_f32_16x16x32_bf16 v[12:15], v[92:95], v[68:71], v[12:15]
	v_mfma_f32_16x16x32_bf16 v[8:11], v[92:95], v[72:75], v[8:11]
	v_mfma_f32_16x16x32_bf16 v[4:7], v[92:95], v[76:79], v[4:7]
	v_mfma_f32_16x16x32_bf16 v[0:3], v[92:95], v[84:87], v[0:3]
	v_mfma_f32_16x16x32_bf16 v[16:19], v[96:99], v[68:71], v[16:19]
	v_mfma_f32_16x16x32_bf16 v[24:27], v[96:99], v[72:75], v[24:27]
	v_mfma_f32_16x16x32_bf16 v[28:31], v[96:99], v[76:79], v[28:31]
	v_mfma_f32_16x16x32_bf16 v[36:39], v[96:99], v[84:87], v[36:39]
	v_mfma_f32_16x16x32_bf16 v[20:23], v[100:103], v[68:71], v[20:23]
	v_mfma_f32_16x16x32_bf16 v[32:35], v[100:103], v[72:75], v[32:35]
	v_mfma_f32_16x16x32_bf16 v[40:43], v[100:103], v[76:79], v[40:43]
	v_mfma_f32_16x16x32_bf16 v[60:63], v[100:103], v[84:87], v[60:63]
	s_waitcnt vmcnt(8)
	ds_read_b128 v[68:71], v124 offset:8192
	ds_read_b128 v[72:75], v124 offset:9216
	ds_read_b128 v[76:79], v124 offset:10240
	ds_read_b128 v[84:87], v124 offset:11264
	ds_read_b128 v[88:91], v124 offset:12288
	ds_read_b128 v[92:95], v124 offset:13312
	ds_read_b128 v[96:99], v124 offset:14336
	ds_read_b128 v[100:103], v124 offset:15360
	s_waitcnt lgkmcnt(0)
	s_add_i32 m0, vcc_lo, 0x2000
	s_nop 0
	global_load_lds_dwordx4 v[82:83], off
	v_lshl_add_u64 v[82:83], v[82:83], 0, s[94:95]
	s_add_i32 m0, vcc_lo, 0x2400
	s_nop 0
	global_load_lds_dwordx4 v[104:105], off
	v_lshl_add_u64 v[104:105], v[104:105], 0, s[94:95]
	s_add_i32 m0, vcc_lo, 0x2800
	s_nop 0
	global_load_lds_dwordx4 v[106:107], off
	v_lshl_add_u64 v[106:107], v[106:107], 0, s[94:95]
	s_add_i32 m0, vcc_lo, 0x2c00
	s_nop 0
	global_load_lds_dwordx4 v[108:109], off
	v_lshl_add_u64 v[108:109], v[108:109], 0, s[94:95]
	s_add_i32 m0, vcc_lo, 0x3000
	s_nop 0
	global_load_lds_dwordx4 v[110:111], off
	v_lshl_add_u64 v[110:111], v[110:111], 0, s[94:95]
	s_add_i32 m0, vcc_lo, 0x3400
	s_nop 0
	global_load_lds_dwordx4 v[112:113], off
	v_lshl_add_u64 v[112:113], v[112:113], 0, s[94:95]
	s_add_i32 m0, vcc_lo, 0x3800
	s_nop 0
	global_load_lds_dwordx4 v[114:115], off
	v_lshl_add_u64 v[114:115], v[114:115], 0, s[94:95]
	s_add_i32 m0, vcc_lo, 0x3c00
	s_nop 0
	global_load_lds_dwordx4 v[116:117], off
	v_lshl_add_u64 v[116:117], v[116:117], 0, s[94:95]
	v_mfma_f32_16x16x32_bf16 v[56:59], v[88:91], v[68:71], v[56:59]
	v_mfma_f32_16x16x32_bf16 v[52:55], v[88:91], v[72:75], v[52:55]
	v_mfma_f32_16x16x32_bf16 v[48:51], v[88:91], v[76:79], v[48:51]
	v_mfma_f32_16x16x32_bf16 v[44:47], v[88:91], v[84:87], v[44:47]
	v_mfma_f32_16x16x32_bf16 v[12:15], v[92:95], v[68:71], v[12:15]
	v_mfma_f32_16x16x32_bf16 v[8:11], v[92:95], v[72:75], v[8:11]
	v_mfma_f32_16x16x32_bf16 v[4:7], v[92:95], v[76:79], v[4:7]
	v_mfma_f32_16x16x32_bf16 v[0:3], v[92:95], v[84:87], v[0:3]
	v_mfma_f32_16x16x32_bf16 v[16:19], v[96:99], v[68:71], v[16:19]
	v_mfma_f32_16x16x32_bf16 v[24:27], v[96:99], v[72:75], v[24:27]
	v_mfma_f32_16x16x32_bf16 v[28:31], v[96:99], v[76:79], v[28:31]
	v_mfma_f32_16x16x32_bf16 v[36:39], v[96:99], v[84:87], v[36:39]
	v_mfma_f32_16x16x32_bf16 v[20:23], v[100:103], v[68:71], v[20:23]
	v_mfma_f32_16x16x32_bf16 v[32:35], v[100:103], v[72:75], v[32:35]
	v_mfma_f32_16x16x32_bf16 v[40:43], v[100:103], v[76:79], v[40:43]
	v_mfma_f32_16x16x32_bf16 v[60:63], v[100:103], v[84:87], v[60:63]
	s_waitcnt vmcnt(8)
	ds_read_b128 v[68:71], v124
	ds_read_b128 v[72:75], v124 offset:1024
	ds_read_b128 v[76:79], v124 offset:2048
	ds_read_b128 v[84:87], v124 offset:3072
	ds_read_b128 v[88:91], v124 offset:4096
	ds_read_b128 v[92:95], v124 offset:5120
	ds_read_b128 v[96:99], v124 offset:6144
	ds_read_b128 v[100:103], v124 offset:7168
	s_waitcnt lgkmcnt(0)
	v_mfma_f32_16x16x32_bf16 v[56:59], v[88:91], v[68:71], v[56:59]
	v_mfma_f32_16x16x32_bf16 v[52:55], v[88:91], v[72:75], v[52:55]
	v_mfma_f32_16x16x32_bf16 v[48:51], v[88:91], v[76:79], v[48:51]
	v_mfma_f32_16x16x32_bf16 v[44:47], v[88:91], v[84:87], v[44:47]
	v_mfma_f32_16x16x32_bf16 v[12:15], v[92:95], v[68:71], v[12:15]
	v_mfma_f32_16x16x32_bf16 v[8:11], v[92:95], v[72:75], v[8:11]
	v_mfma_f32_16x16x32_bf16 v[4:7], v[92:95], v[76:79], v[4:7]
	v_mfma_f32_16x16x32_bf16 v[0:3], v[92:95], v[84:87], v[0:3]
	v_mfma_f32_16x16x32_bf16 v[16:19], v[96:99], v[68:71], v[16:19]
	v_mfma_f32_16x16x32_bf16 v[24:27], v[96:99], v[72:75], v[24:27]
	v_mfma_f32_16x16x32_bf16 v[28:31], v[96:99], v[76:79], v[28:31]
	v_mfma_f32_16x16x32_bf16 v[36:39], v[96:99], v[84:87], v[36:39]
	v_mfma_f32_16x16x32_bf16 v[20:23], v[100:103], v[68:71], v[20:23]
	v_mfma_f32_16x16x32_bf16 v[32:35], v[100:103], v[72:75], v[32:35]
	v_mfma_f32_16x16x32_bf16 v[40:43], v[100:103], v[76:79], v[40:43]
	v_mfma_f32_16x16x32_bf16 v[60:63], v[100:103], v[84:87], v[60:63]
	s_waitcnt vmcnt(0)
	ds_read_b128 v[68:71], v124 offset:8192
	ds_read_b128 v[72:75], v124 offset:9216
	ds_read_b128 v[76:79], v124 offset:10240
	ds_read_b128 v[84:87], v124 offset:11264
	ds_read_b128 v[88:91], v124 offset:12288
	ds_read_b128 v[92:95], v124 offset:13312
	ds_read_b128 v[96:99], v124 offset:14336
	ds_read_b128 v[100:103], v124 offset:15360
	s_waitcnt lgkmcnt(0)
	v_mfma_f32_16x16x32_bf16 v[56:59], v[88:91], v[68:71], v[56:59]
	v_mfma_f32_16x16x32_bf16 v[52:55], v[88:91], v[72:75], v[52:55]
	v_mfma_f32_16x16x32_bf16 v[48:51], v[88:91], v[76:79], v[48:51]
	v_mfma_f32_16x16x32_bf16 v[44:47], v[88:91], v[84:87], v[44:47]
	v_mfma_f32_16x16x32_bf16 v[12:15], v[92:95], v[68:71], v[12:15]
	v_mfma_f32_16x16x32_bf16 v[8:11], v[92:95], v[72:75], v[8:11]
	v_mfma_f32_16x16x32_bf16 v[4:7], v[92:95], v[76:79], v[4:7]
	v_mfma_f32_16x16x32_bf16 v[0:3], v[92:95], v[84:87], v[0:3]
	v_mfma_f32_16x16x32_bf16 v[16:19], v[96:99], v[68:71], v[16:19]
	v_mfma_f32_16x16x32_bf16 v[24:27], v[96:99], v[72:75], v[24:27]
	v_mfma_f32_16x16x32_bf16 v[28:31], v[96:99], v[76:79], v[28:31]
	v_mfma_f32_16x16x32_bf16 v[36:39], v[96:99], v[84:87], v[36:39]
	v_mfma_f32_16x16x32_bf16 v[20:23], v[100:103], v[68:71], v[20:23]
	v_mfma_f32_16x16x32_bf16 v[32:35], v[100:103], v[72:75], v[32:35]
	v_mfma_f32_16x16x32_bf16 v[40:43], v[100:103], v[76:79], v[40:43]
	v_mfma_f32_16x16x32_bf16 v[60:63], v[100:103], v[84:87], v[60:63]
	s_nop 7
	s_nop 3
	v_and_b32_e32 v65, 63, v81
	v_lshl_add_u32 v66, v65, 4, 0
	s_ashr_i32 s10, s0, 7
	v_bfe_u32 v64, v81, 4, 2
	v_lshl_add_u32 v67, s3, 14, v66
	s_lshl_b32 s5, s10, 4
	ds_write_b128 v67, v[56:59]
	ds_write_b128 v67, v[52:55] offset:1024
	ds_write_b128 v67, v[48:51] offset:2048
	ds_write_b128 v67, v[44:47] offset:3072
	ds_write_b128 v67, v[12:15] offset:4096
	ds_write_b128 v67, v[8:11] offset:5120
	ds_write_b128 v67, v[4:7] offset:6144
	ds_write_b128 v67, v[0:3] offset:7168
	ds_write_b128 v67, v[16:19] offset:8192
	ds_write_b128 v67, v[24:27] offset:9216
	ds_write_b128 v67, v[28:31] offset:10240
	ds_write_b128 v67, v[36:39] offset:11264
	ds_write_b128 v67, v[20:23] offset:12288
	ds_write_b128 v67, v[32:35] offset:13312
	ds_write_b128 v67, v[40:43] offset:14336
	ds_write_b128 v67, v[60:63] offset:15360
	s_bfe_u32 s3, s0, 0x10006
	s_addk_i32 s5, 0x4000
	v_lshlrev_b32_e32 v1, 2, v64
	v_or_b32_e32 v0, s5, v80
	v_lshl_or_b32 v1, s3, 4, v1
	v_or_b32_e32 v4, s1, v1
	v_ashrrev_i32_e32 v1, 31, v0
	v_lshlrev_b64 v[2:3], 12, v[0:1]
	s_ashr_i32 s5, s4, 31
	v_lshl_add_u64 v[2:3], s[8:9], 0, v[2:3]
	v_lshl_add_u64 v[2:3], s[4:5], 1, v[2:3]
	v_lshlrev_b32_e32 v128, 1, v4
	v_lshl_add_u64 v[14:15], v[2:3], 0, v[128:129]
	s_waitcnt lgkmcnt(0)
	s_barrier
	global_load_dwordx2 v[16:17], v[14:15], off
	global_load_dwordx2 v[18:19], v[14:15], off offset:256
	s_lshl_b32 s1, s3, 2
	s_add_i32 s1, s1, s10
	v_lshl_add_u32 v28, s1, 10, v66
	ds_read_b128 v[2:5], v28
	ds_read_b128 v[6:9], v28 offset:8192
	ds_read_b128 v[10:13], v28 offset:16384
	v_cmp_gt_u32_e32 vcc, 16, v65
	s_waitcnt lgkmcnt(0)
	v_pk_add_f32 v[20:21], v[4:5], 0 op_sel_hi:[1,0]
	v_pk_add_f32 v[22:23], v[2:3], 0 op_sel_hi:[1,0]
	ds_read_b128 v[2:5], v28 offset:24576
	v_pk_add_f32 v[24:25], v[8:9], 0 op_sel_hi:[1,0]
	v_pk_add_f32 v[26:27], v[6:7], 0 op_sel_hi:[1,0]
	ds_read_b128 v[6:9], v28 offset:32768
	v_pk_add_f32 v[22:23], v[22:23], v[10:11]
	s_waitcnt lgkmcnt(0)
	v_pk_add_f32 v[24:25], v[24:25], v[4:5]
	v_pk_add_f32 v[26:27], v[26:27], v[2:3]
	ds_read_b128 v[2:5], v28 offset:49152
	v_pk_add_f32 v[20:21], v[20:21], v[12:13]
	ds_read_b128 v[10:13], v28 offset:40960
	v_pk_add_f32 v[22:23], v[22:23], v[6:7]
	v_pk_add_f32 v[20:21], v[20:21], v[8:9]
	ds_read_b128 v[6:9], v28 offset:57344
	s_waitcnt lgkmcnt(0)
	v_pk_add_f32 v[22:23], v[22:23], v[2:3]
	v_add_u32_e32 v2, 0x10000, v28
	v_pk_add_f32 v[20:21], v[20:21], v[4:5]
	ds_read_b128 v[2:5], v2
	v_pk_add_f32 v[10:11], v[26:27], v[10:11]
	v_pk_add_f32 v[12:13], v[24:25], v[12:13]
	v_pk_add_f32 v[10:11], v[10:11], v[6:7]
	v_add_u32_e32 v6, 0x12000, v28
	v_pk_add_f32 v[12:13], v[12:13], v[8:9]
	ds_read_b128 v[6:9], v6
	s_waitcnt lgkmcnt(0)
	v_pk_add_f32 v[22:23], v[22:23], v[2:3]
	v_add_u32_e32 v2, 0x14000, v28
	v_pk_add_f32 v[20:21], v[20:21], v[4:5]
	ds_read_b128 v[2:5], v2
	v_pk_add_f32 v[10:11], v[10:11], v[6:7]
	v_add_u32_e32 v6, 0x16000, v28
	v_pk_add_f32 v[12:13], v[12:13], v[8:9]
	ds_read_b128 v[6:9], v6
	s_waitcnt lgkmcnt(0)
	v_pk_add_f32 v[22:23], v[22:23], v[2:3]
	v_add_u32_e32 v2, 0x18000, v28
	v_pk_add_f32 v[20:21], v[20:21], v[4:5]
	ds_read_b128 v[2:5], v2
	v_pk_add_f32 v[26:27], v[10:11], v[6:7]
	v_add_u32_e32 v6, 0x1a000, v28
	v_pk_add_f32 v[24:25], v[12:13], v[8:9]
	ds_read_b128 v[6:9], v6
	s_waitcnt lgkmcnt(0)
	v_pk_add_f32 v[22:23], v[22:23], v[2:3]
	v_add_u32_e32 v2, 0x1c000, v28
	v_add_u32_e32 v10, 0x1e000, v28
	v_pk_add_f32 v[20:21], v[20:21], v[4:5]
	ds_read_b128 v[2:5], v2
	ds_read_b128 v[10:13], v10
	v_pk_add_f32 v[6:7], v[26:27], v[6:7]
	v_pk_add_f32 v[8:9], v[24:25], v[8:9]
	s_waitcnt lgkmcnt(0)
	v_pk_add_f32 v[2:3], v[22:23], v[2:3]
	v_pk_add_f32 v[6:7], v[6:7], v[10:11]
	v_pk_add_f32 v[4:5], v[20:21], v[4:5]
	v_pk_add_f32 v[8:9], v[8:9], v[12:13]
	s_waitcnt vmcnt(0)
	v_lshlrev_b32_e32 v10, 16, v16
	v_and_b32_e32 v11, 0xffff0000, v16
	v_pk_add_f32 v[2:3], v[2:3], v[10:11]
	v_lshlrev_b32_e32 v10, 16, v18
	v_and_b32_e32 v11, 0xffff0000, v18
	v_lshlrev_b32_e32 v12, 16, v17
	v_and_b32_e32 v13, 0xffff0000, v17
	v_pk_add_f32 v[6:7], v[6:7], v[10:11]
	v_pk_add_f32 v[4:5], v[4:5], v[12:13]
	v_lshlrev_b32_e32 v12, 16, v19
	v_and_b32_e32 v13, 0xffff0000, v19
	v_mul_f32_e32 v10, v6, v6
	v_mul_f32_e32 v11, v7, v7
	v_pk_add_f32 v[8:9], v[8:9], v[12:13]
	v_fmac_f32_e32 v10, v2, v2
	v_fmac_f32_e32 v11, v3, v3
	v_add_f32_e32 v10, v10, v11
	v_mul_f32_e32 v11, v8, v8
	v_fmac_f32_e32 v11, v4, v4
	v_add_f32_e32 v10, v11, v10
	v_mul_f32_e32 v11, v9, v9
	v_fmac_f32_e32 v11, v5, v5
	v_add_f32_e32 v10, v11, v10
	ds_bpermute_b32 v11, v216, v10
	v_cvt_pk_bf16_f32 v2, v2, v3
	v_cvt_pk_bf16_f32 v3, v4, v5
	global_store_dwordx2 v[14:15], v[2:3], off
	v_cvt_pk_bf16_f32 v2, v6, v7
	s_waitcnt lgkmcnt(0)
	v_add_f32_e32 v4, v10, v11
	ds_bpermute_b32 v5, v217, v4
	v_cvt_pk_bf16_f32 v3, v8, v9
	global_store_dwordx2 v[14:15], v[2:3], off offset:256
	s_waitcnt lgkmcnt(0)
	v_add_f32_e32 v2, v4, v5
	s_and_saveexec_b64 s[4:5], vcc
	s_and_b32 s1, s0, 0xffffffc0
	s_add_i32 s1, s1, 0
	v_lshl_add_u32 v3, v80, 2, s1
	v_add_u32_e32 v3, 0x20100, v3
	ds_write_b32 v3, v2
	s_or_b64 exec, exec, s[4:5]
	v_or_b32_e32 v3, s3, v64
	v_cmp_eq_u32_e32 vcc, 0, v3
	s_waitcnt lgkmcnt(0)
	s_barrier
	s_and_saveexec_b64 s[4:5], vcc
	s_cbranch_execz .LBB0_802
	s_andn2_b32 s0, s0, 63
	s_add_i32 s0, s0, 0
	s_add_i32 s0, s0, 0x20100
	v_lshl_add_u32 v3, v80, 2, s0
	ds_read_b32 v3, v3 offset:64
	v_lshlrev_b64 v[0:1], 7, v[0:1]
	v_lshl_add_u64 v[0:1], s[6:7], 0, v[0:1]
	s_ashr_i32 s3, s2, 31
	v_lshl_add_u64 v[0:1], s[2:3], 2, v[0:1]
	s_waitcnt lgkmcnt(0)
	v_add_f32_e32 v2, v2, v3
	global_store_dword v[0:1], v2, off

.LBB0_884:
	v_lshrrev_b32_e32 v122, 2, v214
	v_and_b32_e32 v123, 15, v214
	v_sub_u32_e32 v122, v122, v123
	v_mul_i32_i24_e32 v122, 0x1000, v122
	v_bfe_u32 v125, v214, 5, 1
	v_lshlrev_b32_e32 v125, 1, v125
	v_and_b32_e32 v124, 3, v214
	v_xor_b32_e32 v125, v125, v124
	v_lshrrev_b32_e32 v124, 4, v214
	v_sub_u32_e32 v125, v125, v124
	v_lshl_add_u32 v122, v125, 4, v122
	v_ashrrev_i32_e32 v125, 31, v122
	v_add_co_u32_e32 v118, vcc, v66, v122
	s_nop 1
	v_addc_co_u32_e32 v119, vcc, v67, v125, vcc
	v_add_co_u32_e32 v120, vcc, v64, v122
	s_nop 1
	v_addc_co_u32_e32 v121, vcc, v65, v125, vcc
	v_add_co_u32_e32 v82, vcc, s84, v118
	s_nop 1
	v_addc_co_u32_e32 v83, vcc, 0, v119, vcc
	v_add_co_u32_e32 v104, vcc, s85, v118
	s_nop 1
	v_addc_co_u32_e32 v105, vcc, 0, v119, vcc
	v_add_co_u32_e32 v106, vcc, s88, v118
	s_nop 1
	v_addc_co_u32_e32 v107, vcc, 0, v119, vcc
	v_add_co_u32_e32 v108, vcc, s89, v118
	s_nop 1
	v_addc_co_u32_e32 v109, vcc, 0, v119, vcc
	v_add_co_u32_e32 v110, vcc, 0x8000, v120
	s_nop 1
	v_addc_co_u32_e32 v111, vcc, 0, v121, vcc
	v_add_co_u32_e32 v112, vcc, 0x18000, v120
	s_nop 1
	v_addc_co_u32_e32 v113, vcc, 0, v121, vcc
	v_add_co_u32_e32 v114, vcc, 0x88000, v120
	s_nop 1
	v_addc_co_u32_e32 v115, vcc, 0, v121, vcc
	v_add_co_u32_e32 v116, vcc, 0x98000, v120
	s_nop 1
	v_addc_co_u32_e32 v117, vcc, 0, v121, vcc
	v_readfirstlane_b32 vcc_lo, v210
	v_bfe_u32 v125, v214, 3, 1
	v_lshlrev_b32_e32 v125, 1, v125
	v_xor_b32_e32 v125, v125, v124
	v_lshlrev_b32_e32 v125, 4, v125
	v_lshl_add_u32 v125, v123, 6, v125
	s_lshr_b32 vcc_lo, vcc_lo, 6
	s_lshl_b32 vcc_lo, vcc_lo, 14
	s_mov_b32 s94, 64
	v_add_u32_e32 v124, vcc_lo, v125
	s_add_i32 m0, vcc_lo, 0x0
	s_nop 0
	global_load_lds_dwordx4 v[82:83], off
	v_lshl_add_u64 v[82:83], v[82:83], 0, s[94:95]
	s_add_i32 m0, vcc_lo, 0x400
	s_nop 0
	global_load_lds_dwordx4 v[104:105], off
	v_lshl_add_u64 v[104:105], v[104:105], 0, s[94:95]
	s_add_i32 m0, vcc_lo, 0x800
	s_nop 0
	global_load_lds_dwordx4 v[106:107], off
	v_lshl_add_u64 v[106:107], v[106:107], 0, s[94:95]
	s_add_i32 m0, vcc_lo, 0xc00
	s_nop 0
	global_load_lds_dwordx4 v[108:109], off
	v_lshl_add_u64 v[108:109], v[108:109], 0, s[94:95]
	s_add_i32 m0, vcc_lo, 0x1000
	s_nop 0
	global_load_lds_dwordx4 v[110:111], off
	v_lshl_add_u64 v[110:111], v[110:111], 0, s[94:95]
	s_add_i32 m0, vcc_lo, 0x1400
	s_nop 0
	global_load_lds_dwordx4 v[112:113], off
	v_lshl_add_u64 v[112:113], v[112:113], 0, s[94:95]
	s_add_i32 m0, vcc_lo, 0x1800
	s_nop 0
	global_load_lds_dwordx4 v[114:115], off
	v_lshl_add_u64 v[114:115], v[114:115], 0, s[94:95]
	s_add_i32 m0, vcc_lo, 0x1c00
	s_nop 0
	global_load_lds_dwordx4 v[116:117], off
	v_lshl_add_u64 v[116:117], v[116:117], 0, s[94:95]
	s_add_i32 m0, vcc_lo, 0x2000
	s_nop 0
	global_load_lds_dwordx4 v[82:83], off
	v_lshl_add_u64 v[82:83], v[82:83], 0, s[94:95]
	s_add_i32 m0, vcc_lo, 0x2400
	s_nop 0
	global_load_lds_dwordx4 v[104:105], off
	v_lshl_add_u64 v[104:105], v[104:105], 0, s[94:95]
	s_add_i32 m0, vcc_lo, 0x2800
	s_nop 0
	global_load_lds_dwordx4 v[106:107], off
	v_lshl_add_u64 v[106:107], v[106:107], 0, s[94:95]
	s_add_i32 m0, vcc_lo, 0x2c00
	s_nop 0
	global_load_lds_dwordx4 v[108:109], off
	v_lshl_add_u64 v[108:109], v[108:109], 0, s[94:95]
	s_add_i32 m0, vcc_lo, 0x3000
	s_nop 0
	global_load_lds_dwordx4 v[110:111], off
	v_lshl_add_u64 v[110:111], v[110:111], 0, s[94:95]
	s_add_i32 m0, vcc_lo, 0x3400
	s_nop 0
	global_load_lds_dwordx4 v[112:113], off
	v_lshl_add_u64 v[112:113], v[112:113], 0, s[94:95]
	s_add_i32 m0, vcc_lo, 0x3800
	s_nop 0
	global_load_lds_dwordx4 v[114:115], off
	v_lshl_add_u64 v[114:115], v[114:115], 0, s[94:95]
	s_add_i32 m0, vcc_lo, 0x3c00
	s_nop 0
	global_load_lds_dwordx4 v[116:117], off
	v_lshl_add_u64 v[116:117], v[116:117], 0, s[94:95]
	s_waitcnt vmcnt(8)
	ds_read_b128 v[68:71], v124
	ds_read_b128 v[72:75], v124 offset:1024
	ds_read_b128 v[76:79], v124 offset:2048
	ds_read_b128 v[84:87], v124 offset:3072
	ds_read_b128 v[88:91], v124 offset:4096
	ds_read_b128 v[92:95], v124 offset:5120
	ds_read_b128 v[96:99], v124 offset:6144
	ds_read_b128 v[100:103], v124 offset:7168
	s_waitcnt lgkmcnt(0)
	s_add_i32 m0, vcc_lo, 0x0
	s_nop 0
	global_load_lds_dwordx4 v[82:83], off
	v_lshl_add_u64 v[82:83], v[82:83], 0, s[94:95]
	s_add_i32 m0, vcc_lo, 0x400
	s_nop 0
	global_load_lds_dwordx4 v[104:105], off
	v_lshl_add_u64 v[104:105], v[104:105], 0, s[94:95]
	s_add_i32 m0, vcc_lo, 0x800
	s_nop 0
	global_load_lds_dwordx4 v[106:107], off
	v_lshl_add_u64 v[106:107], v[106:107], 0, s[94:95]
	s_add_i32 m0, vcc_lo, 0xc00
	s_nop 0
	global_load_lds_dwordx4 v[108:109], off
	v_lshl_add_u64 v[108:109], v[108:109], 0, s[94:95]
	s_add_i32 m0, vcc_lo, 0x1000
	s_nop 0
	global_load_lds_dwordx4 v[110:111], off
	v_lshl_add_u64 v[110:111], v[110:111], 0, s[94:95]
	s_add_i32 m0, vcc_lo, 0x1400
	s_nop 0
	global_load_lds_dwordx4 v[112:113], off
	v_lshl_add_u64 v[112:113], v[112:113], 0, s[94:95]
	s_add_i32 m0, vcc_lo, 0x1800
	s_nop 0
	global_load_lds_dwordx4 v[114:115], off
	v_lshl_add_u64 v[114:115], v[114:115], 0, s[94:95]
	s_add_i32 m0, vcc_lo, 0x1c00
	s_nop 0
	global_load_lds_dwordx4 v[116:117], off
	v_lshl_add_u64 v[116:117], v[116:117], 0, s[94:95]
	v_mfma_f32_16x16x32_bf16 v[56:59], v[88:91], v[68:71], 0
	v_mfma_f32_16x16x32_bf16 v[52:55], v[88:91], v[72:75], 0
	v_mfma_f32_16x16x32_bf16 v[48:51], v[88:91], v[76:79], 0
	v_mfma_f32_16x16x32_bf16 v[44:47], v[88:91], v[84:87], 0
	v_mfma_f32_16x16x32_bf16 v[12:15], v[92:95], v[68:71], 0
	v_mfma_f32_16x16x32_bf16 v[8:11], v[92:95], v[72:75], 0
	v_mfma_f32_16x16x32_bf16 v[4:7], v[92:95], v[76:79], 0
	v_mfma_f32_16x16x32_bf16 v[0:3], v[92:95], v[84:87], 0
	v_mfma_f32_16x16x32_bf16 v[16:19], v[96:99], v[68:71], 0
	v_mfma_f32_16x16x32_bf16 v[24:27], v[96:99], v[72:75], 0
	v_mfma_f32_16x16x32_bf16 v[28:31], v[96:99], v[76:79], 0
	v_mfma_f32_16x16x32_bf16 v[36:39], v[96:99], v[84:87], 0
	v_mfma_f32_16x16x32_bf16 v[20:23], v[100:103], v[68:71], 0
	v_mfma_f32_16x16x32_bf16 v[32:35], v[100:103], v[72:75], 0
	v_mfma_f32_16x16x32_bf16 v[40:43], v[100:103], v[76:79], 0
	v_mfma_f32_16x16x32_bf16 v[60:63], v[100:103], v[84:87], 0
	s_waitcnt vmcnt(8)
	ds_read_b128 v[68:71], v124 offset:8192
	ds_read_b128 v[72:75], v124 offset:9216
	ds_read_b128 v[76:79], v124 offset:10240
	ds_read_b128 v[84:87], v124 offset:11264
	ds_read_b128 v[88:91], v124 offset:12288
	ds_read_b128 v[92:95], v124 offset:13312
	ds_read_b128 v[96:99], v124 offset:14336
	ds_read_b128 v[100:103], v124 offset:15360
	s_waitcnt lgkmcnt(0)
	s_add_i32 m0, vcc_lo, 0x2000
	s_nop 0
	global_load_lds_dwordx4 v[82:83], off
	v_lshl_add_u64 v[82:83], v[82:83], 0, s[94:95]
	s_add_i32 m0, vcc_lo, 0x2400
	s_nop 0
	global_load_lds_dwordx4 v[104:105], off
	v_lshl_add_u64 v[104:105], v[104:105], 0, s[94:95]
	s_add_i32 m0, vcc_lo, 0x2800
	s_nop 0
	global_load_lds_dwordx4 v[106:107], off
	v_lshl_add_u64 v[106:107], v[106:107], 0, s[94:95]
	s_add_i32 m0, vcc_lo, 0x2c00
	s_nop 0
	global_load_lds_dwordx4 v[108:109], off
	v_lshl_add_u64 v[108:109], v[108:109], 0, s[94:95]
	s_add_i32 m0, vcc_lo, 0x3000
	s_nop 0
	global_load_lds_dwordx4 v[110:111], off
	v_lshl_add_u64 v[110:111], v[110:111], 0, s[94:95]
	s_add_i32 m0, vcc_lo, 0x3400
	s_nop 0
	global_load_lds_dwordx4 v[112:113], off
	v_lshl_add_u64 v[112:113], v[112:113], 0, s[94:95]
	s_add_i32 m0, vcc_lo, 0x3800
	s_nop 0
	global_load_lds_dwordx4 v[114:115], off
	v_lshl_add_u64 v[114:115], v[114:115], 0, s[94:95]
	s_add_i32 m0, vcc_lo, 0x3c00
	s_nop 0
	global_load_lds_dwordx4 v[116:117], off
	v_lshl_add_u64 v[116:117], v[116:117], 0, s[94:95]
	v_mfma_f32_16x16x32_bf16 v[56:59], v[88:91], v[68:71], v[56:59]
	v_mfma_f32_16x16x32_bf16 v[52:55], v[88:91], v[72:75], v[52:55]
	v_mfma_f32_16x16x32_bf16 v[48:51], v[88:91], v[76:79], v[48:51]
	v_mfma_f32_16x16x32_bf16 v[44:47], v[88:91], v[84:87], v[44:47]
	v_mfma_f32_16x16x32_bf16 v[12:15], v[92:95], v[68:71], v[12:15]
	v_mfma_f32_16x16x32_bf16 v[8:11], v[92:95], v[72:75], v[8:11]
	v_mfma_f32_16x16x32_bf16 v[4:7], v[92:95], v[76:79], v[4:7]
	v_mfma_f32_16x16x32_bf16 v[0:3], v[92:95], v[84:87], v[0:3]
	v_mfma_f32_16x16x32_bf16 v[16:19], v[96:99], v[68:71], v[16:19]
	v_mfma_f32_16x16x32_bf16 v[24:27], v[96:99], v[72:75], v[24:27]
	v_mfma_f32_16x16x32_bf16 v[28:31], v[96:99], v[76:79], v[28:31]
	v_mfma_f32_16x16x32_bf16 v[36:39], v[96:99], v[84:87], v[36:39]
	v_mfma_f32_16x16x32_bf16 v[20:23], v[100:103], v[68:71], v[20:23]
	v_mfma_f32_16x16x32_bf16 v[32:35], v[100:103], v[72:75], v[32:35]
	v_mfma_f32_16x16x32_bf16 v[40:43], v[100:103], v[76:79], v[40:43]
	v_mfma_f32_16x16x32_bf16 v[60:63], v[100:103], v[84:87], v[60:63]
	s_waitcnt vmcnt(8)
	ds_read_b128 v[68:71], v124
	ds_read_b128 v[72:75], v124 offset:1024
	ds_read_b128 v[76:79], v124 offset:2048
	ds_read_b128 v[84:87], v124 offset:3072
	ds_read_b128 v[88:91], v124 offset:4096
	ds_read_b128 v[92:95], v124 offset:5120
	ds_read_b128 v[96:99], v124 offset:6144
	ds_read_b128 v[100:103], v124 offset:7168
	s_waitcnt lgkmcnt(0)
	s_add_i32 m0, vcc_lo, 0x0
	s_nop 0
	global_load_lds_dwordx4 v[82:83], off
	v_lshl_add_u64 v[82:83], v[82:83], 0, s[94:95]
	s_add_i32 m0, vcc_lo, 0x400
	s_nop 0
	global_load_lds_dwordx4 v[104:105], off
	v_lshl_add_u64 v[104:105], v[104:105], 0, s[94:95]
	s_add_i32 m0, vcc_lo, 0x800
	s_nop 0
	global_load_lds_dwordx4 v[106:107], off
	v_lshl_add_u64 v[106:107], v[106:107], 0, s[94:95]
	s_add_i32 m0, vcc_lo, 0xc00
	s_nop 0
	global_load_lds_dwordx4 v[108:109], off
	v_lshl_add_u64 v[108:109], v[108:109], 0, s[94:95]
	s_add_i32 m0, vcc_lo, 0x1000
	s_nop 0
	global_load_lds_dwordx4 v[110:111], off
	v_lshl_add_u64 v[110:111], v[110:111], 0, s[94:95]
	s_add_i32 m0, vcc_lo, 0x1400
	s_nop 0
	global_load_lds_dwordx4 v[112:113], off
	v_lshl_add_u64 v[112:113], v[112:113], 0, s[94:95]
	s_add_i32 m0, vcc_lo, 0x1800
	s_nop 0
	global_load_lds_dwordx4 v[114:115], off
	v_lshl_add_u64 v[114:115], v[114:115], 0, s[94:95]
	s_add_i32 m0, vcc_lo, 0x1c00
	s_nop 0
	global_load_lds_dwordx4 v[116:117], off
	v_lshl_add_u64 v[116:117], v[116:117], 0, s[94:95]
	v_mfma_f32_16x16x32_bf16 v[56:59], v[88:91], v[68:71], v[56:59]
	v_mfma_f32_16x16x32_bf16 v[52:55], v[88:91], v[72:75], v[52:55]
	v_mfma_f32_16x16x32_bf16 v[48:51], v[88:91], v[76:79], v[48:51]
	v_mfma_f32_16x16x32_bf16 v[44:47], v[88:91], v[84:87], v[44:47]
	v_mfma_f32_16x16x32_bf16 v[12:15], v[92:95], v[68:71], v[12:15]
	v_mfma_f32_16x16x32_bf16 v[8:11], v[92:95], v[72:75], v[8:11]
	v_mfma_f32_16x16x32_bf16 v[4:7], v[92:95], v[76:79], v[4:7]
	v_mfma_f32_16x16x32_bf16 v[0:3], v[92:95], v[84:87], v[0:3]
	v_mfma_f32_16x16x32_bf16 v[16:19], v[96:99], v[68:71], v[16:19]
	v_mfma_f32_16x16x32_bf16 v[24:27], v[96:99], v[72:75], v[24:27]
	v_mfma_f32_16x16x32_bf16 v[28:31], v[96:99], v[76:79], v[28:31]
	v_mfma_f32_16x16x32_bf16 v[36:39], v[96:99], v[84:87], v[36:39]
	v_mfma_f32_16x16x32_bf16 v[20:23], v[100:103], v[68:71], v[20:23]
	v_mfma_f32_16x16x32_bf16 v[32:35], v[100:103], v[72:75], v[32:35]
	v_mfma_f32_16x16x32_bf16 v[40:43], v[100:103], v[76:79], v[40:43]
	v_mfma_f32_16x16x32_bf16 v[60:63], v[100:103], v[84:87], v[60:63]
	s_waitcnt vmcnt(8)
	ds_read_b128 v[68:71], v124 offset:8192
	ds_read_b128 v[72:75], v124 offset:9216
	ds_read_b128 v[76:79], v124 offset:10240
	ds_read_b128 v[84:87], v124 offset:11264
	ds_read_b128 v[88:91], v124 offset:12288
	ds_read_b128 v[92:95], v124 offset:13312
	ds_read_b128 v[96:99], v124 offset:14336
	ds_read_b128 v[100:103], v124 offset:15360
	s_waitcnt lgkmcnt(0)
	s_add_i32 m0, vcc_lo, 0x2000
	s_nop 0
	global_load_lds_dwordx4 v[82:83], off
	v_lshl_add_u64 v[82:83], v[82:83], 0, s[94:95]
	s_add_i32 m0, vcc_lo, 0x2400
	s_nop 0
	global_load_lds_dwordx4 v[104:105], off
	v_lshl_add_u64 v[104:105], v[104:105], 0, s[94:95]
	s_add_i32 m0, vcc_lo, 0x2800
	s_nop 0
	global_load_lds_dwordx4 v[106:107], off
	v_lshl_add_u64 v[106:107], v[106:107], 0, s[94:95]
	s_add_i32 m0, vcc_lo, 0x2c00
	s_nop 0
	global_load_lds_dwordx4 v[108:109], off
	v_lshl_add_u64 v[108:109], v[108:109], 0, s[94:95]
	s_add_i32 m0, vcc_lo, 0x3000
	s_nop 0
	global_load_lds_dwordx4 v[110:111], off
	v_lshl_add_u64 v[110:111], v[110:111], 0, s[94:95]
	s_add_i32 m0, vcc_lo, 0x3400
	s_nop 0
	global_load_lds_dwordx4 v[112:113], off
	v_lshl_add_u64 v[112:113], v[112:113], 0, s[94:95]
	s_add_i32 m0, vcc_lo, 0x3800
	s_nop 0
	global_load_lds_dwordx4 v[114:115], off
	v_lshl_add_u64 v[114:115], v[114:115], 0, s[94:95]
	s_add_i32 m0, vcc_lo, 0x3c00
	s_nop 0
	global_load_lds_dwordx4 v[116:117], off
	v_lshl_add_u64 v[116:117], v[116:117], 0, s[94:95]
	v_mfma_f32_16x16x32_bf16 v[56:59], v[88:91], v[68:71], v[56:59]
	v_mfma_f32_16x16x32_bf16 v[52:55], v[88:91], v[72:75], v[52:55]
	v_mfma_f32_16x16x32_bf16 v[48:51], v[88:91], v[76:79], v[48:51]
	v_mfma_f32_16x16x32_bf16 v[44:47], v[88:91], v[84:87], v[44:47]
	v_mfma_f32_16x16x32_bf16 v[12:15], v[92:95], v[68:71], v[12:15]
	v_mfma_f32_16x16x32_bf16 v[8:11], v[92:95], v[72:75], v[8:11]
	v_mfma_f32_16x16x32_bf16 v[4:7], v[92:95], v[76:79], v[4:7]
	v_mfma_f32_16x16x32_bf16 v[0:3], v[92:95], v[84:87], v[0:3]
	v_mfma_f32_16x16x32_bf16 v[16:19], v[96:99], v[68:71], v[16:19]
	v_mfma_f32_16x16x32_bf16 v[24:27], v[96:99], v[72:75], v[24:27]
	v_mfma_f32_16x16x32_bf16 v[28:31], v[96:99], v[76:79], v[28:31]
	v_mfma_f32_16x16x32_bf16 v[36:39], v[96:99], v[84:87], v[36:39]
	v_mfma_f32_16x16x32_bf16 v[20:23], v[100:103], v[68:71], v[20:23]
	v_mfma_f32_16x16x32_bf16 v[32:35], v[100:103], v[72:75], v[32:35]
	v_mfma_f32_16x16x32_bf16 v[40:43], v[100:103], v[76:79], v[40:43]
	v_mfma_f32_16x16x32_bf16 v[60:63], v[100:103], v[84:87], v[60:63]
	s_waitcnt vmcnt(8)
	ds_read_b128 v[68:71], v124
	ds_read_b128 v[72:75], v124 offset:1024
	ds_read_b128 v[76:79], v124 offset:2048
	ds_read_b128 v[84:87], v124 offset:3072
	ds_read_b128 v[88:91], v124 offset:4096
	ds_read_b128 v[92:95], v124 offset:5120
	ds_read_b128 v[96:99], v124 offset:6144
	ds_read_b128 v[100:103], v124 offset:7168
	s_waitcnt lgkmcnt(0)
	s_add_i32 m0, vcc_lo, 0x0
	s_nop 0
	global_load_lds_dwordx4 v[82:83], off
	v_lshl_add_u64 v[82:83], v[82:83], 0, s[94:95]
	s_add_i32 m0, vcc_lo, 0x400
	s_nop 0
	global_load_lds_dwordx4 v[104:105], off
	v_lshl_add_u64 v[104:105], v[104:105], 0, s[94:95]
	s_add_i32 m0, vcc_lo, 0x800
	s_nop 0
	global_load_lds_dwordx4 v[106:107], off
	v_lshl_add_u64 v[106:107], v[106:107], 0, s[94:95]
	s_add_i32 m0, vcc_lo, 0xc00
	s_nop 0
	global_load_lds_dwordx4 v[108:109], off
	v_lshl_add_u64 v[108:109], v[108:109], 0, s[94:95]
	s_add_i32 m0, vcc_lo, 0x1000
	s_nop 0
	global_load_lds_dwordx4 v[110:111], off
	v_lshl_add_u64 v[110:111], v[110:111], 0, s[94:95]
	s_add_i32 m0, vcc_lo, 0x1400
	s_nop 0
	global_load_lds_dwordx4 v[112:113], off
	v_lshl_add_u64 v[112:113], v[112:113], 0, s[94:95]
	s_add_i32 m0, vcc_lo, 0x1800
	s_nop 0
	global_load_lds_dwordx4 v[114:115], off
	v_lshl_add_u64 v[114:115], v[114:115], 0, s[94:95]
	s_add_i32 m0, vcc_lo, 0x1c00
	s_nop 0
	global_load_lds_dwordx4 v[116:117], off
	v_lshl_add_u64 v[116:117], v[116:117], 0, s[94:95]
	v_mfma_f32_16x16x32_bf16 v[56:59], v[88:91], v[68:71], v[56:59]
	v_mfma_f32_16x16x32_bf16 v[52:55], v[88:91], v[72:75], v[52:55]
	v_mfma_f32_16x16x32_bf16 v[48:51], v[88:91], v[76:79], v[48:51]
	v_mfma_f32_16x16x32_bf16 v[44:47], v[88:91], v[84:87], v[44:47]
	v_mfma_f32_16x16x32_bf16 v[12:15], v[92:95], v[68:71], v[12:15]
	v_mfma_f32_16x16x32_bf16 v[8:11], v[92:95], v[72:75], v[8:11]
	v_mfma_f32_16x16x32_bf16 v[4:7], v[92:95], v[76:79], v[4:7]
	v_mfma_f32_16x16x32_bf16 v[0:3], v[92:95], v[84:87], v[0:3]
	v_mfma_f32_16x16x32_bf16 v[16:19], v[96:99], v[68:71], v[16:19]
	v_mfma_f32_16x16x32_bf16 v[24:27], v[96:99], v[72:75], v[24:27]
	v_mfma_f32_16x16x32_bf16 v[28:31], v[96:99], v[76:79], v[28:31]
	v_mfma_f32_16x16x32_bf16 v[36:39], v[96:99], v[84:87], v[36:39]
	v_mfma_f32_16x16x32_bf16 v[20:23], v[100:103], v[68:71], v[20:23]
	v_mfma_f32_16x16x32_bf16 v[32:35], v[100:103], v[72:75], v[32:35]
	v_mfma_f32_16x16x32_bf16 v[40:43], v[100:103], v[76:79], v[40:43]
	v_mfma_f32_16x16x32_bf16 v[60:63], v[100:103], v[84:87], v[60:63]
	s_waitcnt vmcnt(8)
	ds_read_b128 v[68:71], v124 offset:8192
	ds_read_b128 v[72:75], v124 offset:9216
	ds_read_b128 v[76:79], v124 offset:10240
	ds_read_b128 v[84:87], v124 offset:11264
	ds_read_b128 v[88:91], v124 offset:12288
	ds_read_b128 v[92:95], v124 offset:13312
	ds_read_b128 v[96:99], v124 offset:14336
	ds_read_b128 v[100:103], v124 offset:15360
	s_waitcnt lgkmcnt(0)
	s_add_i32 m0, vcc_lo, 0x2000
	s_nop 0
	global_load_lds_dwordx4 v[82:83], off
	v_lshl_add_u64 v[82:83], v[82:83], 0, s[94:95]
	s_add_i32 m0, vcc_lo, 0x2400
	s_nop 0
	global_load_lds_dwordx4 v[104:105], off
	v_lshl_add_u64 v[104:105], v[104:105], 0, s[94:95]
	s_add_i32 m0, vcc_lo, 0x2800
	s_nop 0
	global_load_lds_dwordx4 v[106:107], off
	v_lshl_add_u64 v[106:107], v[106:107], 0, s[94:95]
	s_add_i32 m0, vcc_lo, 0x2c00
	s_nop 0
	global_load_lds_dwordx4 v[108:109], off
	v_lshl_add_u64 v[108:109], v[108:109], 0, s[94:95]
	s_add_i32 m0, vcc_lo, 0x3000
	s_nop 0
	global_load_lds_dwordx4 v[110:111], off
	v_lshl_add_u64 v[110:111], v[110:111], 0, s[94:95]
	s_add_i32 m0, vcc_lo, 0x3400
	s_nop 0
	global_load_lds_dwordx4 v[112:113], off
	v_lshl_add_u64 v[112:113], v[112:113], 0, s[94:95]
	s_add_i32 m0, vcc_lo, 0x3800
	s_nop 0
	global_load_lds_dwordx4 v[114:115], off
	v_lshl_add_u64 v[114:115], v[114:115], 0, s[94:95]
	s_add_i32 m0, vcc_lo, 0x3c00
	s_nop 0
	global_load_lds_dwordx4 v[116:117], off
	v_lshl_add_u64 v[116:117], v[116:117], 0, s[94:95]
	v_mfma_f32_16x16x32_bf16 v[56:59], v[88:91], v[68:71], v[56:59]
	v_mfma_f32_16x16x32_bf16 v[52:55], v[88:91], v[72:75], v[52:55]
	v_mfma_f32_16x16x32_bf16 v[48:51], v[88:91], v[76:79], v[48:51]
	v_mfma_f32_16x16x32_bf16 v[44:47], v[88:91], v[84:87], v[44:47]
	v_mfma_f32_16x16x32_bf16 v[12:15], v[92:95], v[68:71], v[12:15]
	v_mfma_f32_16x16x32_bf16 v[8:11], v[92:95], v[72:75], v[8:11]
	v_mfma_f32_16x16x32_bf16 v[4:7], v[92:95], v[76:79], v[4:7]
	v_mfma_f32_16x16x32_bf16 v[0:3], v[92:95], v[84:87], v[0:3]
	v_mfma_f32_16x16x32_bf16 v[16:19], v[96:99], v[68:71], v[16:19]
	v_mfma_f32_16x16x32_bf16 v[24:27], v[96:99], v[72:75], v[24:27]
	v_mfma_f32_16x16x32_bf16 v[28:31], v[96:99], v[76:79], v[28:31]
	v_mfma_f32_16x16x32_bf16 v[36:39], v[96:99], v[84:87], v[36:39]
	v_mfma_f32_16x16x32_bf16 v[20:23], v[100:103], v[68:71], v[20:23]
	v_mfma_f32_16x16x32_bf16 v[32:35], v[100:103], v[72:75], v[32:35]
	v_mfma_f32_16x16x32_bf16 v[40:43], v[100:103], v[76:79], v[40:43]
	v_mfma_f32_16x16x32_bf16 v[60:63], v[100:103], v[84:87], v[60:63]
	s_waitcnt vmcnt(8)
	ds_read_b128 v[68:71], v124
	ds_read_b128 v[72:75], v124 offset:1024
	ds_read_b128 v[76:79], v124 offset:2048
	ds_read_b128 v[84:87], v124 offset:3072
	ds_read_b128 v[88:91], v124 offset:4096
	ds_read_b128 v[92:95], v124 offset:5120
	ds_read_b128 v[96:99], v124 offset:6144
	ds_read_b128 v[100:103], v124 offset:7168
	s_waitcnt lgkmcnt(0)
	v_mfma_f32_16x16x32_bf16 v[56:59], v[88:91], v[68:71], v[56:59]
	v_mfma_f32_16x16x32_bf16 v[52:55], v[88:91], v[72:75], v[52:55]
	v_mfma_f32_16x16x32_bf16 v[48:51], v[88:91], v[76:79], v[48:51]
	v_mfma_f32_16x16x32_bf16 v[44:47], v[88:91], v[84:87], v[44:47]
	v_mfma_f32_16x16x32_bf16 v[12:15], v[92:95], v[68:71], v[12:15]
	v_mfma_f32_16x16x32_bf16 v[8:11], v[92:95], v[72:75], v[8:11]
	v_mfma_f32_16x16x32_bf16 v[4:7], v[92:95], v[76:79], v[4:7]
	v_mfma_f32_16x16x32_bf16 v[0:3], v[92:95], v[84:87], v[0:3]
	v_mfma_f32_16x16x32_bf16 v[16:19], v[96:99], v[68:71], v[16:19]
	v_mfma_f32_16x16x32_bf16 v[24:27], v[96:99], v[72:75], v[24:27]
	v_mfma_f32_16x16x32_bf16 v[28:31], v[96:99], v[76:79], v[28:31]
	v_mfma_f32_16x16x32_bf16 v[36:39], v[96:99], v[84:87], v[36:39]
	v_mfma_f32_16x16x32_bf16 v[20:23], v[100:103], v[68:71], v[20:23]
	v_mfma_f32_16x16x32_bf16 v[32:35], v[100:103], v[72:75], v[32:35]
	v_mfma_f32_16x16x32_bf16 v[40:43], v[100:103], v[76:79], v[40:43]
	v_mfma_f32_16x16x32_bf16 v[60:63], v[100:103], v[84:87], v[60:63]
	s_waitcnt vmcnt(0)
	ds_read_b128 v[68:71], v124 offset:8192
	ds_read_b128 v[72:75], v124 offset:9216
	ds_read_b128 v[76:79], v124 offset:10240
	ds_read_b128 v[84:87], v124 offset:11264
	ds_read_b128 v[88:91], v124 offset:12288
	ds_read_b128 v[92:95], v124 offset:13312
	ds_read_b128 v[96:99], v124 offset:14336
	ds_read_b128 v[100:103], v124 offset:15360
	s_waitcnt lgkmcnt(0)
	v_mfma_f32_16x16x32_bf16 v[56:59], v[88:91], v[68:71], v[56:59]
	v_mfma_f32_16x16x32_bf16 v[52:55], v[88:91], v[72:75], v[52:55]
	v_mfma_f32_16x16x32_bf16 v[48:51], v[88:91], v[76:79], v[48:51]
	v_mfma_f32_16x16x32_bf16 v[44:47], v[88:91], v[84:87], v[44:47]
	v_mfma_f32_16x16x32_bf16 v[12:15], v[92:95], v[68:71], v[12:15]
	v_mfma_f32_16x16x32_bf16 v[8:11], v[92:95], v[72:75], v[8:11]
	v_mfma_f32_16x16x32_bf16 v[4:7], v[92:95], v[76:79], v[4:7]
	v_mfma_f32_16x16x32_bf16 v[0:3], v[92:95], v[84:87], v[0:3]
	v_mfma_f32_16x16x32_bf16 v[16:19], v[96:99], v[68:71], v[16:19]
	v_mfma_f32_16x16x32_bf16 v[24:27], v[96:99], v[72:75], v[24:27]
	v_mfma_f32_16x16x32_bf16 v[28:31], v[96:99], v[76:79], v[28:31]
	v_mfma_f32_16x16x32_bf16 v[36:39], v[96:99], v[84:87], v[36:39]
	v_mfma_f32_16x16x32_bf16 v[20:23], v[100:103], v[68:71], v[20:23]
	v_mfma_f32_16x16x32_bf16 v[32:35], v[100:103], v[72:75], v[32:35]
	v_mfma_f32_16x16x32_bf16 v[40:43], v[100:103], v[76:79], v[40:43]
	v_mfma_f32_16x16x32_bf16 v[60:63], v[100:103], v[84:87], v[60:63]
	s_nop 7
	s_nop 3
	v_and_b32_e32 v65, 63, v81
	s_ashr_i32 s4, s3, 7
	v_lshl_add_u32 v65, v65, 4, 0
	s_lshl_b32 s5, s4, 4
	v_lshl_add_u32 v66, s14, 14, v65
	s_addk_i32 s5, 0x4000
	ds_write_b128 v66, v[56:59]
	ds_write_b128 v66, v[52:55] offset:1024
	ds_write_b128 v66, v[48:51] offset:2048
	ds_write_b128 v66, v[44:47] offset:3072
	ds_write_b128 v66, v[12:15] offset:4096
	ds_write_b128 v66, v[8:11] offset:5120
	ds_write_b128 v66, v[4:7] offset:6144
	ds_write_b128 v66, v[0:3] offset:7168
	ds_write_b128 v66, v[16:19] offset:8192
	ds_write_b128 v66, v[24:27] offset:9216
	ds_write_b128 v66, v[28:31] offset:10240
	ds_write_b128 v66, v[36:39] offset:11264
	ds_write_b128 v66, v[20:23] offset:12288
	ds_write_b128 v66, v[32:35] offset:13312
	ds_write_b128 v66, v[40:43] offset:14336
	ds_write_b128 v66, v[60:63] offset:15360
	v_or_b32_e32 v0, s5, v80
	v_ashrrev_i32_e32 v1, 31, v0
	v_bfe_u32 v64, v81, 4, 2
	v_lshlrev_b64 v[2:3], 7, v[0:1]
	v_lshl_add_u64 v[2:3], s[10:11], 0, v[2:3]
	v_lshlrev_b32_e32 v128, 5, v64
	v_lshl_add_u64 v[6:7], v[2:3], 0, v[128:129]
	s_waitcnt lgkmcnt(0)
	s_barrier
	global_load_dwordx4 v[2:5], v[6:7], off
	s_nop 0
	global_load_dwordx4 v[6:9], v[6:7], off offset:16
	s_bfe_u32 s3, s3, 0x10006
	s_lshl_b32 s5, s3, 2
	s_add_i32 s5, s5, s4
	v_lshl_add_u32 v62, s5, 10, v65
	ds_read_b128 v[10:13], v62
	ds_read_b128 v[14:17], v62 offset:8192
	ds_read_b128 v[18:21], v62 offset:16384
	ds_read_b128 v[22:25], v62 offset:24576
	ds_read_b128 v[26:29], v62 offset:32768
	ds_read_b128 v[30:33], v62 offset:40960
	ds_read_b128 v[34:37], v62 offset:49152
	ds_read_b128 v[38:41], v62 offset:57344
	s_waitcnt lgkmcnt(0)
	v_pk_add_f32 v[10:11], v[10:11], 0 op_sel_hi:[1,0]
	v_add_u32_e32 v42, 0x10000, v62
	v_add_u32_e32 v46, 0x12000, v62
	v_add_u32_e32 v50, 0x14000, v62
	v_add_u32_e32 v54, 0x16000, v62
	v_add_u32_e32 v58, 0x18000, v62
	v_pk_add_f32 v[10:11], v[10:11], v[18:19]
	v_add_u32_e32 v63, 0x1a000, v62
	ds_read_b128 v[42:45], v42
	ds_read_b128 v[46:49], v46
	ds_read_b128 v[50:53], v50
	ds_read_b128 v[54:57], v54
	ds_read_b128 v[58:61], v58
	ds_read_b128 v[66:69], v63
	v_pk_add_f32 v[10:11], v[10:11], v[26:27]
	v_pk_add_f32 v[12:13], v[12:13], 0 op_sel_hi:[1,0]
	v_pk_add_f32 v[10:11], v[10:11], v[34:35]
	v_pk_add_f32 v[12:13], v[12:13], v[20:21]
	s_waitcnt lgkmcnt(0)
	v_pk_add_f32 v[10:11], v[10:11], v[42:43]
	v_pk_add_f32 v[14:15], v[14:15], 0 op_sel_hi:[1,0]
	v_pk_add_f32 v[10:11], v[10:11], v[50:51]
	v_pk_add_f32 v[14:15], v[14:15], v[22:23]
	v_pk_add_f32 v[20:21], v[10:11], v[58:59]
	v_pk_add_f32 v[12:13], v[12:13], v[28:29]
	v_pk_add_f32 v[14:15], v[14:15], v[30:31]
	v_pk_add_f32 v[12:13], v[12:13], v[36:37]
	v_pk_add_f32 v[14:15], v[14:15], v[38:39]
	v_pk_add_f32 v[12:13], v[12:13], v[44:45]
	v_pk_add_f32 v[14:15], v[14:15], v[46:47]
	v_pk_add_f32 v[12:13], v[12:13], v[52:53]
	v_pk_add_f32 v[14:15], v[14:15], v[54:55]
	v_pk_add_f32 v[18:19], v[12:13], v[60:61]
	v_pk_add_f32 v[14:15], v[14:15], v[66:67]
	v_pk_add_f32 v[16:17], v[16:17], 0 op_sel_hi:[1,0]
	s_mov_b64 s[4:5], -1
	v_pk_add_f32 v[16:17], v[16:17], v[24:25]
	s_cmp_gt_i32 s0, 7
	v_pk_add_f32 v[16:17], v[16:17], v[32:33]
	v_lshlrev_b64 v[0:1], 12, v[0:1]
	v_pk_add_f32 v[16:17], v[16:17], v[40:41]
	s_waitcnt vmcnt(0)
	v_mov_b32_e32 v10, v2
	v_mov_b32_e32 v11, v6
	v_mov_b32_e32 v6, v3
	v_pk_add_f32 v[2:3], v[10:11], v[6:7]
	v_mov_b32_e32 v6, v4
	v_mov_b32_e32 v7, v8
	v_mov_b32_e32 v8, v5
	v_pk_add_f32 v[4:5], v[6:7], v[8:9]
	v_add_u32_e32 v9, 0x1e000, v62
	v_pk_add_f32 v[2:3], v[2:3], v[4:5]
	v_pk_add_f32 v[16:17], v[16:17], v[48:49]
	v_add_f32_e32 v6, v2, v3
	v_and_b32_e32 v3, 64, v214
	v_xor_b32_e32 v2, 16, v214
	v_add_u32_e32 v7, 64, v3
	v_cmp_lt_i32_e32 vcc, v2, v7
	v_pk_add_f32 v[16:17], v[16:17], v[56:57]
	s_nop 0
	v_cndmask_b32_e32 v2, v214, v2, vcc
	v_lshlrev_b32_e32 v2, 2, v2
	ds_bpermute_b32 v8, v2, v6
	v_add_u32_e32 v2, 0x1c000, v62
	ds_read_b128 v[2:5], v2
	ds_read_b128 v[10:13], v9
	v_pk_add_f32 v[16:17], v[16:17], v[68:69]
	s_waitcnt lgkmcnt(2)
	v_add_f32_e32 v22, v6, v8
	v_xor_b32_e32 v6, 32, v214
	v_cmp_lt_i32_e32 vcc, v6, v7
	s_waitcnt lgkmcnt(1)
	v_pk_add_f32 v[8:9], v[20:21], v[2:3]
	s_waitcnt lgkmcnt(0)
	v_pk_add_f32 v[2:3], v[16:17], v[12:13]
	v_cndmask_b32_e32 v6, v214, v6, vcc
	v_lshlrev_b32_e32 v6, 2, v6
	ds_bpermute_b32 v23, v6, v22
	v_pk_add_f32 v[6:7], v[18:19], v[4:5]
	v_pk_add_f32 v[4:5], v[14:15], v[10:11]
	s_waitcnt lgkmcnt(0)
	v_add_f32_e32 v10, v22, v23
	v_fmamk_f32 v10, v10, 0x3a000000, v190
	v_mul_f32_e32 v11, 0x4b800000, v10
	v_cmp_gt_f32_e32 vcc, s70, v10
	s_nop 1
	v_cndmask_b32_e32 v10, v10, v11, vcc
	v_rsq_f32_e32 v10, v10
	v_lshlrev_b32_e32 v11, 2, v64
	v_lshl_or_b32 v11, s3, 4, v11
	v_or_b32_e32 v11, s1, v11
	v_mul_f32_e32 v12, 0x45800000, v10
	v_cndmask_b32_e32 v10, v10, v12, vcc
	v_lshlrev_b32_e32 v128, 1, v11
	s_cbranch_scc0 .LBB0_887
	v_pk_mul_f32 v[12:13], v[6:7], v[2:3]
	v_pk_mul_f32 v[14:15], v[8:9], v[4:5]
	v_mul_f32_e32 v16, v10, v10
	v_pk_mul_f32 v[12:13], v[12:13], v[16:17] op_sel_hi:[1,0]
	v_pk_mul_f32 v[14:15], v[14:15], v[16:17] op_sel_hi:[1,0]
	s_mov_b32 s3, s95
	v_cvt_pk_bf16_f32 v14, v14, v15
	v_cvt_pk_bf16_f32 v15, v12, v13
	v_lshl_add_u64 v[12:13], s[8:9], 0, v[0:1]
	v_lshl_add_u64 v[12:13], v[12:13], 0, s[2:3]
	v_lshl_add_u64 v[12:13], v[12:13], 0, v[128:129]
	v_add_co_u32_e32 v12, vcc, 0xfffff800, v12
	s_mov_b64 s[4:5], 0
	s_nop 0
	v_addc_co_u32_e32 v13, vcc, -1, v13, vcc
	global_store_dwordx2 v[12:13], v[14:15], off

.LBB0_1031:
	v_lshrrev_b32_e32 v122, 2, v214
	v_and_b32_e32 v123, 15, v214
	v_sub_u32_e32 v122, v122, v123
	v_mul_i32_i24_e32 v122, 0x1000, v122
	v_bfe_u32 v125, v214, 5, 1
	v_lshlrev_b32_e32 v125, 1, v125
	v_and_b32_e32 v124, 3, v214
	v_xor_b32_e32 v125, v125, v124
	v_lshrrev_b32_e32 v124, 4, v214
	v_sub_u32_e32 v125, v125, v124
	v_lshl_add_u32 v122, v125, 4, v122
	v_ashrrev_i32_e32 v125, 31, v122
	v_add_co_u32_e32 v118, vcc, v66, v122
	s_nop 1
	v_addc_co_u32_e32 v119, vcc, v67, v125, vcc
	v_add_co_u32_e32 v120, vcc, v64, v122
	s_nop 1
	v_addc_co_u32_e32 v121, vcc, v65, v125, vcc
	v_add_co_u32_e32 v82, vcc, 0x3b1d0000, v118
	s_nop 1
	v_addc_co_u32_e32 v83, vcc, 0, v119, vcc
	v_add_co_u32_e32 v104, vcc, 0x3b1e0000, v118
	s_nop 1
	v_addc_co_u32_e32 v105, vcc, 0, v119, vcc
	v_add_co_u32_e32 v106, vcc, 0x3b1f0000, v118
	s_nop 1
	v_addc_co_u32_e32 v107, vcc, 0, v119, vcc
	v_add_co_u32_e32 v108, vcc, 0x3b200000, v118
	s_nop 1
	v_addc_co_u32_e32 v109, vcc, 0, v119, vcc
	v_add_co_u32_e32 v110, vcc, 0x3008000, v120
	s_nop 1
	v_addc_co_u32_e32 v111, vcc, 0, v121, vcc
	v_add_co_u32_e32 v112, vcc, 0x3018000, v120
	s_nop 1
	v_addc_co_u32_e32 v113, vcc, 0, v121, vcc
	v_add_co_u32_e32 v114, vcc, 0x3088000, v120
	s_nop 1
	v_addc_co_u32_e32 v115, vcc, 0, v121, vcc
	v_add_co_u32_e32 v116, vcc, 0x3098000, v120
	s_nop 1
	v_addc_co_u32_e32 v117, vcc, 0, v121, vcc
	v_readfirstlane_b32 vcc_lo, v210
	v_bfe_u32 v125, v214, 3, 1
	v_lshlrev_b32_e32 v125, 1, v125
	v_xor_b32_e32 v125, v125, v124
	v_lshlrev_b32_e32 v125, 4, v125
	v_lshl_add_u32 v125, v123, 6, v125
	s_lshr_b32 vcc_lo, vcc_lo, 6
	s_lshl_b32 vcc_lo, vcc_lo, 14
	s_mov_b32 s94, 64
	v_add_u32_e32 v124, vcc_lo, v125
	s_add_i32 m0, vcc_lo, 0x0
	s_nop 0
	global_load_lds_dwordx4 v[82:83], off
	v_lshl_add_u64 v[82:83], v[82:83], 0, s[94:95]
	s_add_i32 m0, vcc_lo, 0x400
	s_nop 0
	global_load_lds_dwordx4 v[104:105], off
	v_lshl_add_u64 v[104:105], v[104:105], 0, s[94:95]
	s_add_i32 m0, vcc_lo, 0x800
	s_nop 0
	global_load_lds_dwordx4 v[106:107], off
	v_lshl_add_u64 v[106:107], v[106:107], 0, s[94:95]
	s_add_i32 m0, vcc_lo, 0xc00
	s_nop 0
	global_load_lds_dwordx4 v[108:109], off
	v_lshl_add_u64 v[108:109], v[108:109], 0, s[94:95]
	s_add_i32 m0, vcc_lo, 0x1000
	s_nop 0
	global_load_lds_dwordx4 v[110:111], off
	v_lshl_add_u64 v[110:111], v[110:111], 0, s[94:95]
	s_add_i32 m0, vcc_lo, 0x1400
	s_nop 0
	global_load_lds_dwordx4 v[112:113], off
	v_lshl_add_u64 v[112:113], v[112:113], 0, s[94:95]
	s_add_i32 m0, vcc_lo, 0x1800
	s_nop 0
	global_load_lds_dwordx4 v[114:115], off
	v_lshl_add_u64 v[114:115], v[114:115], 0, s[94:95]
	s_add_i32 m0, vcc_lo, 0x1c00
	s_nop 0
	global_load_lds_dwordx4 v[116:117], off
	v_lshl_add_u64 v[116:117], v[116:117], 0, s[94:95]
	s_add_i32 m0, vcc_lo, 0x2000
	s_nop 0
	global_load_lds_dwordx4 v[82:83], off
	v_lshl_add_u64 v[82:83], v[82:83], 0, s[94:95]
	s_add_i32 m0, vcc_lo, 0x2400
	s_nop 0
	global_load_lds_dwordx4 v[104:105], off
	v_lshl_add_u64 v[104:105], v[104:105], 0, s[94:95]
	s_add_i32 m0, vcc_lo, 0x2800
	s_nop 0
	global_load_lds_dwordx4 v[106:107], off
	v_lshl_add_u64 v[106:107], v[106:107], 0, s[94:95]
	s_add_i32 m0, vcc_lo, 0x2c00
	s_nop 0
	global_load_lds_dwordx4 v[108:109], off
	v_lshl_add_u64 v[108:109], v[108:109], 0, s[94:95]
	s_add_i32 m0, vcc_lo, 0x3000
	s_nop 0
	global_load_lds_dwordx4 v[110:111], off
	v_lshl_add_u64 v[110:111], v[110:111], 0, s[94:95]
	s_add_i32 m0, vcc_lo, 0x3400
	s_nop 0
	global_load_lds_dwordx4 v[112:113], off
	v_lshl_add_u64 v[112:113], v[112:113], 0, s[94:95]
	s_add_i32 m0, vcc_lo, 0x3800
	s_nop 0
	global_load_lds_dwordx4 v[114:115], off
	v_lshl_add_u64 v[114:115], v[114:115], 0, s[94:95]
	s_add_i32 m0, vcc_lo, 0x3c00
	s_nop 0
	global_load_lds_dwordx4 v[116:117], off
	v_lshl_add_u64 v[116:117], v[116:117], 0, s[94:95]
	s_waitcnt vmcnt(8)
	ds_read_b128 v[68:71], v124
	ds_read_b128 v[72:75], v124 offset:1024
	ds_read_b128 v[76:79], v124 offset:2048
	ds_read_b128 v[84:87], v124 offset:3072
	ds_read_b128 v[88:91], v124 offset:4096
	ds_read_b128 v[92:95], v124 offset:5120
	ds_read_b128 v[96:99], v124 offset:6144
	ds_read_b128 v[100:103], v124 offset:7168
	s_waitcnt lgkmcnt(0)
	s_add_i32 m0, vcc_lo, 0x0
	s_nop 0
	global_load_lds_dwordx4 v[82:83], off
	v_lshl_add_u64 v[82:83], v[82:83], 0, s[94:95]
	s_add_i32 m0, vcc_lo, 0x400
	s_nop 0
	global_load_lds_dwordx4 v[104:105], off
	v_lshl_add_u64 v[104:105], v[104:105], 0, s[94:95]
	s_add_i32 m0, vcc_lo, 0x800
	s_nop 0
	global_load_lds_dwordx4 v[106:107], off
	v_lshl_add_u64 v[106:107], v[106:107], 0, s[94:95]
	s_add_i32 m0, vcc_lo, 0xc00
	s_nop 0
	global_load_lds_dwordx4 v[108:109], off
	v_lshl_add_u64 v[108:109], v[108:109], 0, s[94:95]
	s_add_i32 m0, vcc_lo, 0x1000
	s_nop 0
	global_load_lds_dwordx4 v[110:111], off
	v_lshl_add_u64 v[110:111], v[110:111], 0, s[94:95]
	s_add_i32 m0, vcc_lo, 0x1400
	s_nop 0
	global_load_lds_dwordx4 v[112:113], off
	v_lshl_add_u64 v[112:113], v[112:113], 0, s[94:95]
	s_add_i32 m0, vcc_lo, 0x1800
	s_nop 0
	global_load_lds_dwordx4 v[114:115], off
	v_lshl_add_u64 v[114:115], v[114:115], 0, s[94:95]
	s_add_i32 m0, vcc_lo, 0x1c00
	s_nop 0
	global_load_lds_dwordx4 v[116:117], off
	v_lshl_add_u64 v[116:117], v[116:117], 0, s[94:95]
	v_mfma_f32_16x16x32_bf16 v[56:59], v[88:91], v[68:71], 0
	v_mfma_f32_16x16x32_bf16 v[52:55], v[88:91], v[72:75], 0
	v_mfma_f32_16x16x32_bf16 v[48:51], v[88:91], v[76:79], 0
	v_mfma_f32_16x16x32_bf16 v[44:47], v[88:91], v[84:87], 0
	v_mfma_f32_16x16x32_bf16 v[12:15], v[92:95], v[68:71], 0
	v_mfma_f32_16x16x32_bf16 v[8:11], v[92:95], v[72:75], 0
	v_mfma_f32_16x16x32_bf16 v[4:7], v[92:95], v[76:79], 0
	v_mfma_f32_16x16x32_bf16 v[0:3], v[92:95], v[84:87], 0
	v_mfma_f32_16x16x32_bf16 v[16:19], v[96:99], v[68:71], 0
	v_mfma_f32_16x16x32_bf16 v[24:27], v[96:99], v[72:75], 0
	v_mfma_f32_16x16x32_bf16 v[28:31], v[96:99], v[76:79], 0
	v_mfma_f32_16x16x32_bf16 v[36:39], v[96:99], v[84:87], 0
	v_mfma_f32_16x16x32_bf16 v[20:23], v[100:103], v[68:71], 0
	v_mfma_f32_16x16x32_bf16 v[32:35], v[100:103], v[72:75], 0
	v_mfma_f32_16x16x32_bf16 v[40:43], v[100:103], v[76:79], 0
	v_mfma_f32_16x16x32_bf16 v[60:63], v[100:103], v[84:87], 0
	s_waitcnt vmcnt(8)
	ds_read_b128 v[68:71], v124 offset:8192
	ds_read_b128 v[72:75], v124 offset:9216
	ds_read_b128 v[76:79], v124 offset:10240
	ds_read_b128 v[84:87], v124 offset:11264
	ds_read_b128 v[88:91], v124 offset:12288
	ds_read_b128 v[92:95], v124 offset:13312
	ds_read_b128 v[96:99], v124 offset:14336
	ds_read_b128 v[100:103], v124 offset:15360
	s_waitcnt lgkmcnt(0)
	s_add_i32 m0, vcc_lo, 0x2000
	s_nop 0
	global_load_lds_dwordx4 v[82:83], off
	v_lshl_add_u64 v[82:83], v[82:83], 0, s[94:95]
	s_add_i32 m0, vcc_lo, 0x2400
	s_nop 0
	global_load_lds_dwordx4 v[104:105], off
	v_lshl_add_u64 v[104:105], v[104:105], 0, s[94:95]
	s_add_i32 m0, vcc_lo, 0x2800
	s_nop 0
	global_load_lds_dwordx4 v[106:107], off
	v_lshl_add_u64 v[106:107], v[106:107], 0, s[94:95]
	s_add_i32 m0, vcc_lo, 0x2c00
	s_nop 0
	global_load_lds_dwordx4 v[108:109], off
	v_lshl_add_u64 v[108:109], v[108:109], 0, s[94:95]
	s_add_i32 m0, vcc_lo, 0x3000
	s_nop 0
	global_load_lds_dwordx4 v[110:111], off
	v_lshl_add_u64 v[110:111], v[110:111], 0, s[94:95]
	s_add_i32 m0, vcc_lo, 0x3400
	s_nop 0
	global_load_lds_dwordx4 v[112:113], off
	v_lshl_add_u64 v[112:113], v[112:113], 0, s[94:95]
	s_add_i32 m0, vcc_lo, 0x3800
	s_nop 0
	global_load_lds_dwordx4 v[114:115], off
	v_lshl_add_u64 v[114:115], v[114:115], 0, s[94:95]
	s_add_i32 m0, vcc_lo, 0x3c00
	s_nop 0
	global_load_lds_dwordx4 v[116:117], off
	v_lshl_add_u64 v[116:117], v[116:117], 0, s[94:95]
	v_mfma_f32_16x16x32_bf16 v[56:59], v[88:91], v[68:71], v[56:59]
	v_mfma_f32_16x16x32_bf16 v[52:55], v[88:91], v[72:75], v[52:55]
	v_mfma_f32_16x16x32_bf16 v[48:51], v[88:91], v[76:79], v[48:51]
	v_mfma_f32_16x16x32_bf16 v[44:47], v[88:91], v[84:87], v[44:47]
	v_mfma_f32_16x16x32_bf16 v[12:15], v[92:95], v[68:71], v[12:15]
	v_mfma_f32_16x16x32_bf16 v[8:11], v[92:95], v[72:75], v[8:11]
	v_mfma_f32_16x16x32_bf16 v[4:7], v[92:95], v[76:79], v[4:7]
	v_mfma_f32_16x16x32_bf16 v[0:3], v[92:95], v[84:87], v[0:3]
	v_mfma_f32_16x16x32_bf16 v[16:19], v[96:99], v[68:71], v[16:19]
	v_mfma_f32_16x16x32_bf16 v[24:27], v[96:99], v[72:75], v[24:27]
	v_mfma_f32_16x16x32_bf16 v[28:31], v[96:99], v[76:79], v[28:31]
	v_mfma_f32_16x16x32_bf16 v[36:39], v[96:99], v[84:87], v[36:39]
	v_mfma_f32_16x16x32_bf16 v[20:23], v[100:103], v[68:71], v[20:23]
	v_mfma_f32_16x16x32_bf16 v[32:35], v[100:103], v[72:75], v[32:35]
	v_mfma_f32_16x16x32_bf16 v[40:43], v[100:103], v[76:79], v[40:43]
	v_mfma_f32_16x16x32_bf16 v[60:63], v[100:103], v[84:87], v[60:63]
	s_waitcnt vmcnt(8)
	ds_read_b128 v[68:71], v124
	ds_read_b128 v[72:75], v124 offset:1024
	ds_read_b128 v[76:79], v124 offset:2048
	ds_read_b128 v[84:87], v124 offset:3072
	ds_read_b128 v[88:91], v124 offset:4096
	ds_read_b128 v[92:95], v124 offset:5120
	ds_read_b128 v[96:99], v124 offset:6144
	ds_read_b128 v[100:103], v124 offset:7168
	s_waitcnt lgkmcnt(0)
	s_add_i32 m0, vcc_lo, 0x0
	s_nop 0
	global_load_lds_dwordx4 v[82:83], off
	v_lshl_add_u64 v[82:83], v[82:83], 0, s[94:95]
	s_add_i32 m0, vcc_lo, 0x400
	s_nop 0
	global_load_lds_dwordx4 v[104:105], off
	v_lshl_add_u64 v[104:105], v[104:105], 0, s[94:95]
	s_add_i32 m0, vcc_lo, 0x800
	s_nop 0
	global_load_lds_dwordx4 v[106:107], off
	v_lshl_add_u64 v[106:107], v[106:107], 0, s[94:95]
	s_add_i32 m0, vcc_lo, 0xc00
	s_nop 0
	global_load_lds_dwordx4 v[108:109], off
	v_lshl_add_u64 v[108:109], v[108:109], 0, s[94:95]
	s_add_i32 m0, vcc_lo, 0x1000
	s_nop 0
	global_load_lds_dwordx4 v[110:111], off
	v_lshl_add_u64 v[110:111], v[110:111], 0, s[94:95]
	s_add_i32 m0, vcc_lo, 0x1400
	s_nop 0
	global_load_lds_dwordx4 v[112:113], off
	v_lshl_add_u64 v[112:113], v[112:113], 0, s[94:95]
	s_add_i32 m0, vcc_lo, 0x1800
	s_nop 0
	global_load_lds_dwordx4 v[114:115], off
	v_lshl_add_u64 v[114:115], v[114:115], 0, s[94:95]
	s_add_i32 m0, vcc_lo, 0x1c00
	s_nop 0
	global_load_lds_dwordx4 v[116:117], off
	v_lshl_add_u64 v[116:117], v[116:117], 0, s[94:95]
	v_mfma_f32_16x16x32_bf16 v[56:59], v[88:91], v[68:71], v[56:59]
	v_mfma_f32_16x16x32_bf16 v[52:55], v[88:91], v[72:75], v[52:55]
	v_mfma_f32_16x16x32_bf16 v[48:51], v[88:91], v[76:79], v[48:51]
	v_mfma_f32_16x16x32_bf16 v[44:47], v[88:91], v[84:87], v[44:47]
	v_mfma_f32_16x16x32_bf16 v[12:15], v[92:95], v[68:71], v[12:15]
	v_mfma_f32_16x16x32_bf16 v[8:11], v[92:95], v[72:75], v[8:11]
	v_mfma_f32_16x16x32_bf16 v[4:7], v[92:95], v[76:79], v[4:7]
	v_mfma_f32_16x16x32_bf16 v[0:3], v[92:95], v[84:87], v[0:3]
	v_mfma_f32_16x16x32_bf16 v[16:19], v[96:99], v[68:71], v[16:19]
	v_mfma_f32_16x16x32_bf16 v[24:27], v[96:99], v[72:75], v[24:27]
	v_mfma_f32_16x16x32_bf16 v[28:31], v[96:99], v[76:79], v[28:31]
	v_mfma_f32_16x16x32_bf16 v[36:39], v[96:99], v[84:87], v[36:39]
	v_mfma_f32_16x16x32_bf16 v[20:23], v[100:103], v[68:71], v[20:23]
	v_mfma_f32_16x16x32_bf16 v[32:35], v[100:103], v[72:75], v[32:35]
	v_mfma_f32_16x16x32_bf16 v[40:43], v[100:103], v[76:79], v[40:43]
	v_mfma_f32_16x16x32_bf16 v[60:63], v[100:103], v[84:87], v[60:63]
	s_waitcnt vmcnt(8)
	ds_read_b128 v[68:71], v124 offset:8192
	ds_read_b128 v[72:75], v124 offset:9216
	ds_read_b128 v[76:79], v124 offset:10240
	ds_read_b128 v[84:87], v124 offset:11264
	ds_read_b128 v[88:91], v124 offset:12288
	ds_read_b128 v[92:95], v124 offset:13312
	ds_read_b128 v[96:99], v124 offset:14336
	ds_read_b128 v[100:103], v124 offset:15360
	s_waitcnt lgkmcnt(0)
	s_add_i32 m0, vcc_lo, 0x2000
	s_nop 0
	global_load_lds_dwordx4 v[82:83], off
	v_lshl_add_u64 v[82:83], v[82:83], 0, s[94:95]
	s_add_i32 m0, vcc_lo, 0x2400
	s_nop 0
	global_load_lds_dwordx4 v[104:105], off
	v_lshl_add_u64 v[104:105], v[104:105], 0, s[94:95]
	s_add_i32 m0, vcc_lo, 0x2800
	s_nop 0
	global_load_lds_dwordx4 v[106:107], off
	v_lshl_add_u64 v[106:107], v[106:107], 0, s[94:95]
	s_add_i32 m0, vcc_lo, 0x2c00
	s_nop 0
	global_load_lds_dwordx4 v[108:109], off
	v_lshl_add_u64 v[108:109], v[108:109], 0, s[94:95]
	s_add_i32 m0, vcc_lo, 0x3000
	s_nop 0
	global_load_lds_dwordx4 v[110:111], off
	v_lshl_add_u64 v[110:111], v[110:111], 0, s[94:95]
	s_add_i32 m0, vcc_lo, 0x3400
	s_nop 0
	global_load_lds_dwordx4 v[112:113], off
	v_lshl_add_u64 v[112:113], v[112:113], 0, s[94:95]
	s_add_i32 m0, vcc_lo, 0x3800
	s_nop 0
	global_load_lds_dwordx4 v[114:115], off
	v_lshl_add_u64 v[114:115], v[114:115], 0, s[94:95]
	s_add_i32 m0, vcc_lo, 0x3c00
	s_nop 0
	global_load_lds_dwordx4 v[116:117], off
	v_lshl_add_u64 v[116:117], v[116:117], 0, s[94:95]
	v_mfma_f32_16x16x32_bf16 v[56:59], v[88:91], v[68:71], v[56:59]
	v_mfma_f32_16x16x32_bf16 v[52:55], v[88:91], v[72:75], v[52:55]
	v_mfma_f32_16x16x32_bf16 v[48:51], v[88:91], v[76:79], v[48:51]
	v_mfma_f32_16x16x32_bf16 v[44:47], v[88:91], v[84:87], v[44:47]
	v_mfma_f32_16x16x32_bf16 v[12:15], v[92:95], v[68:71], v[12:15]
	v_mfma_f32_16x16x32_bf16 v[8:11], v[92:95], v[72:75], v[8:11]
	v_mfma_f32_16x16x32_bf16 v[4:7], v[92:95], v[76:79], v[4:7]
	v_mfma_f32_16x16x32_bf16 v[0:3], v[92:95], v[84:87], v[0:3]
	v_mfma_f32_16x16x32_bf16 v[16:19], v[96:99], v[68:71], v[16:19]
	v_mfma_f32_16x16x32_bf16 v[24:27], v[96:99], v[72:75], v[24:27]
	v_mfma_f32_16x16x32_bf16 v[28:31], v[96:99], v[76:79], v[28:31]
	v_mfma_f32_16x16x32_bf16 v[36:39], v[96:99], v[84:87], v[36:39]
	v_mfma_f32_16x16x32_bf16 v[20:23], v[100:103], v[68:71], v[20:23]
	v_mfma_f32_16x16x32_bf16 v[32:35], v[100:103], v[72:75], v[32:35]
	v_mfma_f32_16x16x32_bf16 v[40:43], v[100:103], v[76:79], v[40:43]
	v_mfma_f32_16x16x32_bf16 v[60:63], v[100:103], v[84:87], v[60:63]
	s_waitcnt vmcnt(8)
	ds_read_b128 v[68:71], v124
	ds_read_b128 v[72:75], v124 offset:1024
	ds_read_b128 v[76:79], v124 offset:2048
	ds_read_b128 v[84:87], v124 offset:3072
	ds_read_b128 v[88:91], v124 offset:4096
	ds_read_b128 v[92:95], v124 offset:5120
	ds_read_b128 v[96:99], v124 offset:6144
	ds_read_b128 v[100:103], v124 offset:7168
	s_waitcnt lgkmcnt(0)
	s_add_i32 m0, vcc_lo, 0x0
	s_nop 0
	global_load_lds_dwordx4 v[82:83], off
	v_lshl_add_u64 v[82:83], v[82:83], 0, s[94:95]
	s_add_i32 m0, vcc_lo, 0x400
	s_nop 0
	global_load_lds_dwordx4 v[104:105], off
	v_lshl_add_u64 v[104:105], v[104:105], 0, s[94:95]
	s_add_i32 m0, vcc_lo, 0x800
	s_nop 0
	global_load_lds_dwordx4 v[106:107], off
	v_lshl_add_u64 v[106:107], v[106:107], 0, s[94:95]
	s_add_i32 m0, vcc_lo, 0xc00
	s_nop 0
	global_load_lds_dwordx4 v[108:109], off
	v_lshl_add_u64 v[108:109], v[108:109], 0, s[94:95]
	s_add_i32 m0, vcc_lo, 0x1000
	s_nop 0
	global_load_lds_dwordx4 v[110:111], off
	v_lshl_add_u64 v[110:111], v[110:111], 0, s[94:95]
	s_add_i32 m0, vcc_lo, 0x1400
	s_nop 0
	global_load_lds_dwordx4 v[112:113], off
	v_lshl_add_u64 v[112:113], v[112:113], 0, s[94:95]
	s_add_i32 m0, vcc_lo, 0x1800
	s_nop 0
	global_load_lds_dwordx4 v[114:115], off
	v_lshl_add_u64 v[114:115], v[114:115], 0, s[94:95]
	s_add_i32 m0, vcc_lo, 0x1c00
	s_nop 0
	global_load_lds_dwordx4 v[116:117], off
	v_lshl_add_u64 v[116:117], v[116:117], 0, s[94:95]
	v_mfma_f32_16x16x32_bf16 v[56:59], v[88:91], v[68:71], v[56:59]
	v_mfma_f32_16x16x32_bf16 v[52:55], v[88:91], v[72:75], v[52:55]
	v_mfma_f32_16x16x32_bf16 v[48:51], v[88:91], v[76:79], v[48:51]
	v_mfma_f32_16x16x32_bf16 v[44:47], v[88:91], v[84:87], v[44:47]
	v_mfma_f32_16x16x32_bf16 v[12:15], v[92:95], v[68:71], v[12:15]
	v_mfma_f32_16x16x32_bf16 v[8:11], v[92:95], v[72:75], v[8:11]
	v_mfma_f32_16x16x32_bf16 v[4:7], v[92:95], v[76:79], v[4:7]
	v_mfma_f32_16x16x32_bf16 v[0:3], v[92:95], v[84:87], v[0:3]
	v_mfma_f32_16x16x32_bf16 v[16:19], v[96:99], v[68:71], v[16:19]
	v_mfma_f32_16x16x32_bf16 v[24:27], v[96:99], v[72:75], v[24:27]
	v_mfma_f32_16x16x32_bf16 v[28:31], v[96:99], v[76:79], v[28:31]
	v_mfma_f32_16x16x32_bf16 v[36:39], v[96:99], v[84:87], v[36:39]
	v_mfma_f32_16x16x32_bf16 v[20:23], v[100:103], v[68:71], v[20:23]
	v_mfma_f32_16x16x32_bf16 v[32:35], v[100:103], v[72:75], v[32:35]
	v_mfma_f32_16x16x32_bf16 v[40:43], v[100:103], v[76:79], v[40:43]
	v_mfma_f32_16x16x32_bf16 v[60:63], v[100:103], v[84:87], v[60:63]
	s_waitcnt vmcnt(8)
	ds_read_b128 v[68:71], v124 offset:8192
	ds_read_b128 v[72:75], v124 offset:9216
	ds_read_b128 v[76:79], v124 offset:10240
	ds_read_b128 v[84:87], v124 offset:11264
	ds_read_b128 v[88:91], v124 offset:12288
	ds_read_b128 v[92:95], v124 offset:13312
	ds_read_b128 v[96:99], v124 offset:14336
	ds_read_b128 v[100:103], v124 offset:15360
	s_waitcnt lgkmcnt(0)
	s_add_i32 m0, vcc_lo, 0x2000
	s_nop 0
	global_load_lds_dwordx4 v[82:83], off
	v_lshl_add_u64 v[82:83], v[82:83], 0, s[94:95]
	s_add_i32 m0, vcc_lo, 0x2400
	s_nop 0
	global_load_lds_dwordx4 v[104:105], off
	v_lshl_add_u64 v[104:105], v[104:105], 0, s[94:95]
	s_add_i32 m0, vcc_lo, 0x2800
	s_nop 0
	global_load_lds_dwordx4 v[106:107], off
	v_lshl_add_u64 v[106:107], v[106:107], 0, s[94:95]
	s_add_i32 m0, vcc_lo, 0x2c00
	s_nop 0
	global_load_lds_dwordx4 v[108:109], off
	v_lshl_add_u64 v[108:109], v[108:109], 0, s[94:95]
	s_add_i32 m0, vcc_lo, 0x3000
	s_nop 0
	global_load_lds_dwordx4 v[110:111], off
	v_lshl_add_u64 v[110:111], v[110:111], 0, s[94:95]
	s_add_i32 m0, vcc_lo, 0x3400
	s_nop 0
	global_load_lds_dwordx4 v[112:113], off
	v_lshl_add_u64 v[112:113], v[112:113], 0, s[94:95]
	s_add_i32 m0, vcc_lo, 0x3800
	s_nop 0
	global_load_lds_dwordx4 v[114:115], off
	v_lshl_add_u64 v[114:115], v[114:115], 0, s[94:95]
	s_add_i32 m0, vcc_lo, 0x3c00
	s_nop 0
	global_load_lds_dwordx4 v[116:117], off
	v_lshl_add_u64 v[116:117], v[116:117], 0, s[94:95]
	v_mfma_f32_16x16x32_bf16 v[56:59], v[88:91], v[68:71], v[56:59]
	v_mfma_f32_16x16x32_bf16 v[52:55], v[88:91], v[72:75], v[52:55]
	v_mfma_f32_16x16x32_bf16 v[48:51], v[88:91], v[76:79], v[48:51]
	v_mfma_f32_16x16x32_bf16 v[44:47], v[88:91], v[84:87], v[44:47]
	v_mfma_f32_16x16x32_bf16 v[12:15], v[92:95], v[68:71], v[12:15]
	v_mfma_f32_16x16x32_bf16 v[8:11], v[92:95], v[72:75], v[8:11]
	v_mfma_f32_16x16x32_bf16 v[4:7], v[92:95], v[76:79], v[4:7]
	v_mfma_f32_16x16x32_bf16 v[0:3], v[92:95], v[84:87], v[0:3]
	v_mfma_f32_16x16x32_bf16 v[16:19], v[96:99], v[68:71], v[16:19]
	v_mfma_f32_16x16x32_bf16 v[24:27], v[96:99], v[72:75], v[24:27]
	v_mfma_f32_16x16x32_bf16 v[28:31], v[96:99], v[76:79], v[28:31]
	v_mfma_f32_16x16x32_bf16 v[36:39], v[96:99], v[84:87], v[36:39]
	v_mfma_f32_16x16x32_bf16 v[20:23], v[100:103], v[68:71], v[20:23]
	v_mfma_f32_16x16x32_bf16 v[32:35], v[100:103], v[72:75], v[32:35]
	v_mfma_f32_16x16x32_bf16 v[40:43], v[100:103], v[76:79], v[40:43]
	v_mfma_f32_16x16x32_bf16 v[60:63], v[100:103], v[84:87], v[60:63]
	s_waitcnt vmcnt(8)
	ds_read_b128 v[68:71], v124
	ds_read_b128 v[72:75], v124 offset:1024
	ds_read_b128 v[76:79], v124 offset:2048
	ds_read_b128 v[84:87], v124 offset:3072
	ds_read_b128 v[88:91], v124 offset:4096
	ds_read_b128 v[92:95], v124 offset:5120
	ds_read_b128 v[96:99], v124 offset:6144
	ds_read_b128 v[100:103], v124 offset:7168
	s_waitcnt lgkmcnt(0)
	v_mfma_f32_16x16x32_bf16 v[56:59], v[88:91], v[68:71], v[56:59]
	v_mfma_f32_16x16x32_bf16 v[52:55], v[88:91], v[72:75], v[52:55]
	v_mfma_f32_16x16x32_bf16 v[48:51], v[88:91], v[76:79], v[48:51]
	v_mfma_f32_16x16x32_bf16 v[44:47], v[88:91], v[84:87], v[44:47]
	v_mfma_f32_16x16x32_bf16 v[12:15], v[92:95], v[68:71], v[12:15]
	v_mfma_f32_16x16x32_bf16 v[8:11], v[92:95], v[72:75], v[8:11]
	v_mfma_f32_16x16x32_bf16 v[4:7], v[92:95], v[76:79], v[4:7]
	v_mfma_f32_16x16x32_bf16 v[0:3], v[92:95], v[84:87], v[0:3]
	v_mfma_f32_16x16x32_bf16 v[16:19], v[96:99], v[68:71], v[16:19]
	v_mfma_f32_16x16x32_bf16 v[24:27], v[96:99], v[72:75], v[24:27]
	v_mfma_f32_16x16x32_bf16 v[28:31], v[96:99], v[76:79], v[28:31]
	v_mfma_f32_16x16x32_bf16 v[36:39], v[96:99], v[84:87], v[36:39]
	v_mfma_f32_16x16x32_bf16 v[20:23], v[100:103], v[68:71], v[20:23]
	v_mfma_f32_16x16x32_bf16 v[32:35], v[100:103], v[72:75], v[32:35]
	v_mfma_f32_16x16x32_bf16 v[40:43], v[100:103], v[76:79], v[40:43]
	v_mfma_f32_16x16x32_bf16 v[60:63], v[100:103], v[84:87], v[60:63]
	s_waitcnt vmcnt(0)
	ds_read_b128 v[68:71], v124 offset:8192
	ds_read_b128 v[72:75], v124 offset:9216
	ds_read_b128 v[76:79], v124 offset:10240
	ds_read_b128 v[84:87], v124 offset:11264
	ds_read_b128 v[88:91], v124 offset:12288
	ds_read_b128 v[92:95], v124 offset:13312
	ds_read_b128 v[96:99], v124 offset:14336
	ds_read_b128 v[100:103], v124 offset:15360
	s_waitcnt lgkmcnt(0)
	v_mfma_f32_16x16x32_bf16 v[56:59], v[88:91], v[68:71], v[56:59]
	v_mfma_f32_16x16x32_bf16 v[52:55], v[88:91], v[72:75], v[52:55]
	v_mfma_f32_16x16x32_bf16 v[48:51], v[88:91], v[76:79], v[48:51]
	v_mfma_f32_16x16x32_bf16 v[44:47], v[88:91], v[84:87], v[44:47]
	v_mfma_f32_16x16x32_bf16 v[12:15], v[92:95], v[68:71], v[12:15]
	v_mfma_f32_16x16x32_bf16 v[8:11], v[92:95], v[72:75], v[8:11]
	v_mfma_f32_16x16x32_bf16 v[4:7], v[92:95], v[76:79], v[4:7]
	v_mfma_f32_16x16x32_bf16 v[0:3], v[92:95], v[84:87], v[0:3]
	v_mfma_f32_16x16x32_bf16 v[16:19], v[96:99], v[68:71], v[16:19]
	v_mfma_f32_16x16x32_bf16 v[24:27], v[96:99], v[72:75], v[24:27]
	v_mfma_f32_16x16x32_bf16 v[28:31], v[96:99], v[76:79], v[28:31]
	v_mfma_f32_16x16x32_bf16 v[36:39], v[96:99], v[84:87], v[36:39]
	v_mfma_f32_16x16x32_bf16 v[20:23], v[100:103], v[68:71], v[20:23]
	v_mfma_f32_16x16x32_bf16 v[32:35], v[100:103], v[72:75], v[32:35]
	v_mfma_f32_16x16x32_bf16 v[40:43], v[100:103], v[76:79], v[40:43]
	v_mfma_f32_16x16x32_bf16 v[60:63], v[100:103], v[84:87], v[60:63]
	s_nop 7
	s_nop 3
	v_and_b32_e32 v65, 63, v81
	v_lshl_add_u32 v66, v65, 4, 0
	s_ashr_i32 s10, s0, 7
	v_bfe_u32 v64, v81, 4, 2
	v_lshl_add_u32 v67, s3, 14, v66
	s_lshl_b32 s5, s10, 4
	ds_write_b128 v67, v[56:59]
	ds_write_b128 v67, v[52:55] offset:1024
	ds_write_b128 v67, v[48:51] offset:2048
	ds_write_b128 v67, v[44:47] offset:3072
	ds_write_b128 v67, v[12:15] offset:4096
	ds_write_b128 v67, v[8:11] offset:5120
	ds_write_b128 v67, v[4:7] offset:6144
	ds_write_b128 v67, v[0:3] offset:7168
	ds_write_b128 v67, v[16:19] offset:8192
	ds_write_b128 v67, v[24:27] offset:9216
	ds_write_b128 v67, v[28:31] offset:10240
	ds_write_b128 v67, v[36:39] offset:11264
	ds_write_b128 v67, v[20:23] offset:12288
	ds_write_b128 v67, v[32:35] offset:13312
	ds_write_b128 v67, v[40:43] offset:14336
	ds_write_b128 v67, v[60:63] offset:15360
	s_bfe_u32 s3, s0, 0x10006
	s_addk_i32 s5, 0x4000
	v_lshlrev_b32_e32 v1, 2, v64
	v_or_b32_e32 v0, s5, v80
	v_lshl_or_b32 v1, s3, 4, v1
	v_or_b32_e32 v4, s1, v1
	v_ashrrev_i32_e32 v1, 31, v0
	v_lshlrev_b64 v[2:3], 12, v[0:1]
	s_ashr_i32 s5, s4, 31
	v_lshl_add_u64 v[2:3], s[8:9], 0, v[2:3]
	v_lshl_add_u64 v[2:3], s[4:5], 1, v[2:3]
	v_lshlrev_b32_e32 v128, 1, v4
	v_lshl_add_u64 v[14:15], v[2:3], 0, v[128:129]
	s_waitcnt lgkmcnt(0)
	s_barrier
	global_load_dwordx2 v[16:17], v[14:15], off
	global_load_dwordx2 v[18:19], v[14:15], off offset:256
	s_lshl_b32 s1, s3, 2
	s_add_i32 s1, s1, s10
	v_lshl_add_u32 v28, s1, 10, v66
	ds_read_b128 v[2:5], v28
	ds_read_b128 v[6:9], v28 offset:8192
	ds_read_b128 v[10:13], v28 offset:16384
	s_waitcnt lgkmcnt(0)
	v_pk_add_f32 v[20:21], v[4:5], 0 op_sel_hi:[1,0]
	v_pk_add_f32 v[22:23], v[2:3], 0 op_sel_hi:[1,0]
	ds_read_b128 v[2:5], v28 offset:24576
	v_pk_add_f32 v[24:25], v[8:9], 0 op_sel_hi:[1,0]
	v_pk_add_f32 v[26:27], v[6:7], 0 op_sel_hi:[1,0]
	ds_read_b128 v[6:9], v28 offset:32768
	v_pk_add_f32 v[22:23], v[22:23], v[10:11]
	s_waitcnt lgkmcnt(0)
	v_pk_add_f32 v[24:25], v[24:25], v[4:5]
	v_pk_add_f32 v[26:27], v[26:27], v[2:3]
	ds_read_b128 v[2:5], v28 offset:49152
	v_pk_add_f32 v[20:21], v[20:21], v[12:13]
	ds_read_b128 v[10:13], v28 offset:40960
	v_pk_add_f32 v[22:23], v[22:23], v[6:7]
	v_pk_add_f32 v[20:21], v[20:21], v[8:9]
	ds_read_b128 v[6:9], v28 offset:57344
	s_waitcnt lgkmcnt(0)
	v_pk_add_f32 v[22:23], v[22:23], v[2:3]
	v_add_u32_e32 v2, 0x10000, v28
	v_pk_add_f32 v[20:21], v[20:21], v[4:5]
	ds_read_b128 v[2:5], v2
	v_pk_add_f32 v[10:11], v[26:27], v[10:11]
	v_pk_add_f32 v[12:13], v[24:25], v[12:13]
	v_pk_add_f32 v[10:11], v[10:11], v[6:7]
	v_add_u32_e32 v6, 0x12000, v28
	v_pk_add_f32 v[12:13], v[12:13], v[8:9]
	ds_read_b128 v[6:9], v6
	s_waitcnt lgkmcnt(0)
	v_pk_add_f32 v[22:23], v[22:23], v[2:3]
	v_add_u32_e32 v2, 0x14000, v28
	v_pk_add_f32 v[20:21], v[20:21], v[4:5]
	ds_read_b128 v[2:5], v2
	v_pk_add_f32 v[10:11], v[10:11], v[6:7]
	v_add_u32_e32 v6, 0x16000, v28
	v_pk_add_f32 v[12:13], v[12:13], v[8:9]
	ds_read_b128 v[6:9], v6
	s_waitcnt lgkmcnt(0)
	v_pk_add_f32 v[22:23], v[22:23], v[2:3]
	v_add_u32_e32 v2, 0x18000, v28
	v_pk_add_f32 v[20:21], v[20:21], v[4:5]
	ds_read_b128 v[2:5], v2
	v_pk_add_f32 v[26:27], v[10:11], v[6:7]
	v_add_u32_e32 v6, 0x1a000, v28
	v_pk_add_f32 v[24:25], v[12:13], v[8:9]
	ds_read_b128 v[6:9], v6
	s_waitcnt lgkmcnt(0)
	v_pk_add_f32 v[22:23], v[22:23], v[2:3]
	v_add_u32_e32 v2, 0x1c000, v28
	v_add_u32_e32 v10, 0x1e000, v28
	v_pk_add_f32 v[20:21], v[20:21], v[4:5]
	ds_read_b128 v[2:5], v2
	ds_read_b128 v[10:13], v10
	v_pk_add_f32 v[6:7], v[26:27], v[6:7]
	v_pk_add_f32 v[8:9], v[24:25], v[8:9]
	s_waitcnt lgkmcnt(0)
	v_pk_add_f32 v[2:3], v[22:23], v[2:3]
	v_pk_add_f32 v[6:7], v[6:7], v[10:11]
	v_pk_add_f32 v[4:5], v[20:21], v[4:5]
	v_pk_add_f32 v[8:9], v[8:9], v[12:13]
	s_waitcnt vmcnt(0)
	v_lshlrev_b32_e32 v10, 16, v16
	v_and_b32_e32 v11, 0xffff0000, v16
	v_pk_add_f32 v[2:3], v[2:3], v[10:11]
	v_lshlrev_b32_e32 v10, 16, v18
	v_and_b32_e32 v11, 0xffff0000, v18
	v_lshlrev_b32_e32 v12, 16, v17
	v_and_b32_e32 v13, 0xffff0000, v17
	v_pk_add_f32 v[6:7], v[6:7], v[10:11]
	v_pk_add_f32 v[4:5], v[4:5], v[12:13]
	v_lshlrev_b32_e32 v12, 16, v19
	v_and_b32_e32 v13, 0xffff0000, v19
	v_mul_f32_e32 v10, v6, v6
	v_mul_f32_e32 v11, v7, v7
	v_pk_add_f32 v[8:9], v[8:9], v[12:13]
	v_fmac_f32_e32 v10, v2, v2
	v_fmac_f32_e32 v11, v3, v3
	v_add_f32_e32 v10, v10, v11
	v_mul_f32_e32 v11, v8, v8
	v_fmac_f32_e32 v11, v4, v4
	v_add_f32_e32 v10, v11, v10
	v_mul_f32_e32 v11, v9, v9
	v_fmac_f32_e32 v11, v5, v5
	v_and_b32_e32 v12, 64, v214
	v_add_f32_e32 v10, v11, v10
	v_xor_b32_e32 v11, 16, v214
	v_add_u32_e32 v12, 64, v12
	v_cmp_lt_i32_e32 vcc, v11, v12
	v_cvt_pk_bf16_f32 v2, v2, v3
	v_cvt_pk_bf16_f32 v3, v4, v5
	v_xor_b32_e32 v5, 32, v214
	global_store_dwordx2 v[14:15], v[2:3], off
	v_cndmask_b32_e32 v11, v214, v11, vcc
	v_lshlrev_b32_e32 v11, 2, v11
	ds_bpermute_b32 v11, v11, v10
	v_cmp_lt_i32_e32 vcc, v5, v12
	v_cvt_pk_bf16_f32 v2, v6, v7
	v_cvt_pk_bf16_f32 v3, v8, v9
	global_store_dwordx2 v[14:15], v[2:3], off offset:256
	s_waitcnt lgkmcnt(0)
	v_add_f32_e32 v4, v10, v11
	v_cndmask_b32_e32 v5, v214, v5, vcc
	v_lshlrev_b32_e32 v5, 2, v5
	ds_bpermute_b32 v5, v5, v4
	v_cmp_gt_u32_e32 vcc, 16, v65
	s_waitcnt lgkmcnt(0)
	v_add_f32_e32 v2, v4, v5
	s_and_saveexec_b64 s[4:5], vcc
	s_and_b32 s1, s0, 0xffffffc0
	s_add_i32 s1, s1, 0
	v_lshl_add_u32 v3, v80, 2, s1
	v_add_u32_e32 v3, 0x20100, v3
	ds_write_b32 v3, v2
	s_or_b64 exec, exec, s[4:5]
	v_or_b32_e32 v3, s3, v64
	v_cmp_eq_u32_e32 vcc, 0, v3
	s_waitcnt lgkmcnt(0)
	s_barrier
	s_and_saveexec_b64 s[4:5], vcc
	s_cbranch_execz .LBB0_1036
	s_andn2_b32 s0, s0, 63
	s_add_i32 s0, s0, 0
	s_add_i32 s0, s0, 0x20100
	v_lshl_add_u32 v3, v80, 2, s0
	ds_read_b32 v3, v3 offset:64
	v_lshlrev_b64 v[0:1], 7, v[0:1]
	v_lshl_add_u64 v[0:1], s[6:7], 0, v[0:1]
	s_ashr_i32 s3, s2, 31
	v_lshl_add_u64 v[0:1], s[2:3], 2, v[0:1]
	s_waitcnt lgkmcnt(0)
	v_add_f32_e32 v2, v2, v3
	global_store_dword v[0:1], v2, off

.LBB0_1111:
	v_lshrrev_b32_e32 v122, 2, v214
	v_and_b32_e32 v123, 15, v214
	v_sub_u32_e32 v122, v122, v123
	v_mul_i32_i24_e32 v122, 0x1000, v122
	v_bfe_u32 v125, v214, 5, 1
	v_lshlrev_b32_e32 v125, 1, v125
	v_and_b32_e32 v124, 3, v214
	v_xor_b32_e32 v125, v125, v124
	v_lshrrev_b32_e32 v124, 4, v214
	v_sub_u32_e32 v125, v125, v124
	v_lshl_add_u32 v122, v125, 4, v122
	v_ashrrev_i32_e32 v125, 31, v122
	v_add_co_u32_e32 v118, vcc, v66, v122
	s_nop 1
	v_addc_co_u32_e32 v119, vcc, v67, v125, vcc
	v_add_co_u32_e32 v120, vcc, v64, v122
	s_nop 1
	v_addc_co_u32_e32 v121, vcc, v65, v125, vcc
	v_add_co_u32_e32 v82, vcc, s84, v118
	s_nop 1
	v_addc_co_u32_e32 v83, vcc, 0, v119, vcc
	v_add_co_u32_e32 v104, vcc, s85, v118
	s_nop 1
	v_addc_co_u32_e32 v105, vcc, 0, v119, vcc
	v_add_co_u32_e32 v106, vcc, s88, v118
	s_nop 1
	v_addc_co_u32_e32 v107, vcc, 0, v119, vcc
	v_add_co_u32_e32 v108, vcc, s89, v118
	s_nop 1
	v_addc_co_u32_e32 v109, vcc, 0, v119, vcc
	v_add_co_u32_e32 v110, vcc, 0x7008000, v120
	s_nop 1
	v_addc_co_u32_e32 v111, vcc, 0, v121, vcc
	v_add_co_u32_e32 v112, vcc, 0x7018000, v120
	s_nop 1
	v_addc_co_u32_e32 v113, vcc, 0, v121, vcc
	v_add_co_u32_e32 v114, vcc, 0x7088000, v120
	s_nop 1
	v_addc_co_u32_e32 v115, vcc, 0, v121, vcc
	v_add_co_u32_e32 v116, vcc, 0x7098000, v120
	s_nop 1
	v_addc_co_u32_e32 v117, vcc, 0, v121, vcc
	v_readfirstlane_b32 vcc_lo, v210
	v_bfe_u32 v125, v214, 3, 1
	v_lshlrev_b32_e32 v125, 1, v125
	v_xor_b32_e32 v125, v125, v124
	v_lshlrev_b32_e32 v125, 4, v125
	v_lshl_add_u32 v125, v123, 6, v125
	s_lshr_b32 vcc_lo, vcc_lo, 6
	s_lshl_b32 vcc_lo, vcc_lo, 14
	s_mov_b32 s94, 64
	v_add_u32_e32 v124, vcc_lo, v125
	s_add_i32 m0, vcc_lo, 0x0
	s_nop 0
	global_load_lds_dwordx4 v[82:83], off
	v_lshl_add_u64 v[82:83], v[82:83], 0, s[94:95]
	s_add_i32 m0, vcc_lo, 0x400
	s_nop 0
	global_load_lds_dwordx4 v[104:105], off
	v_lshl_add_u64 v[104:105], v[104:105], 0, s[94:95]
	s_add_i32 m0, vcc_lo, 0x800
	s_nop 0
	global_load_lds_dwordx4 v[106:107], off
	v_lshl_add_u64 v[106:107], v[106:107], 0, s[94:95]
	s_add_i32 m0, vcc_lo, 0xc00
	s_nop 0
	global_load_lds_dwordx4 v[108:109], off
	v_lshl_add_u64 v[108:109], v[108:109], 0, s[94:95]
	s_add_i32 m0, vcc_lo, 0x1000
	s_nop 0
	global_load_lds_dwordx4 v[110:111], off
	v_lshl_add_u64 v[110:111], v[110:111], 0, s[94:95]
	s_add_i32 m0, vcc_lo, 0x1400
	s_nop 0
	global_load_lds_dwordx4 v[112:113], off
	v_lshl_add_u64 v[112:113], v[112:113], 0, s[94:95]
	s_add_i32 m0, vcc_lo, 0x1800
	s_nop 0
	global_load_lds_dwordx4 v[114:115], off
	v_lshl_add_u64 v[114:115], v[114:115], 0, s[94:95]
	s_add_i32 m0, vcc_lo, 0x1c00
	s_nop 0
	global_load_lds_dwordx4 v[116:117], off
	v_lshl_add_u64 v[116:117], v[116:117], 0, s[94:95]
	s_add_i32 m0, vcc_lo, 0x2000
	s_nop 0
	global_load_lds_dwordx4 v[82:83], off
	v_lshl_add_u64 v[82:83], v[82:83], 0, s[94:95]
	s_add_i32 m0, vcc_lo, 0x2400
	s_nop 0
	global_load_lds_dwordx4 v[104:105], off
	v_lshl_add_u64 v[104:105], v[104:105], 0, s[94:95]
	s_add_i32 m0, vcc_lo, 0x2800
	s_nop 0
	global_load_lds_dwordx4 v[106:107], off
	v_lshl_add_u64 v[106:107], v[106:107], 0, s[94:95]
	s_add_i32 m0, vcc_lo, 0x2c00
	s_nop 0
	global_load_lds_dwordx4 v[108:109], off
	v_lshl_add_u64 v[108:109], v[108:109], 0, s[94:95]
	s_add_i32 m0, vcc_lo, 0x3000
	s_nop 0
	global_load_lds_dwordx4 v[110:111], off
	v_lshl_add_u64 v[110:111], v[110:111], 0, s[94:95]
	s_add_i32 m0, vcc_lo, 0x3400
	s_nop 0
	global_load_lds_dwordx4 v[112:113], off
	v_lshl_add_u64 v[112:113], v[112:113], 0, s[94:95]
	s_add_i32 m0, vcc_lo, 0x3800
	s_nop 0
	global_load_lds_dwordx4 v[114:115], off
	v_lshl_add_u64 v[114:115], v[114:115], 0, s[94:95]
	s_add_i32 m0, vcc_lo, 0x3c00
	s_nop 0
	global_load_lds_dwordx4 v[116:117], off
	v_lshl_add_u64 v[116:117], v[116:117], 0, s[94:95]
	s_waitcnt vmcnt(8)
	ds_read_b128 v[68:71], v124
	ds_read_b128 v[72:75], v124 offset:1024
	ds_read_b128 v[76:79], v124 offset:2048
	ds_read_b128 v[84:87], v124 offset:3072
	ds_read_b128 v[88:91], v124 offset:4096
	ds_read_b128 v[92:95], v124 offset:5120
	ds_read_b128 v[96:99], v124 offset:6144
	ds_read_b128 v[100:103], v124 offset:7168
	s_waitcnt lgkmcnt(0)
	s_add_i32 m0, vcc_lo, 0x0
	s_nop 0
	global_load_lds_dwordx4 v[82:83], off
	v_lshl_add_u64 v[82:83], v[82:83], 0, s[94:95]
	s_add_i32 m0, vcc_lo, 0x400
	s_nop 0
	global_load_lds_dwordx4 v[104:105], off
	v_lshl_add_u64 v[104:105], v[104:105], 0, s[94:95]
	s_add_i32 m0, vcc_lo, 0x800
	s_nop 0
	global_load_lds_dwordx4 v[106:107], off
	v_lshl_add_u64 v[106:107], v[106:107], 0, s[94:95]
	s_add_i32 m0, vcc_lo, 0xc00
	s_nop 0
	global_load_lds_dwordx4 v[108:109], off
	v_lshl_add_u64 v[108:109], v[108:109], 0, s[94:95]
	s_add_i32 m0, vcc_lo, 0x1000
	s_nop 0
	global_load_lds_dwordx4 v[110:111], off
	v_lshl_add_u64 v[110:111], v[110:111], 0, s[94:95]
	s_add_i32 m0, vcc_lo, 0x1400
	s_nop 0
	global_load_lds_dwordx4 v[112:113], off
	v_lshl_add_u64 v[112:113], v[112:113], 0, s[94:95]
	s_add_i32 m0, vcc_lo, 0x1800
	s_nop 0
	global_load_lds_dwordx4 v[114:115], off
	v_lshl_add_u64 v[114:115], v[114:115], 0, s[94:95]
	s_add_i32 m0, vcc_lo, 0x1c00
	s_nop 0
	global_load_lds_dwordx4 v[116:117], off
	v_lshl_add_u64 v[116:117], v[116:117], 0, s[94:95]
	v_mfma_f32_16x16x32_bf16 v[56:59], v[88:91], v[68:71], 0
	v_mfma_f32_16x16x32_bf16 v[52:55], v[88:91], v[72:75], 0
	v_mfma_f32_16x16x32_bf16 v[48:51], v[88:91], v[76:79], 0
	v_mfma_f32_16x16x32_bf16 v[44:47], v[88:91], v[84:87], 0
	v_mfma_f32_16x16x32_bf16 v[12:15], v[92:95], v[68:71], 0
	v_mfma_f32_16x16x32_bf16 v[8:11], v[92:95], v[72:75], 0
	v_mfma_f32_16x16x32_bf16 v[4:7], v[92:95], v[76:79], 0
	v_mfma_f32_16x16x32_bf16 v[0:3], v[92:95], v[84:87], 0
	v_mfma_f32_16x16x32_bf16 v[16:19], v[96:99], v[68:71], 0
	v_mfma_f32_16x16x32_bf16 v[24:27], v[96:99], v[72:75], 0
	v_mfma_f32_16x16x32_bf16 v[28:31], v[96:99], v[76:79], 0
	v_mfma_f32_16x16x32_bf16 v[36:39], v[96:99], v[84:87], 0
	v_mfma_f32_16x16x32_bf16 v[20:23], v[100:103], v[68:71], 0
	v_mfma_f32_16x16x32_bf16 v[32:35], v[100:103], v[72:75], 0
	v_mfma_f32_16x16x32_bf16 v[40:43], v[100:103], v[76:79], 0
	v_mfma_f32_16x16x32_bf16 v[60:63], v[100:103], v[84:87], 0
	s_waitcnt vmcnt(8)
	ds_read_b128 v[68:71], v124 offset:8192
	ds_read_b128 v[72:75], v124 offset:9216
	ds_read_b128 v[76:79], v124 offset:10240
	ds_read_b128 v[84:87], v124 offset:11264
	ds_read_b128 v[88:91], v124 offset:12288
	ds_read_b128 v[92:95], v124 offset:13312
	ds_read_b128 v[96:99], v124 offset:14336
	ds_read_b128 v[100:103], v124 offset:15360
	s_waitcnt lgkmcnt(0)
	s_add_i32 m0, vcc_lo, 0x2000
	s_nop 0
	global_load_lds_dwordx4 v[82:83], off
	v_lshl_add_u64 v[82:83], v[82:83], 0, s[94:95]
	s_add_i32 m0, vcc_lo, 0x2400
	s_nop 0
	global_load_lds_dwordx4 v[104:105], off
	v_lshl_add_u64 v[104:105], v[104:105], 0, s[94:95]
	s_add_i32 m0, vcc_lo, 0x2800
	s_nop 0
	global_load_lds_dwordx4 v[106:107], off
	v_lshl_add_u64 v[106:107], v[106:107], 0, s[94:95]
	s_add_i32 m0, vcc_lo, 0x2c00
	s_nop 0
	global_load_lds_dwordx4 v[108:109], off
	v_lshl_add_u64 v[108:109], v[108:109], 0, s[94:95]
	s_add_i32 m0, vcc_lo, 0x3000
	s_nop 0
	global_load_lds_dwordx4 v[110:111], off
	v_lshl_add_u64 v[110:111], v[110:111], 0, s[94:95]
	s_add_i32 m0, vcc_lo, 0x3400
	s_nop 0
	global_load_lds_dwordx4 v[112:113], off
	v_lshl_add_u64 v[112:113], v[112:113], 0, s[94:95]
	s_add_i32 m0, vcc_lo, 0x3800
	s_nop 0
	global_load_lds_dwordx4 v[114:115], off
	v_lshl_add_u64 v[114:115], v[114:115], 0, s[94:95]
	s_add_i32 m0, vcc_lo, 0x3c00
	s_nop 0
	global_load_lds_dwordx4 v[116:117], off
	v_lshl_add_u64 v[116:117], v[116:117], 0, s[94:95]
	v_mfma_f32_16x16x32_bf16 v[56:59], v[88:91], v[68:71], v[56:59]
	v_mfma_f32_16x16x32_bf16 v[52:55], v[88:91], v[72:75], v[52:55]
	v_mfma_f32_16x16x32_bf16 v[48:51], v[88:91], v[76:79], v[48:51]
	v_mfma_f32_16x16x32_bf16 v[44:47], v[88:91], v[84:87], v[44:47]
	v_mfma_f32_16x16x32_bf16 v[12:15], v[92:95], v[68:71], v[12:15]
	v_mfma_f32_16x16x32_bf16 v[8:11], v[92:95], v[72:75], v[8:11]
	v_mfma_f32_16x16x32_bf16 v[4:7], v[92:95], v[76:79], v[4:7]
	v_mfma_f32_16x16x32_bf16 v[0:3], v[92:95], v[84:87], v[0:3]
	v_mfma_f32_16x16x32_bf16 v[16:19], v[96:99], v[68:71], v[16:19]
	v_mfma_f32_16x16x32_bf16 v[24:27], v[96:99], v[72:75], v[24:27]
	v_mfma_f32_16x16x32_bf16 v[28:31], v[96:99], v[76:79], v[28:31]
	v_mfma_f32_16x16x32_bf16 v[36:39], v[96:99], v[84:87], v[36:39]
	v_mfma_f32_16x16x32_bf16 v[20:23], v[100:103], v[68:71], v[20:23]
	v_mfma_f32_16x16x32_bf16 v[32:35], v[100:103], v[72:75], v[32:35]
	v_mfma_f32_16x16x32_bf16 v[40:43], v[100:103], v[76:79], v[40:43]
	v_mfma_f32_16x16x32_bf16 v[60:63], v[100:103], v[84:87], v[60:63]
	s_waitcnt vmcnt(8)
	ds_read_b128 v[68:71], v124
	ds_read_b128 v[72:75], v124 offset:1024
	ds_read_b128 v[76:79], v124 offset:2048
	ds_read_b128 v[84:87], v124 offset:3072
	ds_read_b128 v[88:91], v124 offset:4096
	ds_read_b128 v[92:95], v124 offset:5120
	ds_read_b128 v[96:99], v124 offset:6144
	ds_read_b128 v[100:103], v124 offset:7168
	s_waitcnt lgkmcnt(0)
	s_add_i32 m0, vcc_lo, 0x0
	s_nop 0
	global_load_lds_dwordx4 v[82:83], off
	v_lshl_add_u64 v[82:83], v[82:83], 0, s[94:95]
	s_add_i32 m0, vcc_lo, 0x400
	s_nop 0
	global_load_lds_dwordx4 v[104:105], off
	v_lshl_add_u64 v[104:105], v[104:105], 0, s[94:95]
	s_add_i32 m0, vcc_lo, 0x800
	s_nop 0
	global_load_lds_dwordx4 v[106:107], off
	v_lshl_add_u64 v[106:107], v[106:107], 0, s[94:95]
	s_add_i32 m0, vcc_lo, 0xc00
	s_nop 0
	global_load_lds_dwordx4 v[108:109], off
	v_lshl_add_u64 v[108:109], v[108:109], 0, s[94:95]
	s_add_i32 m0, vcc_lo, 0x1000
	s_nop 0
	global_load_lds_dwordx4 v[110:111], off
	v_lshl_add_u64 v[110:111], v[110:111], 0, s[94:95]
	s_add_i32 m0, vcc_lo, 0x1400
	s_nop 0
	global_load_lds_dwordx4 v[112:113], off
	v_lshl_add_u64 v[112:113], v[112:113], 0, s[94:95]
	s_add_i32 m0, vcc_lo, 0x1800
	s_nop 0
	global_load_lds_dwordx4 v[114:115], off
	v_lshl_add_u64 v[114:115], v[114:115], 0, s[94:95]
	s_add_i32 m0, vcc_lo, 0x1c00
	s_nop 0
	global_load_lds_dwordx4 v[116:117], off
	v_lshl_add_u64 v[116:117], v[116:117], 0, s[94:95]
	v_mfma_f32_16x16x32_bf16 v[56:59], v[88:91], v[68:71], v[56:59]
	v_mfma_f32_16x16x32_bf16 v[52:55], v[88:91], v[72:75], v[52:55]
	v_mfma_f32_16x16x32_bf16 v[48:51], v[88:91], v[76:79], v[48:51]
	v_mfma_f32_16x16x32_bf16 v[44:47], v[88:91], v[84:87], v[44:47]
	v_mfma_f32_16x16x32_bf16 v[12:15], v[92:95], v[68:71], v[12:15]
	v_mfma_f32_16x16x32_bf16 v[8:11], v[92:95], v[72:75], v[8:11]
	v_mfma_f32_16x16x32_bf16 v[4:7], v[92:95], v[76:79], v[4:7]
	v_mfma_f32_16x16x32_bf16 v[0:3], v[92:95], v[84:87], v[0:3]
	v_mfma_f32_16x16x32_bf16 v[16:19], v[96:99], v[68:71], v[16:19]
	v_mfma_f32_16x16x32_bf16 v[24:27], v[96:99], v[72:75], v[24:27]
	v_mfma_f32_16x16x32_bf16 v[28:31], v[96:99], v[76:79], v[28:31]
	v_mfma_f32_16x16x32_bf16 v[36:39], v[96:99], v[84:87], v[36:39]
	v_mfma_f32_16x16x32_bf16 v[20:23], v[100:103], v[68:71], v[20:23]
	v_mfma_f32_16x16x32_bf16 v[32:35], v[100:103], v[72:75], v[32:35]
	v_mfma_f32_16x16x32_bf16 v[40:43], v[100:103], v[76:79], v[40:43]
	v_mfma_f32_16x16x32_bf16 v[60:63], v[100:103], v[84:87], v[60:63]
	s_waitcnt vmcnt(8)
	ds_read_b128 v[68:71], v124 offset:8192
	ds_read_b128 v[72:75], v124 offset:9216
	ds_read_b128 v[76:79], v124 offset:10240
	ds_read_b128 v[84:87], v124 offset:11264
	ds_read_b128 v[88:91], v124 offset:12288
	ds_read_b128 v[92:95], v124 offset:13312
	ds_read_b128 v[96:99], v124 offset:14336
	ds_read_b128 v[100:103], v124 offset:15360
	s_waitcnt lgkmcnt(0)
	s_add_i32 m0, vcc_lo, 0x2000
	s_nop 0
	global_load_lds_dwordx4 v[82:83], off
	v_lshl_add_u64 v[82:83], v[82:83], 0, s[94:95]
	s_add_i32 m0, vcc_lo, 0x2400
	s_nop 0
	global_load_lds_dwordx4 v[104:105], off
	v_lshl_add_u64 v[104:105], v[104:105], 0, s[94:95]
	s_add_i32 m0, vcc_lo, 0x2800
	s_nop 0
	global_load_lds_dwordx4 v[106:107], off
	v_lshl_add_u64 v[106:107], v[106:107], 0, s[94:95]
	s_add_i32 m0, vcc_lo, 0x2c00
	s_nop 0
	global_load_lds_dwordx4 v[108:109], off
	v_lshl_add_u64 v[108:109], v[108:109], 0, s[94:95]
	s_add_i32 m0, vcc_lo, 0x3000
	s_nop 0
	global_load_lds_dwordx4 v[110:111], off
	v_lshl_add_u64 v[110:111], v[110:111], 0, s[94:95]
	s_add_i32 m0, vcc_lo, 0x3400
	s_nop 0
	global_load_lds_dwordx4 v[112:113], off
	v_lshl_add_u64 v[112:113], v[112:113], 0, s[94:95]
	s_add_i32 m0, vcc_lo, 0x3800
	s_nop 0
	global_load_lds_dwordx4 v[114:115], off
	v_lshl_add_u64 v[114:115], v[114:115], 0, s[94:95]
	s_add_i32 m0, vcc_lo, 0x3c00
	s_nop 0
	global_load_lds_dwordx4 v[116:117], off
	v_lshl_add_u64 v[116:117], v[116:117], 0, s[94:95]
	v_mfma_f32_16x16x32_bf16 v[56:59], v[88:91], v[68:71], v[56:59]
	v_mfma_f32_16x16x32_bf16 v[52:55], v[88:91], v[72:75], v[52:55]
	v_mfma_f32_16x16x32_bf16 v[48:51], v[88:91], v[76:79], v[48:51]
	v_mfma_f32_16x16x32_bf16 v[44:47], v[88:91], v[84:87], v[44:47]
	v_mfma_f32_16x16x32_bf16 v[12:15], v[92:95], v[68:71], v[12:15]
	v_mfma_f32_16x16x32_bf16 v[8:11], v[92:95], v[72:75], v[8:11]
	v_mfma_f32_16x16x32_bf16 v[4:7], v[92:95], v[76:79], v[4:7]
	v_mfma_f32_16x16x32_bf16 v[0:3], v[92:95], v[84:87], v[0:3]
	v_mfma_f32_16x16x32_bf16 v[16:19], v[96:99], v[68:71], v[16:19]
	v_mfma_f32_16x16x32_bf16 v[24:27], v[96:99], v[72:75], v[24:27]
	v_mfma_f32_16x16x32_bf16 v[28:31], v[96:99], v[76:79], v[28:31]
	v_mfma_f32_16x16x32_bf16 v[36:39], v[96:99], v[84:87], v[36:39]
	v_mfma_f32_16x16x32_bf16 v[20:23], v[100:103], v[68:71], v[20:23]
	v_mfma_f32_16x16x32_bf16 v[32:35], v[100:103], v[72:75], v[32:35]
	v_mfma_f32_16x16x32_bf16 v[40:43], v[100:103], v[76:79], v[40:43]
	v_mfma_f32_16x16x32_bf16 v[60:63], v[100:103], v[84:87], v[60:63]
	s_waitcnt vmcnt(8)
	ds_read_b128 v[68:71], v124
	ds_read_b128 v[72:75], v124 offset:1024
	ds_read_b128 v[76:79], v124 offset:2048
	ds_read_b128 v[84:87], v124 offset:3072
	ds_read_b128 v[88:91], v124 offset:4096
	ds_read_b128 v[92:95], v124 offset:5120
	ds_read_b128 v[96:99], v124 offset:6144
	ds_read_b128 v[100:103], v124 offset:7168
	s_waitcnt lgkmcnt(0)
	s_add_i32 m0, vcc_lo, 0x0
	s_nop 0
	global_load_lds_dwordx4 v[82:83], off
	v_lshl_add_u64 v[82:83], v[82:83], 0, s[94:95]
	s_add_i32 m0, vcc_lo, 0x400
	s_nop 0
	global_load_lds_dwordx4 v[104:105], off
	v_lshl_add_u64 v[104:105], v[104:105], 0, s[94:95]
	s_add_i32 m0, vcc_lo, 0x800
	s_nop 0
	global_load_lds_dwordx4 v[106:107], off
	v_lshl_add_u64 v[106:107], v[106:107], 0, s[94:95]
	s_add_i32 m0, vcc_lo, 0xc00
	s_nop 0
	global_load_lds_dwordx4 v[108:109], off
	v_lshl_add_u64 v[108:109], v[108:109], 0, s[94:95]
	s_add_i32 m0, vcc_lo, 0x1000
	s_nop 0
	global_load_lds_dwordx4 v[110:111], off
	v_lshl_add_u64 v[110:111], v[110:111], 0, s[94:95]
	s_add_i32 m0, vcc_lo, 0x1400
	s_nop 0
	global_load_lds_dwordx4 v[112:113], off
	v_lshl_add_u64 v[112:113], v[112:113], 0, s[94:95]
	s_add_i32 m0, vcc_lo, 0x1800
	s_nop 0
	global_load_lds_dwordx4 v[114:115], off
	v_lshl_add_u64 v[114:115], v[114:115], 0, s[94:95]
	s_add_i32 m0, vcc_lo, 0x1c00
	s_nop 0
	global_load_lds_dwordx4 v[116:117], off
	v_lshl_add_u64 v[116:117], v[116:117], 0, s[94:95]
	v_mfma_f32_16x16x32_bf16 v[56:59], v[88:91], v[68:71], v[56:59]
	v_mfma_f32_16x16x32_bf16 v[52:55], v[88:91], v[72:75], v[52:55]
	v_mfma_f32_16x16x32_bf16 v[48:51], v[88:91], v[76:79], v[48:51]
	v_mfma_f32_16x16x32_bf16 v[44:47], v[88:91], v[84:87], v[44:47]
	v_mfma_f32_16x16x32_bf16 v[12:15], v[92:95], v[68:71], v[12:15]
	v_mfma_f32_16x16x32_bf16 v[8:11], v[92:95], v[72:75], v[8:11]
	v_mfma_f32_16x16x32_bf16 v[4:7], v[92:95], v[76:79], v[4:7]
	v_mfma_f32_16x16x32_bf16 v[0:3], v[92:95], v[84:87], v[0:3]
	v_mfma_f32_16x16x32_bf16 v[16:19], v[96:99], v[68:71], v[16:19]
	v_mfma_f32_16x16x32_bf16 v[24:27], v[96:99], v[72:75], v[24:27]
	v_mfma_f32_16x16x32_bf16 v[28:31], v[96:99], v[76:79], v[28:31]
	v_mfma_f32_16x16x32_bf16 v[36:39], v[96:99], v[84:87], v[36:39]
	v_mfma_f32_16x16x32_bf16 v[20:23], v[100:103], v[68:71], v[20:23]
	v_mfma_f32_16x16x32_bf16 v[32:35], v[100:103], v[72:75], v[32:35]
	v_mfma_f32_16x16x32_bf16 v[40:43], v[100:103], v[76:79], v[40:43]
	v_mfma_f32_16x16x32_bf16 v[60:63], v[100:103], v[84:87], v[60:63]
	s_waitcnt vmcnt(8)
	ds_read_b128 v[68:71], v124 offset:8192
	ds_read_b128 v[72:75], v124 offset:9216
	ds_read_b128 v[76:79], v124 offset:10240
	ds_read_b128 v[84:87], v124 offset:11264
	ds_read_b128 v[88:91], v124 offset:12288
	ds_read_b128 v[92:95], v124 offset:13312
	ds_read_b128 v[96:99], v124 offset:14336
	ds_read_b128 v[100:103], v124 offset:15360
	s_waitcnt lgkmcnt(0)
	s_add_i32 m0, vcc_lo, 0x2000
	s_nop 0
	global_load_lds_dwordx4 v[82:83], off
	v_lshl_add_u64 v[82:83], v[82:83], 0, s[94:95]
	s_add_i32 m0, vcc_lo, 0x2400
	s_nop 0
	global_load_lds_dwordx4 v[104:105], off
	v_lshl_add_u64 v[104:105], v[104:105], 0, s[94:95]
	s_add_i32 m0, vcc_lo, 0x2800
	s_nop 0
	global_load_lds_dwordx4 v[106:107], off
	v_lshl_add_u64 v[106:107], v[106:107], 0, s[94:95]
	s_add_i32 m0, vcc_lo, 0x2c00
	s_nop 0
	global_load_lds_dwordx4 v[108:109], off
	v_lshl_add_u64 v[108:109], v[108:109], 0, s[94:95]
	s_add_i32 m0, vcc_lo, 0x3000
	s_nop 0
	global_load_lds_dwordx4 v[110:111], off
	v_lshl_add_u64 v[110:111], v[110:111], 0, s[94:95]
	s_add_i32 m0, vcc_lo, 0x3400
	s_nop 0
	global_load_lds_dwordx4 v[112:113], off
	v_lshl_add_u64 v[112:113], v[112:113], 0, s[94:95]
	s_add_i32 m0, vcc_lo, 0x3800
	s_nop 0
	global_load_lds_dwordx4 v[114:115], off
	v_lshl_add_u64 v[114:115], v[114:115], 0, s[94:95]
	s_add_i32 m0, vcc_lo, 0x3c00
	s_nop 0
	global_load_lds_dwordx4 v[116:117], off
	v_lshl_add_u64 v[116:117], v[116:117], 0, s[94:95]
	v_mfma_f32_16x16x32_bf16 v[56:59], v[88:91], v[68:71], v[56:59]
	v_mfma_f32_16x16x32_bf16 v[52:55], v[88:91], v[72:75], v[52:55]
	v_mfma_f32_16x16x32_bf16 v[48:51], v[88:91], v[76:79], v[48:51]
	v_mfma_f32_16x16x32_bf16 v[44:47], v[88:91], v[84:87], v[44:47]
	v_mfma_f32_16x16x32_bf16 v[12:15], v[92:95], v[68:71], v[12:15]
	v_mfma_f32_16x16x32_bf16 v[8:11], v[92:95], v[72:75], v[8:11]
	v_mfma_f32_16x16x32_bf16 v[4:7], v[92:95], v[76:79], v[4:7]
	v_mfma_f32_16x16x32_bf16 v[0:3], v[92:95], v[84:87], v[0:3]
	v_mfma_f32_16x16x32_bf16 v[16:19], v[96:99], v[68:71], v[16:19]
	v_mfma_f32_16x16x32_bf16 v[24:27], v[96:99], v[72:75], v[24:27]
	v_mfma_f32_16x16x32_bf16 v[28:31], v[96:99], v[76:79], v[28:31]
	v_mfma_f32_16x16x32_bf16 v[36:39], v[96:99], v[84:87], v[36:39]
	v_mfma_f32_16x16x32_bf16 v[20:23], v[100:103], v[68:71], v[20:23]
	v_mfma_f32_16x16x32_bf16 v[32:35], v[100:103], v[72:75], v[32:35]
	v_mfma_f32_16x16x32_bf16 v[40:43], v[100:103], v[76:79], v[40:43]
	v_mfma_f32_16x16x32_bf16 v[60:63], v[100:103], v[84:87], v[60:63]
	s_waitcnt vmcnt(8)
	ds_read_b128 v[68:71], v124
	ds_read_b128 v[72:75], v124 offset:1024
	ds_read_b128 v[76:79], v124 offset:2048
	ds_read_b128 v[84:87], v124 offset:3072
	ds_read_b128 v[88:91], v124 offset:4096
	ds_read_b128 v[92:95], v124 offset:5120
	ds_read_b128 v[96:99], v124 offset:6144
	ds_read_b128 v[100:103], v124 offset:7168
	s_waitcnt lgkmcnt(0)
	v_mfma_f32_16x16x32_bf16 v[56:59], v[88:91], v[68:71], v[56:59]
	v_mfma_f32_16x16x32_bf16 v[52:55], v[88:91], v[72:75], v[52:55]
	v_mfma_f32_16x16x32_bf16 v[48:51], v[88:91], v[76:79], v[48:51]
	v_mfma_f32_16x16x32_bf16 v[44:47], v[88:91], v[84:87], v[44:47]
	v_mfma_f32_16x16x32_bf16 v[12:15], v[92:95], v[68:71], v[12:15]
	v_mfma_f32_16x16x32_bf16 v[8:11], v[92:95], v[72:75], v[8:11]
	v_mfma_f32_16x16x32_bf16 v[4:7], v[92:95], v[76:79], v[4:7]
	v_mfma_f32_16x16x32_bf16 v[0:3], v[92:95], v[84:87], v[0:3]
	v_mfma_f32_16x16x32_bf16 v[16:19], v[96:99], v[68:71], v[16:19]
	v_mfma_f32_16x16x32_bf16 v[24:27], v[96:99], v[72:75], v[24:27]
	v_mfma_f32_16x16x32_bf16 v[28:31], v[96:99], v[76:79], v[28:31]
	v_mfma_f32_16x16x32_bf16 v[36:39], v[96:99], v[84:87], v[36:39]
	v_mfma_f32_16x16x32_bf16 v[20:23], v[100:103], v[68:71], v[20:23]
	v_mfma_f32_16x16x32_bf16 v[32:35], v[100:103], v[72:75], v[32:35]
	v_mfma_f32_16x16x32_bf16 v[40:43], v[100:103], v[76:79], v[40:43]
	v_mfma_f32_16x16x32_bf16 v[60:63], v[100:103], v[84:87], v[60:63]
	s_waitcnt vmcnt(0)
	ds_read_b128 v[68:71], v124 offset:8192
	ds_read_b128 v[72:75], v124 offset:9216
	ds_read_b128 v[76:79], v124 offset:10240
	ds_read_b128 v[84:87], v124 offset:11264
	ds_read_b128 v[88:91], v124 offset:12288
	ds_read_b128 v[92:95], v124 offset:13312
	ds_read_b128 v[96:99], v124 offset:14336
	ds_read_b128 v[100:103], v124 offset:15360
	s_waitcnt lgkmcnt(0)
	v_mfma_f32_16x16x32_bf16 v[56:59], v[88:91], v[68:71], v[56:59]
	v_mfma_f32_16x16x32_bf16 v[52:55], v[88:91], v[72:75], v[52:55]
	v_mfma_f32_16x16x32_bf16 v[48:51], v[88:91], v[76:79], v[48:51]
	v_mfma_f32_16x16x32_bf16 v[44:47], v[88:91], v[84:87], v[44:47]
	v_mfma_f32_16x16x32_bf16 v[12:15], v[92:95], v[68:71], v[12:15]
	v_mfma_f32_16x16x32_bf16 v[8:11], v[92:95], v[72:75], v[8:11]
	v_mfma_f32_16x16x32_bf16 v[4:7], v[92:95], v[76:79], v[4:7]
	v_mfma_f32_16x16x32_bf16 v[0:3], v[92:95], v[84:87], v[0:3]
	v_mfma_f32_16x16x32_bf16 v[16:19], v[96:99], v[68:71], v[16:19]
	v_mfma_f32_16x16x32_bf16 v[24:27], v[96:99], v[72:75], v[24:27]
	v_mfma_f32_16x16x32_bf16 v[28:31], v[96:99], v[76:79], v[28:31]
	v_mfma_f32_16x16x32_bf16 v[36:39], v[96:99], v[84:87], v[36:39]
	v_mfma_f32_16x16x32_bf16 v[20:23], v[100:103], v[68:71], v[20:23]
	v_mfma_f32_16x16x32_bf16 v[32:35], v[100:103], v[72:75], v[32:35]
	v_mfma_f32_16x16x32_bf16 v[40:43], v[100:103], v[76:79], v[40:43]
	v_mfma_f32_16x16x32_bf16 v[60:63], v[100:103], v[84:87], v[60:63]
	s_nop 7
	s_nop 3
	v_and_b32_e32 v65, 63, v81
	s_ashr_i32 s2, s4, 7
	v_lshl_add_u32 v65, v65, 4, 0
	s_lshl_b32 s3, s2, 4
	v_lshl_add_u32 v66, s5, 14, v65
	s_addk_i32 s3, 0x4000
	ds_write_b128 v66, v[56:59]
	ds_write_b128 v66, v[52:55] offset:1024
	ds_write_b128 v66, v[48:51] offset:2048
	ds_write_b128 v66, v[44:47] offset:3072
	ds_write_b128 v66, v[12:15] offset:4096
	ds_write_b128 v66, v[8:11] offset:5120
	ds_write_b128 v66, v[4:7] offset:6144
	ds_write_b128 v66, v[0:3] offset:7168
	ds_write_b128 v66, v[16:19] offset:8192
	ds_write_b128 v66, v[24:27] offset:9216
	ds_write_b128 v66, v[28:31] offset:10240
	ds_write_b128 v66, v[36:39] offset:11264
	ds_write_b128 v66, v[20:23] offset:12288
	ds_write_b128 v66, v[32:35] offset:13312
	ds_write_b128 v66, v[40:43] offset:14336
	ds_write_b128 v66, v[60:63] offset:15360
	v_or_b32_e32 v0, s3, v80
	v_ashrrev_i32_e32 v1, 31, v0
	v_bfe_u32 v64, v81, 4, 2
	v_lshlrev_b64 v[2:3], 7, v[0:1]
	v_lshl_add_u64 v[2:3], s[8:9], 0, v[2:3]
	v_lshlrev_b32_e32 v128, 5, v64
	v_lshl_add_u64 v[6:7], v[2:3], 0, v[128:129]
	s_waitcnt lgkmcnt(0)
	s_barrier
	global_load_dwordx4 v[2:5], v[6:7], off
	s_nop 0
	global_load_dwordx4 v[6:9], v[6:7], off offset:16
	s_bfe_u32 s3, s4, 0x10006
	s_lshl_b32 s4, s3, 2
	s_add_i32 s4, s4, s2
	v_lshl_add_u32 v1, s4, 10, v65
	ds_read_b128 v[10:13], v1
	ds_read_b128 v[14:17], v1 offset:8192
	ds_read_b128 v[18:21], v1 offset:16384
	ds_read_b128 v[22:25], v1 offset:24576
	ds_read_b128 v[26:29], v1 offset:32768
	ds_read_b128 v[30:33], v1 offset:40960
	ds_read_b128 v[34:37], v1 offset:49152
	ds_read_b128 v[38:41], v1 offset:57344
	s_waitcnt lgkmcnt(0)
	v_pk_add_f32 v[10:11], v[10:11], 0 op_sel_hi:[1,0]
	v_add_u32_e32 v42, 0x10000, v1
	v_pk_add_f32 v[10:11], v[10:11], v[18:19]
	v_add_u32_e32 v46, 0x12000, v1
	v_add_u32_e32 v50, 0x14000, v1
	v_add_u32_e32 v54, 0x16000, v1
	v_add_u32_e32 v58, 0x18000, v1
	v_add_u32_e32 v62, 0x1a000, v1
	ds_read_b128 v[42:45], v42
	ds_read_b128 v[46:49], v46
	ds_read_b128 v[50:53], v50
	ds_read_b128 v[54:57], v54
	ds_read_b128 v[58:61], v58
	ds_read_b128 v[66:69], v62
	v_pk_add_f32 v[14:15], v[14:15], 0 op_sel_hi:[1,0]
	v_pk_add_f32 v[12:13], v[12:13], 0 op_sel_hi:[1,0]
	v_pk_add_f32 v[14:15], v[14:15], v[22:23]
	v_pk_add_f32 v[12:13], v[12:13], v[20:21]
	v_pk_add_f32 v[10:11], v[10:11], v[26:27]
	v_pk_add_f32 v[14:15], v[14:15], v[30:31]
	v_pk_add_f32 v[12:13], v[12:13], v[28:29]
	v_pk_add_f32 v[10:11], v[10:11], v[34:35]
	v_pk_add_f32 v[14:15], v[14:15], v[38:39]
	v_pk_add_f32 v[12:13], v[12:13], v[36:37]
	s_waitcnt lgkmcnt(0)
	v_pk_add_f32 v[10:11], v[10:11], v[42:43]
	v_pk_add_f32 v[14:15], v[14:15], v[46:47]
	v_pk_add_f32 v[12:13], v[12:13], v[44:45]
	v_pk_add_f32 v[10:11], v[10:11], v[50:51]
	v_pk_add_f32 v[14:15], v[14:15], v[54:55]
	v_pk_add_f32 v[12:13], v[12:13], v[52:53]
	v_pk_add_f32 v[10:11], v[10:11], v[58:59]
	v_pk_add_f32 v[14:15], v[14:15], v[66:67]
	v_pk_add_f32 v[12:13], v[12:13], v[60:61]
	v_pk_add_f32 v[16:17], v[16:17], 0 op_sel_hi:[1,0]
	s_lshl_b32 s0, s0, 7
	v_pk_add_f32 v[16:17], v[16:17], v[24:25]
	s_waitcnt vmcnt(0)
	v_mov_b32_e32 v18, v2
	v_mov_b32_e32 v19, v6
	v_mov_b32_e32 v6, v3
	v_mov_b32_e32 v2, v4
	v_mov_b32_e32 v3, v8
	v_mov_b32_e32 v8, v5
	v_pk_add_f32 v[4:5], v[18:19], v[6:7]
	v_pk_add_f32 v[2:3], v[2:3], v[8:9]
	v_pk_add_f32 v[16:17], v[16:17], v[32:33]
	v_pk_add_f32 v[2:3], v[4:5], v[2:3]
	v_and_b32_e32 v4, 64, v214
	v_add_f32_e32 v2, v2, v3
	v_xor_b32_e32 v3, 16, v214
	v_add_u32_e32 v4, 64, v4
	v_cmp_lt_i32_e32 vcc, v3, v4
	v_pk_add_f32 v[16:17], v[16:17], v[40:41]
	s_nop 0
	v_cndmask_b32_e32 v3, v214, v3, vcc
	v_lshlrev_b32_e32 v3, 2, v3
	ds_bpermute_b32 v3, v3, v2
	v_pk_add_f32 v[16:17], v[16:17], v[48:49]
	s_waitcnt lgkmcnt(0)
	v_add_f32_e32 v18, v2, v3
	v_xor_b32_e32 v2, 32, v214
	v_cmp_lt_i32_e32 vcc, v2, v4
	v_pk_add_f32 v[16:17], v[16:17], v[56:57]
	s_nop 0
	v_cndmask_b32_e32 v2, v214, v2, vcc
	v_lshlrev_b32_e32 v2, 2, v2
	ds_bpermute_b32 v19, v2, v18
	v_add_u32_e32 v2, 0x1c000, v1
	v_add_u32_e32 v1, 0x1e000, v1
	ds_read_b128 v[2:5], v2
	ds_read_b128 v[6:9], v1
	v_pk_add_f32 v[16:17], v[16:17], v[68:69]
	s_waitcnt lgkmcnt(2)
	v_add_f32_e32 v1, v18, v19
	v_fmamk_f32 v1, v1, 0x3a000000, v190
	v_mul_f32_e32 v18, 0x4b800000, v1
	v_cmp_gt_f32_e32 vcc, s70, v1
	s_waitcnt lgkmcnt(1)
	v_pk_add_f32 v[2:3], v[10:11], v[2:3]
	s_waitcnt lgkmcnt(0)
	v_pk_add_f32 v[6:7], v[14:15], v[6:7]
	v_cndmask_b32_e32 v1, v1, v18, vcc
	v_rsq_f32_e32 v1, v1
	v_pk_add_f32 v[4:5], v[12:13], v[4:5]
	v_mov_b32_e32 v12, v6
	v_mov_b32_e32 v13, v2
	v_mul_f32_e32 v10, 0x45800000, v1
	v_cndmask_b32_e32 v10, v1, v10, vcc
	v_pk_mul_f32 v[12:13], v[12:13], v[10:11] op_sel_hi:[1,0]
	v_lshlrev_b32_e32 v2, 2, v64
	v_mul_f32_e32 v1, 0xbfb8aa3b, v13
	v_exp_f32_e32 v1, v1
	v_lshl_or_b32 v6, s3, 4, v2
	v_mov_b32_e32 v2, v7
	v_pk_mul_f32 v[2:3], v[2:3], v[10:11] op_sel_hi:[1,0]
	v_add_f32_e32 v1, 1.0, v1
	v_mul_f32_e32 v7, 0xbfb8aa3b, v3
	v_rcp_f32_e32 v1, v1
	v_exp_f32_e32 v7, v7
	v_pk_add_f32 v[8:9], v[16:17], v[8:9]
	v_or_b32_e32 v11, s1, v6
	v_mul_f32_e32 v1, v13, v1
	v_add_f32_e32 v6, 1.0, v7
	v_mul_f32_e32 v1, v12, v1
	v_rcp_f32_e32 v12, v6
	v_mov_b32_e32 v6, v8
	v_mov_b32_e32 v7, v4
	v_pk_mul_f32 v[6:7], v[6:7], v[10:11] op_sel_hi:[1,0]
	v_mul_f32_e32 v3, v3, v12
	v_mul_f32_e32 v4, 0xbfb8aa3b, v7
	v_exp_f32_e32 v8, v4
	v_mov_b32_e32 v4, v9
	v_pk_mul_f32 v[4:5], v[4:5], v[10:11] op_sel_hi:[1,0]
	v_mul_f32_e32 v2, v2, v3
	v_mul_f32_e32 v9, 0xbfb8aa3b, v5
	v_exp_f32_e32 v9, v9
	v_add_f32_e32 v8, 1.0, v8
	v_rcp_f32_e32 v8, v8
	v_cvt_pk_bf16_f32 v2, v1, v2
	v_add_f32_e32 v9, 1.0, v9
	v_rcp_f32_e32 v9, v9
	v_mul_f32_e32 v3, v7, v8
	v_mul_f32_e32 v3, v6, v3
	s_movk_i32 s1, 0x2c00
	v_mul_f32_e32 v5, v5, v9
	v_mul_f32_e32 v4, v4, v5
	v_cvt_pk_bf16_f32 v3, v3, v4
	v_mov_b64_e32 v[4:5], s[6:7]
	v_mad_i64_i32 v[0:1], s[2:3], v0, s1, v[4:5]
	s_ashr_i32 s1, s0, 31
	v_lshl_add_u64 v[0:1], s[0:1], 1, v[0:1]
	v_lshlrev_b32_e32 v128, 1, v11
	v_lshl_add_u64 v[0:1], v[0:1], 0, v[128:129]
	global_store_dwordx2 v[0:1], v[2:3], off
	s_waitcnt lgkmcnt(0)
	s_barrier

.LBB0_1205:
	v_mov_b32_e32 v97, v210
	s_mov_b32 s2, s73
	s_cmp_gt_i32 s2, 31
	v_readfirstlane_b32 s1, v97
	s_cbranch_scc1 .LBB0_1211
	v_and_b32_e32 v96, 15, v97
	s_ashr_i32 s5, s1, 6
	v_mul_u32_u24_e32 v0, 0x1600, v96
	v_lshlrev_b32_e32 v128, 1, v0
	s_mul_i32 s6, s5, 0x2c0
	s_lshl_b32 s3, s2, 5
	s_waitcnt lgkmcnt(0)
	v_lshl_add_u64 v[0:1], s[14:15], 0, v[128:129]
	v_and_b32_e32 v128, 48, v97
	s_ashr_i32 s7, s6, 31
	s_lshl_b32 s4, s2, 6
	s_and_b32 s3, s3, 0x60
	v_lshl_add_u64 v[0:1], v[0:1], 0, v[128:129]
	s_lshl_b64 s[6:7], s[6:7], 1
	s_and_b32 s4, s4, 0xffffff00
	v_lshl_add_u64 v[28:29], v[0:1], 0, s[6:7]
	v_or_b32_e32 v0, s3, v96
	v_or_b32_e32 v2, s4, v0
	v_mov_b64_e32 v[0:1], s[12:13]
	s_movk_i32 s12, 0x2c00
	v_mad_i64_i32 v[0:1], s[12:13], v2, s12, v[0:1]
	v_lshl_add_u64 v[0:1], v[0:1], 0, v[128:129]
	v_lshl_add_u64 v[24:25], v[0:1], 0, s[6:7]
	s_mov_b32 s6, 0xb000000
	s_mov_b32 s6, 0xb02c000
	s_mov_b32 s6, 0xb058000
	s_mov_b64 s[6:7], 0xb000000
	s_mov_b32 s6, 0xb084000
	s_mov_b32 s6, 0x2c000
	s_mov_b32 s6, 0x160000
	s_mov_b32 s6, 0x18c000
	s_ashr_i32 s7, s1, 7
	s_and_b32 s6, s5, 1
	v_lshrrev_b32_e32 v130, 2, v214
	v_and_b32_e32 v131, 15, v214
	v_sub_u32_e32 v130, v130, v131
	v_mul_i32_i24_e32 v130, 0x2c00, v130
	v_bfe_u32 v133, v214, 5, 1
	v_lshlrev_b32_e32 v133, 1, v133
	v_and_b32_e32 v132, 3, v214
	v_xor_b32_e32 v133, v133, v132
	v_lshrrev_b32_e32 v132, 4, v214
	v_sub_u32_e32 v133, v133, v132
	v_lshl_add_u32 v130, v133, 4, v130
	v_ashrrev_i32_e32 v133, 31, v130
	v_add_co_u32_e32 v124, vcc, v28, v130
	s_nop 1
	v_addc_co_u32_e32 v125, vcc, v29, v133, vcc
	v_add_co_u32_e32 v126, vcc, v24, v130
	s_nop 1
	v_addc_co_u32_e32 v127, vcc, v25, v133, vcc
	v_add_co_u32_e32 v26, vcc, 0xb000000, v124
	s_nop 1
	v_addc_co_u32_e32 v27, vcc, 0, v125, vcc
	v_add_co_u32_e32 v30, vcc, 0xb02c000, v124
	s_nop 1
	v_addc_co_u32_e32 v31, vcc, 0, v125, vcc
	v_add_co_u32_e32 v70, vcc, 0xb058000, v124
	s_nop 1
	v_addc_co_u32_e32 v71, vcc, 0, v125, vcc
	v_add_co_u32_e32 v98, vcc, 0xb084000, v124
	s_nop 1
	v_addc_co_u32_e32 v99, vcc, 0, v125, vcc
	v_mov_b32_e32 v116, v126
	v_mov_b32_e32 v117, v127
	v_add_co_u32_e32 v118, vcc, 0x2c000, v126
	s_nop 1
	v_addc_co_u32_e32 v119, vcc, 0, v127, vcc
	v_add_co_u32_e32 v120, vcc, 0x160000, v126
	s_nop 1
	v_addc_co_u32_e32 v121, vcc, 0, v127, vcc
	v_add_co_u32_e32 v122, vcc, 0x18c000, v126
	s_nop 1
	v_addc_co_u32_e32 v123, vcc, 0, v127, vcc
	v_readfirstlane_b32 vcc_lo, v210
	v_bfe_u32 v133, v214, 3, 1
	v_lshlrev_b32_e32 v133, 1, v133
	v_xor_b32_e32 v133, v133, v132
	v_lshlrev_b32_e32 v133, 4, v133
	v_lshl_add_u32 v133, v131, 6, v133
	s_lshr_b32 vcc_lo, vcc_lo, 6
	s_lshl_b32 vcc_lo, vcc_lo, 14
	s_mov_b32 s94, 64
	v_add_u32_e32 v132, vcc_lo, v133
	s_add_i32 m0, vcc_lo, 0x0
	s_nop 0
	global_load_lds_dwordx4 v[26:27], off
	v_lshl_add_u64 v[26:27], v[26:27], 0, s[94:95]
	s_add_i32 m0, vcc_lo, 0x400
	s_nop 0
	global_load_lds_dwordx4 v[30:31], off
	v_lshl_add_u64 v[30:31], v[30:31], 0, s[94:95]
	s_add_i32 m0, vcc_lo, 0x800
	s_nop 0
	global_load_lds_dwordx4 v[70:71], off
	v_lshl_add_u64 v[70:71], v[70:71], 0, s[94:95]
	s_add_i32 m0, vcc_lo, 0xc00
	s_nop 0
	global_load_lds_dwordx4 v[98:99], off
	v_lshl_add_u64 v[98:99], v[98:99], 0, s[94:95]
	s_add_i32 m0, vcc_lo, 0x1000
	s_nop 0
	global_load_lds_dwordx4 v[116:117], off
	v_lshl_add_u64 v[116:117], v[116:117], 0, s[94:95]
	s_add_i32 m0, vcc_lo, 0x1400
	s_nop 0
	global_load_lds_dwordx4 v[118:119], off
	v_lshl_add_u64 v[118:119], v[118:119], 0, s[94:95]
	s_add_i32 m0, vcc_lo, 0x1800
	s_nop 0
	global_load_lds_dwordx4 v[120:121], off
	v_lshl_add_u64 v[120:121], v[120:121], 0, s[94:95]
	s_add_i32 m0, vcc_lo, 0x1c00
	s_nop 0
	global_load_lds_dwordx4 v[122:123], off
	v_lshl_add_u64 v[122:123], v[122:123], 0, s[94:95]
	s_add_i32 m0, vcc_lo, 0x2000
	s_nop 0
	global_load_lds_dwordx4 v[26:27], off
	v_lshl_add_u64 v[26:27], v[26:27], 0, s[94:95]
	s_add_i32 m0, vcc_lo, 0x2400
	s_nop 0
	global_load_lds_dwordx4 v[30:31], off
	v_lshl_add_u64 v[30:31], v[30:31], 0, s[94:95]
	s_add_i32 m0, vcc_lo, 0x2800
	s_nop 0
	global_load_lds_dwordx4 v[70:71], off
	v_lshl_add_u64 v[70:71], v[70:71], 0, s[94:95]
	s_add_i32 m0, vcc_lo, 0x2c00
	s_nop 0
	global_load_lds_dwordx4 v[98:99], off
	v_lshl_add_u64 v[98:99], v[98:99], 0, s[94:95]
	s_add_i32 m0, vcc_lo, 0x3000
	s_nop 0
	global_load_lds_dwordx4 v[116:117], off
	v_lshl_add_u64 v[116:117], v[116:117], 0, s[94:95]
	s_add_i32 m0, vcc_lo, 0x3400
	s_nop 0
	global_load_lds_dwordx4 v[118:119], off
	v_lshl_add_u64 v[118:119], v[118:119], 0, s[94:95]
	s_add_i32 m0, vcc_lo, 0x3800
	s_nop 0
	global_load_lds_dwordx4 v[120:121], off
	v_lshl_add_u64 v[120:121], v[120:121], 0, s[94:95]
	s_add_i32 m0, vcc_lo, 0x3c00
	s_nop 0
	global_load_lds_dwordx4 v[122:123], off
	v_lshl_add_u64 v[122:123], v[122:123], 0, s[94:95]
	s_waitcnt vmcnt(8)
	ds_read_b128 v[80:83], v132
	ds_read_b128 v[84:87], v132 offset:1024
	ds_read_b128 v[88:91], v132 offset:2048
	ds_read_b128 v[92:95], v132 offset:3072
	ds_read_b128 v[100:103], v132 offset:4096
	ds_read_b128 v[104:107], v132 offset:5120
	ds_read_b128 v[108:111], v132 offset:6144
	ds_read_b128 v[112:115], v132 offset:7168
	s_waitcnt lgkmcnt(0)
	s_add_i32 m0, vcc_lo, 0x0
	s_nop 0
	global_load_lds_dwordx4 v[26:27], off
	v_lshl_add_u64 v[26:27], v[26:27], 0, s[94:95]
	s_add_i32 m0, vcc_lo, 0x400
	s_nop 0
	global_load_lds_dwordx4 v[30:31], off
	v_lshl_add_u64 v[30:31], v[30:31], 0, s[94:95]
	s_add_i32 m0, vcc_lo, 0x800
	s_nop 0
	global_load_lds_dwordx4 v[70:71], off
	v_lshl_add_u64 v[70:71], v[70:71], 0, s[94:95]
	s_add_i32 m0, vcc_lo, 0xc00
	s_nop 0
	global_load_lds_dwordx4 v[98:99], off
	v_lshl_add_u64 v[98:99], v[98:99], 0, s[94:95]
	s_add_i32 m0, vcc_lo, 0x1000
	s_nop 0
	global_load_lds_dwordx4 v[116:117], off
	v_lshl_add_u64 v[116:117], v[116:117], 0, s[94:95]
	s_add_i32 m0, vcc_lo, 0x1400
	s_nop 0
	global_load_lds_dwordx4 v[118:119], off
	v_lshl_add_u64 v[118:119], v[118:119], 0, s[94:95]
	s_add_i32 m0, vcc_lo, 0x1800
	s_nop 0
	global_load_lds_dwordx4 v[120:121], off
	v_lshl_add_u64 v[120:121], v[120:121], 0, s[94:95]
	s_add_i32 m0, vcc_lo, 0x1c00
	s_nop 0
	global_load_lds_dwordx4 v[122:123], off
	v_lshl_add_u64 v[122:123], v[122:123], 0, s[94:95]
	v_mfma_f32_16x16x32_bf16 v[4:7], v[100:103], v[80:83], 0
	v_mfma_f32_16x16x32_bf16 v[8:11], v[100:103], v[84:87], 0
	v_mfma_f32_16x16x32_bf16 v[12:15], v[100:103], v[88:91], 0
	v_mfma_f32_16x16x32_bf16 v[16:19], v[100:103], v[92:95], 0
	v_mfma_f32_16x16x32_bf16 v[20:23], v[104:107], v[80:83], 0
	v_mfma_f32_16x16x32_bf16 v[32:35], v[104:107], v[84:87], 0
	v_mfma_f32_16x16x32_bf16 v[36:39], v[104:107], v[88:91], 0
	v_mfma_f32_16x16x32_bf16 v[40:43], v[104:107], v[92:95], 0
	v_mfma_f32_16x16x32_bf16 v[44:47], v[108:111], v[80:83], 0
	v_mfma_f32_16x16x32_bf16 v[48:51], v[108:111], v[84:87], 0
	v_mfma_f32_16x16x32_bf16 v[52:55], v[108:111], v[88:91], 0
	v_mfma_f32_16x16x32_bf16 v[56:59], v[108:111], v[92:95], 0
	v_mfma_f32_16x16x32_bf16 v[60:63], v[112:115], v[80:83], 0
	v_mfma_f32_16x16x32_bf16 v[64:67], v[112:115], v[84:87], 0
	v_mfma_f32_16x16x32_bf16 v[72:75], v[112:115], v[88:91], 0
	v_mfma_f32_16x16x32_bf16 v[76:79], v[112:115], v[92:95], 0
	s_waitcnt vmcnt(8)
	ds_read_b128 v[80:83], v132 offset:8192
	ds_read_b128 v[84:87], v132 offset:9216
	ds_read_b128 v[88:91], v132 offset:10240
	ds_read_b128 v[92:95], v132 offset:11264
	ds_read_b128 v[100:103], v132 offset:12288
	ds_read_b128 v[104:107], v132 offset:13312
	ds_read_b128 v[108:111], v132 offset:14336
	ds_read_b128 v[112:115], v132 offset:15360
	s_waitcnt lgkmcnt(0)
	s_add_i32 m0, vcc_lo, 0x2000
	s_nop 0
	global_load_lds_dwordx4 v[26:27], off
	v_lshl_add_u64 v[26:27], v[26:27], 0, s[94:95]
	s_add_i32 m0, vcc_lo, 0x2400
	s_nop 0
	global_load_lds_dwordx4 v[30:31], off
	v_lshl_add_u64 v[30:31], v[30:31], 0, s[94:95]
	s_add_i32 m0, vcc_lo, 0x2800
	s_nop 0
	global_load_lds_dwordx4 v[70:71], off
	v_lshl_add_u64 v[70:71], v[70:71], 0, s[94:95]
	s_add_i32 m0, vcc_lo, 0x2c00
	s_nop 0
	global_load_lds_dwordx4 v[98:99], off
	v_lshl_add_u64 v[98:99], v[98:99], 0, s[94:95]
	s_add_i32 m0, vcc_lo, 0x3000
	s_nop 0
	global_load_lds_dwordx4 v[116:117], off
	v_lshl_add_u64 v[116:117], v[116:117], 0, s[94:95]
	s_add_i32 m0, vcc_lo, 0x3400
	s_nop 0
	global_load_lds_dwordx4 v[118:119], off
	v_lshl_add_u64 v[118:119], v[118:119], 0, s[94:95]
	s_add_i32 m0, vcc_lo, 0x3800
	s_nop 0
	global_load_lds_dwordx4 v[120:121], off
	v_lshl_add_u64 v[120:121], v[120:121], 0, s[94:95]
	s_add_i32 m0, vcc_lo, 0x3c00
	s_nop 0
	global_load_lds_dwordx4 v[122:123], off
	v_lshl_add_u64 v[122:123], v[122:123], 0, s[94:95]
	v_mfma_f32_16x16x32_bf16 v[4:7], v[100:103], v[80:83], v[4:7]
	v_mfma_f32_16x16x32_bf16 v[8:11], v[100:103], v[84:87], v[8:11]
	v_mfma_f32_16x16x32_bf16 v[12:15], v[100:103], v[88:91], v[12:15]
	v_mfma_f32_16x16x32_bf16 v[16:19], v[100:103], v[92:95], v[16:19]
	v_mfma_f32_16x16x32_bf16 v[20:23], v[104:107], v[80:83], v[20:23]
	v_mfma_f32_16x16x32_bf16 v[32:35], v[104:107], v[84:87], v[32:35]
	v_mfma_f32_16x16x32_bf16 v[36:39], v[104:107], v[88:91], v[36:39]
	v_mfma_f32_16x16x32_bf16 v[40:43], v[104:107], v[92:95], v[40:43]
	v_mfma_f32_16x16x32_bf16 v[44:47], v[108:111], v[80:83], v[44:47]
	v_mfma_f32_16x16x32_bf16 v[48:51], v[108:111], v[84:87], v[48:51]
	v_mfma_f32_16x16x32_bf16 v[52:55], v[108:111], v[88:91], v[52:55]
	v_mfma_f32_16x16x32_bf16 v[56:59], v[108:111], v[92:95], v[56:59]
	v_mfma_f32_16x16x32_bf16 v[60:63], v[112:115], v[80:83], v[60:63]
	v_mfma_f32_16x16x32_bf16 v[64:67], v[112:115], v[84:87], v[64:67]
	v_mfma_f32_16x16x32_bf16 v[72:75], v[112:115], v[88:91], v[72:75]
	v_mfma_f32_16x16x32_bf16 v[76:79], v[112:115], v[92:95], v[76:79]
	s_waitcnt vmcnt(8)
	ds_read_b128 v[80:83], v132
	ds_read_b128 v[84:87], v132 offset:1024
	ds_read_b128 v[88:91], v132 offset:2048
	ds_read_b128 v[92:95], v132 offset:3072
	ds_read_b128 v[100:103], v132 offset:4096
	ds_read_b128 v[104:107], v132 offset:5120
	ds_read_b128 v[108:111], v132 offset:6144
	ds_read_b128 v[112:115], v132 offset:7168
	s_waitcnt lgkmcnt(0)
	s_add_i32 m0, vcc_lo, 0x0
	s_nop 0
	global_load_lds_dwordx4 v[26:27], off
	v_lshl_add_u64 v[26:27], v[26:27], 0, s[94:95]
	s_add_i32 m0, vcc_lo, 0x400
	s_nop 0
	global_load_lds_dwordx4 v[30:31], off
	v_lshl_add_u64 v[30:31], v[30:31], 0, s[94:95]
	s_add_i32 m0, vcc_lo, 0x800
	s_nop 0
	global_load_lds_dwordx4 v[70:71], off
	v_lshl_add_u64 v[70:71], v[70:71], 0, s[94:95]
	s_add_i32 m0, vcc_lo, 0xc00
	s_nop 0
	global_load_lds_dwordx4 v[98:99], off
	v_lshl_add_u64 v[98:99], v[98:99], 0, s[94:95]
	s_add_i32 m0, vcc_lo, 0x1000
	s_nop 0
	global_load_lds_dwordx4 v[116:117], off
	v_lshl_add_u64 v[116:117], v[116:117], 0, s[94:95]
	s_add_i32 m0, vcc_lo, 0x1400
	s_nop 0
	global_load_lds_dwordx4 v[118:119], off
	v_lshl_add_u64 v[118:119], v[118:119], 0, s[94:95]
	s_add_i32 m0, vcc_lo, 0x1800
	s_nop 0
	global_load_lds_dwordx4 v[120:121], off
	v_lshl_add_u64 v[120:121], v[120:121], 0, s[94:95]
	s_add_i32 m0, vcc_lo, 0x1c00
	s_nop 0
	global_load_lds_dwordx4 v[122:123], off
	v_lshl_add_u64 v[122:123], v[122:123], 0, s[94:95]
	v_mfma_f32_16x16x32_bf16 v[4:7], v[100:103], v[80:83], v[4:7]
	v_mfma_f32_16x16x32_bf16 v[8:11], v[100:103], v[84:87], v[8:11]
	v_mfma_f32_16x16x32_bf16 v[12:15], v[100:103], v[88:91], v[12:15]
	v_mfma_f32_16x16x32_bf16 v[16:19], v[100:103], v[92:95], v[16:19]
	v_mfma_f32_16x16x32_bf16 v[20:23], v[104:107], v[80:83], v[20:23]
	v_mfma_f32_16x16x32_bf16 v[32:35], v[104:107], v[84:87], v[32:35]
	v_mfma_f32_16x16x32_bf16 v[36:39], v[104:107], v[88:91], v[36:39]
	v_mfma_f32_16x16x32_bf16 v[40:43], v[104:107], v[92:95], v[40:43]
	v_mfma_f32_16x16x32_bf16 v[44:47], v[108:111], v[80:83], v[44:47]
	v_mfma_f32_16x16x32_bf16 v[48:51], v[108:111], v[84:87], v[48:51]
	v_mfma_f32_16x16x32_bf16 v[52:55], v[108:111], v[88:91], v[52:55]
	v_mfma_f32_16x16x32_bf16 v[56:59], v[108:111], v[92:95], v[56:59]
	v_mfma_f32_16x16x32_bf16 v[60:63], v[112:115], v[80:83], v[60:63]
	v_mfma_f32_16x16x32_bf16 v[64:67], v[112:115], v[84:87], v[64:67]
	v_mfma_f32_16x16x32_bf16 v[72:75], v[112:115], v[88:91], v[72:75]
	v_mfma_f32_16x16x32_bf16 v[76:79], v[112:115], v[92:95], v[76:79]
	s_waitcnt vmcnt(8)
	ds_read_b128 v[80:83], v132 offset:8192
	ds_read_b128 v[84:87], v132 offset:9216
	ds_read_b128 v[88:91], v132 offset:10240
	ds_read_b128 v[92:95], v132 offset:11264
	ds_read_b128 v[100:103], v132 offset:12288
	ds_read_b128 v[104:107], v132 offset:13312
	ds_read_b128 v[108:111], v132 offset:14336
	ds_read_b128 v[112:115], v132 offset:15360
	s_waitcnt lgkmcnt(0)
	s_add_i32 m0, vcc_lo, 0x2000
	s_nop 0
	global_load_lds_dwordx4 v[26:27], off
	v_lshl_add_u64 v[26:27], v[26:27], 0, s[94:95]
	s_add_i32 m0, vcc_lo, 0x2400
	s_nop 0
	global_load_lds_dwordx4 v[30:31], off
	v_lshl_add_u64 v[30:31], v[30:31], 0, s[94:95]
	s_add_i32 m0, vcc_lo, 0x2800
	s_nop 0
	global_load_lds_dwordx4 v[70:71], off
	v_lshl_add_u64 v[70:71], v[70:71], 0, s[94:95]
	s_add_i32 m0, vcc_lo, 0x2c00
	s_nop 0
	global_load_lds_dwordx4 v[98:99], off
	v_lshl_add_u64 v[98:99], v[98:99], 0, s[94:95]
	s_add_i32 m0, vcc_lo, 0x3000
	s_nop 0
	global_load_lds_dwordx4 v[116:117], off
	v_lshl_add_u64 v[116:117], v[116:117], 0, s[94:95]
	s_add_i32 m0, vcc_lo, 0x3400
	s_nop 0
	global_load_lds_dwordx4 v[118:119], off
	v_lshl_add_u64 v[118:119], v[118:119], 0, s[94:95]
	s_add_i32 m0, vcc_lo, 0x3800
	s_nop 0
	global_load_lds_dwordx4 v[120:121], off
	v_lshl_add_u64 v[120:121], v[120:121], 0, s[94:95]
	s_add_i32 m0, vcc_lo, 0x3c00
	s_nop 0
	global_load_lds_dwordx4 v[122:123], off
	v_lshl_add_u64 v[122:123], v[122:123], 0, s[94:95]
	v_mfma_f32_16x16x32_bf16 v[4:7], v[100:103], v[80:83], v[4:7]
	v_mfma_f32_16x16x32_bf16 v[8:11], v[100:103], v[84:87], v[8:11]
	v_mfma_f32_16x16x32_bf16 v[12:15], v[100:103], v[88:91], v[12:15]
	v_mfma_f32_16x16x32_bf16 v[16:19], v[100:103], v[92:95], v[16:19]
	v_mfma_f32_16x16x32_bf16 v[20:23], v[104:107], v[80:83], v[20:23]
	v_mfma_f32_16x16x32_bf16 v[32:35], v[104:107], v[84:87], v[32:35]
	v_mfma_f32_16x16x32_bf16 v[36:39], v[104:107], v[88:91], v[36:39]
	v_mfma_f32_16x16x32_bf16 v[40:43], v[104:107], v[92:95], v[40:43]
	v_mfma_f32_16x16x32_bf16 v[44:47], v[108:111], v[80:83], v[44:47]
	v_mfma_f32_16x16x32_bf16 v[48:51], v[108:111], v[84:87], v[48:51]
	v_mfma_f32_16x16x32_bf16 v[52:55], v[108:111], v[88:91], v[52:55]
	v_mfma_f32_16x16x32_bf16 v[56:59], v[108:111], v[92:95], v[56:59]
	v_mfma_f32_16x16x32_bf16 v[60:63], v[112:115], v[80:83], v[60:63]
	v_mfma_f32_16x16x32_bf16 v[64:67], v[112:115], v[84:87], v[64:67]
	v_mfma_f32_16x16x32_bf16 v[72:75], v[112:115], v[88:91], v[72:75]
	v_mfma_f32_16x16x32_bf16 v[76:79], v[112:115], v[92:95], v[76:79]
	s_waitcnt vmcnt(8)
	ds_read_b128 v[80:83], v132
	ds_read_b128 v[84:87], v132 offset:1024
	ds_read_b128 v[88:91], v132 offset:2048
	ds_read_b128 v[92:95], v132 offset:3072
	ds_read_b128 v[100:103], v132 offset:4096
	ds_read_b128 v[104:107], v132 offset:5120
	ds_read_b128 v[108:111], v132 offset:6144
	ds_read_b128 v[112:115], v132 offset:7168
	s_waitcnt lgkmcnt(0)
	s_add_i32 m0, vcc_lo, 0x0
	s_nop 0
	global_load_lds_dwordx4 v[26:27], off
	v_lshl_add_u64 v[26:27], v[26:27], 0, s[94:95]
	s_add_i32 m0, vcc_lo, 0x400
	s_nop 0
	global_load_lds_dwordx4 v[30:31], off
	v_lshl_add_u64 v[30:31], v[30:31], 0, s[94:95]
	s_add_i32 m0, vcc_lo, 0x800
	s_nop 0
	global_load_lds_dwordx4 v[70:71], off
	v_lshl_add_u64 v[70:71], v[70:71], 0, s[94:95]
	s_add_i32 m0, vcc_lo, 0xc00
	s_nop 0
	global_load_lds_dwordx4 v[98:99], off
	v_lshl_add_u64 v[98:99], v[98:99], 0, s[94:95]
	s_add_i32 m0, vcc_lo, 0x1000
	s_nop 0
	global_load_lds_dwordx4 v[116:117], off
	v_lshl_add_u64 v[116:117], v[116:117], 0, s[94:95]
	s_add_i32 m0, vcc_lo, 0x1400
	s_nop 0
	global_load_lds_dwordx4 v[118:119], off
	v_lshl_add_u64 v[118:119], v[118:119], 0, s[94:95]
	s_add_i32 m0, vcc_lo, 0x1800
	s_nop 0
	global_load_lds_dwordx4 v[120:121], off
	v_lshl_add_u64 v[120:121], v[120:121], 0, s[94:95]
	s_add_i32 m0, vcc_lo, 0x1c00
	s_nop 0
	global_load_lds_dwordx4 v[122:123], off
	v_lshl_add_u64 v[122:123], v[122:123], 0, s[94:95]
	v_mfma_f32_16x16x32_bf16 v[4:7], v[100:103], v[80:83], v[4:7]
	v_mfma_f32_16x16x32_bf16 v[8:11], v[100:103], v[84:87], v[8:11]
	v_mfma_f32_16x16x32_bf16 v[12:15], v[100:103], v[88:91], v[12:15]
	v_mfma_f32_16x16x32_bf16 v[16:19], v[100:103], v[92:95], v[16:19]
	v_mfma_f32_16x16x32_bf16 v[20:23], v[104:107], v[80:83], v[20:23]
	v_mfma_f32_16x16x32_bf16 v[32:35], v[104:107], v[84:87], v[32:35]
	v_mfma_f32_16x16x32_bf16 v[36:39], v[104:107], v[88:91], v[36:39]
	v_mfma_f32_16x16x32_bf16 v[40:43], v[104:107], v[92:95], v[40:43]
	v_mfma_f32_16x16x32_bf16 v[44:47], v[108:111], v[80:83], v[44:47]
	v_mfma_f32_16x16x32_bf16 v[48:51], v[108:111], v[84:87], v[48:51]
	v_mfma_f32_16x16x32_bf16 v[52:55], v[108:111], v[88:91], v[52:55]
	v_mfma_f32_16x16x32_bf16 v[56:59], v[108:111], v[92:95], v[56:59]
	v_mfma_f32_16x16x32_bf16 v[60:63], v[112:115], v[80:83], v[60:63]
	v_mfma_f32_16x16x32_bf16 v[64:67], v[112:115], v[84:87], v[64:67]
	v_mfma_f32_16x16x32_bf16 v[72:75], v[112:115], v[88:91], v[72:75]
	v_mfma_f32_16x16x32_bf16 v[76:79], v[112:115], v[92:95], v[76:79]
	s_waitcnt vmcnt(8)
	ds_read_b128 v[80:83], v132 offset:8192
	ds_read_b128 v[84:87], v132 offset:9216
	ds_read_b128 v[88:91], v132 offset:10240
	ds_read_b128 v[92:95], v132 offset:11264
	ds_read_b128 v[100:103], v132 offset:12288
	ds_read_b128 v[104:107], v132 offset:13312
	ds_read_b128 v[108:111], v132 offset:14336
	ds_read_b128 v[112:115], v132 offset:15360
	s_waitcnt lgkmcnt(0)
	s_add_i32 m0, vcc_lo, 0x2000
	s_nop 0
	global_load_lds_dwordx4 v[26:27], off
	v_lshl_add_u64 v[26:27], v[26:27], 0, s[94:95]
	s_add_i32 m0, vcc_lo, 0x2400
	s_nop 0
	global_load_lds_dwordx4 v[30:31], off
	v_lshl_add_u64 v[30:31], v[30:31], 0, s[94:95]
	s_add_i32 m0, vcc_lo, 0x2800
	s_nop 0
	global_load_lds_dwordx4 v[70:71], off
	v_lshl_add_u64 v[70:71], v[70:71], 0, s[94:95]
	s_add_i32 m0, vcc_lo, 0x2c00
	s_nop 0
	global_load_lds_dwordx4 v[98:99], off
	v_lshl_add_u64 v[98:99], v[98:99], 0, s[94:95]
	s_add_i32 m0, vcc_lo, 0x3000
	s_nop 0
	global_load_lds_dwordx4 v[116:117], off
	v_lshl_add_u64 v[116:117], v[116:117], 0, s[94:95]
	s_add_i32 m0, vcc_lo, 0x3400
	s_nop 0
	global_load_lds_dwordx4 v[118:119], off
	v_lshl_add_u64 v[118:119], v[118:119], 0, s[94:95]
	s_add_i32 m0, vcc_lo, 0x3800
	s_nop 0
	global_load_lds_dwordx4 v[120:121], off
	v_lshl_add_u64 v[120:121], v[120:121], 0, s[94:95]
	s_add_i32 m0, vcc_lo, 0x3c00
	s_nop 0
	global_load_lds_dwordx4 v[122:123], off
	v_lshl_add_u64 v[122:123], v[122:123], 0, s[94:95]
	v_mfma_f32_16x16x32_bf16 v[4:7], v[100:103], v[80:83], v[4:7]
	v_mfma_f32_16x16x32_bf16 v[8:11], v[100:103], v[84:87], v[8:11]
	v_mfma_f32_16x16x32_bf16 v[12:15], v[100:103], v[88:91], v[12:15]
	v_mfma_f32_16x16x32_bf16 v[16:19], v[100:103], v[92:95], v[16:19]
	v_mfma_f32_16x16x32_bf16 v[20:23], v[104:107], v[80:83], v[20:23]
	v_mfma_f32_16x16x32_bf16 v[32:35], v[104:107], v[84:87], v[32:35]
	v_mfma_f32_16x16x32_bf16 v[36:39], v[104:107], v[88:91], v[36:39]
	v_mfma_f32_16x16x32_bf16 v[40:43], v[104:107], v[92:95], v[40:43]
	v_mfma_f32_16x16x32_bf16 v[44:47], v[108:111], v[80:83], v[44:47]
	v_mfma_f32_16x16x32_bf16 v[48:51], v[108:111], v[84:87], v[48:51]
	v_mfma_f32_16x16x32_bf16 v[52:55], v[108:111], v[88:91], v[52:55]
	v_mfma_f32_16x16x32_bf16 v[56:59], v[108:111], v[92:95], v[56:59]
	v_mfma_f32_16x16x32_bf16 v[60:63], v[112:115], v[80:83], v[60:63]
	v_mfma_f32_16x16x32_bf16 v[64:67], v[112:115], v[84:87], v[64:67]
	v_mfma_f32_16x16x32_bf16 v[72:75], v[112:115], v[88:91], v[72:75]
	v_mfma_f32_16x16x32_bf16 v[76:79], v[112:115], v[92:95], v[76:79]
	s_waitcnt vmcnt(8)
	ds_read_b128 v[80:83], v132
	ds_read_b128 v[84:87], v132 offset:1024
	ds_read_b128 v[88:91], v132 offset:2048
	ds_read_b128 v[92:95], v132 offset:3072
	ds_read_b128 v[100:103], v132 offset:4096
	ds_read_b128 v[104:107], v132 offset:5120
	ds_read_b128 v[108:111], v132 offset:6144
	ds_read_b128 v[112:115], v132 offset:7168
	s_waitcnt lgkmcnt(0)
	s_add_i32 m0, vcc_lo, 0x0
	s_nop 0
	global_load_lds_dwordx4 v[26:27], off
	v_lshl_add_u64 v[26:27], v[26:27], 0, s[94:95]
	s_add_i32 m0, vcc_lo, 0x400
	s_nop 0
	global_load_lds_dwordx4 v[30:31], off
	v_lshl_add_u64 v[30:31], v[30:31], 0, s[94:95]
	s_add_i32 m0, vcc_lo, 0x800
	s_nop 0
	global_load_lds_dwordx4 v[70:71], off
	v_lshl_add_u64 v[70:71], v[70:71], 0, s[94:95]
	s_add_i32 m0, vcc_lo, 0xc00
	s_nop 0
	global_load_lds_dwordx4 v[98:99], off
	v_lshl_add_u64 v[98:99], v[98:99], 0, s[94:95]
	s_add_i32 m0, vcc_lo, 0x1000
	s_nop 0
	global_load_lds_dwordx4 v[116:117], off
	v_lshl_add_u64 v[116:117], v[116:117], 0, s[94:95]
	s_add_i32 m0, vcc_lo, 0x1400
	s_nop 0
	global_load_lds_dwordx4 v[118:119], off
	v_lshl_add_u64 v[118:119], v[118:119], 0, s[94:95]
	s_add_i32 m0, vcc_lo, 0x1800
	s_nop 0
	global_load_lds_dwordx4 v[120:121], off
	v_lshl_add_u64 v[120:121], v[120:121], 0, s[94:95]
	s_add_i32 m0, vcc_lo, 0x1c00
	s_nop 0
	global_load_lds_dwordx4 v[122:123], off
	v_lshl_add_u64 v[122:123], v[122:123], 0, s[94:95]
	v_mfma_f32_16x16x32_bf16 v[4:7], v[100:103], v[80:83], v[4:7]
	v_mfma_f32_16x16x32_bf16 v[8:11], v[100:103], v[84:87], v[8:11]
	v_mfma_f32_16x16x32_bf16 v[12:15], v[100:103], v[88:91], v[12:15]
	v_mfma_f32_16x16x32_bf16 v[16:19], v[100:103], v[92:95], v[16:19]
	v_mfma_f32_16x16x32_bf16 v[20:23], v[104:107], v[80:83], v[20:23]
	v_mfma_f32_16x16x32_bf16 v[32:35], v[104:107], v[84:87], v[32:35]
	v_mfma_f32_16x16x32_bf16 v[36:39], v[104:107], v[88:91], v[36:39]
	v_mfma_f32_16x16x32_bf16 v[40:43], v[104:107], v[92:95], v[40:43]
	v_mfma_f32_16x16x32_bf16 v[44:47], v[108:111], v[80:83], v[44:47]
	v_mfma_f32_16x16x32_bf16 v[48:51], v[108:111], v[84:87], v[48:51]
	v_mfma_f32_16x16x32_bf16 v[52:55], v[108:111], v[88:91], v[52:55]
	v_mfma_f32_16x16x32_bf16 v[56:59], v[108:111], v[92:95], v[56:59]
	v_mfma_f32_16x16x32_bf16 v[60:63], v[112:115], v[80:83], v[60:63]
	v_mfma_f32_16x16x32_bf16 v[64:67], v[112:115], v[84:87], v[64:67]
	v_mfma_f32_16x16x32_bf16 v[72:75], v[112:115], v[88:91], v[72:75]
	v_mfma_f32_16x16x32_bf16 v[76:79], v[112:115], v[92:95], v[76:79]
	s_waitcnt vmcnt(8)
	ds_read_b128 v[80:83], v132 offset:8192
	ds_read_b128 v[84:87], v132 offset:9216
	ds_read_b128 v[88:91], v132 offset:10240
	ds_read_b128 v[92:95], v132 offset:11264
	ds_read_b128 v[100:103], v132 offset:12288
	ds_read_b128 v[104:107], v132 offset:13312
	ds_read_b128 v[108:111], v132 offset:14336
	ds_read_b128 v[112:115], v132 offset:15360
	s_waitcnt lgkmcnt(0)
	s_add_i32 m0, vcc_lo, 0x2000
	s_nop 0
	global_load_lds_dwordx4 v[26:27], off
	v_lshl_add_u64 v[26:27], v[26:27], 0, s[94:95]
	s_add_i32 m0, vcc_lo, 0x2400
	s_nop 0
	global_load_lds_dwordx4 v[30:31], off
	v_lshl_add_u64 v[30:31], v[30:31], 0, s[94:95]
	s_add_i32 m0, vcc_lo, 0x2800
	s_nop 0
	global_load_lds_dwordx4 v[70:71], off
	v_lshl_add_u64 v[70:71], v[70:71], 0, s[94:95]
	s_add_i32 m0, vcc_lo, 0x2c00
	s_nop 0
	global_load_lds_dwordx4 v[98:99], off
	v_lshl_add_u64 v[98:99], v[98:99], 0, s[94:95]
	s_add_i32 m0, vcc_lo, 0x3000
	s_nop 0
	global_load_lds_dwordx4 v[116:117], off
	v_lshl_add_u64 v[116:117], v[116:117], 0, s[94:95]
	s_add_i32 m0, vcc_lo, 0x3400
	s_nop 0
	global_load_lds_dwordx4 v[118:119], off
	v_lshl_add_u64 v[118:119], v[118:119], 0, s[94:95]
	s_add_i32 m0, vcc_lo, 0x3800
	s_nop 0
	global_load_lds_dwordx4 v[120:121], off
	v_lshl_add_u64 v[120:121], v[120:121], 0, s[94:95]
	s_add_i32 m0, vcc_lo, 0x3c00
	s_nop 0
	global_load_lds_dwordx4 v[122:123], off
	v_lshl_add_u64 v[122:123], v[122:123], 0, s[94:95]
	v_mfma_f32_16x16x32_bf16 v[4:7], v[100:103], v[80:83], v[4:7]
	v_mfma_f32_16x16x32_bf16 v[8:11], v[100:103], v[84:87], v[8:11]
	v_mfma_f32_16x16x32_bf16 v[12:15], v[100:103], v[88:91], v[12:15]
	v_mfma_f32_16x16x32_bf16 v[16:19], v[100:103], v[92:95], v[16:19]
	v_mfma_f32_16x16x32_bf16 v[20:23], v[104:107], v[80:83], v[20:23]
	v_mfma_f32_16x16x32_bf16 v[32:35], v[104:107], v[84:87], v[32:35]
	v_mfma_f32_16x16x32_bf16 v[36:39], v[104:107], v[88:91], v[36:39]
	v_mfma_f32_16x16x32_bf16 v[40:43], v[104:107], v[92:95], v[40:43]
	v_mfma_f32_16x16x32_bf16 v[44:47], v[108:111], v[80:83], v[44:47]
	v_mfma_f32_16x16x32_bf16 v[48:51], v[108:111], v[84:87], v[48:51]
	v_mfma_f32_16x16x32_bf16 v[52:55], v[108:111], v[88:91], v[52:55]
	v_mfma_f32_16x16x32_bf16 v[56:59], v[108:111], v[92:95], v[56:59]
	v_mfma_f32_16x16x32_bf16 v[60:63], v[112:115], v[80:83], v[60:63]
	v_mfma_f32_16x16x32_bf16 v[64:67], v[112:115], v[84:87], v[64:67]
	v_mfma_f32_16x16x32_bf16 v[72:75], v[112:115], v[88:91], v[72:75]
	v_mfma_f32_16x16x32_bf16 v[76:79], v[112:115], v[92:95], v[76:79]
	s_waitcnt vmcnt(8)
	ds_read_b128 v[80:83], v132
	ds_read_b128 v[84:87], v132 offset:1024
	ds_read_b128 v[88:91], v132 offset:2048
	ds_read_b128 v[92:95], v132 offset:3072
	ds_read_b128 v[100:103], v132 offset:4096
	ds_read_b128 v[104:107], v132 offset:5120
	ds_read_b128 v[108:111], v132 offset:6144
	ds_read_b128 v[112:115], v132 offset:7168
	s_waitcnt lgkmcnt(0)
	s_add_i32 m0, vcc_lo, 0x0
	s_nop 0
	global_load_lds_dwordx4 v[26:27], off
	v_lshl_add_u64 v[26:27], v[26:27], 0, s[94:95]
	s_add_i32 m0, vcc_lo, 0x400
	s_nop 0
	global_load_lds_dwordx4 v[30:31], off
	v_lshl_add_u64 v[30:31], v[30:31], 0, s[94:95]
	s_add_i32 m0, vcc_lo, 0x800
	s_nop 0
	global_load_lds_dwordx4 v[70:71], off
	v_lshl_add_u64 v[70:71], v[70:71], 0, s[94:95]
	s_add_i32 m0, vcc_lo, 0xc00
	s_nop 0
	global_load_lds_dwordx4 v[98:99], off
	v_lshl_add_u64 v[98:99], v[98:99], 0, s[94:95]
	s_add_i32 m0, vcc_lo, 0x1000
	s_nop 0
	global_load_lds_dwordx4 v[116:117], off
	v_lshl_add_u64 v[116:117], v[116:117], 0, s[94:95]
	s_add_i32 m0, vcc_lo, 0x1400
	s_nop 0
	global_load_lds_dwordx4 v[118:119], off
	v_lshl_add_u64 v[118:119], v[118:119], 0, s[94:95]
	s_add_i32 m0, vcc_lo, 0x1800
	s_nop 0
	global_load_lds_dwordx4 v[120:121], off
	v_lshl_add_u64 v[120:121], v[120:121], 0, s[94:95]
	s_add_i32 m0, vcc_lo, 0x1c00
	s_nop 0
	global_load_lds_dwordx4 v[122:123], off
	v_lshl_add_u64 v[122:123], v[122:123], 0, s[94:95]
	v_mfma_f32_16x16x32_bf16 v[4:7], v[100:103], v[80:83], v[4:7]
	v_mfma_f32_16x16x32_bf16 v[8:11], v[100:103], v[84:87], v[8:11]
	v_mfma_f32_16x16x32_bf16 v[12:15], v[100:103], v[88:91], v[12:15]
	v_mfma_f32_16x16x32_bf16 v[16:19], v[100:103], v[92:95], v[16:19]
	v_mfma_f32_16x16x32_bf16 v[20:23], v[104:107], v[80:83], v[20:23]
	v_mfma_f32_16x16x32_bf16 v[32:35], v[104:107], v[84:87], v[32:35]
	v_mfma_f32_16x16x32_bf16 v[36:39], v[104:107], v[88:91], v[36:39]
	v_mfma_f32_16x16x32_bf16 v[40:43], v[104:107], v[92:95], v[40:43]
	v_mfma_f32_16x16x32_bf16 v[44:47], v[108:111], v[80:83], v[44:47]
	v_mfma_f32_16x16x32_bf16 v[48:51], v[108:111], v[84:87], v[48:51]
	v_mfma_f32_16x16x32_bf16 v[52:55], v[108:111], v[88:91], v[52:55]
	v_mfma_f32_16x16x32_bf16 v[56:59], v[108:111], v[92:95], v[56:59]
	v_mfma_f32_16x16x32_bf16 v[60:63], v[112:115], v[80:83], v[60:63]
	v_mfma_f32_16x16x32_bf16 v[64:67], v[112:115], v[84:87], v[64:67]
	v_mfma_f32_16x16x32_bf16 v[72:75], v[112:115], v[88:91], v[72:75]
	v_mfma_f32_16x16x32_bf16 v[76:79], v[112:115], v[92:95], v[76:79]
	s_waitcnt vmcnt(8)
	ds_read_b128 v[80:83], v132 offset:8192
	ds_read_b128 v[84:87], v132 offset:9216
	ds_read_b128 v[88:91], v132 offset:10240
	ds_read_b128 v[92:95], v132 offset:11264
	ds_read_b128 v[100:103], v132 offset:12288
	ds_read_b128 v[104:107], v132 offset:13312
	ds_read_b128 v[108:111], v132 offset:14336
	ds_read_b128 v[112:115], v132 offset:15360
	s_waitcnt lgkmcnt(0)
	s_add_i32 m0, vcc_lo, 0x2000
	s_nop 0
	global_load_lds_dwordx4 v[26:27], off
	v_lshl_add_u64 v[26:27], v[26:27], 0, s[94:95]
	s_add_i32 m0, vcc_lo, 0x2400
	s_nop 0
	global_load_lds_dwordx4 v[30:31], off
	v_lshl_add_u64 v[30:31], v[30:31], 0, s[94:95]
	s_add_i32 m0, vcc_lo, 0x2800
	s_nop 0
	global_load_lds_dwordx4 v[70:71], off
	v_lshl_add_u64 v[70:71], v[70:71], 0, s[94:95]
	s_add_i32 m0, vcc_lo, 0x2c00
	s_nop 0
	global_load_lds_dwordx4 v[98:99], off
	v_lshl_add_u64 v[98:99], v[98:99], 0, s[94:95]
	s_add_i32 m0, vcc_lo, 0x3000
	s_nop 0
	global_load_lds_dwordx4 v[116:117], off
	v_lshl_add_u64 v[116:117], v[116:117], 0, s[94:95]
	s_add_i32 m0, vcc_lo, 0x3400
	s_nop 0
	global_load_lds_dwordx4 v[118:119], off
	v_lshl_add_u64 v[118:119], v[118:119], 0, s[94:95]
	s_add_i32 m0, vcc_lo, 0x3800
	s_nop 0
	global_load_lds_dwordx4 v[120:121], off
	v_lshl_add_u64 v[120:121], v[120:121], 0, s[94:95]
	s_add_i32 m0, vcc_lo, 0x3c00
	s_nop 0
	global_load_lds_dwordx4 v[122:123], off
	v_lshl_add_u64 v[122:123], v[122:123], 0, s[94:95]
	v_mfma_f32_16x16x32_bf16 v[4:7], v[100:103], v[80:83], v[4:7]
	v_mfma_f32_16x16x32_bf16 v[8:11], v[100:103], v[84:87], v[8:11]
	v_mfma_f32_16x16x32_bf16 v[12:15], v[100:103], v[88:91], v[12:15]
	v_mfma_f32_16x16x32_bf16 v[16:19], v[100:103], v[92:95], v[16:19]
	v_mfma_f32_16x16x32_bf16 v[20:23], v[104:107], v[80:83], v[20:23]
	v_mfma_f32_16x16x32_bf16 v[32:35], v[104:107], v[84:87], v[32:35]
	v_mfma_f32_16x16x32_bf16 v[36:39], v[104:107], v[88:91], v[36:39]
	v_mfma_f32_16x16x32_bf16 v[40:43], v[104:107], v[92:95], v[40:43]
	v_mfma_f32_16x16x32_bf16 v[44:47], v[108:111], v[80:83], v[44:47]
	v_mfma_f32_16x16x32_bf16 v[48:51], v[108:111], v[84:87], v[48:51]
	v_mfma_f32_16x16x32_bf16 v[52:55], v[108:111], v[88:91], v[52:55]
	v_mfma_f32_16x16x32_bf16 v[56:59], v[108:111], v[92:95], v[56:59]
	v_mfma_f32_16x16x32_bf16 v[60:63], v[112:115], v[80:83], v[60:63]
	v_mfma_f32_16x16x32_bf16 v[64:67], v[112:115], v[84:87], v[64:67]
	v_mfma_f32_16x16x32_bf16 v[72:75], v[112:115], v[88:91], v[72:75]
	v_mfma_f32_16x16x32_bf16 v[76:79], v[112:115], v[92:95], v[76:79]
	s_waitcnt vmcnt(8)
	ds_read_b128 v[80:83], v132
	ds_read_b128 v[84:87], v132 offset:1024
	ds_read_b128 v[88:91], v132 offset:2048
	ds_read_b128 v[92:95], v132 offset:3072
	ds_read_b128 v[100:103], v132 offset:4096
	ds_read_b128 v[104:107], v132 offset:5120
	ds_read_b128 v[108:111], v132 offset:6144
	ds_read_b128 v[112:115], v132 offset:7168
	s_waitcnt lgkmcnt(0)
	s_add_i32 m0, vcc_lo, 0x0
	s_nop 0
	global_load_lds_dwordx4 v[26:27], off
	v_lshl_add_u64 v[26:27], v[26:27], 0, s[94:95]
	s_add_i32 m0, vcc_lo, 0x400
	s_nop 0
	global_load_lds_dwordx4 v[30:31], off
	v_lshl_add_u64 v[30:31], v[30:31], 0, s[94:95]
	s_add_i32 m0, vcc_lo, 0x800
	s_nop 0
	global_load_lds_dwordx4 v[70:71], off
	v_lshl_add_u64 v[70:71], v[70:71], 0, s[94:95]
	s_add_i32 m0, vcc_lo, 0xc00
	s_nop 0
	global_load_lds_dwordx4 v[98:99], off
	v_lshl_add_u64 v[98:99], v[98:99], 0, s[94:95]
	s_add_i32 m0, vcc_lo, 0x1000
	s_nop 0
	global_load_lds_dwordx4 v[116:117], off
	v_lshl_add_u64 v[116:117], v[116:117], 0, s[94:95]
	s_add_i32 m0, vcc_lo, 0x1400
	s_nop 0
	global_load_lds_dwordx4 v[118:119], off
	v_lshl_add_u64 v[118:119], v[118:119], 0, s[94:95]
	s_add_i32 m0, vcc_lo, 0x1800
	s_nop 0
	global_load_lds_dwordx4 v[120:121], off
	v_lshl_add_u64 v[120:121], v[120:121], 0, s[94:95]
	s_add_i32 m0, vcc_lo, 0x1c00
	s_nop 0
	global_load_lds_dwordx4 v[122:123], off
	v_lshl_add_u64 v[122:123], v[122:123], 0, s[94:95]
	v_mfma_f32_16x16x32_bf16 v[4:7], v[100:103], v[80:83], v[4:7]
	v_mfma_f32_16x16x32_bf16 v[8:11], v[100:103], v[84:87], v[8:11]
	v_mfma_f32_16x16x32_bf16 v[12:15], v[100:103], v[88:91], v[12:15]
	v_mfma_f32_16x16x32_bf16 v[16:19], v[100:103], v[92:95], v[16:19]
	v_mfma_f32_16x16x32_bf16 v[20:23], v[104:107], v[80:83], v[20:23]
	v_mfma_f32_16x16x32_bf16 v[32:35], v[104:107], v[84:87], v[32:35]
	v_mfma_f32_16x16x32_bf16 v[36:39], v[104:107], v[88:91], v[36:39]
	v_mfma_f32_16x16x32_bf16 v[40:43], v[104:107], v[92:95], v[40:43]
	v_mfma_f32_16x16x32_bf16 v[44:47], v[108:111], v[80:83], v[44:47]
	v_mfma_f32_16x16x32_bf16 v[48:51], v[108:111], v[84:87], v[48:51]
	v_mfma_f32_16x16x32_bf16 v[52:55], v[108:111], v[88:91], v[52:55]
	v_mfma_f32_16x16x32_bf16 v[56:59], v[108:111], v[92:95], v[56:59]
	v_mfma_f32_16x16x32_bf16 v[60:63], v[112:115], v[80:83], v[60:63]
	v_mfma_f32_16x16x32_bf16 v[64:67], v[112:115], v[84:87], v[64:67]
	v_mfma_f32_16x16x32_bf16 v[72:75], v[112:115], v[88:91], v[72:75]
	v_mfma_f32_16x16x32_bf16 v[76:79], v[112:115], v[92:95], v[76:79]
	s_waitcnt vmcnt(8)
	ds_read_b128 v[80:83], v132 offset:8192
	ds_read_b128 v[84:87], v132 offset:9216
	ds_read_b128 v[88:91], v132 offset:10240
	ds_read_b128 v[92:95], v132 offset:11264
	ds_read_b128 v[100:103], v132 offset:12288
	ds_read_b128 v[104:107], v132 offset:13312
	ds_read_b128 v[108:111], v132 offset:14336
	ds_read_b128 v[112:115], v132 offset:15360
	s_waitcnt lgkmcnt(0)
	s_add_i32 m0, vcc_lo, 0x2000
	s_nop 0
	global_load_lds_dwordx4 v[26:27], off
	v_lshl_add_u64 v[26:27], v[26:27], 0, s[94:95]
	s_add_i32 m0, vcc_lo, 0x2400
	s_nop 0
	global_load_lds_dwordx4 v[30:31], off
	v_lshl_add_u64 v[30:31], v[30:31], 0, s[94:95]
	s_add_i32 m0, vcc_lo, 0x2800
	s_nop 0
	global_load_lds_dwordx4 v[70:71], off
	v_lshl_add_u64 v[70:71], v[70:71], 0, s[94:95]
	s_add_i32 m0, vcc_lo, 0x2c00
	s_nop 0
	global_load_lds_dwordx4 v[98:99], off
	v_lshl_add_u64 v[98:99], v[98:99], 0, s[94:95]
	s_add_i32 m0, vcc_lo, 0x3000
	s_nop 0
	global_load_lds_dwordx4 v[116:117], off
	v_lshl_add_u64 v[116:117], v[116:117], 0, s[94:95]
	s_add_i32 m0, vcc_lo, 0x3400
	s_nop 0
	global_load_lds_dwordx4 v[118:119], off
	v_lshl_add_u64 v[118:119], v[118:119], 0, s[94:95]
	s_add_i32 m0, vcc_lo, 0x3800
	s_nop 0
	global_load_lds_dwordx4 v[120:121], off
	v_lshl_add_u64 v[120:121], v[120:121], 0, s[94:95]
	s_add_i32 m0, vcc_lo, 0x3c00
	s_nop 0
	global_load_lds_dwordx4 v[122:123], off
	v_lshl_add_u64 v[122:123], v[122:123], 0, s[94:95]
	v_mfma_f32_16x16x32_bf16 v[4:7], v[100:103], v[80:83], v[4:7]
	v_mfma_f32_16x16x32_bf16 v[8:11], v[100:103], v[84:87], v[8:11]
	v_mfma_f32_16x16x32_bf16 v[12:15], v[100:103], v[88:91], v[12:15]
	v_mfma_f32_16x16x32_bf16 v[16:19], v[100:103], v[92:95], v[16:19]
	v_mfma_f32_16x16x32_bf16 v[20:23], v[104:107], v[80:83], v[20:23]
	v_mfma_f32_16x16x32_bf16 v[32:35], v[104:107], v[84:87], v[32:35]
	v_mfma_f32_16x16x32_bf16 v[36:39], v[104:107], v[88:91], v[36:39]
	v_mfma_f32_16x16x32_bf16 v[40:43], v[104:107], v[92:95], v[40:43]
	v_mfma_f32_16x16x32_bf16 v[44:47], v[108:111], v[80:83], v[44:47]
	v_mfma_f32_16x16x32_bf16 v[48:51], v[108:111], v[84:87], v[48:51]
	v_mfma_f32_16x16x32_bf16 v[52:55], v[108:111], v[88:91], v[52:55]
	v_mfma_f32_16x16x32_bf16 v[56:59], v[108:111], v[92:95], v[56:59]
	v_mfma_f32_16x16x32_bf16 v[60:63], v[112:115], v[80:83], v[60:63]
	v_mfma_f32_16x16x32_bf16 v[64:67], v[112:115], v[84:87], v[64:67]
	v_mfma_f32_16x16x32_bf16 v[72:75], v[112:115], v[88:91], v[72:75]
	v_mfma_f32_16x16x32_bf16 v[76:79], v[112:115], v[92:95], v[76:79]
	s_waitcnt vmcnt(8)
	ds_read_b128 v[80:83], v132
	ds_read_b128 v[84:87], v132 offset:1024
	ds_read_b128 v[88:91], v132 offset:2048
	ds_read_b128 v[92:95], v132 offset:3072
	ds_read_b128 v[100:103], v132 offset:4096
	ds_read_b128 v[104:107], v132 offset:5120
	ds_read_b128 v[108:111], v132 offset:6144
	ds_read_b128 v[112:115], v132 offset:7168
	s_waitcnt lgkmcnt(0)
	s_add_i32 m0, vcc_lo, 0x0
	s_nop 0
	global_load_lds_dwordx4 v[26:27], off
	v_lshl_add_u64 v[26:27], v[26:27], 0, s[94:95]
	s_add_i32 m0, vcc_lo, 0x400
	s_nop 0
	global_load_lds_dwordx4 v[30:31], off
	v_lshl_add_u64 v[30:31], v[30:31], 0, s[94:95]
	s_add_i32 m0, vcc_lo, 0x800
	s_nop 0
	global_load_lds_dwordx4 v[70:71], off
	v_lshl_add_u64 v[70:71], v[70:71], 0, s[94:95]
	s_add_i32 m0, vcc_lo, 0xc00
	s_nop 0
	global_load_lds_dwordx4 v[98:99], off
	v_lshl_add_u64 v[98:99], v[98:99], 0, s[94:95]
	s_add_i32 m0, vcc_lo, 0x1000
	s_nop 0
	global_load_lds_dwordx4 v[116:117], off
	v_lshl_add_u64 v[116:117], v[116:117], 0, s[94:95]
	s_add_i32 m0, vcc_lo, 0x1400
	s_nop 0
	global_load_lds_dwordx4 v[118:119], off
	v_lshl_add_u64 v[118:119], v[118:119], 0, s[94:95]
	s_add_i32 m0, vcc_lo, 0x1800
	s_nop 0
	global_load_lds_dwordx4 v[120:121], off
	v_lshl_add_u64 v[120:121], v[120:121], 0, s[94:95]
	s_add_i32 m0, vcc_lo, 0x1c00
	s_nop 0
	global_load_lds_dwordx4 v[122:123], off
	v_lshl_add_u64 v[122:123], v[122:123], 0, s[94:95]
	v_mfma_f32_16x16x32_bf16 v[4:7], v[100:103], v[80:83], v[4:7]
	v_mfma_f32_16x16x32_bf16 v[8:11], v[100:103], v[84:87], v[8:11]
	v_mfma_f32_16x16x32_bf16 v[12:15], v[100:103], v[88:91], v[12:15]
	v_mfma_f32_16x16x32_bf16 v[16:19], v[100:103], v[92:95], v[16:19]
	v_mfma_f32_16x16x32_bf16 v[20:23], v[104:107], v[80:83], v[20:23]
	v_mfma_f32_16x16x32_bf16 v[32:35], v[104:107], v[84:87], v[32:35]
	v_mfma_f32_16x16x32_bf16 v[36:39], v[104:107], v[88:91], v[36:39]
	v_mfma_f32_16x16x32_bf16 v[40:43], v[104:107], v[92:95], v[40:43]
	v_mfma_f32_16x16x32_bf16 v[44:47], v[108:111], v[80:83], v[44:47]
	v_mfma_f32_16x16x32_bf16 v[48:51], v[108:111], v[84:87], v[48:51]
	v_mfma_f32_16x16x32_bf16 v[52:55], v[108:111], v[88:91], v[52:55]
	v_mfma_f32_16x16x32_bf16 v[56:59], v[108:111], v[92:95], v[56:59]
	v_mfma_f32_16x16x32_bf16 v[60:63], v[112:115], v[80:83], v[60:63]
	v_mfma_f32_16x16x32_bf16 v[64:67], v[112:115], v[84:87], v[64:67]
	v_mfma_f32_16x16x32_bf16 v[72:75], v[112:115], v[88:91], v[72:75]
	v_mfma_f32_16x16x32_bf16 v[76:79], v[112:115], v[92:95], v[76:79]
	s_waitcnt vmcnt(8)
	ds_read_b128 v[80:83], v132 offset:8192
	ds_read_b128 v[84:87], v132 offset:9216
	ds_read_b128 v[88:91], v132 offset:10240
	ds_read_b128 v[92:95], v132 offset:11264
	ds_read_b128 v[100:103], v132 offset:12288
	ds_read_b128 v[104:107], v132 offset:13312
	ds_read_b128 v[108:111], v132 offset:14336
	ds_read_b128 v[112:115], v132 offset:15360
	s_waitcnt lgkmcnt(0)
	s_add_i32 m0, vcc_lo, 0x2000
	s_nop 0
	global_load_lds_dwordx4 v[26:27], off
	v_lshl_add_u64 v[26:27], v[26:27], 0, s[94:95]
	s_add_i32 m0, vcc_lo, 0x2400
	s_nop 0
	global_load_lds_dwordx4 v[30:31], off
	v_lshl_add_u64 v[30:31], v[30:31], 0, s[94:95]
	s_add_i32 m0, vcc_lo, 0x2800
	s_nop 0
	global_load_lds_dwordx4 v[70:71], off
	v_lshl_add_u64 v[70:71], v[70:71], 0, s[94:95]
	s_add_i32 m0, vcc_lo, 0x2c00
	s_nop 0
	global_load_lds_dwordx4 v[98:99], off
	v_lshl_add_u64 v[98:99], v[98:99], 0, s[94:95]
	s_add_i32 m0, vcc_lo, 0x3000
	s_nop 0
	global_load_lds_dwordx4 v[116:117], off
	v_lshl_add_u64 v[116:117], v[116:117], 0, s[94:95]
	s_add_i32 m0, vcc_lo, 0x3400
	s_nop 0
	global_load_lds_dwordx4 v[118:119], off
	v_lshl_add_u64 v[118:119], v[118:119], 0, s[94:95]
	s_add_i32 m0, vcc_lo, 0x3800
	s_nop 0
	global_load_lds_dwordx4 v[120:121], off
	v_lshl_add_u64 v[120:121], v[120:121], 0, s[94:95]
	s_add_i32 m0, vcc_lo, 0x3c00
	s_nop 0
	global_load_lds_dwordx4 v[122:123], off
	v_lshl_add_u64 v[122:123], v[122:123], 0, s[94:95]
	v_mfma_f32_16x16x32_bf16 v[4:7], v[100:103], v[80:83], v[4:7]
	v_mfma_f32_16x16x32_bf16 v[8:11], v[100:103], v[84:87], v[8:11]
	v_mfma_f32_16x16x32_bf16 v[12:15], v[100:103], v[88:91], v[12:15]
	v_mfma_f32_16x16x32_bf16 v[16:19], v[100:103], v[92:95], v[16:19]
	v_mfma_f32_16x16x32_bf16 v[20:23], v[104:107], v[80:83], v[20:23]
	v_mfma_f32_16x16x32_bf16 v[32:35], v[104:107], v[84:87], v[32:35]
	v_mfma_f32_16x16x32_bf16 v[36:39], v[104:107], v[88:91], v[36:39]
	v_mfma_f32_16x16x32_bf16 v[40:43], v[104:107], v[92:95], v[40:43]
	v_mfma_f32_16x16x32_bf16 v[44:47], v[108:111], v[80:83], v[44:47]
	v_mfma_f32_16x16x32_bf16 v[48:51], v[108:111], v[84:87], v[48:51]
	v_mfma_f32_16x16x32_bf16 v[52:55], v[108:111], v[88:91], v[52:55]
	v_mfma_f32_16x16x32_bf16 v[56:59], v[108:111], v[92:95], v[56:59]
	v_mfma_f32_16x16x32_bf16 v[60:63], v[112:115], v[80:83], v[60:63]
	v_mfma_f32_16x16x32_bf16 v[64:67], v[112:115], v[84:87], v[64:67]
	v_mfma_f32_16x16x32_bf16 v[72:75], v[112:115], v[88:91], v[72:75]
	v_mfma_f32_16x16x32_bf16 v[76:79], v[112:115], v[92:95], v[76:79]
	s_waitcnt vmcnt(8)
	ds_read_b128 v[80:83], v132
	ds_read_b128 v[84:87], v132 offset:1024
	ds_read_b128 v[88:91], v132 offset:2048
	ds_read_b128 v[92:95], v132 offset:3072
	ds_read_b128 v[100:103], v132 offset:4096
	ds_read_b128 v[104:107], v132 offset:5120
	ds_read_b128 v[108:111], v132 offset:6144
	ds_read_b128 v[112:115], v132 offset:7168
	s_waitcnt lgkmcnt(0)
	s_add_i32 m0, vcc_lo, 0x0
	s_nop 0
	global_load_lds_dwordx4 v[26:27], off
	v_lshl_add_u64 v[26:27], v[26:27], 0, s[94:95]
	s_add_i32 m0, vcc_lo, 0x400
	s_nop 0
	global_load_lds_dwordx4 v[30:31], off
	v_lshl_add_u64 v[30:31], v[30:31], 0, s[94:95]
	s_add_i32 m0, vcc_lo, 0x800
	s_nop 0
	global_load_lds_dwordx4 v[70:71], off
	v_lshl_add_u64 v[70:71], v[70:71], 0, s[94:95]
	s_add_i32 m0, vcc_lo, 0xc00
	s_nop 0
	global_load_lds_dwordx4 v[98:99], off
	v_lshl_add_u64 v[98:99], v[98:99], 0, s[94:95]
	s_add_i32 m0, vcc_lo, 0x1000
	s_nop 0
	global_load_lds_dwordx4 v[116:117], off
	v_lshl_add_u64 v[116:117], v[116:117], 0, s[94:95]
	s_add_i32 m0, vcc_lo, 0x1400
	s_nop 0
	global_load_lds_dwordx4 v[118:119], off
	v_lshl_add_u64 v[118:119], v[118:119], 0, s[94:95]
	s_add_i32 m0, vcc_lo, 0x1800
	s_nop 0
	global_load_lds_dwordx4 v[120:121], off
	v_lshl_add_u64 v[120:121], v[120:121], 0, s[94:95]
	s_add_i32 m0, vcc_lo, 0x1c00
	s_nop 0
	global_load_lds_dwordx4 v[122:123], off
	v_lshl_add_u64 v[122:123], v[122:123], 0, s[94:95]
	v_mfma_f32_16x16x32_bf16 v[4:7], v[100:103], v[80:83], v[4:7]
	v_mfma_f32_16x16x32_bf16 v[8:11], v[100:103], v[84:87], v[8:11]
	v_mfma_f32_16x16x32_bf16 v[12:15], v[100:103], v[88:91], v[12:15]
	v_mfma_f32_16x16x32_bf16 v[16:19], v[100:103], v[92:95], v[16:19]
	v_mfma_f32_16x16x32_bf16 v[20:23], v[104:107], v[80:83], v[20:23]
	v_mfma_f32_16x16x32_bf16 v[32:35], v[104:107], v[84:87], v[32:35]
	v_mfma_f32_16x16x32_bf16 v[36:39], v[104:107], v[88:91], v[36:39]
	v_mfma_f32_16x16x32_bf16 v[40:43], v[104:107], v[92:95], v[40:43]
	v_mfma_f32_16x16x32_bf16 v[44:47], v[108:111], v[80:83], v[44:47]
	v_mfma_f32_16x16x32_bf16 v[48:51], v[108:111], v[84:87], v[48:51]
	v_mfma_f32_16x16x32_bf16 v[52:55], v[108:111], v[88:91], v[52:55]
	v_mfma_f32_16x16x32_bf16 v[56:59], v[108:111], v[92:95], v[56:59]
	v_mfma_f32_16x16x32_bf16 v[60:63], v[112:115], v[80:83], v[60:63]
	v_mfma_f32_16x16x32_bf16 v[64:67], v[112:115], v[84:87], v[64:67]
	v_mfma_f32_16x16x32_bf16 v[72:75], v[112:115], v[88:91], v[72:75]
	v_mfma_f32_16x16x32_bf16 v[76:79], v[112:115], v[92:95], v[76:79]
	s_waitcnt vmcnt(8)
	ds_read_b128 v[80:83], v132 offset:8192
	ds_read_b128 v[84:87], v132 offset:9216
	ds_read_b128 v[88:91], v132 offset:10240
	ds_read_b128 v[92:95], v132 offset:11264
	ds_read_b128 v[100:103], v132 offset:12288
	ds_read_b128 v[104:107], v132 offset:13312
	ds_read_b128 v[108:111], v132 offset:14336
	ds_read_b128 v[112:115], v132 offset:15360
	s_waitcnt lgkmcnt(0)
	s_add_i32 m0, vcc_lo, 0x2000
	s_nop 0
	global_load_lds_dwordx4 v[26:27], off
	v_lshl_add_u64 v[26:27], v[26:27], 0, s[94:95]
	s_add_i32 m0, vcc_lo, 0x2400
	s_nop 0
	global_load_lds_dwordx4 v[30:31], off
	v_lshl_add_u64 v[30:31], v[30:31], 0, s[94:95]
	s_add_i32 m0, vcc_lo, 0x2800
	s_nop 0
	global_load_lds_dwordx4 v[70:71], off
	v_lshl_add_u64 v[70:71], v[70:71], 0, s[94:95]
	s_add_i32 m0, vcc_lo, 0x2c00
	s_nop 0
	global_load_lds_dwordx4 v[98:99], off
	v_lshl_add_u64 v[98:99], v[98:99], 0, s[94:95]
	s_add_i32 m0, vcc_lo, 0x3000
	s_nop 0
	global_load_lds_dwordx4 v[116:117], off
	v_lshl_add_u64 v[116:117], v[116:117], 0, s[94:95]
	s_add_i32 m0, vcc_lo, 0x3400
	s_nop 0
	global_load_lds_dwordx4 v[118:119], off
	v_lshl_add_u64 v[118:119], v[118:119], 0, s[94:95]
	s_add_i32 m0, vcc_lo, 0x3800
	s_nop 0
	global_load_lds_dwordx4 v[120:121], off
	v_lshl_add_u64 v[120:121], v[120:121], 0, s[94:95]
	s_add_i32 m0, vcc_lo, 0x3c00
	s_nop 0
	global_load_lds_dwordx4 v[122:123], off
	v_lshl_add_u64 v[122:123], v[122:123], 0, s[94:95]
	v_mfma_f32_16x16x32_bf16 v[4:7], v[100:103], v[80:83], v[4:7]
	v_mfma_f32_16x16x32_bf16 v[8:11], v[100:103], v[84:87], v[8:11]
	v_mfma_f32_16x16x32_bf16 v[12:15], v[100:103], v[88:91], v[12:15]
	v_mfma_f32_16x16x32_bf16 v[16:19], v[100:103], v[92:95], v[16:19]
	v_mfma_f32_16x16x32_bf16 v[20:23], v[104:107], v[80:83], v[20:23]
	v_mfma_f32_16x16x32_bf16 v[32:35], v[104:107], v[84:87], v[32:35]
	v_mfma_f32_16x16x32_bf16 v[36:39], v[104:107], v[88:91], v[36:39]
	v_mfma_f32_16x16x32_bf16 v[40:43], v[104:107], v[92:95], v[40:43]
	v_mfma_f32_16x16x32_bf16 v[44:47], v[108:111], v[80:83], v[44:47]
	v_mfma_f32_16x16x32_bf16 v[48:51], v[108:111], v[84:87], v[48:51]
	v_mfma_f32_16x16x32_bf16 v[52:55], v[108:111], v[88:91], v[52:55]
	v_mfma_f32_16x16x32_bf16 v[56:59], v[108:111], v[92:95], v[56:59]
	v_mfma_f32_16x16x32_bf16 v[60:63], v[112:115], v[80:83], v[60:63]
	v_mfma_f32_16x16x32_bf16 v[64:67], v[112:115], v[84:87], v[64:67]
	v_mfma_f32_16x16x32_bf16 v[72:75], v[112:115], v[88:91], v[72:75]
	v_mfma_f32_16x16x32_bf16 v[76:79], v[112:115], v[92:95], v[76:79]
	s_waitcnt vmcnt(8)
	ds_read_b128 v[80:83], v132
	ds_read_b128 v[84:87], v132 offset:1024
	ds_read_b128 v[88:91], v132 offset:2048
	ds_read_b128 v[92:95], v132 offset:3072
	ds_read_b128 v[100:103], v132 offset:4096
	ds_read_b128 v[104:107], v132 offset:5120
	ds_read_b128 v[108:111], v132 offset:6144
	ds_read_b128 v[112:115], v132 offset:7168
	s_waitcnt lgkmcnt(0)
	s_add_i32 m0, vcc_lo, 0x0
	s_nop 0
	global_load_lds_dwordx4 v[26:27], off
	v_lshl_add_u64 v[26:27], v[26:27], 0, s[94:95]
	s_add_i32 m0, vcc_lo, 0x400
	s_nop 0
	global_load_lds_dwordx4 v[30:31], off
	v_lshl_add_u64 v[30:31], v[30:31], 0, s[94:95]
	s_add_i32 m0, vcc_lo, 0x800
	s_nop 0
	global_load_lds_dwordx4 v[70:71], off
	v_lshl_add_u64 v[70:71], v[70:71], 0, s[94:95]
	s_add_i32 m0, vcc_lo, 0xc00
	s_nop 0
	global_load_lds_dwordx4 v[98:99], off
	v_lshl_add_u64 v[98:99], v[98:99], 0, s[94:95]
	s_add_i32 m0, vcc_lo, 0x1000
	s_nop 0
	global_load_lds_dwordx4 v[116:117], off
	v_lshl_add_u64 v[116:117], v[116:117], 0, s[94:95]
	s_add_i32 m0, vcc_lo, 0x1400
	s_nop 0
	global_load_lds_dwordx4 v[118:119], off
	v_lshl_add_u64 v[118:119], v[118:119], 0, s[94:95]
	s_add_i32 m0, vcc_lo, 0x1800
	s_nop 0
	global_load_lds_dwordx4 v[120:121], off
	v_lshl_add_u64 v[120:121], v[120:121], 0, s[94:95]
	s_add_i32 m0, vcc_lo, 0x1c00
	s_nop 0
	global_load_lds_dwordx4 v[122:123], off
	v_lshl_add_u64 v[122:123], v[122:123], 0, s[94:95]
	v_mfma_f32_16x16x32_bf16 v[4:7], v[100:103], v[80:83], v[4:7]
	v_mfma_f32_16x16x32_bf16 v[8:11], v[100:103], v[84:87], v[8:11]
	v_mfma_f32_16x16x32_bf16 v[12:15], v[100:103], v[88:91], v[12:15]
	v_mfma_f32_16x16x32_bf16 v[16:19], v[100:103], v[92:95], v[16:19]
	v_mfma_f32_16x16x32_bf16 v[20:23], v[104:107], v[80:83], v[20:23]
	v_mfma_f32_16x16x32_bf16 v[32:35], v[104:107], v[84:87], v[32:35]
	v_mfma_f32_16x16x32_bf16 v[36:39], v[104:107], v[88:91], v[36:39]
	v_mfma_f32_16x16x32_bf16 v[40:43], v[104:107], v[92:95], v[40:43]
	v_mfma_f32_16x16x32_bf16 v[44:47], v[108:111], v[80:83], v[44:47]
	v_mfma_f32_16x16x32_bf16 v[48:51], v[108:111], v[84:87], v[48:51]
	v_mfma_f32_16x16x32_bf16 v[52:55], v[108:111], v[88:91], v[52:55]
	v_mfma_f32_16x16x32_bf16 v[56:59], v[108:111], v[92:95], v[56:59]
	v_mfma_f32_16x16x32_bf16 v[60:63], v[112:115], v[80:83], v[60:63]
	v_mfma_f32_16x16x32_bf16 v[64:67], v[112:115], v[84:87], v[64:67]
	v_mfma_f32_16x16x32_bf16 v[72:75], v[112:115], v[88:91], v[72:75]
	v_mfma_f32_16x16x32_bf16 v[76:79], v[112:115], v[92:95], v[76:79]
	s_waitcnt vmcnt(8)
	ds_read_b128 v[80:83], v132 offset:8192
	ds_read_b128 v[84:87], v132 offset:9216
	ds_read_b128 v[88:91], v132 offset:10240
	ds_read_b128 v[92:95], v132 offset:11264
	ds_read_b128 v[100:103], v132 offset:12288
	ds_read_b128 v[104:107], v132 offset:13312
	ds_read_b128 v[108:111], v132 offset:14336
	ds_read_b128 v[112:115], v132 offset:15360
	s_waitcnt lgkmcnt(0)
	s_add_i32 m0, vcc_lo, 0x2000
	s_nop 0
	global_load_lds_dwordx4 v[26:27], off
	v_lshl_add_u64 v[26:27], v[26:27], 0, s[94:95]
	s_add_i32 m0, vcc_lo, 0x2400
	s_nop 0
	global_load_lds_dwordx4 v[30:31], off
	v_lshl_add_u64 v[30:31], v[30:31], 0, s[94:95]
	s_add_i32 m0, vcc_lo, 0x2800
	s_nop 0
	global_load_lds_dwordx4 v[70:71], off
	v_lshl_add_u64 v[70:71], v[70:71], 0, s[94:95]
	s_add_i32 m0, vcc_lo, 0x2c00
	s_nop 0
	global_load_lds_dwordx4 v[98:99], off
	v_lshl_add_u64 v[98:99], v[98:99], 0, s[94:95]
	s_add_i32 m0, vcc_lo, 0x3000
	s_nop 0
	global_load_lds_dwordx4 v[116:117], off
	v_lshl_add_u64 v[116:117], v[116:117], 0, s[94:95]
	s_add_i32 m0, vcc_lo, 0x3400
	s_nop 0
	global_load_lds_dwordx4 v[118:119], off
	v_lshl_add_u64 v[118:119], v[118:119], 0, s[94:95]
	s_add_i32 m0, vcc_lo, 0x3800
	s_nop 0
	global_load_lds_dwordx4 v[120:121], off
	v_lshl_add_u64 v[120:121], v[120:121], 0, s[94:95]
	s_add_i32 m0, vcc_lo, 0x3c00
	s_nop 0
	global_load_lds_dwordx4 v[122:123], off
	v_lshl_add_u64 v[122:123], v[122:123], 0, s[94:95]
	v_mfma_f32_16x16x32_bf16 v[4:7], v[100:103], v[80:83], v[4:7]
	v_mfma_f32_16x16x32_bf16 v[8:11], v[100:103], v[84:87], v[8:11]
	v_mfma_f32_16x16x32_bf16 v[12:15], v[100:103], v[88:91], v[12:15]
	v_mfma_f32_16x16x32_bf16 v[16:19], v[100:103], v[92:95], v[16:19]
	v_mfma_f32_16x16x32_bf16 v[20:23], v[104:107], v[80:83], v[20:23]
	v_mfma_f32_16x16x32_bf16 v[32:35], v[104:107], v[84:87], v[32:35]
	v_mfma_f32_16x16x32_bf16 v[36:39], v[104:107], v[88:91], v[36:39]
	v_mfma_f32_16x16x32_bf16 v[40:43], v[104:107], v[92:95], v[40:43]
	v_mfma_f32_16x16x32_bf16 v[44:47], v[108:111], v[80:83], v[44:47]
	v_mfma_f32_16x16x32_bf16 v[48:51], v[108:111], v[84:87], v[48:51]
	v_mfma_f32_16x16x32_bf16 v[52:55], v[108:111], v[88:91], v[52:55]
	v_mfma_f32_16x16x32_bf16 v[56:59], v[108:111], v[92:95], v[56:59]
	v_mfma_f32_16x16x32_bf16 v[60:63], v[112:115], v[80:83], v[60:63]
	v_mfma_f32_16x16x32_bf16 v[64:67], v[112:115], v[84:87], v[64:67]
	v_mfma_f32_16x16x32_bf16 v[72:75], v[112:115], v[88:91], v[72:75]
	v_mfma_f32_16x16x32_bf16 v[76:79], v[112:115], v[92:95], v[76:79]
	s_waitcnt vmcnt(8)
	ds_read_b128 v[80:83], v132
	ds_read_b128 v[84:87], v132 offset:1024
	ds_read_b128 v[88:91], v132 offset:2048
	ds_read_b128 v[92:95], v132 offset:3072
	ds_read_b128 v[100:103], v132 offset:4096
	ds_read_b128 v[104:107], v132 offset:5120
	ds_read_b128 v[108:111], v132 offset:6144
	ds_read_b128 v[112:115], v132 offset:7168
	s_waitcnt lgkmcnt(0)
	s_add_i32 m0, vcc_lo, 0x0
	s_nop 0
	global_load_lds_dwordx4 v[26:27], off
	v_lshl_add_u64 v[26:27], v[26:27], 0, s[94:95]
	s_add_i32 m0, vcc_lo, 0x400
	s_nop 0
	global_load_lds_dwordx4 v[30:31], off
	v_lshl_add_u64 v[30:31], v[30:31], 0, s[94:95]
	s_add_i32 m0, vcc_lo, 0x800
	s_nop 0
	global_load_lds_dwordx4 v[70:71], off
	v_lshl_add_u64 v[70:71], v[70:71], 0, s[94:95]
	s_add_i32 m0, vcc_lo, 0xc00
	s_nop 0
	global_load_lds_dwordx4 v[98:99], off
	v_lshl_add_u64 v[98:99], v[98:99], 0, s[94:95]
	s_add_i32 m0, vcc_lo, 0x1000
	s_nop 0
	global_load_lds_dwordx4 v[116:117], off
	v_lshl_add_u64 v[116:117], v[116:117], 0, s[94:95]
	s_add_i32 m0, vcc_lo, 0x1400
	s_nop 0
	global_load_lds_dwordx4 v[118:119], off
	v_lshl_add_u64 v[118:119], v[118:119], 0, s[94:95]
	s_add_i32 m0, vcc_lo, 0x1800
	s_nop 0
	global_load_lds_dwordx4 v[120:121], off
	v_lshl_add_u64 v[120:121], v[120:121], 0, s[94:95]
	s_add_i32 m0, vcc_lo, 0x1c00
	s_nop 0
	global_load_lds_dwordx4 v[122:123], off
	v_lshl_add_u64 v[122:123], v[122:123], 0, s[94:95]
	v_mfma_f32_16x16x32_bf16 v[4:7], v[100:103], v[80:83], v[4:7]
	v_mfma_f32_16x16x32_bf16 v[8:11], v[100:103], v[84:87], v[8:11]
	v_mfma_f32_16x16x32_bf16 v[12:15], v[100:103], v[88:91], v[12:15]
	v_mfma_f32_16x16x32_bf16 v[16:19], v[100:103], v[92:95], v[16:19]
	v_mfma_f32_16x16x32_bf16 v[20:23], v[104:107], v[80:83], v[20:23]
	v_mfma_f32_16x16x32_bf16 v[32:35], v[104:107], v[84:87], v[32:35]
	v_mfma_f32_16x16x32_bf16 v[36:39], v[104:107], v[88:91], v[36:39]
	v_mfma_f32_16x16x32_bf16 v[40:43], v[104:107], v[92:95], v[40:43]
	v_mfma_f32_16x16x32_bf16 v[44:47], v[108:111], v[80:83], v[44:47]
	v_mfma_f32_16x16x32_bf16 v[48:51], v[108:111], v[84:87], v[48:51]
	v_mfma_f32_16x16x32_bf16 v[52:55], v[108:111], v[88:91], v[52:55]
	v_mfma_f32_16x16x32_bf16 v[56:59], v[108:111], v[92:95], v[56:59]
	v_mfma_f32_16x16x32_bf16 v[60:63], v[112:115], v[80:83], v[60:63]
	v_mfma_f32_16x16x32_bf16 v[64:67], v[112:115], v[84:87], v[64:67]
	v_mfma_f32_16x16x32_bf16 v[72:75], v[112:115], v[88:91], v[72:75]
	v_mfma_f32_16x16x32_bf16 v[76:79], v[112:115], v[92:95], v[76:79]
	s_waitcnt vmcnt(8)
	ds_read_b128 v[80:83], v132 offset:8192
	ds_read_b128 v[84:87], v132 offset:9216
	ds_read_b128 v[88:91], v132 offset:10240
	ds_read_b128 v[92:95], v132 offset:11264
	ds_read_b128 v[100:103], v132 offset:12288
	ds_read_b128 v[104:107], v132 offset:13312
	ds_read_b128 v[108:111], v132 offset:14336
	ds_read_b128 v[112:115], v132 offset:15360
	s_waitcnt lgkmcnt(0)
	s_add_i32 m0, vcc_lo, 0x2000
	s_nop 0
	global_load_lds_dwordx4 v[26:27], off
	v_lshl_add_u64 v[26:27], v[26:27], 0, s[94:95]
	s_add_i32 m0, vcc_lo, 0x2400
	s_nop 0
	global_load_lds_dwordx4 v[30:31], off
	v_lshl_add_u64 v[30:31], v[30:31], 0, s[94:95]
	s_add_i32 m0, vcc_lo, 0x2800
	s_nop 0
	global_load_lds_dwordx4 v[70:71], off
	v_lshl_add_u64 v[70:71], v[70:71], 0, s[94:95]
	s_add_i32 m0, vcc_lo, 0x2c00
	s_nop 0
	global_load_lds_dwordx4 v[98:99], off
	v_lshl_add_u64 v[98:99], v[98:99], 0, s[94:95]
	s_add_i32 m0, vcc_lo, 0x3000
	s_nop 0
	global_load_lds_dwordx4 v[116:117], off
	v_lshl_add_u64 v[116:117], v[116:117], 0, s[94:95]
	s_add_i32 m0, vcc_lo, 0x3400
	s_nop 0
	global_load_lds_dwordx4 v[118:119], off
	v_lshl_add_u64 v[118:119], v[118:119], 0, s[94:95]
	s_add_i32 m0, vcc_lo, 0x3800
	s_nop 0
	global_load_lds_dwordx4 v[120:121], off
	v_lshl_add_u64 v[120:121], v[120:121], 0, s[94:95]
	s_add_i32 m0, vcc_lo, 0x3c00
	s_nop 0
	global_load_lds_dwordx4 v[122:123], off
	v_lshl_add_u64 v[122:123], v[122:123], 0, s[94:95]
	v_mfma_f32_16x16x32_bf16 v[4:7], v[100:103], v[80:83], v[4:7]
	v_mfma_f32_16x16x32_bf16 v[8:11], v[100:103], v[84:87], v[8:11]
	v_mfma_f32_16x16x32_bf16 v[12:15], v[100:103], v[88:91], v[12:15]
	v_mfma_f32_16x16x32_bf16 v[16:19], v[100:103], v[92:95], v[16:19]
	v_mfma_f32_16x16x32_bf16 v[20:23], v[104:107], v[80:83], v[20:23]
	v_mfma_f32_16x16x32_bf16 v[32:35], v[104:107], v[84:87], v[32:35]
	v_mfma_f32_16x16x32_bf16 v[36:39], v[104:107], v[88:91], v[36:39]
	v_mfma_f32_16x16x32_bf16 v[40:43], v[104:107], v[92:95], v[40:43]
	v_mfma_f32_16x16x32_bf16 v[44:47], v[108:111], v[80:83], v[44:47]
	v_mfma_f32_16x16x32_bf16 v[48:51], v[108:111], v[84:87], v[48:51]
	v_mfma_f32_16x16x32_bf16 v[52:55], v[108:111], v[88:91], v[52:55]
	v_mfma_f32_16x16x32_bf16 v[56:59], v[108:111], v[92:95], v[56:59]
	v_mfma_f32_16x16x32_bf16 v[60:63], v[112:115], v[80:83], v[60:63]
	v_mfma_f32_16x16x32_bf16 v[64:67], v[112:115], v[84:87], v[64:67]
	v_mfma_f32_16x16x32_bf16 v[72:75], v[112:115], v[88:91], v[72:75]
	v_mfma_f32_16x16x32_bf16 v[76:79], v[112:115], v[92:95], v[76:79]
	s_waitcnt vmcnt(8)
	ds_read_b128 v[80:83], v132
	ds_read_b128 v[84:87], v132 offset:1024
	ds_read_b128 v[88:91], v132 offset:2048
	ds_read_b128 v[92:95], v132 offset:3072
	ds_read_b128 v[100:103], v132 offset:4096
	ds_read_b128 v[104:107], v132 offset:5120
	ds_read_b128 v[108:111], v132 offset:6144
	ds_read_b128 v[112:115], v132 offset:7168
	s_waitcnt lgkmcnt(0)
	v_mfma_f32_16x16x32_bf16 v[4:7], v[100:103], v[80:83], v[4:7]
	v_mfma_f32_16x16x32_bf16 v[8:11], v[100:103], v[84:87], v[8:11]
	v_mfma_f32_16x16x32_bf16 v[12:15], v[100:103], v[88:91], v[12:15]
	v_mfma_f32_16x16x32_bf16 v[16:19], v[100:103], v[92:95], v[16:19]
	v_mfma_f32_16x16x32_bf16 v[20:23], v[104:107], v[80:83], v[20:23]
	v_mfma_f32_16x16x32_bf16 v[32:35], v[104:107], v[84:87], v[32:35]
	v_mfma_f32_16x16x32_bf16 v[36:39], v[104:107], v[88:91], v[36:39]
	v_mfma_f32_16x16x32_bf16 v[40:43], v[104:107], v[92:95], v[40:43]
	v_mfma_f32_16x16x32_bf16 v[44:47], v[108:111], v[80:83], v[44:47]
	v_mfma_f32_16x16x32_bf16 v[48:51], v[108:111], v[84:87], v[48:51]
	v_mfma_f32_16x16x32_bf16 v[52:55], v[108:111], v[88:91], v[52:55]
	v_mfma_f32_16x16x32_bf16 v[56:59], v[108:111], v[92:95], v[56:59]
	v_mfma_f32_16x16x32_bf16 v[60:63], v[112:115], v[80:83], v[60:63]
	v_mfma_f32_16x16x32_bf16 v[64:67], v[112:115], v[84:87], v[64:67]
	v_mfma_f32_16x16x32_bf16 v[72:75], v[112:115], v[88:91], v[72:75]
	v_mfma_f32_16x16x32_bf16 v[76:79], v[112:115], v[92:95], v[76:79]
	s_waitcnt vmcnt(0)
	ds_read_b128 v[80:83], v132 offset:8192
	ds_read_b128 v[84:87], v132 offset:9216
	ds_read_b128 v[88:91], v132 offset:10240
	ds_read_b128 v[92:95], v132 offset:11264
	ds_read_b128 v[100:103], v132 offset:12288
	ds_read_b128 v[104:107], v132 offset:13312
	ds_read_b128 v[108:111], v132 offset:14336
	ds_read_b128 v[112:115], v132 offset:15360
	s_waitcnt lgkmcnt(0)
	v_mfma_f32_16x16x32_bf16 v[4:7], v[100:103], v[80:83], v[4:7]
	v_mfma_f32_16x16x32_bf16 v[8:11], v[100:103], v[84:87], v[8:11]
	v_mfma_f32_16x16x32_bf16 v[12:15], v[100:103], v[88:91], v[12:15]
	v_mfma_f32_16x16x32_bf16 v[16:19], v[100:103], v[92:95], v[16:19]
	v_mfma_f32_16x16x32_bf16 v[20:23], v[104:107], v[80:83], v[20:23]
	v_mfma_f32_16x16x32_bf16 v[32:35], v[104:107], v[84:87], v[32:35]
	v_mfma_f32_16x16x32_bf16 v[36:39], v[104:107], v[88:91], v[36:39]
	v_mfma_f32_16x16x32_bf16 v[40:43], v[104:107], v[92:95], v[40:43]
	v_mfma_f32_16x16x32_bf16 v[44:47], v[108:111], v[80:83], v[44:47]
	v_mfma_f32_16x16x32_bf16 v[48:51], v[108:111], v[84:87], v[48:51]
	v_mfma_f32_16x16x32_bf16 v[52:55], v[108:111], v[88:91], v[52:55]
	v_mfma_f32_16x16x32_bf16 v[56:59], v[108:111], v[92:95], v[56:59]
	v_mfma_f32_16x16x32_bf16 v[60:63], v[112:115], v[80:83], v[60:63]
	v_mfma_f32_16x16x32_bf16 v[64:67], v[112:115], v[84:87], v[64:67]
	v_mfma_f32_16x16x32_bf16 v[72:75], v[112:115], v[88:91], v[72:75]
	v_mfma_f32_16x16x32_bf16 v[76:79], v[112:115], v[92:95], v[76:79]
	s_nop 7
	s_nop 3
	v_bfe_u32 v2, v97, 4, 2
	v_lshlrev_b32_e32 v1, 2, v2
	v_lshl_or_b32 v1, s6, 4, v1
	s_nop 2
	v_and_b32_e32 v68, 63, v97
	v_lshl_add_u32 v3, v68, 4, 0
	v_lshl_add_u32 v0, s5, 14, v3
	ds_write_b128 v0, v[4:7]
	ds_write_b128 v0, v[8:11] offset:1024
	ds_write_b128 v0, v[12:15] offset:2048
	ds_write_b128 v0, v[16:19] offset:3072
	ds_write_b128 v0, v[20:23] offset:4096
	ds_write_b128 v0, v[32:35] offset:5120
	ds_write_b128 v0, v[36:39] offset:6144
	ds_write_b128 v0, v[40:43] offset:7168
	ds_write_b128 v0, v[44:47] offset:8192
	ds_write_b128 v0, v[48:51] offset:9216
	ds_write_b128 v0, v[52:55] offset:10240
	ds_write_b128 v0, v[56:59] offset:11264
	ds_write_b128 v0, v[60:63] offset:12288
	ds_write_b128 v0, v[64:67] offset:13312
	ds_write_b128 v0, v[72:75] offset:14336
	ds_write_b128 v0, v[76:79] offset:15360
	s_lshl_b32 s5, s7, 4
	s_addk_i32 s5, 0x4000
	s_waitcnt vmcnt(0) lgkmcnt(0)
	s_nop 2
	s_nop 2
	s_nop 5
	s_nop 5
	s_nop 5
	s_nop 7
	v_or_b32_e32 v0, s5, v96
	v_or_b32_e32 v6, s3, v1
	v_ashrrev_i32_e32 v1, 31, v0
	v_lshlrev_b64 v[4:5], 12, v[0:1]
	s_ashr_i32 s5, s4, 31
	v_lshl_add_u64 v[4:5], s[10:11], 0, v[4:5]
	v_lshl_add_u64 v[4:5], s[4:5], 1, v[4:5]
	v_lshlrev_b32_e32 v128, 1, v6
	v_lshl_add_u64 v[16:17], v[4:5], 0, v[128:129]
	s_waitcnt lgkmcnt(0)
	s_barrier
	global_load_dwordx2 v[18:19], v[16:17], off
	global_load_dwordx2 v[20:21], v[16:17], off offset:256
	s_lshl_b32 s3, s6, 2
	s_add_i32 s3, s3, s7
	v_lshl_add_u32 v3, s3, 10, v3
	ds_read_b128 v[4:7], v3
	ds_read_b128 v[8:11], v3 offset:8192
	ds_read_b128 v[12:15], v3 offset:16384
	s_waitcnt lgkmcnt(0)
	v_pk_add_f32 v[22:23], v[6:7], 0 op_sel_hi:[1,0]
	v_pk_add_f32 v[24:25], v[4:5], 0 op_sel_hi:[1,0]
	ds_read_b128 v[4:7], v3 offset:24576
	v_pk_add_f32 v[26:27], v[10:11], 0 op_sel_hi:[1,0]
	v_pk_add_f32 v[28:29], v[8:9], 0 op_sel_hi:[1,0]
	v_pk_add_f32 v[22:23], v[22:23], v[14:15]
	v_pk_add_f32 v[24:25], v[24:25], v[12:13]
	ds_read_b128 v[8:11], v3 offset:32768
	ds_read_b128 v[12:15], v3 offset:40960
	s_waitcnt lgkmcnt(0)
	v_pk_add_f32 v[26:27], v[26:27], v[6:7]
	v_pk_add_f32 v[28:29], v[28:29], v[4:5]
	ds_read_b128 v[4:7], v3 offset:49152
	v_pk_add_f32 v[22:23], v[22:23], v[10:11]
	v_pk_add_f32 v[24:25], v[24:25], v[8:9]
	v_pk_add_f32 v[28:29], v[28:29], v[12:13]
	ds_read_b128 v[8:11], v3 offset:57344
	v_add_u32_e32 v12, 0x12000, v3
	v_pk_add_f32 v[26:27], v[26:27], v[14:15]
	s_waitcnt lgkmcnt(0)
	v_pk_add_f32 v[24:25], v[24:25], v[4:5]
	v_add_u32_e32 v4, 0x10000, v3
	ds_read_b128 v[12:15], v12
	v_pk_add_f32 v[22:23], v[22:23], v[6:7]
	ds_read_b128 v[4:7], v4
	v_pk_add_f32 v[8:9], v[28:29], v[8:9]
	v_pk_add_f32 v[10:11], v[26:27], v[10:11]
	s_waitcnt lgkmcnt(0)
	v_pk_add_f32 v[28:29], v[8:9], v[12:13]
	v_add_u32_e32 v8, 0x16000, v3
	v_pk_add_f32 v[26:27], v[10:11], v[14:15]
	ds_read_b128 v[8:11], v8
	v_pk_add_f32 v[24:25], v[24:25], v[4:5]
	v_add_u32_e32 v4, 0x14000, v3
	v_pk_add_f32 v[22:23], v[22:23], v[6:7]
	ds_read_b128 v[4:7], v4
	v_add_u32_e32 v12, 0x18000, v3
	ds_read_b128 v[12:15], v12
	s_waitcnt lgkmcnt(0)
	v_pk_add_f32 v[28:29], v[28:29], v[8:9]
	v_add_u32_e32 v8, 0x1c000, v3
	v_pk_add_f32 v[26:27], v[26:27], v[10:11]
	ds_read_b128 v[8:11], v8
	v_pk_add_f32 v[24:25], v[24:25], v[4:5]
	v_add_u32_e32 v4, 0x1a000, v3
	v_pk_add_f32 v[22:23], v[22:23], v[6:7]
	ds_read_b128 v[4:7], v4
	v_add_u32_e32 v3, 0x1e000, v3
	v_pk_add_f32 v[22:23], v[22:23], v[14:15]
	v_pk_add_f32 v[24:25], v[24:25], v[12:13]
	ds_read_b128 v[12:15], v3
	s_waitcnt lgkmcnt(0)
	v_pk_add_f32 v[4:5], v[28:29], v[4:5]
	v_pk_add_f32 v[8:9], v[24:25], v[8:9]
	v_pk_add_f32 v[6:7], v[26:27], v[6:7]
	v_pk_add_f32 v[10:11], v[22:23], v[10:11]
	v_pk_add_f32 v[4:5], v[4:5], v[12:13]
	v_pk_add_f32 v[6:7], v[6:7], v[14:15]
	s_waitcnt vmcnt(0)
	v_lshlrev_b32_e32 v12, 16, v18
	v_and_b32_e32 v13, 0xffff0000, v18
	v_pk_add_f32 v[8:9], v[8:9], v[12:13]
	v_lshlrev_b32_e32 v12, 16, v20
	v_and_b32_e32 v13, 0xffff0000, v20
	v_lshlrev_b32_e32 v14, 16, v19
	v_and_b32_e32 v15, 0xffff0000, v19
	v_pk_add_f32 v[4:5], v[4:5], v[12:13]
	v_pk_add_f32 v[10:11], v[10:11], v[14:15]
	v_lshlrev_b32_e32 v14, 16, v21
	v_and_b32_e32 v15, 0xffff0000, v21
	v_mul_f32_e32 v3, v4, v4
	v_mul_f32_e32 v12, v5, v5
	v_pk_add_f32 v[6:7], v[6:7], v[14:15]
	v_fmac_f32_e32 v3, v8, v8
	v_fmac_f32_e32 v12, v9, v9
	v_add_f32_e32 v3, v3, v12
	v_mul_f32_e32 v12, v6, v6
	v_fmac_f32_e32 v12, v10, v10
	v_add_f32_e32 v3, v12, v3
	v_mul_f32_e32 v12, v7, v7
	v_fmac_f32_e32 v12, v11, v11
	v_and_b32_e32 v13, 64, v214
	v_add_f32_e32 v3, v12, v3
	v_xor_b32_e32 v12, 16, v214
	v_add_u32_e32 v13, 64, v13
	v_cmp_lt_i32_e32 vcc, v12, v13
	v_cvt_pk_bf16_f32 v8, v8, v9
	v_cvt_pk_bf16_f32 v9, v10, v11
	v_xor_b32_e32 v10, 32, v214
	global_store_dwordx2 v[16:17], v[8:9], off
	v_cndmask_b32_e32 v12, v214, v12, vcc
	v_lshlrev_b32_e32 v12, 2, v12
	ds_bpermute_b32 v12, v12, v3
	v_cmp_lt_i32_e32 vcc, v10, v13
	v_cvt_pk_bf16_f32 v4, v4, v5
	v_cvt_pk_bf16_f32 v5, v6, v7
	global_store_dwordx2 v[16:17], v[4:5], off offset:256
	s_waitcnt lgkmcnt(0)
	v_add_f32_e32 v3, v3, v12
	v_cndmask_b32_e32 v10, v214, v10, vcc
	v_lshlrev_b32_e32 v10, 2, v10
	ds_bpermute_b32 v10, v10, v3
	v_cmp_gt_u32_e32 vcc, 16, v68
	s_waitcnt lgkmcnt(0)
	v_add_f32_e32 v3, v3, v10
	s_and_saveexec_b64 s[4:5], vcc
	s_and_b32 s3, s1, 0xffffffc0
	s_add_i32 s3, s3, 0
	v_lshl_add_u32 v4, v96, 2, s3
	v_add_u32_e32 v4, 0x20100, v4
	ds_write_b32 v4, v3
	s_or_b64 exec, exec, s[4:5]
	v_or_b32_e32 v2, s6, v2
	v_cmp_eq_u32_e32 vcc, 0, v2
	s_waitcnt lgkmcnt(0)
	s_barrier
	s_and_saveexec_b64 s[4:5], vcc
	s_cbranch_execz .LBB0_1210
	s_andn2_b32 s1, s1, 63
	s_add_i32 s1, s1, 0
	s_add_i32 s1, s1, 0x20100
	v_lshl_add_u32 v2, v96, 2, s1
	ds_read_b32 v2, v2 offset:64
	v_lshlrev_b64 v[0:1], 7, v[0:1]
	v_lshl_add_u64 v[0:1], s[8:9], 0, v[0:1]
	s_ashr_i32 s3, s2, 31
	v_lshl_add_u64 v[0:1], s[2:3], 2, v[0:1]
	s_waitcnt lgkmcnt(0)
	v_add_f32_e32 v2, v3, v2
	global_store_dword v[0:1], v2, off

.LBB0_1302:
	s_waitcnt vmcnt(0) lgkmcnt(0)
	v_mov_b32_e32 v96, v210
	s_mov_b32 s0, s73
	s_cmp_gt_i32 s0, 31
	v_readfirstlane_b32 s1, v96
	s_cbranch_scc1 .LBB0_1304
	v_and_b32_e32 v97, 15, v96
	s_ashr_i32 s3, s1, 6
	v_mul_u32_u24_e32 v0, 0x1600, v97
	v_lshlrev_b32_e32 v128, 1, v0
	s_mul_i32 s4, s3, 0x2c0
	s_lshl_b32 s2, s0, 6
	s_lshl_b32 s0, s0, 5
	v_lshl_add_u64 v[0:1], s[14:15], 0, v[128:129]
	v_and_b32_e32 v128, 48, v96
	s_ashr_i32 s5, s4, 31
	s_and_b32 s0, s0, 0x60
	v_lshl_add_u64 v[0:1], v[0:1], 0, v[128:129]
	s_lshl_b64 s[4:5], s[4:5], 1
	s_and_b32 s2, s2, 0xffffff00
	v_lshl_add_u64 v[28:29], v[0:1], 0, s[4:5]
	v_or_b32_e32 v0, s0, v97
	v_or_b32_e32 v2, s2, v0
	v_mov_b64_e32 v[0:1], s[12:13]
	s_movk_i32 s10, 0x2c00
	v_mad_i64_i32 v[0:1], s[10:11], v2, s10, v[0:1]
	v_lshl_add_u64 v[0:1], v[0:1], 0, v[128:129]
	v_lshl_add_u64 v[24:25], v[0:1], 0, s[4:5]
	s_mov_b32 s4, 0xb000000
	s_mov_b32 s4, 0xb02c000
	s_mov_b32 s4, 0xb058000
	s_mov_b64 s[4:5], 0xb000000
	s_mov_b32 s4, 0xb084000
	s_mov_b32 s4, 0x2c000
	s_mov_b32 s4, 0x160000
	s_mov_b32 s4, 0x18c000
	s_ashr_i32 s1, s1, 7
	s_and_b32 s4, s3, 1
	s_mov_b64 s[10:11], -1
	v_lshrrev_b32_e32 v126, 2, v214
	v_and_b32_e32 v127, 15, v214
	v_sub_u32_e32 v126, v126, v127
	v_mul_i32_i24_e32 v126, 0x2c00, v126
	v_bfe_u32 v131, v214, 5, 1
	v_lshlrev_b32_e32 v131, 1, v131
	v_and_b32_e32 v130, 3, v214
	v_xor_b32_e32 v131, v131, v130
	v_lshrrev_b32_e32 v130, 4, v214
	v_sub_u32_e32 v131, v131, v130
	v_lshl_add_u32 v126, v131, 4, v126
	v_ashrrev_i32_e32 v131, 31, v126
	v_add_co_u32_e32 v122, vcc, v28, v126
	s_nop 1
	v_addc_co_u32_e32 v123, vcc, v29, v131, vcc
	v_add_co_u32_e32 v124, vcc, v24, v126
	s_nop 1
	v_addc_co_u32_e32 v125, vcc, v25, v131, vcc
	v_add_co_u32_e32 v14, vcc, 0xb000000, v122
	s_nop 1
	v_addc_co_u32_e32 v15, vcc, 0, v123, vcc
	v_add_co_u32_e32 v26, vcc, 0xb02c000, v122
	s_nop 1
	v_addc_co_u32_e32 v27, vcc, 0, v123, vcc
	v_add_co_u32_e32 v30, vcc, 0xb058000, v122
	s_nop 1
	v_addc_co_u32_e32 v31, vcc, 0, v123, vcc
	v_add_co_u32_e32 v70, vcc, 0xb084000, v122
	s_nop 1
	v_addc_co_u32_e32 v71, vcc, 0, v123, vcc
	v_mov_b32_e32 v98, v124
	v_mov_b32_e32 v99, v125
	v_add_co_u32_e32 v116, vcc, 0x2c000, v124
	s_nop 1
	v_addc_co_u32_e32 v117, vcc, 0, v125, vcc
	v_add_co_u32_e32 v118, vcc, 0x160000, v124
	s_nop 1
	v_addc_co_u32_e32 v119, vcc, 0, v125, vcc
	v_add_co_u32_e32 v120, vcc, 0x18c000, v124
	s_nop 1
	v_addc_co_u32_e32 v121, vcc, 0, v125, vcc
	v_readfirstlane_b32 vcc_lo, v210
	v_bfe_u32 v131, v214, 3, 1
	v_lshlrev_b32_e32 v131, 1, v131
	v_xor_b32_e32 v131, v131, v130
	v_lshlrev_b32_e32 v131, 4, v131
	v_lshl_add_u32 v131, v127, 6, v131
	s_lshr_b32 vcc_lo, vcc_lo, 6
	s_lshl_b32 vcc_lo, vcc_lo, 14
	s_mov_b32 s94, 64
	v_add_u32_e32 v130, vcc_lo, v131
	s_add_i32 m0, vcc_lo, 0x0
	s_nop 0
	global_load_lds_dwordx4 v[14:15], off
	v_lshl_add_u64 v[14:15], v[14:15], 0, s[94:95]
	s_add_i32 m0, vcc_lo, 0x400
	s_nop 0
	global_load_lds_dwordx4 v[26:27], off
	v_lshl_add_u64 v[26:27], v[26:27], 0, s[94:95]
	s_add_i32 m0, vcc_lo, 0x800
	s_nop 0
	global_load_lds_dwordx4 v[30:31], off
	v_lshl_add_u64 v[30:31], v[30:31], 0, s[94:95]
	s_add_i32 m0, vcc_lo, 0xc00
	s_nop 0
	global_load_lds_dwordx4 v[70:71], off
	v_lshl_add_u64 v[70:71], v[70:71], 0, s[94:95]
	s_add_i32 m0, vcc_lo, 0x1000
	s_nop 0
	global_load_lds_dwordx4 v[98:99], off
	v_lshl_add_u64 v[98:99], v[98:99], 0, s[94:95]
	s_add_i32 m0, vcc_lo, 0x1400
	s_nop 0
	global_load_lds_dwordx4 v[116:117], off
	v_lshl_add_u64 v[116:117], v[116:117], 0, s[94:95]
	s_add_i32 m0, vcc_lo, 0x1800
	s_nop 0
	global_load_lds_dwordx4 v[118:119], off
	v_lshl_add_u64 v[118:119], v[118:119], 0, s[94:95]
	s_add_i32 m0, vcc_lo, 0x1c00
	s_nop 0
	global_load_lds_dwordx4 v[120:121], off
	v_lshl_add_u64 v[120:121], v[120:121], 0, s[94:95]
	s_add_i32 m0, vcc_lo, 0x2000
	s_nop 0
	global_load_lds_dwordx4 v[14:15], off
	v_lshl_add_u64 v[14:15], v[14:15], 0, s[94:95]
	s_add_i32 m0, vcc_lo, 0x2400
	s_nop 0
	global_load_lds_dwordx4 v[26:27], off
	v_lshl_add_u64 v[26:27], v[26:27], 0, s[94:95]
	s_add_i32 m0, vcc_lo, 0x2800
	s_nop 0
	global_load_lds_dwordx4 v[30:31], off
	v_lshl_add_u64 v[30:31], v[30:31], 0, s[94:95]
	s_add_i32 m0, vcc_lo, 0x2c00
	s_nop 0
	global_load_lds_dwordx4 v[70:71], off
	v_lshl_add_u64 v[70:71], v[70:71], 0, s[94:95]
	s_add_i32 m0, vcc_lo, 0x3000
	s_nop 0
	global_load_lds_dwordx4 v[98:99], off
	v_lshl_add_u64 v[98:99], v[98:99], 0, s[94:95]
	s_add_i32 m0, vcc_lo, 0x3400
	s_nop 0
	global_load_lds_dwordx4 v[116:117], off
	v_lshl_add_u64 v[116:117], v[116:117], 0, s[94:95]
	s_add_i32 m0, vcc_lo, 0x3800
	s_nop 0
	global_load_lds_dwordx4 v[118:119], off
	v_lshl_add_u64 v[118:119], v[118:119], 0, s[94:95]
	s_add_i32 m0, vcc_lo, 0x3c00
	s_nop 0
	global_load_lds_dwordx4 v[120:121], off
	v_lshl_add_u64 v[120:121], v[120:121], 0, s[94:95]
	s_waitcnt vmcnt(8)
	ds_read_b128 v[80:83], v130
	ds_read_b128 v[84:87], v130 offset:1024
	ds_read_b128 v[88:91], v130 offset:2048
	ds_read_b128 v[92:95], v130 offset:3072
	ds_read_b128 v[100:103], v130 offset:4096
	ds_read_b128 v[104:107], v130 offset:5120
	ds_read_b128 v[108:111], v130 offset:6144
	ds_read_b128 v[112:115], v130 offset:7168
	s_waitcnt lgkmcnt(0)
	s_add_i32 m0, vcc_lo, 0x0
	s_nop 0
	global_load_lds_dwordx4 v[14:15], off
	v_lshl_add_u64 v[14:15], v[14:15], 0, s[94:95]
	s_add_i32 m0, vcc_lo, 0x400
	s_nop 0
	global_load_lds_dwordx4 v[26:27], off
	v_lshl_add_u64 v[26:27], v[26:27], 0, s[94:95]
	s_add_i32 m0, vcc_lo, 0x800
	s_nop 0
	global_load_lds_dwordx4 v[30:31], off
	v_lshl_add_u64 v[30:31], v[30:31], 0, s[94:95]
	s_add_i32 m0, vcc_lo, 0xc00
	s_nop 0
	global_load_lds_dwordx4 v[70:71], off
	v_lshl_add_u64 v[70:71], v[70:71], 0, s[94:95]
	s_add_i32 m0, vcc_lo, 0x1000
	s_nop 0
	global_load_lds_dwordx4 v[98:99], off
	v_lshl_add_u64 v[98:99], v[98:99], 0, s[94:95]
	s_add_i32 m0, vcc_lo, 0x1400
	s_nop 0
	global_load_lds_dwordx4 v[116:117], off
	v_lshl_add_u64 v[116:117], v[116:117], 0, s[94:95]
	s_add_i32 m0, vcc_lo, 0x1800
	s_nop 0
	global_load_lds_dwordx4 v[118:119], off
	v_lshl_add_u64 v[118:119], v[118:119], 0, s[94:95]
	s_add_i32 m0, vcc_lo, 0x1c00
	s_nop 0
	global_load_lds_dwordx4 v[120:121], off
	v_lshl_add_u64 v[120:121], v[120:121], 0, s[94:95]
	v_mfma_f32_16x16x32_bf16 v[0:3], v[100:103], v[80:83], 0
	v_mfma_f32_16x16x32_bf16 v[4:7], v[100:103], v[84:87], 0
	v_mfma_f32_16x16x32_bf16 v[8:11], v[100:103], v[88:91], 0
	v_mfma_f32_16x16x32_bf16 v[16:19], v[100:103], v[92:95], 0
	v_mfma_f32_16x16x32_bf16 v[20:23], v[104:107], v[80:83], 0
	v_mfma_f32_16x16x32_bf16 v[32:35], v[104:107], v[84:87], 0
	v_mfma_f32_16x16x32_bf16 v[36:39], v[104:107], v[88:91], 0
	v_mfma_f32_16x16x32_bf16 v[40:43], v[104:107], v[92:95], 0
	v_mfma_f32_16x16x32_bf16 v[44:47], v[108:111], v[80:83], 0
	v_mfma_f32_16x16x32_bf16 v[48:51], v[108:111], v[84:87], 0
	v_mfma_f32_16x16x32_bf16 v[52:55], v[108:111], v[88:91], 0
	v_mfma_f32_16x16x32_bf16 v[56:59], v[108:111], v[92:95], 0
	v_mfma_f32_16x16x32_bf16 v[60:63], v[112:115], v[80:83], 0
	v_mfma_f32_16x16x32_bf16 v[64:67], v[112:115], v[84:87], 0
	v_mfma_f32_16x16x32_bf16 v[72:75], v[112:115], v[88:91], 0
	v_mfma_f32_16x16x32_bf16 v[76:79], v[112:115], v[92:95], 0
	s_waitcnt vmcnt(8)
	ds_read_b128 v[80:83], v130 offset:8192
	ds_read_b128 v[84:87], v130 offset:9216
	ds_read_b128 v[88:91], v130 offset:10240
	ds_read_b128 v[92:95], v130 offset:11264
	ds_read_b128 v[100:103], v130 offset:12288
	ds_read_b128 v[104:107], v130 offset:13312
	ds_read_b128 v[108:111], v130 offset:14336
	ds_read_b128 v[112:115], v130 offset:15360
	s_waitcnt lgkmcnt(0)
	s_add_i32 m0, vcc_lo, 0x2000
	s_nop 0
	global_load_lds_dwordx4 v[14:15], off
	v_lshl_add_u64 v[14:15], v[14:15], 0, s[94:95]
	s_add_i32 m0, vcc_lo, 0x2400
	s_nop 0
	global_load_lds_dwordx4 v[26:27], off
	v_lshl_add_u64 v[26:27], v[26:27], 0, s[94:95]
	s_add_i32 m0, vcc_lo, 0x2800
	s_nop 0
	global_load_lds_dwordx4 v[30:31], off
	v_lshl_add_u64 v[30:31], v[30:31], 0, s[94:95]
	s_add_i32 m0, vcc_lo, 0x2c00
	s_nop 0
	global_load_lds_dwordx4 v[70:71], off
	v_lshl_add_u64 v[70:71], v[70:71], 0, s[94:95]
	s_add_i32 m0, vcc_lo, 0x3000
	s_nop 0
	global_load_lds_dwordx4 v[98:99], off
	v_lshl_add_u64 v[98:99], v[98:99], 0, s[94:95]
	s_add_i32 m0, vcc_lo, 0x3400
	s_nop 0
	global_load_lds_dwordx4 v[116:117], off
	v_lshl_add_u64 v[116:117], v[116:117], 0, s[94:95]
	s_add_i32 m0, vcc_lo, 0x3800
	s_nop 0
	global_load_lds_dwordx4 v[118:119], off
	v_lshl_add_u64 v[118:119], v[118:119], 0, s[94:95]
	s_add_i32 m0, vcc_lo, 0x3c00
	s_nop 0
	global_load_lds_dwordx4 v[120:121], off
	v_lshl_add_u64 v[120:121], v[120:121], 0, s[94:95]
	v_mfma_f32_16x16x32_bf16 v[0:3], v[100:103], v[80:83], v[0:3]
	v_mfma_f32_16x16x32_bf16 v[4:7], v[100:103], v[84:87], v[4:7]
	v_mfma_f32_16x16x32_bf16 v[8:11], v[100:103], v[88:91], v[8:11]
	v_mfma_f32_16x16x32_bf16 v[16:19], v[100:103], v[92:95], v[16:19]
	v_mfma_f32_16x16x32_bf16 v[20:23], v[104:107], v[80:83], v[20:23]
	v_mfma_f32_16x16x32_bf16 v[32:35], v[104:107], v[84:87], v[32:35]
	v_mfma_f32_16x16x32_bf16 v[36:39], v[104:107], v[88:91], v[36:39]
	v_mfma_f32_16x16x32_bf16 v[40:43], v[104:107], v[92:95], v[40:43]
	v_mfma_f32_16x16x32_bf16 v[44:47], v[108:111], v[80:83], v[44:47]
	v_mfma_f32_16x16x32_bf16 v[48:51], v[108:111], v[84:87], v[48:51]
	v_mfma_f32_16x16x32_bf16 v[52:55], v[108:111], v[88:91], v[52:55]
	v_mfma_f32_16x16x32_bf16 v[56:59], v[108:111], v[92:95], v[56:59]
	v_mfma_f32_16x16x32_bf16 v[60:63], v[112:115], v[80:83], v[60:63]
	v_mfma_f32_16x16x32_bf16 v[64:67], v[112:115], v[84:87], v[64:67]
	v_mfma_f32_16x16x32_bf16 v[72:75], v[112:115], v[88:91], v[72:75]
	v_mfma_f32_16x16x32_bf16 v[76:79], v[112:115], v[92:95], v[76:79]
	s_waitcnt vmcnt(8)
	ds_read_b128 v[80:83], v130
	ds_read_b128 v[84:87], v130 offset:1024
	ds_read_b128 v[88:91], v130 offset:2048
	ds_read_b128 v[92:95], v130 offset:3072
	ds_read_b128 v[100:103], v130 offset:4096
	ds_read_b128 v[104:107], v130 offset:5120
	ds_read_b128 v[108:111], v130 offset:6144
	ds_read_b128 v[112:115], v130 offset:7168
	s_waitcnt lgkmcnt(0)
	s_add_i32 m0, vcc_lo, 0x0
	s_nop 0
	global_load_lds_dwordx4 v[14:15], off
	v_lshl_add_u64 v[14:15], v[14:15], 0, s[94:95]
	s_add_i32 m0, vcc_lo, 0x400
	s_nop 0
	global_load_lds_dwordx4 v[26:27], off
	v_lshl_add_u64 v[26:27], v[26:27], 0, s[94:95]
	s_add_i32 m0, vcc_lo, 0x800
	s_nop 0
	global_load_lds_dwordx4 v[30:31], off
	v_lshl_add_u64 v[30:31], v[30:31], 0, s[94:95]
	s_add_i32 m0, vcc_lo, 0xc00
	s_nop 0
	global_load_lds_dwordx4 v[70:71], off
	v_lshl_add_u64 v[70:71], v[70:71], 0, s[94:95]
	s_add_i32 m0, vcc_lo, 0x1000
	s_nop 0
	global_load_lds_dwordx4 v[98:99], off
	v_lshl_add_u64 v[98:99], v[98:99], 0, s[94:95]
	s_add_i32 m0, vcc_lo, 0x1400
	s_nop 0
	global_load_lds_dwordx4 v[116:117], off
	v_lshl_add_u64 v[116:117], v[116:117], 0, s[94:95]
	s_add_i32 m0, vcc_lo, 0x1800
	s_nop 0
	global_load_lds_dwordx4 v[118:119], off
	v_lshl_add_u64 v[118:119], v[118:119], 0, s[94:95]
	s_add_i32 m0, vcc_lo, 0x1c00
	s_nop 0
	global_load_lds_dwordx4 v[120:121], off
	v_lshl_add_u64 v[120:121], v[120:121], 0, s[94:95]
	v_mfma_f32_16x16x32_bf16 v[0:3], v[100:103], v[80:83], v[0:3]
	v_mfma_f32_16x16x32_bf16 v[4:7], v[100:103], v[84:87], v[4:7]
	v_mfma_f32_16x16x32_bf16 v[8:11], v[100:103], v[88:91], v[8:11]
	v_mfma_f32_16x16x32_bf16 v[16:19], v[100:103], v[92:95], v[16:19]
	v_mfma_f32_16x16x32_bf16 v[20:23], v[104:107], v[80:83], v[20:23]
	v_mfma_f32_16x16x32_bf16 v[32:35], v[104:107], v[84:87], v[32:35]
	v_mfma_f32_16x16x32_bf16 v[36:39], v[104:107], v[88:91], v[36:39]
	v_mfma_f32_16x16x32_bf16 v[40:43], v[104:107], v[92:95], v[40:43]
	v_mfma_f32_16x16x32_bf16 v[44:47], v[108:111], v[80:83], v[44:47]
	v_mfma_f32_16x16x32_bf16 v[48:51], v[108:111], v[84:87], v[48:51]
	v_mfma_f32_16x16x32_bf16 v[52:55], v[108:111], v[88:91], v[52:55]
	v_mfma_f32_16x16x32_bf16 v[56:59], v[108:111], v[92:95], v[56:59]
	v_mfma_f32_16x16x32_bf16 v[60:63], v[112:115], v[80:83], v[60:63]
	v_mfma_f32_16x16x32_bf16 v[64:67], v[112:115], v[84:87], v[64:67]
	v_mfma_f32_16x16x32_bf16 v[72:75], v[112:115], v[88:91], v[72:75]
	v_mfma_f32_16x16x32_bf16 v[76:79], v[112:115], v[92:95], v[76:79]
	s_waitcnt vmcnt(8)
	ds_read_b128 v[80:83], v130 offset:8192
	ds_read_b128 v[84:87], v130 offset:9216
	ds_read_b128 v[88:91], v130 offset:10240
	ds_read_b128 v[92:95], v130 offset:11264
	ds_read_b128 v[100:103], v130 offset:12288
	ds_read_b128 v[104:107], v130 offset:13312
	ds_read_b128 v[108:111], v130 offset:14336
	ds_read_b128 v[112:115], v130 offset:15360
	s_waitcnt lgkmcnt(0)
	s_add_i32 m0, vcc_lo, 0x2000
	s_nop 0
	global_load_lds_dwordx4 v[14:15], off
	v_lshl_add_u64 v[14:15], v[14:15], 0, s[94:95]
	s_add_i32 m0, vcc_lo, 0x2400
	s_nop 0
	global_load_lds_dwordx4 v[26:27], off
	v_lshl_add_u64 v[26:27], v[26:27], 0, s[94:95]
	s_add_i32 m0, vcc_lo, 0x2800
	s_nop 0
	global_load_lds_dwordx4 v[30:31], off
	v_lshl_add_u64 v[30:31], v[30:31], 0, s[94:95]
	s_add_i32 m0, vcc_lo, 0x2c00
	s_nop 0
	global_load_lds_dwordx4 v[70:71], off
	v_lshl_add_u64 v[70:71], v[70:71], 0, s[94:95]
	s_add_i32 m0, vcc_lo, 0x3000
	s_nop 0
	global_load_lds_dwordx4 v[98:99], off
	v_lshl_add_u64 v[98:99], v[98:99], 0, s[94:95]
	s_add_i32 m0, vcc_lo, 0x3400
	s_nop 0
	global_load_lds_dwordx4 v[116:117], off
	v_lshl_add_u64 v[116:117], v[116:117], 0, s[94:95]
	s_add_i32 m0, vcc_lo, 0x3800
	s_nop 0
	global_load_lds_dwordx4 v[118:119], off
	v_lshl_add_u64 v[118:119], v[118:119], 0, s[94:95]
	s_add_i32 m0, vcc_lo, 0x3c00
	s_nop 0
	global_load_lds_dwordx4 v[120:121], off
	v_lshl_add_u64 v[120:121], v[120:121], 0, s[94:95]
	v_mfma_f32_16x16x32_bf16 v[0:3], v[100:103], v[80:83], v[0:3]
	v_mfma_f32_16x16x32_bf16 v[4:7], v[100:103], v[84:87], v[4:7]
	v_mfma_f32_16x16x32_bf16 v[8:11], v[100:103], v[88:91], v[8:11]
	v_mfma_f32_16x16x32_bf16 v[16:19], v[100:103], v[92:95], v[16:19]
	v_mfma_f32_16x16x32_bf16 v[20:23], v[104:107], v[80:83], v[20:23]
	v_mfma_f32_16x16x32_bf16 v[32:35], v[104:107], v[84:87], v[32:35]
	v_mfma_f32_16x16x32_bf16 v[36:39], v[104:107], v[88:91], v[36:39]
	v_mfma_f32_16x16x32_bf16 v[40:43], v[104:107], v[92:95], v[40:43]
	v_mfma_f32_16x16x32_bf16 v[44:47], v[108:111], v[80:83], v[44:47]
	v_mfma_f32_16x16x32_bf16 v[48:51], v[108:111], v[84:87], v[48:51]
	v_mfma_f32_16x16x32_bf16 v[52:55], v[108:111], v[88:91], v[52:55]
	v_mfma_f32_16x16x32_bf16 v[56:59], v[108:111], v[92:95], v[56:59]
	v_mfma_f32_16x16x32_bf16 v[60:63], v[112:115], v[80:83], v[60:63]
	v_mfma_f32_16x16x32_bf16 v[64:67], v[112:115], v[84:87], v[64:67]
	v_mfma_f32_16x16x32_bf16 v[72:75], v[112:115], v[88:91], v[72:75]
	v_mfma_f32_16x16x32_bf16 v[76:79], v[112:115], v[92:95], v[76:79]
	s_waitcnt vmcnt(8)
	ds_read_b128 v[80:83], v130
	ds_read_b128 v[84:87], v130 offset:1024
	ds_read_b128 v[88:91], v130 offset:2048
	ds_read_b128 v[92:95], v130 offset:3072
	ds_read_b128 v[100:103], v130 offset:4096
	ds_read_b128 v[104:107], v130 offset:5120
	ds_read_b128 v[108:111], v130 offset:6144
	ds_read_b128 v[112:115], v130 offset:7168
	s_waitcnt lgkmcnt(0)
	s_add_i32 m0, vcc_lo, 0x0
	s_nop 0
	global_load_lds_dwordx4 v[14:15], off
	v_lshl_add_u64 v[14:15], v[14:15], 0, s[94:95]
	s_add_i32 m0, vcc_lo, 0x400
	s_nop 0
	global_load_lds_dwordx4 v[26:27], off
	v_lshl_add_u64 v[26:27], v[26:27], 0, s[94:95]
	s_add_i32 m0, vcc_lo, 0x800
	s_nop 0
	global_load_lds_dwordx4 v[30:31], off
	v_lshl_add_u64 v[30:31], v[30:31], 0, s[94:95]
	s_add_i32 m0, vcc_lo, 0xc00
	s_nop 0
	global_load_lds_dwordx4 v[70:71], off
	v_lshl_add_u64 v[70:71], v[70:71], 0, s[94:95]
	s_add_i32 m0, vcc_lo, 0x1000
	s_nop 0
	global_load_lds_dwordx4 v[98:99], off
	v_lshl_add_u64 v[98:99], v[98:99], 0, s[94:95]
	s_add_i32 m0, vcc_lo, 0x1400
	s_nop 0
	global_load_lds_dwordx4 v[116:117], off
	v_lshl_add_u64 v[116:117], v[116:117], 0, s[94:95]
	s_add_i32 m0, vcc_lo, 0x1800
	s_nop 0
	global_load_lds_dwordx4 v[118:119], off
	v_lshl_add_u64 v[118:119], v[118:119], 0, s[94:95]
	s_add_i32 m0, vcc_lo, 0x1c00
	s_nop 0
	global_load_lds_dwordx4 v[120:121], off
	v_lshl_add_u64 v[120:121], v[120:121], 0, s[94:95]
	v_mfma_f32_16x16x32_bf16 v[0:3], v[100:103], v[80:83], v[0:3]
	v_mfma_f32_16x16x32_bf16 v[4:7], v[100:103], v[84:87], v[4:7]
	v_mfma_f32_16x16x32_bf16 v[8:11], v[100:103], v[88:91], v[8:11]
	v_mfma_f32_16x16x32_bf16 v[16:19], v[100:103], v[92:95], v[16:19]
	v_mfma_f32_16x16x32_bf16 v[20:23], v[104:107], v[80:83], v[20:23]
	v_mfma_f32_16x16x32_bf16 v[32:35], v[104:107], v[84:87], v[32:35]
	v_mfma_f32_16x16x32_bf16 v[36:39], v[104:107], v[88:91], v[36:39]
	v_mfma_f32_16x16x32_bf16 v[40:43], v[104:107], v[92:95], v[40:43]
	v_mfma_f32_16x16x32_bf16 v[44:47], v[108:111], v[80:83], v[44:47]
	v_mfma_f32_16x16x32_bf16 v[48:51], v[108:111], v[84:87], v[48:51]
	v_mfma_f32_16x16x32_bf16 v[52:55], v[108:111], v[88:91], v[52:55]
	v_mfma_f32_16x16x32_bf16 v[56:59], v[108:111], v[92:95], v[56:59]
	v_mfma_f32_16x16x32_bf16 v[60:63], v[112:115], v[80:83], v[60:63]
	v_mfma_f32_16x16x32_bf16 v[64:67], v[112:115], v[84:87], v[64:67]
	v_mfma_f32_16x16x32_bf16 v[72:75], v[112:115], v[88:91], v[72:75]
	v_mfma_f32_16x16x32_bf16 v[76:79], v[112:115], v[92:95], v[76:79]
	s_waitcnt vmcnt(8)
	ds_read_b128 v[80:83], v130 offset:8192
	ds_read_b128 v[84:87], v130 offset:9216
	ds_read_b128 v[88:91], v130 offset:10240
	ds_read_b128 v[92:95], v130 offset:11264
	ds_read_b128 v[100:103], v130 offset:12288
	ds_read_b128 v[104:107], v130 offset:13312
	ds_read_b128 v[108:111], v130 offset:14336
	ds_read_b128 v[112:115], v130 offset:15360
	s_waitcnt lgkmcnt(0)
	s_add_i32 m0, vcc_lo, 0x2000
	s_nop 0
	global_load_lds_dwordx4 v[14:15], off
	v_lshl_add_u64 v[14:15], v[14:15], 0, s[94:95]
	s_add_i32 m0, vcc_lo, 0x2400
	s_nop 0
	global_load_lds_dwordx4 v[26:27], off
	v_lshl_add_u64 v[26:27], v[26:27], 0, s[94:95]
	s_add_i32 m0, vcc_lo, 0x2800
	s_nop 0
	global_load_lds_dwordx4 v[30:31], off
	v_lshl_add_u64 v[30:31], v[30:31], 0, s[94:95]
	s_add_i32 m0, vcc_lo, 0x2c00
	s_nop 0
	global_load_lds_dwordx4 v[70:71], off
	v_lshl_add_u64 v[70:71], v[70:71], 0, s[94:95]
	s_add_i32 m0, vcc_lo, 0x3000
	s_nop 0
	global_load_lds_dwordx4 v[98:99], off
	v_lshl_add_u64 v[98:99], v[98:99], 0, s[94:95]
	s_add_i32 m0, vcc_lo, 0x3400
	s_nop 0
	global_load_lds_dwordx4 v[116:117], off
	v_lshl_add_u64 v[116:117], v[116:117], 0, s[94:95]
	s_add_i32 m0, vcc_lo, 0x3800
	s_nop 0
	global_load_lds_dwordx4 v[118:119], off
	v_lshl_add_u64 v[118:119], v[118:119], 0, s[94:95]
	s_add_i32 m0, vcc_lo, 0x3c00
	s_nop 0
	global_load_lds_dwordx4 v[120:121], off
	v_lshl_add_u64 v[120:121], v[120:121], 0, s[94:95]
	v_mfma_f32_16x16x32_bf16 v[0:3], v[100:103], v[80:83], v[0:3]
	v_mfma_f32_16x16x32_bf16 v[4:7], v[100:103], v[84:87], v[4:7]
	v_mfma_f32_16x16x32_bf16 v[8:11], v[100:103], v[88:91], v[8:11]
	v_mfma_f32_16x16x32_bf16 v[16:19], v[100:103], v[92:95], v[16:19]
	v_mfma_f32_16x16x32_bf16 v[20:23], v[104:107], v[80:83], v[20:23]
	v_mfma_f32_16x16x32_bf16 v[32:35], v[104:107], v[84:87], v[32:35]
	v_mfma_f32_16x16x32_bf16 v[36:39], v[104:107], v[88:91], v[36:39]
	v_mfma_f32_16x16x32_bf16 v[40:43], v[104:107], v[92:95], v[40:43]
	v_mfma_f32_16x16x32_bf16 v[44:47], v[108:111], v[80:83], v[44:47]
	v_mfma_f32_16x16x32_bf16 v[48:51], v[108:111], v[84:87], v[48:51]
	v_mfma_f32_16x16x32_bf16 v[52:55], v[108:111], v[88:91], v[52:55]
	v_mfma_f32_16x16x32_bf16 v[56:59], v[108:111], v[92:95], v[56:59]
	v_mfma_f32_16x16x32_bf16 v[60:63], v[112:115], v[80:83], v[60:63]
	v_mfma_f32_16x16x32_bf16 v[64:67], v[112:115], v[84:87], v[64:67]
	v_mfma_f32_16x16x32_bf16 v[72:75], v[112:115], v[88:91], v[72:75]
	v_mfma_f32_16x16x32_bf16 v[76:79], v[112:115], v[92:95], v[76:79]
	s_waitcnt vmcnt(8)
	ds_read_b128 v[80:83], v130
	ds_read_b128 v[84:87], v130 offset:1024
	ds_read_b128 v[88:91], v130 offset:2048
	ds_read_b128 v[92:95], v130 offset:3072
	ds_read_b128 v[100:103], v130 offset:4096
	ds_read_b128 v[104:107], v130 offset:5120
	ds_read_b128 v[108:111], v130 offset:6144
	ds_read_b128 v[112:115], v130 offset:7168
	s_waitcnt lgkmcnt(0)
	s_add_i32 m0, vcc_lo, 0x0
	s_nop 0
	global_load_lds_dwordx4 v[14:15], off
	v_lshl_add_u64 v[14:15], v[14:15], 0, s[94:95]
	s_add_i32 m0, vcc_lo, 0x400
	s_nop 0
	global_load_lds_dwordx4 v[26:27], off
	v_lshl_add_u64 v[26:27], v[26:27], 0, s[94:95]
	s_add_i32 m0, vcc_lo, 0x800
	s_nop 0
	global_load_lds_dwordx4 v[30:31], off
	v_lshl_add_u64 v[30:31], v[30:31], 0, s[94:95]
	s_add_i32 m0, vcc_lo, 0xc00
	s_nop 0
	global_load_lds_dwordx4 v[70:71], off
	v_lshl_add_u64 v[70:71], v[70:71], 0, s[94:95]
	s_add_i32 m0, vcc_lo, 0x1000
	s_nop 0
	global_load_lds_dwordx4 v[98:99], off
	v_lshl_add_u64 v[98:99], v[98:99], 0, s[94:95]
	s_add_i32 m0, vcc_lo, 0x1400
	s_nop 0
	global_load_lds_dwordx4 v[116:117], off
	v_lshl_add_u64 v[116:117], v[116:117], 0, s[94:95]
	s_add_i32 m0, vcc_lo, 0x1800
	s_nop 0
	global_load_lds_dwordx4 v[118:119], off
	v_lshl_add_u64 v[118:119], v[118:119], 0, s[94:95]
	s_add_i32 m0, vcc_lo, 0x1c00
	s_nop 0
	global_load_lds_dwordx4 v[120:121], off
	v_lshl_add_u64 v[120:121], v[120:121], 0, s[94:95]
	v_mfma_f32_16x16x32_bf16 v[0:3], v[100:103], v[80:83], v[0:3]
	v_mfma_f32_16x16x32_bf16 v[4:7], v[100:103], v[84:87], v[4:7]
	v_mfma_f32_16x16x32_bf16 v[8:11], v[100:103], v[88:91], v[8:11]
	v_mfma_f32_16x16x32_bf16 v[16:19], v[100:103], v[92:95], v[16:19]
	v_mfma_f32_16x16x32_bf16 v[20:23], v[104:107], v[80:83], v[20:23]
	v_mfma_f32_16x16x32_bf16 v[32:35], v[104:107], v[84:87], v[32:35]
	v_mfma_f32_16x16x32_bf16 v[36:39], v[104:107], v[88:91], v[36:39]
	v_mfma_f32_16x16x32_bf16 v[40:43], v[104:107], v[92:95], v[40:43]
	v_mfma_f32_16x16x32_bf16 v[44:47], v[108:111], v[80:83], v[44:47]
	v_mfma_f32_16x16x32_bf16 v[48:51], v[108:111], v[84:87], v[48:51]
	v_mfma_f32_16x16x32_bf16 v[52:55], v[108:111], v[88:91], v[52:55]
	v_mfma_f32_16x16x32_bf16 v[56:59], v[108:111], v[92:95], v[56:59]
	v_mfma_f32_16x16x32_bf16 v[60:63], v[112:115], v[80:83], v[60:63]
	v_mfma_f32_16x16x32_bf16 v[64:67], v[112:115], v[84:87], v[64:67]
	v_mfma_f32_16x16x32_bf16 v[72:75], v[112:115], v[88:91], v[72:75]
	v_mfma_f32_16x16x32_bf16 v[76:79], v[112:115], v[92:95], v[76:79]
	s_waitcnt vmcnt(8)
	ds_read_b128 v[80:83], v130 offset:8192
	ds_read_b128 v[84:87], v130 offset:9216
	ds_read_b128 v[88:91], v130 offset:10240
	ds_read_b128 v[92:95], v130 offset:11264
	ds_read_b128 v[100:103], v130 offset:12288
	ds_read_b128 v[104:107], v130 offset:13312
	ds_read_b128 v[108:111], v130 offset:14336
	ds_read_b128 v[112:115], v130 offset:15360
	s_waitcnt lgkmcnt(0)
	s_add_i32 m0, vcc_lo, 0x2000
	s_nop 0
	global_load_lds_dwordx4 v[14:15], off
	v_lshl_add_u64 v[14:15], v[14:15], 0, s[94:95]
	s_add_i32 m0, vcc_lo, 0x2400
	s_nop 0
	global_load_lds_dwordx4 v[26:27], off
	v_lshl_add_u64 v[26:27], v[26:27], 0, s[94:95]
	s_add_i32 m0, vcc_lo, 0x2800
	s_nop 0
	global_load_lds_dwordx4 v[30:31], off
	v_lshl_add_u64 v[30:31], v[30:31], 0, s[94:95]
	s_add_i32 m0, vcc_lo, 0x2c00
	s_nop 0
	global_load_lds_dwordx4 v[70:71], off
	v_lshl_add_u64 v[70:71], v[70:71], 0, s[94:95]
	s_add_i32 m0, vcc_lo, 0x3000
	s_nop 0
	global_load_lds_dwordx4 v[98:99], off
	v_lshl_add_u64 v[98:99], v[98:99], 0, s[94:95]
	s_add_i32 m0, vcc_lo, 0x3400
	s_nop 0
	global_load_lds_dwordx4 v[116:117], off
	v_lshl_add_u64 v[116:117], v[116:117], 0, s[94:95]
	s_add_i32 m0, vcc_lo, 0x3800
	s_nop 0
	global_load_lds_dwordx4 v[118:119], off
	v_lshl_add_u64 v[118:119], v[118:119], 0, s[94:95]
	s_add_i32 m0, vcc_lo, 0x3c00
	s_nop 0
	global_load_lds_dwordx4 v[120:121], off
	v_lshl_add_u64 v[120:121], v[120:121], 0, s[94:95]
	v_mfma_f32_16x16x32_bf16 v[0:3], v[100:103], v[80:83], v[0:3]
	v_mfma_f32_16x16x32_bf16 v[4:7], v[100:103], v[84:87], v[4:7]
	v_mfma_f32_16x16x32_bf16 v[8:11], v[100:103], v[88:91], v[8:11]
	v_mfma_f32_16x16x32_bf16 v[16:19], v[100:103], v[92:95], v[16:19]
	v_mfma_f32_16x16x32_bf16 v[20:23], v[104:107], v[80:83], v[20:23]
	v_mfma_f32_16x16x32_bf16 v[32:35], v[104:107], v[84:87], v[32:35]
	v_mfma_f32_16x16x32_bf16 v[36:39], v[104:107], v[88:91], v[36:39]
	v_mfma_f32_16x16x32_bf16 v[40:43], v[104:107], v[92:95], v[40:43]
	v_mfma_f32_16x16x32_bf16 v[44:47], v[108:111], v[80:83], v[44:47]
	v_mfma_f32_16x16x32_bf16 v[48:51], v[108:111], v[84:87], v[48:51]
	v_mfma_f32_16x16x32_bf16 v[52:55], v[108:111], v[88:91], v[52:55]
	v_mfma_f32_16x16x32_bf16 v[56:59], v[108:111], v[92:95], v[56:59]
	v_mfma_f32_16x16x32_bf16 v[60:63], v[112:115], v[80:83], v[60:63]
	v_mfma_f32_16x16x32_bf16 v[64:67], v[112:115], v[84:87], v[64:67]
	v_mfma_f32_16x16x32_bf16 v[72:75], v[112:115], v[88:91], v[72:75]
	v_mfma_f32_16x16x32_bf16 v[76:79], v[112:115], v[92:95], v[76:79]
	s_waitcnt vmcnt(8)
	ds_read_b128 v[80:83], v130
	ds_read_b128 v[84:87], v130 offset:1024
	ds_read_b128 v[88:91], v130 offset:2048
	ds_read_b128 v[92:95], v130 offset:3072
	ds_read_b128 v[100:103], v130 offset:4096
	ds_read_b128 v[104:107], v130 offset:5120
	ds_read_b128 v[108:111], v130 offset:6144
	ds_read_b128 v[112:115], v130 offset:7168
	s_waitcnt lgkmcnt(0)
	s_add_i32 m0, vcc_lo, 0x0
	s_nop 0
	global_load_lds_dwordx4 v[14:15], off
	v_lshl_add_u64 v[14:15], v[14:15], 0, s[94:95]
	s_add_i32 m0, vcc_lo, 0x400
	s_nop 0
	global_load_lds_dwordx4 v[26:27], off
	v_lshl_add_u64 v[26:27], v[26:27], 0, s[94:95]
	s_add_i32 m0, vcc_lo, 0x800
	s_nop 0
	global_load_lds_dwordx4 v[30:31], off
	v_lshl_add_u64 v[30:31], v[30:31], 0, s[94:95]
	s_add_i32 m0, vcc_lo, 0xc00
	s_nop 0
	global_load_lds_dwordx4 v[70:71], off
	v_lshl_add_u64 v[70:71], v[70:71], 0, s[94:95]
	s_add_i32 m0, vcc_lo, 0x1000
	s_nop 0
	global_load_lds_dwordx4 v[98:99], off
	v_lshl_add_u64 v[98:99], v[98:99], 0, s[94:95]
	s_add_i32 m0, vcc_lo, 0x1400
	s_nop 0
	global_load_lds_dwordx4 v[116:117], off
	v_lshl_add_u64 v[116:117], v[116:117], 0, s[94:95]
	s_add_i32 m0, vcc_lo, 0x1800
	s_nop 0
	global_load_lds_dwordx4 v[118:119], off
	v_lshl_add_u64 v[118:119], v[118:119], 0, s[94:95]
	s_add_i32 m0, vcc_lo, 0x1c00
	s_nop 0
	global_load_lds_dwordx4 v[120:121], off
	v_lshl_add_u64 v[120:121], v[120:121], 0, s[94:95]
	v_mfma_f32_16x16x32_bf16 v[0:3], v[100:103], v[80:83], v[0:3]
	v_mfma_f32_16x16x32_bf16 v[4:7], v[100:103], v[84:87], v[4:7]
	v_mfma_f32_16x16x32_bf16 v[8:11], v[100:103], v[88:91], v[8:11]
	v_mfma_f32_16x16x32_bf16 v[16:19], v[100:103], v[92:95], v[16:19]
	v_mfma_f32_16x16x32_bf16 v[20:23], v[104:107], v[80:83], v[20:23]
	v_mfma_f32_16x16x32_bf16 v[32:35], v[104:107], v[84:87], v[32:35]
	v_mfma_f32_16x16x32_bf16 v[36:39], v[104:107], v[88:91], v[36:39]
	v_mfma_f32_16x16x32_bf16 v[40:43], v[104:107], v[92:95], v[40:43]
	v_mfma_f32_16x16x32_bf16 v[44:47], v[108:111], v[80:83], v[44:47]
	v_mfma_f32_16x16x32_bf16 v[48:51], v[108:111], v[84:87], v[48:51]
	v_mfma_f32_16x16x32_bf16 v[52:55], v[108:111], v[88:91], v[52:55]
	v_mfma_f32_16x16x32_bf16 v[56:59], v[108:111], v[92:95], v[56:59]
	v_mfma_f32_16x16x32_bf16 v[60:63], v[112:115], v[80:83], v[60:63]
	v_mfma_f32_16x16x32_bf16 v[64:67], v[112:115], v[84:87], v[64:67]
	v_mfma_f32_16x16x32_bf16 v[72:75], v[112:115], v[88:91], v[72:75]
	v_mfma_f32_16x16x32_bf16 v[76:79], v[112:115], v[92:95], v[76:79]
	s_waitcnt vmcnt(8)
	ds_read_b128 v[80:83], v130 offset:8192
	ds_read_b128 v[84:87], v130 offset:9216
	ds_read_b128 v[88:91], v130 offset:10240
	ds_read_b128 v[92:95], v130 offset:11264
	ds_read_b128 v[100:103], v130 offset:12288
	ds_read_b128 v[104:107], v130 offset:13312
	ds_read_b128 v[108:111], v130 offset:14336
	ds_read_b128 v[112:115], v130 offset:15360
	s_waitcnt lgkmcnt(0)
	s_add_i32 m0, vcc_lo, 0x2000
	s_nop 0
	global_load_lds_dwordx4 v[14:15], off
	v_lshl_add_u64 v[14:15], v[14:15], 0, s[94:95]
	s_add_i32 m0, vcc_lo, 0x2400
	s_nop 0
	global_load_lds_dwordx4 v[26:27], off
	v_lshl_add_u64 v[26:27], v[26:27], 0, s[94:95]
	s_add_i32 m0, vcc_lo, 0x2800
	s_nop 0
	global_load_lds_dwordx4 v[30:31], off
	v_lshl_add_u64 v[30:31], v[30:31], 0, s[94:95]
	s_add_i32 m0, vcc_lo, 0x2c00
	s_nop 0
	global_load_lds_dwordx4 v[70:71], off
	v_lshl_add_u64 v[70:71], v[70:71], 0, s[94:95]
	s_add_i32 m0, vcc_lo, 0x3000
	s_nop 0
	global_load_lds_dwordx4 v[98:99], off
	v_lshl_add_u64 v[98:99], v[98:99], 0, s[94:95]
	s_add_i32 m0, vcc_lo, 0x3400
	s_nop 0
	global_load_lds_dwordx4 v[116:117], off
	v_lshl_add_u64 v[116:117], v[116:117], 0, s[94:95]
	s_add_i32 m0, vcc_lo, 0x3800
	s_nop 0
	global_load_lds_dwordx4 v[118:119], off
	v_lshl_add_u64 v[118:119], v[118:119], 0, s[94:95]
	s_add_i32 m0, vcc_lo, 0x3c00
	s_nop 0
	global_load_lds_dwordx4 v[120:121], off
	v_lshl_add_u64 v[120:121], v[120:121], 0, s[94:95]
	v_mfma_f32_16x16x32_bf16 v[0:3], v[100:103], v[80:83], v[0:3]
	v_mfma_f32_16x16x32_bf16 v[4:7], v[100:103], v[84:87], v[4:7]
	v_mfma_f32_16x16x32_bf16 v[8:11], v[100:103], v[88:91], v[8:11]
	v_mfma_f32_16x16x32_bf16 v[16:19], v[100:103], v[92:95], v[16:19]
	v_mfma_f32_16x16x32_bf16 v[20:23], v[104:107], v[80:83], v[20:23]
	v_mfma_f32_16x16x32_bf16 v[32:35], v[104:107], v[84:87], v[32:35]
	v_mfma_f32_16x16x32_bf16 v[36:39], v[104:107], v[88:91], v[36:39]
	v_mfma_f32_16x16x32_bf16 v[40:43], v[104:107], v[92:95], v[40:43]
	v_mfma_f32_16x16x32_bf16 v[44:47], v[108:111], v[80:83], v[44:47]
	v_mfma_f32_16x16x32_bf16 v[48:51], v[108:111], v[84:87], v[48:51]
	v_mfma_f32_16x16x32_bf16 v[52:55], v[108:111], v[88:91], v[52:55]
	v_mfma_f32_16x16x32_bf16 v[56:59], v[108:111], v[92:95], v[56:59]
	v_mfma_f32_16x16x32_bf16 v[60:63], v[112:115], v[80:83], v[60:63]
	v_mfma_f32_16x16x32_bf16 v[64:67], v[112:115], v[84:87], v[64:67]
	v_mfma_f32_16x16x32_bf16 v[72:75], v[112:115], v[88:91], v[72:75]
	v_mfma_f32_16x16x32_bf16 v[76:79], v[112:115], v[92:95], v[76:79]
	s_waitcnt vmcnt(8)
	ds_read_b128 v[80:83], v130
	ds_read_b128 v[84:87], v130 offset:1024
	ds_read_b128 v[88:91], v130 offset:2048
	ds_read_b128 v[92:95], v130 offset:3072
	ds_read_b128 v[100:103], v130 offset:4096
	ds_read_b128 v[104:107], v130 offset:5120
	ds_read_b128 v[108:111], v130 offset:6144
	ds_read_b128 v[112:115], v130 offset:7168
	s_waitcnt lgkmcnt(0)
	s_add_i32 m0, vcc_lo, 0x0
	s_nop 0
	global_load_lds_dwordx4 v[14:15], off
	v_lshl_add_u64 v[14:15], v[14:15], 0, s[94:95]
	s_add_i32 m0, vcc_lo, 0x400
	s_nop 0
	global_load_lds_dwordx4 v[26:27], off
	v_lshl_add_u64 v[26:27], v[26:27], 0, s[94:95]
	s_add_i32 m0, vcc_lo, 0x800
	s_nop 0
	global_load_lds_dwordx4 v[30:31], off
	v_lshl_add_u64 v[30:31], v[30:31], 0, s[94:95]
	s_add_i32 m0, vcc_lo, 0xc00
	s_nop 0
	global_load_lds_dwordx4 v[70:71], off
	v_lshl_add_u64 v[70:71], v[70:71], 0, s[94:95]
	s_add_i32 m0, vcc_lo, 0x1000
	s_nop 0
	global_load_lds_dwordx4 v[98:99], off
	v_lshl_add_u64 v[98:99], v[98:99], 0, s[94:95]
	s_add_i32 m0, vcc_lo, 0x1400
	s_nop 0
	global_load_lds_dwordx4 v[116:117], off
	v_lshl_add_u64 v[116:117], v[116:117], 0, s[94:95]
	s_add_i32 m0, vcc_lo, 0x1800
	s_nop 0
	global_load_lds_dwordx4 v[118:119], off
	v_lshl_add_u64 v[118:119], v[118:119], 0, s[94:95]
	s_add_i32 m0, vcc_lo, 0x1c00
	s_nop 0
	global_load_lds_dwordx4 v[120:121], off
	v_lshl_add_u64 v[120:121], v[120:121], 0, s[94:95]
	v_mfma_f32_16x16x32_bf16 v[0:3], v[100:103], v[80:83], v[0:3]
	v_mfma_f32_16x16x32_bf16 v[4:7], v[100:103], v[84:87], v[4:7]
	v_mfma_f32_16x16x32_bf16 v[8:11], v[100:103], v[88:91], v[8:11]
	v_mfma_f32_16x16x32_bf16 v[16:19], v[100:103], v[92:95], v[16:19]
	v_mfma_f32_16x16x32_bf16 v[20:23], v[104:107], v[80:83], v[20:23]
	v_mfma_f32_16x16x32_bf16 v[32:35], v[104:107], v[84:87], v[32:35]
	v_mfma_f32_16x16x32_bf16 v[36:39], v[104:107], v[88:91], v[36:39]
	v_mfma_f32_16x16x32_bf16 v[40:43], v[104:107], v[92:95], v[40:43]
	v_mfma_f32_16x16x32_bf16 v[44:47], v[108:111], v[80:83], v[44:47]
	v_mfma_f32_16x16x32_bf16 v[48:51], v[108:111], v[84:87], v[48:51]
	v_mfma_f32_16x16x32_bf16 v[52:55], v[108:111], v[88:91], v[52:55]
	v_mfma_f32_16x16x32_bf16 v[56:59], v[108:111], v[92:95], v[56:59]
	v_mfma_f32_16x16x32_bf16 v[60:63], v[112:115], v[80:83], v[60:63]
	v_mfma_f32_16x16x32_bf16 v[64:67], v[112:115], v[84:87], v[64:67]
	v_mfma_f32_16x16x32_bf16 v[72:75], v[112:115], v[88:91], v[72:75]
	v_mfma_f32_16x16x32_bf16 v[76:79], v[112:115], v[92:95], v[76:79]
	s_waitcnt vmcnt(8)
	ds_read_b128 v[80:83], v130 offset:8192
	ds_read_b128 v[84:87], v130 offset:9216
	ds_read_b128 v[88:91], v130 offset:10240
	ds_read_b128 v[92:95], v130 offset:11264
	ds_read_b128 v[100:103], v130 offset:12288
	ds_read_b128 v[104:107], v130 offset:13312
	ds_read_b128 v[108:111], v130 offset:14336
	ds_read_b128 v[112:115], v130 offset:15360
	s_waitcnt lgkmcnt(0)
	s_add_i32 m0, vcc_lo, 0x2000
	s_nop 0
	global_load_lds_dwordx4 v[14:15], off
	v_lshl_add_u64 v[14:15], v[14:15], 0, s[94:95]
	s_add_i32 m0, vcc_lo, 0x2400
	s_nop 0
	global_load_lds_dwordx4 v[26:27], off
	v_lshl_add_u64 v[26:27], v[26:27], 0, s[94:95]
	s_add_i32 m0, vcc_lo, 0x2800
	s_nop 0
	global_load_lds_dwordx4 v[30:31], off
	v_lshl_add_u64 v[30:31], v[30:31], 0, s[94:95]
	s_add_i32 m0, vcc_lo, 0x2c00
	s_nop 0
	global_load_lds_dwordx4 v[70:71], off
	v_lshl_add_u64 v[70:71], v[70:71], 0, s[94:95]
	s_add_i32 m0, vcc_lo, 0x3000
	s_nop 0
	global_load_lds_dwordx4 v[98:99], off
	v_lshl_add_u64 v[98:99], v[98:99], 0, s[94:95]
	s_add_i32 m0, vcc_lo, 0x3400
	s_nop 0
	global_load_lds_dwordx4 v[116:117], off
	v_lshl_add_u64 v[116:117], v[116:117], 0, s[94:95]
	s_add_i32 m0, vcc_lo, 0x3800
	s_nop 0
	global_load_lds_dwordx4 v[118:119], off
	v_lshl_add_u64 v[118:119], v[118:119], 0, s[94:95]
	s_add_i32 m0, vcc_lo, 0x3c00
	s_nop 0
	global_load_lds_dwordx4 v[120:121], off
	v_lshl_add_u64 v[120:121], v[120:121], 0, s[94:95]
	v_mfma_f32_16x16x32_bf16 v[0:3], v[100:103], v[80:83], v[0:3]
	v_mfma_f32_16x16x32_bf16 v[4:7], v[100:103], v[84:87], v[4:7]
	v_mfma_f32_16x16x32_bf16 v[8:11], v[100:103], v[88:91], v[8:11]
	v_mfma_f32_16x16x32_bf16 v[16:19], v[100:103], v[92:95], v[16:19]
	v_mfma_f32_16x16x32_bf16 v[20:23], v[104:107], v[80:83], v[20:23]
	v_mfma_f32_16x16x32_bf16 v[32:35], v[104:107], v[84:87], v[32:35]
	v_mfma_f32_16x16x32_bf16 v[36:39], v[104:107], v[88:91], v[36:39]
	v_mfma_f32_16x16x32_bf16 v[40:43], v[104:107], v[92:95], v[40:43]
	v_mfma_f32_16x16x32_bf16 v[44:47], v[108:111], v[80:83], v[44:47]
	v_mfma_f32_16x16x32_bf16 v[48:51], v[108:111], v[84:87], v[48:51]
	v_mfma_f32_16x16x32_bf16 v[52:55], v[108:111], v[88:91], v[52:55]
	v_mfma_f32_16x16x32_bf16 v[56:59], v[108:111], v[92:95], v[56:59]
	v_mfma_f32_16x16x32_bf16 v[60:63], v[112:115], v[80:83], v[60:63]
	v_mfma_f32_16x16x32_bf16 v[64:67], v[112:115], v[84:87], v[64:67]
	v_mfma_f32_16x16x32_bf16 v[72:75], v[112:115], v[88:91], v[72:75]
	v_mfma_f32_16x16x32_bf16 v[76:79], v[112:115], v[92:95], v[76:79]
	s_waitcnt vmcnt(8)
	ds_read_b128 v[80:83], v130
	ds_read_b128 v[84:87], v130 offset:1024
	ds_read_b128 v[88:91], v130 offset:2048
	ds_read_b128 v[92:95], v130 offset:3072
	ds_read_b128 v[100:103], v130 offset:4096
	ds_read_b128 v[104:107], v130 offset:5120
	ds_read_b128 v[108:111], v130 offset:6144
	ds_read_b128 v[112:115], v130 offset:7168
	s_waitcnt lgkmcnt(0)
	s_add_i32 m0, vcc_lo, 0x0
	s_nop 0
	global_load_lds_dwordx4 v[14:15], off
	v_lshl_add_u64 v[14:15], v[14:15], 0, s[94:95]
	s_add_i32 m0, vcc_lo, 0x400
	s_nop 0
	global_load_lds_dwordx4 v[26:27], off
	v_lshl_add_u64 v[26:27], v[26:27], 0, s[94:95]
	s_add_i32 m0, vcc_lo, 0x800
	s_nop 0
	global_load_lds_dwordx4 v[30:31], off
	v_lshl_add_u64 v[30:31], v[30:31], 0, s[94:95]
	s_add_i32 m0, vcc_lo, 0xc00
	s_nop 0
	global_load_lds_dwordx4 v[70:71], off
	v_lshl_add_u64 v[70:71], v[70:71], 0, s[94:95]
	s_add_i32 m0, vcc_lo, 0x1000
	s_nop 0
	global_load_lds_dwordx4 v[98:99], off
	v_lshl_add_u64 v[98:99], v[98:99], 0, s[94:95]
	s_add_i32 m0, vcc_lo, 0x1400
	s_nop 0
	global_load_lds_dwordx4 v[116:117], off
	v_lshl_add_u64 v[116:117], v[116:117], 0, s[94:95]
	s_add_i32 m0, vcc_lo, 0x1800
	s_nop 0
	global_load_lds_dwordx4 v[118:119], off
	v_lshl_add_u64 v[118:119], v[118:119], 0, s[94:95]
	s_add_i32 m0, vcc_lo, 0x1c00
	s_nop 0
	global_load_lds_dwordx4 v[120:121], off
	v_lshl_add_u64 v[120:121], v[120:121], 0, s[94:95]
	v_mfma_f32_16x16x32_bf16 v[0:3], v[100:103], v[80:83], v[0:3]
	v_mfma_f32_16x16x32_bf16 v[4:7], v[100:103], v[84:87], v[4:7]
	v_mfma_f32_16x16x32_bf16 v[8:11], v[100:103], v[88:91], v[8:11]
	v_mfma_f32_16x16x32_bf16 v[16:19], v[100:103], v[92:95], v[16:19]
	v_mfma_f32_16x16x32_bf16 v[20:23], v[104:107], v[80:83], v[20:23]
	v_mfma_f32_16x16x32_bf16 v[32:35], v[104:107], v[84:87], v[32:35]
	v_mfma_f32_16x16x32_bf16 v[36:39], v[104:107], v[88:91], v[36:39]
	v_mfma_f32_16x16x32_bf16 v[40:43], v[104:107], v[92:95], v[40:43]
	v_mfma_f32_16x16x32_bf16 v[44:47], v[108:111], v[80:83], v[44:47]
	v_mfma_f32_16x16x32_bf16 v[48:51], v[108:111], v[84:87], v[48:51]
	v_mfma_f32_16x16x32_bf16 v[52:55], v[108:111], v[88:91], v[52:55]
	v_mfma_f32_16x16x32_bf16 v[56:59], v[108:111], v[92:95], v[56:59]
	v_mfma_f32_16x16x32_bf16 v[60:63], v[112:115], v[80:83], v[60:63]
	v_mfma_f32_16x16x32_bf16 v[64:67], v[112:115], v[84:87], v[64:67]
	v_mfma_f32_16x16x32_bf16 v[72:75], v[112:115], v[88:91], v[72:75]
	v_mfma_f32_16x16x32_bf16 v[76:79], v[112:115], v[92:95], v[76:79]
	s_waitcnt vmcnt(8)
	ds_read_b128 v[80:83], v130 offset:8192
	ds_read_b128 v[84:87], v130 offset:9216
	ds_read_b128 v[88:91], v130 offset:10240
	ds_read_b128 v[92:95], v130 offset:11264
	ds_read_b128 v[100:103], v130 offset:12288
	ds_read_b128 v[104:107], v130 offset:13312
	ds_read_b128 v[108:111], v130 offset:14336
	ds_read_b128 v[112:115], v130 offset:15360
	s_waitcnt lgkmcnt(0)
	s_add_i32 m0, vcc_lo, 0x2000
	s_nop 0
	global_load_lds_dwordx4 v[14:15], off
	v_lshl_add_u64 v[14:15], v[14:15], 0, s[94:95]
	s_add_i32 m0, vcc_lo, 0x2400
	s_nop 0
	global_load_lds_dwordx4 v[26:27], off
	v_lshl_add_u64 v[26:27], v[26:27], 0, s[94:95]
	s_add_i32 m0, vcc_lo, 0x2800
	s_nop 0
	global_load_lds_dwordx4 v[30:31], off
	v_lshl_add_u64 v[30:31], v[30:31], 0, s[94:95]
	s_add_i32 m0, vcc_lo, 0x2c00
	s_nop 0
	global_load_lds_dwordx4 v[70:71], off
	v_lshl_add_u64 v[70:71], v[70:71], 0, s[94:95]
	s_add_i32 m0, vcc_lo, 0x3000
	s_nop 0
	global_load_lds_dwordx4 v[98:99], off
	v_lshl_add_u64 v[98:99], v[98:99], 0, s[94:95]
	s_add_i32 m0, vcc_lo, 0x3400
	s_nop 0
	global_load_lds_dwordx4 v[116:117], off
	v_lshl_add_u64 v[116:117], v[116:117], 0, s[94:95]
	s_add_i32 m0, vcc_lo, 0x3800
	s_nop 0
	global_load_lds_dwordx4 v[118:119], off
	v_lshl_add_u64 v[118:119], v[118:119], 0, s[94:95]
	s_add_i32 m0, vcc_lo, 0x3c00
	s_nop 0
	global_load_lds_dwordx4 v[120:121], off
	v_lshl_add_u64 v[120:121], v[120:121], 0, s[94:95]
	v_mfma_f32_16x16x32_bf16 v[0:3], v[100:103], v[80:83], v[0:3]
	v_mfma_f32_16x16x32_bf16 v[4:7], v[100:103], v[84:87], v[4:7]
	v_mfma_f32_16x16x32_bf16 v[8:11], v[100:103], v[88:91], v[8:11]
	v_mfma_f32_16x16x32_bf16 v[16:19], v[100:103], v[92:95], v[16:19]
	v_mfma_f32_16x16x32_bf16 v[20:23], v[104:107], v[80:83], v[20:23]
	v_mfma_f32_16x16x32_bf16 v[32:35], v[104:107], v[84:87], v[32:35]
	v_mfma_f32_16x16x32_bf16 v[36:39], v[104:107], v[88:91], v[36:39]
	v_mfma_f32_16x16x32_bf16 v[40:43], v[104:107], v[92:95], v[40:43]
	v_mfma_f32_16x16x32_bf16 v[44:47], v[108:111], v[80:83], v[44:47]
	v_mfma_f32_16x16x32_bf16 v[48:51], v[108:111], v[84:87], v[48:51]
	v_mfma_f32_16x16x32_bf16 v[52:55], v[108:111], v[88:91], v[52:55]
	v_mfma_f32_16x16x32_bf16 v[56:59], v[108:111], v[92:95], v[56:59]
	v_mfma_f32_16x16x32_bf16 v[60:63], v[112:115], v[80:83], v[60:63]
	v_mfma_f32_16x16x32_bf16 v[64:67], v[112:115], v[84:87], v[64:67]
	v_mfma_f32_16x16x32_bf16 v[72:75], v[112:115], v[88:91], v[72:75]
	v_mfma_f32_16x16x32_bf16 v[76:79], v[112:115], v[92:95], v[76:79]
	s_waitcnt vmcnt(8)
	ds_read_b128 v[80:83], v130
	ds_read_b128 v[84:87], v130 offset:1024
	ds_read_b128 v[88:91], v130 offset:2048
	ds_read_b128 v[92:95], v130 offset:3072
	ds_read_b128 v[100:103], v130 offset:4096
	ds_read_b128 v[104:107], v130 offset:5120
	ds_read_b128 v[108:111], v130 offset:6144
	ds_read_b128 v[112:115], v130 offset:7168
	s_waitcnt lgkmcnt(0)
	s_add_i32 m0, vcc_lo, 0x0
	s_nop 0
	global_load_lds_dwordx4 v[14:15], off
	v_lshl_add_u64 v[14:15], v[14:15], 0, s[94:95]
	s_add_i32 m0, vcc_lo, 0x400
	s_nop 0
	global_load_lds_dwordx4 v[26:27], off
	v_lshl_add_u64 v[26:27], v[26:27], 0, s[94:95]
	s_add_i32 m0, vcc_lo, 0x800
	s_nop 0
	global_load_lds_dwordx4 v[30:31], off
	v_lshl_add_u64 v[30:31], v[30:31], 0, s[94:95]
	s_add_i32 m0, vcc_lo, 0xc00
	s_nop 0
	global_load_lds_dwordx4 v[70:71], off
	v_lshl_add_u64 v[70:71], v[70:71], 0, s[94:95]
	s_add_i32 m0, vcc_lo, 0x1000
	s_nop 0
	global_load_lds_dwordx4 v[98:99], off
	v_lshl_add_u64 v[98:99], v[98:99], 0, s[94:95]
	s_add_i32 m0, vcc_lo, 0x1400
	s_nop 0
	global_load_lds_dwordx4 v[116:117], off
	v_lshl_add_u64 v[116:117], v[116:117], 0, s[94:95]
	s_add_i32 m0, vcc_lo, 0x1800
	s_nop 0
	global_load_lds_dwordx4 v[118:119], off
	v_lshl_add_u64 v[118:119], v[118:119], 0, s[94:95]
	s_add_i32 m0, vcc_lo, 0x1c00
	s_nop 0
	global_load_lds_dwordx4 v[120:121], off
	v_lshl_add_u64 v[120:121], v[120:121], 0, s[94:95]
	v_mfma_f32_16x16x32_bf16 v[0:3], v[100:103], v[80:83], v[0:3]
	v_mfma_f32_16x16x32_bf16 v[4:7], v[100:103], v[84:87], v[4:7]
	v_mfma_f32_16x16x32_bf16 v[8:11], v[100:103], v[88:91], v[8:11]
	v_mfma_f32_16x16x32_bf16 v[16:19], v[100:103], v[92:95], v[16:19]
	v_mfma_f32_16x16x32_bf16 v[20:23], v[104:107], v[80:83], v[20:23]
	v_mfma_f32_16x16x32_bf16 v[32:35], v[104:107], v[84:87], v[32:35]
	v_mfma_f32_16x16x32_bf16 v[36:39], v[104:107], v[88:91], v[36:39]
	v_mfma_f32_16x16x32_bf16 v[40:43], v[104:107], v[92:95], v[40:43]
	v_mfma_f32_16x16x32_bf16 v[44:47], v[108:111], v[80:83], v[44:47]
	v_mfma_f32_16x16x32_bf16 v[48:51], v[108:111], v[84:87], v[48:51]
	v_mfma_f32_16x16x32_bf16 v[52:55], v[108:111], v[88:91], v[52:55]
	v_mfma_f32_16x16x32_bf16 v[56:59], v[108:111], v[92:95], v[56:59]
	v_mfma_f32_16x16x32_bf16 v[60:63], v[112:115], v[80:83], v[60:63]
	v_mfma_f32_16x16x32_bf16 v[64:67], v[112:115], v[84:87], v[64:67]
	v_mfma_f32_16x16x32_bf16 v[72:75], v[112:115], v[88:91], v[72:75]
	v_mfma_f32_16x16x32_bf16 v[76:79], v[112:115], v[92:95], v[76:79]
	s_waitcnt vmcnt(8)
	ds_read_b128 v[80:83], v130 offset:8192
	ds_read_b128 v[84:87], v130 offset:9216
	ds_read_b128 v[88:91], v130 offset:10240
	ds_read_b128 v[92:95], v130 offset:11264
	ds_read_b128 v[100:103], v130 offset:12288
	ds_read_b128 v[104:107], v130 offset:13312
	ds_read_b128 v[108:111], v130 offset:14336
	ds_read_b128 v[112:115], v130 offset:15360
	s_waitcnt lgkmcnt(0)
	s_add_i32 m0, vcc_lo, 0x2000
	s_nop 0
	global_load_lds_dwordx4 v[14:15], off
	v_lshl_add_u64 v[14:15], v[14:15], 0, s[94:95]
	s_add_i32 m0, vcc_lo, 0x2400
	s_nop 0
	global_load_lds_dwordx4 v[26:27], off
	v_lshl_add_u64 v[26:27], v[26:27], 0, s[94:95]
	s_add_i32 m0, vcc_lo, 0x2800
	s_nop 0
	global_load_lds_dwordx4 v[30:31], off
	v_lshl_add_u64 v[30:31], v[30:31], 0, s[94:95]
	s_add_i32 m0, vcc_lo, 0x2c00
	s_nop 0
	global_load_lds_dwordx4 v[70:71], off
	v_lshl_add_u64 v[70:71], v[70:71], 0, s[94:95]
	s_add_i32 m0, vcc_lo, 0x3000
	s_nop 0
	global_load_lds_dwordx4 v[98:99], off
	v_lshl_add_u64 v[98:99], v[98:99], 0, s[94:95]
	s_add_i32 m0, vcc_lo, 0x3400
	s_nop 0
	global_load_lds_dwordx4 v[116:117], off
	v_lshl_add_u64 v[116:117], v[116:117], 0, s[94:95]
	s_add_i32 m0, vcc_lo, 0x3800
	s_nop 0
	global_load_lds_dwordx4 v[118:119], off
	v_lshl_add_u64 v[118:119], v[118:119], 0, s[94:95]
	s_add_i32 m0, vcc_lo, 0x3c00
	s_nop 0
	global_load_lds_dwordx4 v[120:121], off
	v_lshl_add_u64 v[120:121], v[120:121], 0, s[94:95]
	v_mfma_f32_16x16x32_bf16 v[0:3], v[100:103], v[80:83], v[0:3]
	v_mfma_f32_16x16x32_bf16 v[4:7], v[100:103], v[84:87], v[4:7]
	v_mfma_f32_16x16x32_bf16 v[8:11], v[100:103], v[88:91], v[8:11]
	v_mfma_f32_16x16x32_bf16 v[16:19], v[100:103], v[92:95], v[16:19]
	v_mfma_f32_16x16x32_bf16 v[20:23], v[104:107], v[80:83], v[20:23]
	v_mfma_f32_16x16x32_bf16 v[32:35], v[104:107], v[84:87], v[32:35]
	v_mfma_f32_16x16x32_bf16 v[36:39], v[104:107], v[88:91], v[36:39]
	v_mfma_f32_16x16x32_bf16 v[40:43], v[104:107], v[92:95], v[40:43]
	v_mfma_f32_16x16x32_bf16 v[44:47], v[108:111], v[80:83], v[44:47]
	v_mfma_f32_16x16x32_bf16 v[48:51], v[108:111], v[84:87], v[48:51]
	v_mfma_f32_16x16x32_bf16 v[52:55], v[108:111], v[88:91], v[52:55]
	v_mfma_f32_16x16x32_bf16 v[56:59], v[108:111], v[92:95], v[56:59]
	v_mfma_f32_16x16x32_bf16 v[60:63], v[112:115], v[80:83], v[60:63]
	v_mfma_f32_16x16x32_bf16 v[64:67], v[112:115], v[84:87], v[64:67]
	v_mfma_f32_16x16x32_bf16 v[72:75], v[112:115], v[88:91], v[72:75]
	v_mfma_f32_16x16x32_bf16 v[76:79], v[112:115], v[92:95], v[76:79]
	s_waitcnt vmcnt(8)
	ds_read_b128 v[80:83], v130
	ds_read_b128 v[84:87], v130 offset:1024
	ds_read_b128 v[88:91], v130 offset:2048
	ds_read_b128 v[92:95], v130 offset:3072
	ds_read_b128 v[100:103], v130 offset:4096
	ds_read_b128 v[104:107], v130 offset:5120
	ds_read_b128 v[108:111], v130 offset:6144
	ds_read_b128 v[112:115], v130 offset:7168
	s_waitcnt lgkmcnt(0)
	s_add_i32 m0, vcc_lo, 0x0
	s_nop 0
	global_load_lds_dwordx4 v[14:15], off
	v_lshl_add_u64 v[14:15], v[14:15], 0, s[94:95]
	s_add_i32 m0, vcc_lo, 0x400
	s_nop 0
	global_load_lds_dwordx4 v[26:27], off
	v_lshl_add_u64 v[26:27], v[26:27], 0, s[94:95]
	s_add_i32 m0, vcc_lo, 0x800
	s_nop 0
	global_load_lds_dwordx4 v[30:31], off
	v_lshl_add_u64 v[30:31], v[30:31], 0, s[94:95]
	s_add_i32 m0, vcc_lo, 0xc00
	s_nop 0
	global_load_lds_dwordx4 v[70:71], off
	v_lshl_add_u64 v[70:71], v[70:71], 0, s[94:95]
	s_add_i32 m0, vcc_lo, 0x1000
	s_nop 0
	global_load_lds_dwordx4 v[98:99], off
	v_lshl_add_u64 v[98:99], v[98:99], 0, s[94:95]
	s_add_i32 m0, vcc_lo, 0x1400
	s_nop 0
	global_load_lds_dwordx4 v[116:117], off
	v_lshl_add_u64 v[116:117], v[116:117], 0, s[94:95]
	s_add_i32 m0, vcc_lo, 0x1800
	s_nop 0
	global_load_lds_dwordx4 v[118:119], off
	v_lshl_add_u64 v[118:119], v[118:119], 0, s[94:95]
	s_add_i32 m0, vcc_lo, 0x1c00
	s_nop 0
	global_load_lds_dwordx4 v[120:121], off
	v_lshl_add_u64 v[120:121], v[120:121], 0, s[94:95]
	v_mfma_f32_16x16x32_bf16 v[0:3], v[100:103], v[80:83], v[0:3]
	v_mfma_f32_16x16x32_bf16 v[4:7], v[100:103], v[84:87], v[4:7]
	v_mfma_f32_16x16x32_bf16 v[8:11], v[100:103], v[88:91], v[8:11]
	v_mfma_f32_16x16x32_bf16 v[16:19], v[100:103], v[92:95], v[16:19]
	v_mfma_f32_16x16x32_bf16 v[20:23], v[104:107], v[80:83], v[20:23]
	v_mfma_f32_16x16x32_bf16 v[32:35], v[104:107], v[84:87], v[32:35]
	v_mfma_f32_16x16x32_bf16 v[36:39], v[104:107], v[88:91], v[36:39]
	v_mfma_f32_16x16x32_bf16 v[40:43], v[104:107], v[92:95], v[40:43]
	v_mfma_f32_16x16x32_bf16 v[44:47], v[108:111], v[80:83], v[44:47]
	v_mfma_f32_16x16x32_bf16 v[48:51], v[108:111], v[84:87], v[48:51]
	v_mfma_f32_16x16x32_bf16 v[52:55], v[108:111], v[88:91], v[52:55]
	v_mfma_f32_16x16x32_bf16 v[56:59], v[108:111], v[92:95], v[56:59]
	v_mfma_f32_16x16x32_bf16 v[60:63], v[112:115], v[80:83], v[60:63]
	v_mfma_f32_16x16x32_bf16 v[64:67], v[112:115], v[84:87], v[64:67]
	v_mfma_f32_16x16x32_bf16 v[72:75], v[112:115], v[88:91], v[72:75]
	v_mfma_f32_16x16x32_bf16 v[76:79], v[112:115], v[92:95], v[76:79]
	s_waitcnt vmcnt(8)
	ds_read_b128 v[80:83], v130 offset:8192
	ds_read_b128 v[84:87], v130 offset:9216
	ds_read_b128 v[88:91], v130 offset:10240
	ds_read_b128 v[92:95], v130 offset:11264
	ds_read_b128 v[100:103], v130 offset:12288
	ds_read_b128 v[104:107], v130 offset:13312
	ds_read_b128 v[108:111], v130 offset:14336
	ds_read_b128 v[112:115], v130 offset:15360
	s_waitcnt lgkmcnt(0)
	s_add_i32 m0, vcc_lo, 0x2000
	s_nop 0
	global_load_lds_dwordx4 v[14:15], off
	v_lshl_add_u64 v[14:15], v[14:15], 0, s[94:95]
	s_add_i32 m0, vcc_lo, 0x2400
	s_nop 0
	global_load_lds_dwordx4 v[26:27], off
	v_lshl_add_u64 v[26:27], v[26:27], 0, s[94:95]
	s_add_i32 m0, vcc_lo, 0x2800
	s_nop 0
	global_load_lds_dwordx4 v[30:31], off
	v_lshl_add_u64 v[30:31], v[30:31], 0, s[94:95]
	s_add_i32 m0, vcc_lo, 0x2c00
	s_nop 0
	global_load_lds_dwordx4 v[70:71], off
	v_lshl_add_u64 v[70:71], v[70:71], 0, s[94:95]
	s_add_i32 m0, vcc_lo, 0x3000
	s_nop 0
	global_load_lds_dwordx4 v[98:99], off
	v_lshl_add_u64 v[98:99], v[98:99], 0, s[94:95]
	s_add_i32 m0, vcc_lo, 0x3400
	s_nop 0
	global_load_lds_dwordx4 v[116:117], off
	v_lshl_add_u64 v[116:117], v[116:117], 0, s[94:95]
	s_add_i32 m0, vcc_lo, 0x3800
	s_nop 0
	global_load_lds_dwordx4 v[118:119], off
	v_lshl_add_u64 v[118:119], v[118:119], 0, s[94:95]
	s_add_i32 m0, vcc_lo, 0x3c00
	s_nop 0
	global_load_lds_dwordx4 v[120:121], off
	v_lshl_add_u64 v[120:121], v[120:121], 0, s[94:95]
	v_mfma_f32_16x16x32_bf16 v[0:3], v[100:103], v[80:83], v[0:3]
	v_mfma_f32_16x16x32_bf16 v[4:7], v[100:103], v[84:87], v[4:7]
	v_mfma_f32_16x16x32_bf16 v[8:11], v[100:103], v[88:91], v[8:11]
	v_mfma_f32_16x16x32_bf16 v[16:19], v[100:103], v[92:95], v[16:19]
	v_mfma_f32_16x16x32_bf16 v[20:23], v[104:107], v[80:83], v[20:23]
	v_mfma_f32_16x16x32_bf16 v[32:35], v[104:107], v[84:87], v[32:35]
	v_mfma_f32_16x16x32_bf16 v[36:39], v[104:107], v[88:91], v[36:39]
	v_mfma_f32_16x16x32_bf16 v[40:43], v[104:107], v[92:95], v[40:43]
	v_mfma_f32_16x16x32_bf16 v[44:47], v[108:111], v[80:83], v[44:47]
	v_mfma_f32_16x16x32_bf16 v[48:51], v[108:111], v[84:87], v[48:51]
	v_mfma_f32_16x16x32_bf16 v[52:55], v[108:111], v[88:91], v[52:55]
	v_mfma_f32_16x16x32_bf16 v[56:59], v[108:111], v[92:95], v[56:59]
	v_mfma_f32_16x16x32_bf16 v[60:63], v[112:115], v[80:83], v[60:63]
	v_mfma_f32_16x16x32_bf16 v[64:67], v[112:115], v[84:87], v[64:67]
	v_mfma_f32_16x16x32_bf16 v[72:75], v[112:115], v[88:91], v[72:75]
	v_mfma_f32_16x16x32_bf16 v[76:79], v[112:115], v[92:95], v[76:79]
	s_waitcnt vmcnt(8)
	ds_read_b128 v[80:83], v130
	ds_read_b128 v[84:87], v130 offset:1024
	ds_read_b128 v[88:91], v130 offset:2048
	ds_read_b128 v[92:95], v130 offset:3072
	ds_read_b128 v[100:103], v130 offset:4096
	ds_read_b128 v[104:107], v130 offset:5120
	ds_read_b128 v[108:111], v130 offset:6144
	ds_read_b128 v[112:115], v130 offset:7168
	s_waitcnt lgkmcnt(0)
	s_add_i32 m0, vcc_lo, 0x0
	s_nop 0
	global_load_lds_dwordx4 v[14:15], off
	v_lshl_add_u64 v[14:15], v[14:15], 0, s[94:95]
	s_add_i32 m0, vcc_lo, 0x400
	s_nop 0
	global_load_lds_dwordx4 v[26:27], off
	v_lshl_add_u64 v[26:27], v[26:27], 0, s[94:95]
	s_add_i32 m0, vcc_lo, 0x800
	s_nop 0
	global_load_lds_dwordx4 v[30:31], off
	v_lshl_add_u64 v[30:31], v[30:31], 0, s[94:95]
	s_add_i32 m0, vcc_lo, 0xc00
	s_nop 0
	global_load_lds_dwordx4 v[70:71], off
	v_lshl_add_u64 v[70:71], v[70:71], 0, s[94:95]
	s_add_i32 m0, vcc_lo, 0x1000
	s_nop 0
	global_load_lds_dwordx4 v[98:99], off
	v_lshl_add_u64 v[98:99], v[98:99], 0, s[94:95]
	s_add_i32 m0, vcc_lo, 0x1400
	s_nop 0
	global_load_lds_dwordx4 v[116:117], off
	v_lshl_add_u64 v[116:117], v[116:117], 0, s[94:95]
	s_add_i32 m0, vcc_lo, 0x1800
	s_nop 0
	global_load_lds_dwordx4 v[118:119], off
	v_lshl_add_u64 v[118:119], v[118:119], 0, s[94:95]
	s_add_i32 m0, vcc_lo, 0x1c00
	s_nop 0
	global_load_lds_dwordx4 v[120:121], off
	v_lshl_add_u64 v[120:121], v[120:121], 0, s[94:95]
	v_mfma_f32_16x16x32_bf16 v[0:3], v[100:103], v[80:83], v[0:3]
	v_mfma_f32_16x16x32_bf16 v[4:7], v[100:103], v[84:87], v[4:7]
	v_mfma_f32_16x16x32_bf16 v[8:11], v[100:103], v[88:91], v[8:11]
	v_mfma_f32_16x16x32_bf16 v[16:19], v[100:103], v[92:95], v[16:19]
	v_mfma_f32_16x16x32_bf16 v[20:23], v[104:107], v[80:83], v[20:23]
	v_mfma_f32_16x16x32_bf16 v[32:35], v[104:107], v[84:87], v[32:35]
	v_mfma_f32_16x16x32_bf16 v[36:39], v[104:107], v[88:91], v[36:39]
	v_mfma_f32_16x16x32_bf16 v[40:43], v[104:107], v[92:95], v[40:43]
	v_mfma_f32_16x16x32_bf16 v[44:47], v[108:111], v[80:83], v[44:47]
	v_mfma_f32_16x16x32_bf16 v[48:51], v[108:111], v[84:87], v[48:51]
	v_mfma_f32_16x16x32_bf16 v[52:55], v[108:111], v[88:91], v[52:55]
	v_mfma_f32_16x16x32_bf16 v[56:59], v[108:111], v[92:95], v[56:59]
	v_mfma_f32_16x16x32_bf16 v[60:63], v[112:115], v[80:83], v[60:63]
	v_mfma_f32_16x16x32_bf16 v[64:67], v[112:115], v[84:87], v[64:67]
	v_mfma_f32_16x16x32_bf16 v[72:75], v[112:115], v[88:91], v[72:75]
	v_mfma_f32_16x16x32_bf16 v[76:79], v[112:115], v[92:95], v[76:79]
	s_waitcnt vmcnt(8)
	ds_read_b128 v[80:83], v130 offset:8192
	ds_read_b128 v[84:87], v130 offset:9216
	ds_read_b128 v[88:91], v130 offset:10240
	ds_read_b128 v[92:95], v130 offset:11264
	ds_read_b128 v[100:103], v130 offset:12288
	ds_read_b128 v[104:107], v130 offset:13312
	ds_read_b128 v[108:111], v130 offset:14336
	ds_read_b128 v[112:115], v130 offset:15360
	s_waitcnt lgkmcnt(0)
	s_add_i32 m0, vcc_lo, 0x2000
	s_nop 0
	global_load_lds_dwordx4 v[14:15], off
	v_lshl_add_u64 v[14:15], v[14:15], 0, s[94:95]
	s_add_i32 m0, vcc_lo, 0x2400
	s_nop 0
	global_load_lds_dwordx4 v[26:27], off
	v_lshl_add_u64 v[26:27], v[26:27], 0, s[94:95]
	s_add_i32 m0, vcc_lo, 0x2800
	s_nop 0
	global_load_lds_dwordx4 v[30:31], off
	v_lshl_add_u64 v[30:31], v[30:31], 0, s[94:95]
	s_add_i32 m0, vcc_lo, 0x2c00
	s_nop 0
	global_load_lds_dwordx4 v[70:71], off
	v_lshl_add_u64 v[70:71], v[70:71], 0, s[94:95]
	s_add_i32 m0, vcc_lo, 0x3000
	s_nop 0
	global_load_lds_dwordx4 v[98:99], off
	v_lshl_add_u64 v[98:99], v[98:99], 0, s[94:95]
	s_add_i32 m0, vcc_lo, 0x3400
	s_nop 0
	global_load_lds_dwordx4 v[116:117], off
	v_lshl_add_u64 v[116:117], v[116:117], 0, s[94:95]
	s_add_i32 m0, vcc_lo, 0x3800
	s_nop 0
	global_load_lds_dwordx4 v[118:119], off
	v_lshl_add_u64 v[118:119], v[118:119], 0, s[94:95]
	s_add_i32 m0, vcc_lo, 0x3c00
	s_nop 0
	global_load_lds_dwordx4 v[120:121], off
	v_lshl_add_u64 v[120:121], v[120:121], 0, s[94:95]
	v_mfma_f32_16x16x32_bf16 v[0:3], v[100:103], v[80:83], v[0:3]
	v_mfma_f32_16x16x32_bf16 v[4:7], v[100:103], v[84:87], v[4:7]
	v_mfma_f32_16x16x32_bf16 v[8:11], v[100:103], v[88:91], v[8:11]
	v_mfma_f32_16x16x32_bf16 v[16:19], v[100:103], v[92:95], v[16:19]
	v_mfma_f32_16x16x32_bf16 v[20:23], v[104:107], v[80:83], v[20:23]
	v_mfma_f32_16x16x32_bf16 v[32:35], v[104:107], v[84:87], v[32:35]
	v_mfma_f32_16x16x32_bf16 v[36:39], v[104:107], v[88:91], v[36:39]
	v_mfma_f32_16x16x32_bf16 v[40:43], v[104:107], v[92:95], v[40:43]
	v_mfma_f32_16x16x32_bf16 v[44:47], v[108:111], v[80:83], v[44:47]
	v_mfma_f32_16x16x32_bf16 v[48:51], v[108:111], v[84:87], v[48:51]
	v_mfma_f32_16x16x32_bf16 v[52:55], v[108:111], v[88:91], v[52:55]
	v_mfma_f32_16x16x32_bf16 v[56:59], v[108:111], v[92:95], v[56:59]
	v_mfma_f32_16x16x32_bf16 v[60:63], v[112:115], v[80:83], v[60:63]
	v_mfma_f32_16x16x32_bf16 v[64:67], v[112:115], v[84:87], v[64:67]
	v_mfma_f32_16x16x32_bf16 v[72:75], v[112:115], v[88:91], v[72:75]
	v_mfma_f32_16x16x32_bf16 v[76:79], v[112:115], v[92:95], v[76:79]
	s_waitcnt vmcnt(8)
	ds_read_b128 v[80:83], v130
	ds_read_b128 v[84:87], v130 offset:1024
	ds_read_b128 v[88:91], v130 offset:2048
	ds_read_b128 v[92:95], v130 offset:3072
	ds_read_b128 v[100:103], v130 offset:4096
	ds_read_b128 v[104:107], v130 offset:5120
	ds_read_b128 v[108:111], v130 offset:6144
	ds_read_b128 v[112:115], v130 offset:7168
	s_waitcnt lgkmcnt(0)
	v_mfma_f32_16x16x32_bf16 v[0:3], v[100:103], v[80:83], v[0:3]
	v_mfma_f32_16x16x32_bf16 v[4:7], v[100:103], v[84:87], v[4:7]
	v_mfma_f32_16x16x32_bf16 v[8:11], v[100:103], v[88:91], v[8:11]
	v_mfma_f32_16x16x32_bf16 v[16:19], v[100:103], v[92:95], v[16:19]
	v_mfma_f32_16x16x32_bf16 v[20:23], v[104:107], v[80:83], v[20:23]
	v_mfma_f32_16x16x32_bf16 v[32:35], v[104:107], v[84:87], v[32:35]
	v_mfma_f32_16x16x32_bf16 v[36:39], v[104:107], v[88:91], v[36:39]
	v_mfma_f32_16x16x32_bf16 v[40:43], v[104:107], v[92:95], v[40:43]
	v_mfma_f32_16x16x32_bf16 v[44:47], v[108:111], v[80:83], v[44:47]
	v_mfma_f32_16x16x32_bf16 v[48:51], v[108:111], v[84:87], v[48:51]
	v_mfma_f32_16x16x32_bf16 v[52:55], v[108:111], v[88:91], v[52:55]
	v_mfma_f32_16x16x32_bf16 v[56:59], v[108:111], v[92:95], v[56:59]
	v_mfma_f32_16x16x32_bf16 v[60:63], v[112:115], v[80:83], v[60:63]
	v_mfma_f32_16x16x32_bf16 v[64:67], v[112:115], v[84:87], v[64:67]
	v_mfma_f32_16x16x32_bf16 v[72:75], v[112:115], v[88:91], v[72:75]
	v_mfma_f32_16x16x32_bf16 v[76:79], v[112:115], v[92:95], v[76:79]
	s_waitcnt vmcnt(0)
	ds_read_b128 v[80:83], v130 offset:8192
	ds_read_b128 v[84:87], v130 offset:9216
	ds_read_b128 v[88:91], v130 offset:10240
	ds_read_b128 v[92:95], v130 offset:11264
	ds_read_b128 v[100:103], v130 offset:12288
	ds_read_b128 v[104:107], v130 offset:13312
	ds_read_b128 v[108:111], v130 offset:14336
	ds_read_b128 v[112:115], v130 offset:15360
	s_waitcnt lgkmcnt(0)
	v_mfma_f32_16x16x32_bf16 v[0:3], v[100:103], v[80:83], v[0:3]
	v_mfma_f32_16x16x32_bf16 v[4:7], v[100:103], v[84:87], v[4:7]
	v_mfma_f32_16x16x32_bf16 v[8:11], v[100:103], v[88:91], v[8:11]
	v_mfma_f32_16x16x32_bf16 v[16:19], v[100:103], v[92:95], v[16:19]
	v_mfma_f32_16x16x32_bf16 v[20:23], v[104:107], v[80:83], v[20:23]
	v_mfma_f32_16x16x32_bf16 v[32:35], v[104:107], v[84:87], v[32:35]
	v_mfma_f32_16x16x32_bf16 v[36:39], v[104:107], v[88:91], v[36:39]
	v_mfma_f32_16x16x32_bf16 v[40:43], v[104:107], v[92:95], v[40:43]
	v_mfma_f32_16x16x32_bf16 v[44:47], v[108:111], v[80:83], v[44:47]
	v_mfma_f32_16x16x32_bf16 v[48:51], v[108:111], v[84:87], v[48:51]
	v_mfma_f32_16x16x32_bf16 v[52:55], v[108:111], v[88:91], v[52:55]
	v_mfma_f32_16x16x32_bf16 v[56:59], v[108:111], v[92:95], v[56:59]
	v_mfma_f32_16x16x32_bf16 v[60:63], v[112:115], v[80:83], v[60:63]
	v_mfma_f32_16x16x32_bf16 v[64:67], v[112:115], v[84:87], v[64:67]
	v_mfma_f32_16x16x32_bf16 v[72:75], v[112:115], v[88:91], v[72:75]
	v_mfma_f32_16x16x32_bf16 v[76:79], v[112:115], v[92:95], v[76:79]
	s_nop 7
	s_nop 3
	v_and_b32_e32 v68, 63, v96
	v_lshl_add_u32 v68, v68, 4, 0
	v_lshl_add_u32 v69, s3, 14, v68
	ds_write_b128 v69, v[0:3]
	ds_write_b128 v69, v[4:7] offset:1024
	ds_write_b128 v69, v[8:11] offset:2048
	ds_write_b128 v69, v[16:19] offset:3072
	ds_write_b128 v69, v[20:23] offset:4096
	ds_write_b128 v69, v[32:35] offset:5120
	ds_write_b128 v69, v[36:39] offset:6144
	ds_write_b128 v69, v[40:43] offset:7168
	ds_write_b128 v69, v[44:47] offset:8192
	ds_write_b128 v69, v[48:51] offset:9216
	ds_write_b128 v69, v[52:55] offset:10240
	ds_write_b128 v69, v[56:59] offset:11264
	ds_write_b128 v69, v[60:63] offset:12288
	ds_write_b128 v69, v[64:67] offset:13312
	ds_write_b128 v69, v[72:75] offset:14336
	ds_write_b128 v69, v[76:79] offset:15360
	s_lshl_b32 s3, s1, 4
	s_addk_i32 s3, 0x4000
	s_waitcnt vmcnt(0) lgkmcnt(0)
	s_nop 2
	s_nop 2
	s_nop 5
	s_nop 5
	s_nop 5
	s_nop 2
	v_or_b32_e32 v12, s3, v97
	v_ashrrev_i32_e32 v13, 31, v12
	s_nop 2
	v_lshrrev_b32_e32 v0, 2, v96
	v_and_b32_e32 v0, 12, v0
	v_lshl_or_b32 v0, s4, 4, v0
	v_or_b32_e32 v26, s0, v0
	v_lshlrev_b64 v[0:1], 12, v[12:13]
	s_ashr_i32 s3, s2, 31
	v_lshl_add_u64 v[0:1], s[8:9], 0, v[0:1]
	v_lshl_add_u64 v[0:1], s[2:3], 1, v[0:1]
	v_lshlrev_b32_e32 v128, 1, v26
	v_lshl_add_u64 v[0:1], v[0:1], 0, v[128:129]
	s_waitcnt lgkmcnt(0)
	s_barrier
	global_load_dwordx2 v[14:15], v[0:1], off
	global_load_dwordx2 v[16:17], v[0:1], off offset:256
	s_lshl_b32 s0, s4, 2
	s_add_i32 s0, s0, s1
	v_lshl_add_u32 v13, s0, 10, v68
	ds_read_b128 v[0:3], v13
	ds_read_b128 v[4:7], v13 offset:8192
	ds_read_b128 v[8:11], v13 offset:16384
	v_lshlrev_b32_e32 v128, 2, v26
	s_waitcnt lgkmcnt(0)
	v_pk_add_f32 v[18:19], v[2:3], 0 op_sel_hi:[1,0]
	v_pk_add_f32 v[20:21], v[0:1], 0 op_sel_hi:[1,0]
	ds_read_b128 v[0:3], v13 offset:24576
	v_pk_add_f32 v[18:19], v[18:19], v[10:11]
	v_pk_add_f32 v[20:21], v[20:21], v[8:9]
	ds_read_b128 v[8:11], v13 offset:40960
	v_pk_add_f32 v[22:23], v[6:7], 0 op_sel_hi:[1,0]
	v_pk_add_f32 v[24:25], v[4:5], 0 op_sel_hi:[1,0]
	ds_read_b128 v[4:7], v13 offset:32768
	s_waitcnt lgkmcnt(0)
	v_pk_add_f32 v[22:23], v[22:23], v[2:3]
	v_pk_add_f32 v[24:25], v[24:25], v[0:1]
	ds_read_b128 v[0:3], v13 offset:49152
	v_pk_add_f32 v[24:25], v[24:25], v[8:9]
	v_add_u32_e32 v8, 0x12000, v13
	v_pk_add_f32 v[22:23], v[22:23], v[10:11]
	ds_read_b128 v[8:11], v8
	v_pk_add_f32 v[18:19], v[18:19], v[6:7]
	v_pk_add_f32 v[20:21], v[20:21], v[4:5]
	ds_read_b128 v[4:7], v13 offset:57344
	s_waitcnt lgkmcnt(0)
	v_pk_add_f32 v[20:21], v[20:21], v[0:1]
	v_add_u32_e32 v0, 0x10000, v13
	v_pk_add_f32 v[18:19], v[18:19], v[2:3]
	ds_read_b128 v[0:3], v0
	v_pk_add_f32 v[4:5], v[24:25], v[4:5]
	v_pk_add_f32 v[6:7], v[22:23], v[6:7]
	v_pk_add_f32 v[24:25], v[4:5], v[8:9]
	v_add_u32_e32 v4, 0x16000, v13
	v_pk_add_f32 v[22:23], v[6:7], v[10:11]
	ds_read_b128 v[4:7], v4
	s_waitcnt lgkmcnt(0)
	v_pk_add_f32 v[20:21], v[20:21], v[0:1]
	v_add_u32_e32 v0, 0x14000, v13
	v_pk_add_f32 v[18:19], v[18:19], v[2:3]
	ds_read_b128 v[0:3], v0
	v_add_u32_e32 v8, 0x18000, v13
	ds_read_b128 v[8:11], v8
	v_pk_add_f32 v[24:25], v[24:25], v[4:5]
	v_add_u32_e32 v4, 0x1c000, v13
	v_pk_add_f32 v[22:23], v[22:23], v[6:7]
	ds_read_b128 v[4:7], v4
	s_waitcnt lgkmcnt(0)
	v_pk_add_f32 v[20:21], v[20:21], v[0:1]
	v_add_u32_e32 v0, 0x1a000, v13
	v_pk_add_f32 v[18:19], v[18:19], v[2:3]
	ds_read_b128 v[0:3], v0
	v_pk_add_f32 v[20:21], v[20:21], v[8:9]
	v_add_u32_e32 v8, 0x1e000, v13
	v_pk_add_f32 v[18:19], v[18:19], v[10:11]
	ds_read_b128 v[8:11], v8
	s_waitcnt lgkmcnt(0)
	v_pk_add_f32 v[0:1], v[24:25], v[0:1]
	v_pk_add_f32 v[4:5], v[20:21], v[4:5]
	v_pk_add_f32 v[2:3], v[22:23], v[2:3]
	v_pk_add_f32 v[6:7], v[18:19], v[6:7]
	v_pk_add_f32 v[8:9], v[0:1], v[8:9]
	v_pk_add_f32 v[10:11], v[2:3], v[10:11]
	s_waitcnt vmcnt(0)
	v_lshlrev_b32_e32 v0, 16, v14
	v_and_b32_e32 v1, 0xffff0000, v14
	v_pk_add_f32 v[0:1], v[4:5], v[0:1]
	v_lshlrev_b32_e32 v4, 16, v16
	v_and_b32_e32 v5, 0xffff0000, v16
	v_pk_add_f32 v[4:5], v[8:9], v[4:5]
	v_mul_hi_i32 v8, v12, s97
	v_lshlrev_b32_e32 v2, 16, v15
	v_and_b32_e32 v3, 0xffff0000, v15
	v_lshrrev_b32_e32 v9, 31, v8
	v_ashrrev_i32_e32 v8, 11, v8
	v_pk_add_f32 v[2:3], v[6:7], v[2:3]
	v_lshlrev_b32_e32 v6, 16, v17
	v_and_b32_e32 v7, 0xffff0000, v17
	v_add_u32_e32 v8, v8, v9
	v_pk_add_f32 v[6:7], v[10:11], v[6:7]
	v_mul_i32_i24_e32 v10, 0xffffeff0, v8
	v_ashrrev_i32_e32 v9, 31, v8
	v_add3_u32 v10, v12, v10, -16
	v_ashrrev_i32_e32 v11, 31, v10
	v_lshlrev_b64 v[8:9], 25, v[8:9]
	v_lshl_add_u64 v[8:9], s[6:7], 0, v[8:9]
	v_lshlrev_b64 v[10:11], 13, v[10:11]
	v_lshl_add_u64 v[8:9], v[8:9], 0, v[10:11]
	v_lshl_add_u64 v[8:9], s[2:3], 2, v[8:9]
	v_lshl_add_u64 v[8:9], v[8:9], 0, v[128:129]
	global_store_dwordx4 v[8:9], v[0:3], off
	global_store_dwordx4 v[8:9], v[4:7], off offset:512
	s_waitcnt lgkmcnt(0)
	s_barrier
